# speedup vs baseline: 1.0686x; 1.0058x over previous
.LBB0_241:
	s_waitcnt vmcnt(0)
	ds_read_b128 v[156:159], v150
	ds_read_b128 v[160:163], v150 offset:1024
	ds_read_b128 v[164:167], v150 offset:2048
	ds_read_b128 v[168:171], v150 offset:3072
	s_add_u32 s42, s40, 0xfffc0080
	s_addc_u32 s43, s41, -1
	s_cmp_eq_u32 s70, 12
	s_cselect_b32 s45, s7, s43
	s_cselect_b32 s44, s31, s42
	s_cselect_b32 s43, s29, s69
	s_cselect_b32 s42, s39, s68
	s_mov_b32 m0, s63
	v_lshl_add_u64 v[144:145], s[40:41], 0, v[140:141]
	ds_read_b128 v[172:175], v148
	ds_read_b128 v[176:179], v148 offset:1024
	ds_read_b128 v[180:183], v148 offset:2048
	ds_read_b128 v[184:187], v148 offset:3072
	ds_read_b128 v[188:191], v148 offset:4096
	ds_read_b128 v[192:195], v148 offset:5120
	ds_read_b128 v[196:199], v148 offset:6144
	ds_read_b128 v[200:203], v148 offset:7168
	global_load_lds_dwordx4 v[144:145], off
	v_lshl_add_u64 v[144:145], s[40:41], 0, v[142:143]
	s_mov_b32 m0, s64
	s_nop 0
	global_load_lds_dwordx4 v[144:145], off
	s_waitcnt lgkmcnt(8)
	s_barrier
	s_waitcnt lgkmcnt(0)
	s_setprio 1
	s_waitcnt lgkmcnt(0)
	v_mfma_f32_16x16x32_bf16 v[124:127], v[156:159], v[172:175], v[124:127]
	v_mfma_f32_16x16x32_bf16 v[120:123], v[164:167], v[172:175], v[120:123]
	v_mfma_f32_16x16x32_bf16 v[112:115], v[156:159], v[180:183], v[112:115]
	v_mfma_f32_16x16x32_bf16 v[104:107], v[164:167], v[180:183], v[104:107]
	v_mfma_f32_16x16x32_bf16 v[96:99], v[156:159], v[188:191], v[96:99]
	v_mfma_f32_16x16x32_bf16 v[88:91], v[164:167], v[188:191], v[88:91]
	v_mfma_f32_16x16x32_bf16 v[76:79], v[156:159], v[196:199], v[76:79]
	v_mfma_f32_16x16x32_bf16 v[72:75], v[164:167], v[196:199], v[72:75]
	v_mfma_f32_16x16x32_bf16 v[124:127], v[160:163], v[176:179], v[124:127]
	v_mfma_f32_16x16x32_bf16 v[120:123], v[168:171], v[176:179], v[120:123]
	v_mfma_f32_16x16x32_bf16 v[112:115], v[160:163], v[184:187], v[112:115]
	v_mfma_f32_16x16x32_bf16 v[104:107], v[168:171], v[184:187], v[104:107]
	v_mfma_f32_16x16x32_bf16 v[96:99], v[160:163], v[192:195], v[96:99]
	v_mfma_f32_16x16x32_bf16 v[88:91], v[168:171], v[192:195], v[88:91]
	v_mfma_f32_16x16x32_bf16 v[76:79], v[160:163], v[200:203], v[76:79]
	v_mfma_f32_16x16x32_bf16 v[72:75], v[168:171], v[200:203], v[72:75]
	s_setprio 0
	s_barrier
	s_mov_b32 m0, s47
	v_lshl_add_u64 v[144:145], s[42:43], 0, v[132:133]
	s_waitcnt vmcnt(0)
	ds_read_b128 v[204:207], v151
	ds_read_b128 v[208:211], v151 offset:1024
	ds_read_b128 v[212:215], v151 offset:2048
	ds_read_b128 v[216:219], v151 offset:3072
	global_load_lds_dwordx4 v[144:145], off
	v_lshl_add_u64 v[220:221], s[42:43], 0, v[128:129]
	s_mov_b32 m0, s48
	s_nop 0
	global_load_lds_dwordx4 v[220:221], off
	s_barrier
	s_waitcnt lgkmcnt(0)
	s_setprio 1
	s_waitcnt lgkmcnt(0)
	v_mfma_f32_16x16x32_bf16 v[116:119], v[204:207], v[172:175], v[116:119]
	v_mfma_f32_16x16x32_bf16 v[108:111], v[212:215], v[172:175], v[108:111]
	v_mfma_f32_16x16x32_bf16 v[100:103], v[204:207], v[180:183], v[100:103]
	v_mfma_f32_16x16x32_bf16 v[92:95], v[212:215], v[180:183], v[92:95]
	v_mfma_f32_16x16x32_bf16 v[84:87], v[204:207], v[188:191], v[84:87]
	v_mfma_f32_16x16x32_bf16 v[80:83], v[212:215], v[188:191], v[80:83]
	v_mfma_f32_16x16x32_bf16 v[68:71], v[204:207], v[196:199], v[68:71]
	v_mfma_f32_16x16x32_bf16 v[64:67], v[212:215], v[196:199], v[64:67]
	v_mfma_f32_16x16x32_bf16 v[116:119], v[208:211], v[176:179], v[116:119]
	v_mfma_f32_16x16x32_bf16 v[108:111], v[216:219], v[176:179], v[108:111]
	v_mfma_f32_16x16x32_bf16 v[100:103], v[208:211], v[184:187], v[100:103]
	v_mfma_f32_16x16x32_bf16 v[92:95], v[216:219], v[184:187], v[92:95]
	v_mfma_f32_16x16x32_bf16 v[84:87], v[208:211], v[192:195], v[84:87]
	v_mfma_f32_16x16x32_bf16 v[80:83], v[216:219], v[192:195], v[80:83]
	v_mfma_f32_16x16x32_bf16 v[68:71], v[208:211], v[200:203], v[68:71]
	v_mfma_f32_16x16x32_bf16 v[64:67], v[216:219], v[200:203], v[64:67]
	s_setprio 0
	s_mov_b32 m0, s46
	v_lshl_add_u64 v[222:223], s[44:45], 0, v[134:135]
	s_barrier
	s_waitcnt vmcnt(0)
	ds_read_b128 v[172:175], v148 offset:16384
	ds_read_b128 v[176:179], v148 offset:17408
	ds_read_b128 v[180:183], v148 offset:18432
	ds_read_b128 v[184:187], v148 offset:19456
	ds_read_b128 v[188:191], v148 offset:20480
	ds_read_b128 v[192:195], v148 offset:21504
	ds_read_b128 v[196:199], v148 offset:22528
	ds_read_b128 v[200:203], v148 offset:23552
	global_load_lds_dwordx4 v[222:223], off
	v_lshl_add_u64 v[224:225], s[44:45], 0, v[130:131]
	s_mov_b32 m0, s49
	s_nop 0
	global_load_lds_dwordx4 v[224:225], off
	s_barrier
	s_waitcnt lgkmcnt(0)
	s_setprio 1
	s_waitcnt lgkmcnt(0)
	v_mfma_f32_16x16x32_bf16 v[60:63], v[156:159], v[172:175], v[60:63]
	v_mfma_f32_16x16x32_bf16 v[56:59], v[164:167], v[172:175], v[56:59]
	v_mfma_f32_16x16x32_bf16 v[48:51], v[156:159], v[180:183], v[48:51]
	v_mfma_f32_16x16x32_bf16 v[40:43], v[164:167], v[180:183], v[40:43]
	v_mfma_f32_16x16x32_bf16 v[32:35], v[156:159], v[188:191], v[32:35]
	v_mfma_f32_16x16x32_bf16 v[24:27], v[164:167], v[188:191], v[24:27]
	v_mfma_f32_16x16x32_bf16 v[12:15], v[156:159], v[196:199], v[12:15]
	v_mfma_f32_16x16x32_bf16 v[8:11], v[164:167], v[196:199], v[8:11]
	v_mfma_f32_16x16x32_bf16 v[60:63], v[160:163], v[176:179], v[60:63]
	v_mfma_f32_16x16x32_bf16 v[56:59], v[168:171], v[176:179], v[56:59]
	v_mfma_f32_16x16x32_bf16 v[48:51], v[160:163], v[184:187], v[48:51]
	v_mfma_f32_16x16x32_bf16 v[40:43], v[168:171], v[184:187], v[40:43]
	v_mfma_f32_16x16x32_bf16 v[32:35], v[160:163], v[192:195], v[32:35]
	v_mfma_f32_16x16x32_bf16 v[24:27], v[168:171], v[192:195], v[24:27]
	v_mfma_f32_16x16x32_bf16 v[12:15], v[160:163], v[200:203], v[12:15]
	v_mfma_f32_16x16x32_bf16 v[8:11], v[168:171], v[200:203], v[8:11]
	s_setprio 0
	s_barrier
	s_add_u32 s72, s42, 0x40000
	s_addc_u32 s73, s43, 0
	s_mov_b32 m0, s50
	v_lshl_add_u64 v[156:157], s[72:73], 0, v[132:133]
	global_load_lds_dwordx4 v[156:157], off
	v_lshl_add_u64 v[156:157], s[72:73], 0, v[128:129]
	s_mov_b32 m0, s51
	s_nop 0
	global_load_lds_dwordx4 v[156:157], off
	s_waitcnt vmcnt(6)
	s_barrier
	s_setprio 1
	v_mfma_f32_16x16x32_bf16 v[52:55], v[204:207], v[172:175], v[52:55]
	v_mfma_f32_16x16x32_bf16 v[44:47], v[212:215], v[172:175], v[44:47]
	v_mfma_f32_16x16x32_bf16 v[36:39], v[204:207], v[180:183], v[36:39]
	v_mfma_f32_16x16x32_bf16 v[28:31], v[212:215], v[180:183], v[28:31]
	v_mfma_f32_16x16x32_bf16 v[20:23], v[204:207], v[188:191], v[20:23]
	v_mfma_f32_16x16x32_bf16 v[16:19], v[212:215], v[188:191], v[16:19]
	v_mfma_f32_16x16x32_bf16 v[4:7], v[204:207], v[196:199], v[4:7]
	v_mfma_f32_16x16x32_bf16 v[0:3], v[212:215], v[196:199], v[0:3]
	v_mfma_f32_16x16x32_bf16 v[52:55], v[208:211], v[176:179], v[52:55]
	v_mfma_f32_16x16x32_bf16 v[44:47], v[216:219], v[176:179], v[44:47]
	v_mfma_f32_16x16x32_bf16 v[36:39], v[208:211], v[184:187], v[36:39]
	v_mfma_f32_16x16x32_bf16 v[28:31], v[216:219], v[184:187], v[28:31]
	v_mfma_f32_16x16x32_bf16 v[20:23], v[208:211], v[192:195], v[20:23]
	v_mfma_f32_16x16x32_bf16 v[16:19], v[216:219], v[192:195], v[16:19]
	v_mfma_f32_16x16x32_bf16 v[4:7], v[208:211], v[200:203], v[4:7]
	v_mfma_f32_16x16x32_bf16 v[0:3], v[216:219], v[200:203], v[0:3]
	s_setprio 0
	s_barrier
	s_waitcnt vmcnt(0)
	ds_read_b128 v[156:159], v152
	ds_read_b128 v[160:163], v152 offset:1024
	ds_read_b128 v[164:167], v152 offset:2048
	ds_read_b128 v[168:171], v152 offset:3072
	s_add_u32 s44, s44, 0x40000
	s_addc_u32 s45, s45, 0
	s_mov_b32 m0, s52
	v_lshl_add_u64 v[204:205], s[44:45], 0, v[134:135]
	ds_read_b128 v[172:175], v148 offset:32768
	ds_read_b128 v[176:179], v148 offset:33792
	ds_read_b128 v[180:183], v148 offset:34816
	ds_read_b128 v[184:187], v148 offset:35840
	ds_read_b128 v[188:191], v148 offset:36864
	ds_read_b128 v[192:195], v148 offset:37888
	ds_read_b128 v[196:199], v148 offset:38912
	ds_read_b128 v[200:203], v148 offset:39936
	global_load_lds_dwordx4 v[204:205], off
	v_lshl_add_u64 v[204:205], s[44:45], 0, v[130:131]
	s_mov_b32 m0, s53
	s_nop 0
	global_load_lds_dwordx4 v[204:205], off
	s_waitcnt lgkmcnt(8)
	s_barrier
	s_waitcnt lgkmcnt(0)
	s_setprio 1
	s_waitcnt lgkmcnt(0)
	v_mfma_f32_16x16x32_bf16 v[124:127], v[156:159], v[172:175], v[124:127]
	v_mfma_f32_16x16x32_bf16 v[120:123], v[164:167], v[172:175], v[120:123]
	v_mfma_f32_16x16x32_bf16 v[112:115], v[156:159], v[180:183], v[112:115]
	v_mfma_f32_16x16x32_bf16 v[104:107], v[164:167], v[180:183], v[104:107]
	v_mfma_f32_16x16x32_bf16 v[96:99], v[156:159], v[188:191], v[96:99]
	v_mfma_f32_16x16x32_bf16 v[88:91], v[164:167], v[188:191], v[88:91]
	v_mfma_f32_16x16x32_bf16 v[76:79], v[156:159], v[196:199], v[76:79]
	v_mfma_f32_16x16x32_bf16 v[72:75], v[164:167], v[196:199], v[72:75]
	v_mfma_f32_16x16x32_bf16 v[124:127], v[160:163], v[176:179], v[124:127]
	v_mfma_f32_16x16x32_bf16 v[120:123], v[168:171], v[176:179], v[120:123]
	v_mfma_f32_16x16x32_bf16 v[112:115], v[160:163], v[184:187], v[112:115]
	v_mfma_f32_16x16x32_bf16 v[104:107], v[168:171], v[184:187], v[104:107]
	v_mfma_f32_16x16x32_bf16 v[96:99], v[160:163], v[192:195], v[96:99]
	v_mfma_f32_16x16x32_bf16 v[88:91], v[168:171], v[192:195], v[88:91]
	v_mfma_f32_16x16x32_bf16 v[76:79], v[160:163], v[200:203], v[76:79]
	v_mfma_f32_16x16x32_bf16 v[72:75], v[168:171], v[200:203], v[72:75]
	s_setprio 0
	s_barrier
	s_mov_b32 m0, s57
	v_lshl_add_u64 v[144:145], v[144:145], 0, s[22:23]
	s_waitcnt vmcnt(0)
	ds_read_b128 v[204:207], v153
	ds_read_b128 v[208:211], v153 offset:1024
	ds_read_b128 v[212:215], v153 offset:2048
	ds_read_b128 v[216:219], v153 offset:3072
	global_load_lds_dwordx4 v[144:145], off
	v_lshl_add_u64 v[144:145], v[220:221], 0, s[22:23]
	s_mov_b32 m0, s58
	s_nop 0
	global_load_lds_dwordx4 v[144:145], off
	s_barrier
	s_waitcnt lgkmcnt(0)
	s_setprio 1
	s_waitcnt lgkmcnt(0)
	v_mfma_f32_16x16x32_bf16 v[116:119], v[204:207], v[172:175], v[116:119]
	v_mfma_f32_16x16x32_bf16 v[108:111], v[212:215], v[172:175], v[108:111]
	v_mfma_f32_16x16x32_bf16 v[100:103], v[204:207], v[180:183], v[100:103]
	v_mfma_f32_16x16x32_bf16 v[92:95], v[212:215], v[180:183], v[92:95]
	v_mfma_f32_16x16x32_bf16 v[84:87], v[204:207], v[188:191], v[84:87]
	v_mfma_f32_16x16x32_bf16 v[80:83], v[212:215], v[188:191], v[80:83]
	v_mfma_f32_16x16x32_bf16 v[68:71], v[204:207], v[196:199], v[68:71]
	v_mfma_f32_16x16x32_bf16 v[64:67], v[212:215], v[196:199], v[64:67]
	v_mfma_f32_16x16x32_bf16 v[116:119], v[208:211], v[176:179], v[116:119]
	v_mfma_f32_16x16x32_bf16 v[108:111], v[216:219], v[176:179], v[108:111]
	v_mfma_f32_16x16x32_bf16 v[100:103], v[208:211], v[184:187], v[100:103]
	v_mfma_f32_16x16x32_bf16 v[92:95], v[216:219], v[184:187], v[92:95]
	v_mfma_f32_16x16x32_bf16 v[84:87], v[208:211], v[192:195], v[84:87]
	v_mfma_f32_16x16x32_bf16 v[80:83], v[216:219], v[192:195], v[80:83]
	v_mfma_f32_16x16x32_bf16 v[68:71], v[208:211], v[200:203], v[68:71]
	v_mfma_f32_16x16x32_bf16 v[64:67], v[216:219], v[200:203], v[64:67]
	s_setprio 0
	s_mov_b32 m0, s59
	v_lshl_add_u64 v[144:145], v[222:223], 0, s[22:23]
	s_barrier
	s_waitcnt vmcnt(0)
	ds_read_b128 v[172:175], v148 offset:49152
	ds_read_b128 v[176:179], v148 offset:50176
	ds_read_b128 v[180:183], v148 offset:51200
	ds_read_b128 v[184:187], v148 offset:52224
	ds_read_b128 v[188:191], v148 offset:53248
	ds_read_b128 v[192:195], v148 offset:54272
	ds_read_b128 v[196:199], v148 offset:55296
	ds_read_b128 v[200:203], v148 offset:56320
	global_load_lds_dwordx4 v[144:145], off
	v_lshl_add_u64 v[144:145], v[224:225], 0, s[22:23]
	s_mov_b32 m0, s60
	s_nop 0
	global_load_lds_dwordx4 v[144:145], off
	s_barrier
	s_waitcnt lgkmcnt(0)
	s_setprio 1
	s_waitcnt lgkmcnt(0)
	v_mfma_f32_16x16x32_bf16 v[60:63], v[156:159], v[172:175], v[60:63]
	v_mfma_f32_16x16x32_bf16 v[56:59], v[164:167], v[172:175], v[56:59]
	v_mfma_f32_16x16x32_bf16 v[48:51], v[156:159], v[180:183], v[48:51]
	v_mfma_f32_16x16x32_bf16 v[40:43], v[164:167], v[180:183], v[40:43]
	v_mfma_f32_16x16x32_bf16 v[32:35], v[156:159], v[188:191], v[32:35]
	v_mfma_f32_16x16x32_bf16 v[24:27], v[164:167], v[188:191], v[24:27]
	v_mfma_f32_16x16x32_bf16 v[12:15], v[156:159], v[196:199], v[12:15]
	v_mfma_f32_16x16x32_bf16 v[8:11], v[164:167], v[196:199], v[8:11]
	v_mfma_f32_16x16x32_bf16 v[60:63], v[160:163], v[176:179], v[60:63]
	v_mfma_f32_16x16x32_bf16 v[56:59], v[168:171], v[176:179], v[56:59]
	v_mfma_f32_16x16x32_bf16 v[48:51], v[160:163], v[184:187], v[48:51]
	v_mfma_f32_16x16x32_bf16 v[40:43], v[168:171], v[184:187], v[40:43]
	v_mfma_f32_16x16x32_bf16 v[32:35], v[160:163], v[192:195], v[32:35]
	v_mfma_f32_16x16x32_bf16 v[24:27], v[168:171], v[192:195], v[24:27]
	v_mfma_f32_16x16x32_bf16 v[12:15], v[160:163], v[200:203], v[12:15]
	v_mfma_f32_16x16x32_bf16 v[8:11], v[168:171], v[200:203], v[8:11]
	s_setprio 0
	s_barrier
	s_add_u32 s42, s42, 0x40080
	s_addc_u32 s43, s43, 0
	s_mov_b32 m0, s61
	v_lshl_add_u64 v[144:145], s[42:43], 0, v[132:133]
	global_load_lds_dwordx4 v[144:145], off
	v_lshl_add_u64 v[144:145], s[42:43], 0, v[128:129]
	s_mov_b32 m0, s62
	s_nop 0
	global_load_lds_dwordx4 v[144:145], off
	s_waitcnt vmcnt(6)
	s_barrier
	s_setprio 1
	v_mfma_f32_16x16x32_bf16 v[52:55], v[204:207], v[172:175], v[52:55]
	v_mfma_f32_16x16x32_bf16 v[44:47], v[212:215], v[172:175], v[44:47]
	v_mfma_f32_16x16x32_bf16 v[36:39], v[204:207], v[180:183], v[36:39]
	v_mfma_f32_16x16x32_bf16 v[28:31], v[212:215], v[180:183], v[28:31]
	v_mfma_f32_16x16x32_bf16 v[20:23], v[204:207], v[188:191], v[20:23]
	v_mfma_f32_16x16x32_bf16 v[16:19], v[212:215], v[188:191], v[16:19]
	v_mfma_f32_16x16x32_bf16 v[4:7], v[204:207], v[196:199], v[4:7]
	v_mfma_f32_16x16x32_bf16 v[0:3], v[212:215], v[196:199], v[0:3]
	v_mfma_f32_16x16x32_bf16 v[52:55], v[208:211], v[176:179], v[52:55]
	v_mfma_f32_16x16x32_bf16 v[44:47], v[216:219], v[176:179], v[44:47]
	v_mfma_f32_16x16x32_bf16 v[36:39], v[208:211], v[184:187], v[36:39]
	v_mfma_f32_16x16x32_bf16 v[28:31], v[216:219], v[184:187], v[28:31]
	v_mfma_f32_16x16x32_bf16 v[20:23], v[208:211], v[192:195], v[20:23]
	v_mfma_f32_16x16x32_bf16 v[16:19], v[216:219], v[192:195], v[16:19]
	v_mfma_f32_16x16x32_bf16 v[4:7], v[208:211], v[200:203], v[4:7]
	v_mfma_f32_16x16x32_bf16 v[0:3], v[216:219], v[200:203], v[0:3]
	s_setprio 0
	s_add_i32 s70, s70, 2
	s_add_u32 s40, s40, 0x100
	s_addc_u32 s41, s41, 0
	s_add_u32 s68, s68, 0x100
	s_addc_u32 s69, s69, 0
	s_cmp_gt_u32 s70, 13
	s_barrier
	s_cbranch_scc0 .LBB0_241
	s_lshl_b32 s29, s38, 8
	s_add_i32 s29, s29, s56
	v_cvt_pk_bf16_f32 v124, v124, v125
	v_or_b32_e32 v155, s29, v147
	v_lshl_add_u32 v144, s6, 8, v149
	v_lshlrev_b32_e32 v156, 10, v155
	v_cvt_pk_bf16_f32 v125, v126, v127
	v_cvt_pk_bf16_f32 v126, v120, v121
	v_add_u32_e32 v136, v156, v144
	v_cvt_pk_bf16_f32 v116, v116, v117
	v_cvt_pk_bf16_f32 v127, v122, v123
	v_lshl_add_u64 v[120:121], v[136:137], 1, s[10:11]
	global_store_dwordx4 v[120:121], v[124:127], off
	v_add_u32_e32 v120, 0x80, v144
	v_cvt_pk_bf16_f32 v117, v118, v119
	v_cvt_pk_bf16_f32 v118, v108, v109
	v_add_u32_e32 v136, v156, v120
	v_cvt_pk_bf16_f32 v119, v110, v111
	v_lshl_add_u64 v[108:109], v[136:137], 1, s[10:11]
	global_store_dwordx4 v[108:109], v[116:119], off
	v_cvt_pk_bf16_f32 v108, v112, v113
	v_cvt_pk_bf16_f32 v100, v100, v101
	v_or_b32_e32 v116, 0x4000, v156
	v_cvt_pk_bf16_f32 v109, v114, v115
	v_cvt_pk_bf16_f32 v110, v104, v105
	v_add_u32_e32 v136, v116, v144
	v_cvt_pk_bf16_f32 v101, v102, v103
	v_cvt_pk_bf16_f32 v102, v92, v93
	v_cvt_pk_bf16_f32 v111, v106, v107
	v_lshl_add_u64 v[104:105], v[136:137], 1, s[10:11]
	v_add_u32_e32 v136, v116, v120
	v_cvt_pk_bf16_f32 v103, v94, v95
	v_lshl_add_u64 v[92:93], v[136:137], 1, s[10:11]
	global_store_dwordx4 v[104:105], v[108:111], off
	global_store_dwordx4 v[92:93], v[100:103], off
	v_cvt_pk_bf16_f32 v92, v96, v97
	v_cvt_pk_bf16_f32 v84, v84, v85
	v_or_b32_e32 v100, 0x8000, v156
	v_cvt_pk_bf16_f32 v93, v98, v99
	v_cvt_pk_bf16_f32 v94, v88, v89
	v_add_u32_e32 v136, v100, v144
	v_cvt_pk_bf16_f32 v85, v86, v87
	v_cvt_pk_bf16_f32 v86, v80, v81
	v_cvt_pk_bf16_f32 v95, v90, v91
	v_lshl_add_u64 v[88:89], v[136:137], 1, s[10:11]
	v_add_u32_e32 v136, v100, v120
	v_cvt_pk_bf16_f32 v87, v82, v83
	v_lshl_add_u64 v[80:81], v[136:137], 1, s[10:11]
	global_store_dwordx4 v[88:89], v[92:95], off
	global_store_dwordx4 v[80:81], v[84:87], off
	s_add_i32 s6, s29, 0xfff0000
	s_lshr_b32 s6, s6, 6
	s_ashr_i32 s7, s29, 12
	v_cvt_pk_bf16_f32 v84, v76, v77
	s_mul_i32 s31, s7, 3
	v_or_b32_e32 v82, 48, v155
	v_mad_u64_u32 v[80:81], s[6:7], s6, 3, v[138:139]
	v_bitop3_b32 v90, v155, s65, 48 bitop3:0xc8
	v_cvt_pk_bf16_f32 v85, v78, v79
	v_lshlrev_b32_e32 v83, 10, v82
	v_lshl_add_u32 v136, v80, 10, v154
	v_add_lshl_u32 v80, v90, s31, 10
	v_cvt_pk_bf16_f32 v86, v72, v73
	v_ashrrev_i32_e32 v81, 31, v80
	v_cvt_pk_bf16_f32 v87, v74, v75
	v_add_u32_e32 v88, v83, v144
	v_mov_b32_e32 v89, v137
	v_lshl_add_u64 v[88:89], v[88:89], 1, s[10:11]
	v_lshl_add_u64 v[80:81], v[80:81], 2, s[18:19]
	global_store_dwordx4 v[88:89], v[84:87], off
	v_lshl_add_u64 v[80:81], v[80:81], 0, s[24:25]
	v_cmp_gt_i32_e32 vcc, s55, v82
	v_lshl_add_u64 v[84:85], v[136:137], 2, s[20:21]
	v_cmp_lt_u32_e64 s[6:7], s66, v90
	v_cndmask_b32_e32 v80, v84, v80, vcc
	v_cndmask_b32_e64 v82, 0, 1, s[4:5]
	v_cndmask_b32_e64 v84, 0, 1, s[6:7]
	v_cndmask_b32_e32 v84, v82, v84, vcc
	v_cndmask_b32_e32 v81, v85, v81, vcc
	v_and_b32_e32 v84, 1, v84
	v_cmp_eq_u32_e32 vcc, 1, v84
	v_cmp_ne_u64_e64 s[6:7], 0, v[80:81]
	s_and_b64 s[6:7], vcc, s[6:7]
	v_ashrrev_i32_e32 v145, 31, v144
	s_and_saveexec_b64 s[38:39], s[6:7]
	s_cbranch_execz .LBB0_244
	v_lshl_add_u64 v[84:85], v[144:145], 2, v[80:81]
	global_store_dwordx4 v[84:85], v[76:79], off
	global_store_dwordx4 v[84:85], v[72:75], off offset:16
.LBB0_244:
	s_or_b64 exec, exec, s[38:39]
	s_nop 0
	v_cvt_pk_bf16_f32 v72, v68, v69
	v_cvt_pk_bf16_f32 v73, v70, v71
	v_cvt_pk_bf16_f32 v74, v64, v65
	v_add_u32_e32 v136, v83, v120
	v_cvt_pk_bf16_f32 v75, v66, v67
	v_lshl_add_u64 v[76:77], v[136:137], 1, s[10:11]
	global_store_dwordx4 v[76:77], v[72:75], off
	s_and_saveexec_b64 s[38:39], s[6:7]
	s_cbranch_execz .LBB0_246
	v_lshl_add_u64 v[72:73], v[144:145], 2, v[80:81]
	global_store_dwordx4 v[72:73], v[68:71], off offset:512
	global_store_dwordx4 v[72:73], v[64:67], off offset:528
.LBB0_246:
	s_or_b64 exec, exec, s[38:39]
	v_cvt_pk_bf16_f32 v60, v60, v61
	v_add_u32_e32 v64, 0x80, v155
	v_cvt_pk_bf16_f32 v52, v52, v53
	v_ashrrev_i32_e32 v65, 12, v64
	v_lshlrev_b32_e32 v64, 10, v64
	v_cvt_pk_bf16_f32 v61, v62, v63
	v_cvt_pk_bf16_f32 v62, v56, v57
	v_add_u32_e32 v136, v64, v144
	v_cvt_pk_bf16_f32 v53, v54, v55
	v_cvt_pk_bf16_f32 v54, v44, v45
	v_cvt_pk_bf16_f32 v63, v58, v59
	v_lshl_add_u64 v[56:57], v[136:137], 1, s[10:11]
	v_add_u32_e32 v136, v64, v120
	v_cvt_pk_bf16_f32 v55, v46, v47
	v_lshl_add_u64 v[44:45], v[136:137], 1, s[10:11]
	global_store_dwordx4 v[56:57], v[60:63], off
	global_store_dwordx4 v[44:45], v[52:55], off
	v_cvt_pk_bf16_f32 v44, v48, v49
	v_cvt_pk_bf16_f32 v36, v36, v37
	v_add_u32_e32 v52, 0x24000, v156
	v_cvt_pk_bf16_f32 v45, v50, v51
	v_cvt_pk_bf16_f32 v46, v40, v41
	v_add_u32_e32 v136, v52, v144
	v_cvt_pk_bf16_f32 v37, v38, v39
	v_cvt_pk_bf16_f32 v38, v28, v29
	v_cvt_pk_bf16_f32 v47, v42, v43
	v_lshl_add_u64 v[40:41], v[136:137], 1, s[10:11]
	v_add_u32_e32 v136, v52, v120
	v_cvt_pk_bf16_f32 v39, v30, v31
	v_lshl_add_u64 v[28:29], v[136:137], 1, s[10:11]
	global_store_dwordx4 v[40:41], v[44:47], off
	global_store_dwordx4 v[28:29], v[36:39], off
	v_cvt_pk_bf16_f32 v28, v32, v33
	v_cvt_pk_bf16_f32 v20, v20, v21
	v_add_u32_e32 v36, 0x28000, v156
	v_cvt_pk_bf16_f32 v29, v34, v35
	v_cvt_pk_bf16_f32 v30, v24, v25
	v_add_u32_e32 v136, v36, v144
	v_cvt_pk_bf16_f32 v21, v22, v23
	v_cvt_pk_bf16_f32 v22, v16, v17
	v_cvt_pk_bf16_f32 v31, v26, v27
	v_lshl_add_u64 v[24:25], v[136:137], 1, s[10:11]
	v_add_u32_e32 v136, v36, v120
	v_cvt_pk_bf16_f32 v23, v18, v19
	v_lshl_add_u64 v[16:17], v[136:137], 1, s[10:11]
	global_store_dwordx4 v[24:25], v[28:31], off
	global_store_dwordx4 v[16:17], v[20:23], off
	s_add_i32 s29, s29, 0xfff0080
	s_lshr_b32 s6, s29, 6
	v_add_u32_e32 v19, 0xb0, v155
	v_cvt_pk_bf16_f32 v20, v12, v13
	v_mul_i32_i24_e32 v65, 3, v65
	v_lshlrev_b32_e32 v18, 10, v19
	v_mad_u64_u32 v[16:17], s[6:7], s6, 3, v[138:139]
	v_and_b32_e32 v19, 0xfff, v19
	v_cvt_pk_bf16_f32 v21, v14, v15
	v_lshl_add_u32 v136, v16, 10, v154
	v_add_lshl_u32 v16, v65, v19, 10
	v_cvt_pk_bf16_f32 v22, v8, v9
	v_ashrrev_i32_e32 v17, 31, v16
	v_cvt_pk_bf16_f32 v23, v10, v11
	v_add_u32_e32 v24, v18, v144
	v_mov_b32_e32 v25, v137
	v_cmp_lt_u32_e64 s[6:7], s66, v19
	v_lshl_add_u64 v[24:25], v[24:25], 1, s[10:11]
	v_lshl_add_u64 v[16:17], v[16:17], 2, s[18:19]
	v_cmp_gt_i32_e32 vcc, s67, v155
	v_cndmask_b32_e64 v19, 0, 1, s[6:7]
	global_store_dwordx4 v[24:25], v[20:23], off
	v_lshl_add_u64 v[16:17], v[16:17], 0, s[24:25]
	v_cndmask_b32_e32 v19, v82, v19, vcc
	v_lshl_add_u64 v[20:21], v[136:137], 2, s[20:21]
	v_cndmask_b32_e32 v17, v21, v17, vcc
	v_cndmask_b32_e32 v16, v20, v16, vcc
	v_and_b32_e32 v19, 1, v19
	v_cmp_eq_u32_e32 vcc, 1, v19
	v_cmp_ne_u64_e64 s[6:7], 0, v[16:17]
	s_and_b64 s[6:7], vcc, s[6:7]
	s_and_saveexec_b64 s[38:39], s[6:7]
	s_cbranch_execz .LBB0_248
	v_lshl_add_u64 v[20:21], v[144:145], 2, v[16:17]
	global_store_dwordx4 v[20:21], v[12:15], off
	global_store_dwordx4 v[20:21], v[8:11], off offset:16
.LBB0_248:
	s_or_b64 exec, exec, s[38:39]
	s_nop 0
	v_cvt_pk_bf16_f32 v8, v4, v5
	v_cvt_pk_bf16_f32 v9, v6, v7
	v_cvt_pk_bf16_f32 v10, v0, v1
	v_add_u32_e32 v136, v18, v120
	v_cvt_pk_bf16_f32 v11, v2, v3
	v_lshl_add_u64 v[12:13], v[136:137], 1, s[10:11]
	global_store_dwordx4 v[12:13], v[8:11], off
	s_and_saveexec_b64 s[38:39], s[6:7]
	s_cbranch_execz .LBB0_237
	v_lshl_add_u64 v[8:9], v[144:145], 2, v[16:17]
	global_store_dwordx4 v[8:9], v[4:7], off offset:512
	global_store_dwordx4 v[8:9], v[0:3], off offset:528
	s_branch .LBB0_237

.LBB0_259:
	s_or_b64 exec, exec, s[4:5]
	v_cvt_pk_bf16_f32 v4, v4, v5
	v_cvt_pk_bf16_f32 v5, v6, v7
	v_cvt_pk_bf16_f32 v6, v0, v1
	v_and_or_b32 v136, v9, v120, v8
	v_cvt_pk_bf16_f32 v7, v2, v3
	v_lshl_add_u64 v[0:1], v[136:137], 1, s[12:13]
	global_store_dwordx4 v[0:1], v[4:7], off

.LBB0_269:
	s_andn2_b64 vcc, exec, s[28:29]
	s_cbranch_vccnz .LBB0_260
	v_lshl_add_u32 v159, s4, 8, v143
	v_cmp_lt_i32_e32 vcc, s56, v157
	v_lshl_add_u32 v158, v157, 4, v155
	s_and_saveexec_b64 s[4:5], vcc
	s_xor_b64 s[4:5], exec, s[4:5]
	v_and_b32_e32 v136, 0x3fffc00, v158
	v_add_u32_e32 v136, v136, v159
	v_lshl_add_u32 v136, v136, 6, v156
	s_or_saveexec_b64 s[4:5], s[4:5]
	v_lshrrev_b32_e32 v160, 2, v157
	v_mov_b32_e32 v161, 63
	v_and_b32_e32 v160, 0xffc00, v160
	s_xor_b64 exec, exec, s[4:5]
	v_add_lshl_u32 v136, v160, v159, 12
	v_mov_b32_e32 v161, 0xfff
	s_or_b64 exec, exec, s[4:5]
	v_cvt_pk_bf16_f32 v124, v124, v125
	v_cvt_pk_bf16_f32 v125, v126, v127
	v_cvt_pk_bf16_f32 v126, v120, v121
	v_and_or_b32 v136, v161, v157, v136
	v_cvt_pk_bf16_f32 v127, v122, v123
	v_lshl_add_u64 v[120:121], v[136:137], 1, s[12:13]
	global_store_dwordx4 v[120:121], v[124:127], off
	v_add_u32_e32 v120, 0x80, v157
	v_cmp_lt_i32_e64 s[4:5], s57, v157
	v_lshl_add_u32 v121, v120, 4, v155
	s_and_saveexec_b64 s[28:29], s[4:5]
	s_xor_b64 s[28:29], exec, s[28:29]
	v_and_b32_e32 v122, 0x3fffc00, v121
	v_add_u32_e32 v122, v122, v159
	v_lshl_add_u32 v123, v122, 6, v156
	s_or_saveexec_b64 s[28:29], s[28:29]
	v_lshrrev_b32_e32 v122, 2, v120
	v_mov_b32_e32 v124, 63
	v_and_b32_e32 v122, 0xffc00, v122
	s_xor_b64 exec, exec, s[28:29]
	v_add_lshl_u32 v123, v122, v159, 12
	v_mov_b32_e32 v124, 0xfff
	s_or_b64 exec, exec, s[28:29]
	v_cvt_pk_bf16_f32 v116, v116, v117
	v_cvt_pk_bf16_f32 v117, v118, v119
	v_cvt_pk_bf16_f32 v118, v112, v113
	v_and_or_b32 v136, v124, v120, v123
	v_cvt_pk_bf16_f32 v119, v114, v115
	v_lshl_add_u64 v[112:113], v[136:137], 1, s[12:13]
	global_store_dwordx4 v[112:113], v[116:119], off
	v_or_b32_e32 v112, 16, v159
	s_and_saveexec_b64 s[28:29], vcc
	s_xor_b64 s[28:29], exec, s[28:29]
	v_and_b32_e32 v113, 0x3fffc00, v158
	v_add_u32_e32 v113, v113, v112
	v_lshl_add_u32 v113, v113, 6, v156
	s_or_saveexec_b64 s[28:29], s[28:29]
	v_mov_b32_e32 v114, 63
	s_xor_b64 exec, exec, s[28:29]
	v_add_lshl_u32 v113, v160, v112, 12
	v_mov_b32_e32 v114, 0xfff
	s_or_b64 exec, exec, s[28:29]
	v_cvt_pk_bf16_f32 v108, v108, v109
	v_cvt_pk_bf16_f32 v109, v110, v111
	v_cvt_pk_bf16_f32 v110, v104, v105
	v_and_or_b32 v136, v114, v157, v113
	v_cvt_pk_bf16_f32 v111, v106, v107
	v_lshl_add_u64 v[104:105], v[136:137], 1, s[12:13]
	global_store_dwordx4 v[104:105], v[108:111], off
	s_and_saveexec_b64 s[28:29], s[4:5]
	s_xor_b64 s[28:29], exec, s[28:29]
	v_and_b32_e32 v104, 0x3fffc00, v121
	v_add_u32_e32 v104, v104, v112
	v_lshl_add_u32 v104, v104, 6, v156
	s_or_saveexec_b64 s[28:29], s[28:29]
	v_mov_b32_e32 v105, 63
	s_xor_b64 exec, exec, s[28:29]
	v_add_lshl_u32 v104, v122, v112, 12
	v_mov_b32_e32 v105, 0xfff
	s_or_b64 exec, exec, s[28:29]
	v_cvt_pk_bf16_f32 v100, v100, v101
	v_cvt_pk_bf16_f32 v101, v102, v103
	v_cvt_pk_bf16_f32 v102, v96, v97
	v_and_or_b32 v136, v105, v120, v104
	v_cvt_pk_bf16_f32 v103, v98, v99
	v_lshl_add_u64 v[96:97], v[136:137], 1, s[12:13]
	global_store_dwordx4 v[96:97], v[100:103], off
	v_or_b32_e32 v96, 32, v159
	s_and_saveexec_b64 s[28:29], vcc
	s_xor_b64 s[28:29], exec, s[28:29]
	v_and_b32_e32 v97, 0x3fffc00, v158
	v_add_u32_e32 v97, v97, v96
	v_lshl_add_u32 v97, v97, 6, v156
	s_or_saveexec_b64 s[28:29], s[28:29]
	v_mov_b32_e32 v98, 63
	s_xor_b64 exec, exec, s[28:29]
	v_add_lshl_u32 v97, v160, v96, 12
	v_mov_b32_e32 v98, 0xfff
	s_or_b64 exec, exec, s[28:29]
	v_cvt_pk_bf16_f32 v92, v92, v93
	v_cvt_pk_bf16_f32 v93, v94, v95
	v_cvt_pk_bf16_f32 v94, v88, v89
	v_and_or_b32 v136, v98, v157, v97
	v_cvt_pk_bf16_f32 v95, v90, v91
	v_lshl_add_u64 v[88:89], v[136:137], 1, s[12:13]
	global_store_dwordx4 v[88:89], v[92:95], off
	s_and_saveexec_b64 s[28:29], s[4:5]
	s_xor_b64 s[28:29], exec, s[28:29]
	v_and_b32_e32 v88, 0x3fffc00, v121
	v_add_u32_e32 v88, v88, v96
	v_lshl_add_u32 v88, v88, 6, v156
	s_or_saveexec_b64 s[28:29], s[28:29]
	v_mov_b32_e32 v89, 63
	s_xor_b64 exec, exec, s[28:29]
	v_add_lshl_u32 v88, v122, v96, 12
	v_mov_b32_e32 v89, 0xfff
	s_or_b64 exec, exec, s[28:29]
	v_cvt_pk_bf16_f32 v84, v84, v85
	v_cvt_pk_bf16_f32 v85, v86, v87
	v_cvt_pk_bf16_f32 v86, v80, v81
	v_and_or_b32 v136, v89, v120, v88
	v_cvt_pk_bf16_f32 v87, v82, v83
	v_lshl_add_u64 v[80:81], v[136:137], 1, s[12:13]
	global_store_dwordx4 v[80:81], v[84:87], off
	v_or_b32_e32 v80, 48, v159
	s_and_saveexec_b64 s[28:29], vcc
	s_xor_b64 s[28:29], exec, s[28:29]
	v_and_b32_e32 v81, 0x3fffc00, v158
	v_add_u32_e32 v81, v81, v80
	v_lshl_add_u32 v81, v81, 6, v156
	s_or_saveexec_b64 s[28:29], s[28:29]
	v_mov_b32_e32 v82, 63
	s_xor_b64 exec, exec, s[28:29]
	v_add_lshl_u32 v81, v160, v80, 12
	v_mov_b32_e32 v82, 0xfff
	s_or_b64 exec, exec, s[28:29]
	v_cvt_pk_bf16_f32 v76, v76, v77
	v_cvt_pk_bf16_f32 v77, v78, v79
	v_cvt_pk_bf16_f32 v78, v72, v73
	v_and_or_b32 v136, v82, v157, v81
	v_cvt_pk_bf16_f32 v79, v74, v75
	v_lshl_add_u64 v[72:73], v[136:137], 1, s[12:13]
	global_store_dwordx4 v[72:73], v[76:79], off
	s_and_saveexec_b64 s[28:29], s[4:5]
	s_xor_b64 s[28:29], exec, s[28:29]
	v_and_b32_e32 v72, 0x3fffc00, v121
	v_add_u32_e32 v72, v72, v80
	v_lshl_add_u32 v72, v72, 6, v156
	s_or_saveexec_b64 s[28:29], s[28:29]
	v_mov_b32_e32 v73, 63
	s_xor_b64 exec, exec, s[28:29]
	v_add_lshl_u32 v72, v122, v80, 12
	v_mov_b32_e32 v73, 0xfff
	s_or_b64 exec, exec, s[28:29]
	v_cvt_pk_bf16_f32 v68, v68, v69
	v_cvt_pk_bf16_f32 v69, v70, v71
	v_cvt_pk_bf16_f32 v70, v64, v65
	v_and_or_b32 v136, v73, v120, v72
	v_cvt_pk_bf16_f32 v71, v66, v67
	v_lshl_add_u64 v[64:65], v[136:137], 1, s[12:13]
	global_store_dwordx4 v[64:65], v[68:71], off
	v_add_u32_e32 v64, 0x80, v159
	s_and_saveexec_b64 s[28:29], vcc
	s_xor_b64 s[28:29], exec, s[28:29]
	v_and_b32_e32 v65, 0x3fffc00, v158
	v_add_u32_e32 v65, v65, v64
	v_lshl_add_u32 v65, v65, 6, v156
	s_or_saveexec_b64 s[28:29], s[28:29]
	v_mov_b32_e32 v66, 63
	s_xor_b64 exec, exec, s[28:29]
	v_add_lshl_u32 v65, v160, v64, 12
	v_mov_b32_e32 v66, 0xfff
	s_or_b64 exec, exec, s[28:29]
	v_cvt_pk_bf16_f32 v60, v60, v61
	v_cvt_pk_bf16_f32 v61, v62, v63
	v_cvt_pk_bf16_f32 v62, v56, v57
	v_and_or_b32 v136, v66, v157, v65
	v_cvt_pk_bf16_f32 v63, v58, v59
	v_lshl_add_u64 v[56:57], v[136:137], 1, s[12:13]
	global_store_dwordx4 v[56:57], v[60:63], off
	s_and_saveexec_b64 s[28:29], s[4:5]
	s_xor_b64 s[28:29], exec, s[28:29]
	v_and_b32_e32 v56, 0x3fffc00, v121
	v_add_u32_e32 v56, v56, v64
	v_lshl_add_u32 v56, v56, 6, v156
	s_or_saveexec_b64 s[28:29], s[28:29]
	v_mov_b32_e32 v57, 63
	s_xor_b64 exec, exec, s[28:29]
	v_add_lshl_u32 v56, v122, v64, 12
	v_mov_b32_e32 v57, 0xfff
	s_or_b64 exec, exec, s[28:29]
	v_cvt_pk_bf16_f32 v52, v52, v53
	v_cvt_pk_bf16_f32 v53, v54, v55
	v_cvt_pk_bf16_f32 v54, v48, v49
	v_and_or_b32 v136, v57, v120, v56
	v_cvt_pk_bf16_f32 v55, v50, v51
	v_lshl_add_u64 v[48:49], v[136:137], 1, s[12:13]
	global_store_dwordx4 v[48:49], v[52:55], off
	v_add_u32_e32 v48, 0x90, v159
	s_and_saveexec_b64 s[28:29], vcc
	s_xor_b64 s[28:29], exec, s[28:29]
	v_and_b32_e32 v49, 0x3fffc00, v158
	v_add_u32_e32 v49, v49, v48
	v_lshl_add_u32 v49, v49, 6, v156
	s_or_saveexec_b64 s[28:29], s[28:29]
	v_mov_b32_e32 v50, 63
	s_xor_b64 exec, exec, s[28:29]
	v_add_lshl_u32 v49, v160, v48, 12
	v_mov_b32_e32 v50, 0xfff
	s_or_b64 exec, exec, s[28:29]
	v_cvt_pk_bf16_f32 v44, v44, v45
	v_cvt_pk_bf16_f32 v45, v46, v47
	v_cvt_pk_bf16_f32 v46, v40, v41
	v_and_or_b32 v136, v50, v157, v49
	v_cvt_pk_bf16_f32 v47, v42, v43
	v_lshl_add_u64 v[40:41], v[136:137], 1, s[12:13]
	global_store_dwordx4 v[40:41], v[44:47], off
	s_and_saveexec_b64 s[28:29], s[4:5]
	s_xor_b64 s[28:29], exec, s[28:29]
	v_and_b32_e32 v40, 0x3fffc00, v121
	v_add_u32_e32 v40, v40, v48
	v_lshl_add_u32 v40, v40, 6, v156
	s_or_saveexec_b64 s[28:29], s[28:29]
	v_mov_b32_e32 v41, 63
	s_xor_b64 exec, exec, s[28:29]
	v_add_lshl_u32 v40, v122, v48, 12
	v_mov_b32_e32 v41, 0xfff
	s_or_b64 exec, exec, s[28:29]
	v_cvt_pk_bf16_f32 v36, v36, v37
	v_cvt_pk_bf16_f32 v37, v38, v39
	v_cvt_pk_bf16_f32 v38, v32, v33
	v_and_or_b32 v136, v41, v120, v40
	v_cvt_pk_bf16_f32 v39, v34, v35
	v_lshl_add_u64 v[32:33], v[136:137], 1, s[12:13]
	global_store_dwordx4 v[32:33], v[36:39], off
	v_add_u32_e32 v32, 0xa0, v159
	s_and_saveexec_b64 s[28:29], vcc
	s_xor_b64 s[28:29], exec, s[28:29]
	v_and_b32_e32 v33, 0x3fffc00, v158
	v_add_u32_e32 v33, v33, v32
	v_lshl_add_u32 v33, v33, 6, v156
	s_or_saveexec_b64 s[28:29], s[28:29]
	v_mov_b32_e32 v34, 63
	s_xor_b64 exec, exec, s[28:29]
	v_add_lshl_u32 v33, v160, v32, 12
	v_mov_b32_e32 v34, 0xfff
	s_or_b64 exec, exec, s[28:29]
	v_cvt_pk_bf16_f32 v28, v28, v29
	v_cvt_pk_bf16_f32 v29, v30, v31
	v_cvt_pk_bf16_f32 v30, v24, v25
	v_and_or_b32 v136, v34, v157, v33
	v_cvt_pk_bf16_f32 v31, v26, v27
	v_lshl_add_u64 v[24:25], v[136:137], 1, s[12:13]
	global_store_dwordx4 v[24:25], v[28:31], off
	s_and_saveexec_b64 s[28:29], s[4:5]
	s_xor_b64 s[28:29], exec, s[28:29]
	v_and_b32_e32 v24, 0x3fffc00, v121
	v_add_u32_e32 v24, v24, v32
	v_lshl_add_u32 v24, v24, 6, v156
	s_or_saveexec_b64 s[28:29], s[28:29]
	v_mov_b32_e32 v25, 63
	s_xor_b64 exec, exec, s[28:29]
	v_add_lshl_u32 v24, v122, v32, 12
	v_mov_b32_e32 v25, 0xfff
	s_or_b64 exec, exec, s[28:29]
	v_cvt_pk_bf16_f32 v20, v20, v21
	v_cvt_pk_bf16_f32 v21, v22, v23
	v_cvt_pk_bf16_f32 v22, v16, v17
	v_and_or_b32 v136, v25, v120, v24
	v_cvt_pk_bf16_f32 v23, v18, v19
	v_lshl_add_u64 v[16:17], v[136:137], 1, s[12:13]
	global_store_dwordx4 v[16:17], v[20:23], off
	v_add_u32_e32 v16, 0xb0, v159
	s_and_saveexec_b64 s[28:29], vcc
	s_xor_b64 s[28:29], exec, s[28:29]
	v_and_b32_e32 v17, 0x3fffc00, v158
	v_add_u32_e32 v17, v17, v16
	v_lshl_add_u32 v17, v17, 6, v156
	s_or_saveexec_b64 s[28:29], s[28:29]
	v_mov_b32_e32 v18, 63
	s_xor_b64 exec, exec, s[28:29]
	v_add_lshl_u32 v17, v160, v16, 12
	v_mov_b32_e32 v18, 0xfff
	s_or_b64 exec, exec, s[28:29]
	v_cvt_pk_bf16_f32 v12, v12, v13
	v_cvt_pk_bf16_f32 v13, v14, v15
	v_cvt_pk_bf16_f32 v14, v8, v9
	v_and_or_b32 v136, v18, v157, v17
	v_cvt_pk_bf16_f32 v15, v10, v11
	v_lshl_add_u64 v[8:9], v[136:137], 1, s[12:13]
	global_store_dwordx4 v[8:9], v[12:15], off
	s_and_saveexec_b64 s[28:29], s[4:5]
	s_xor_b64 s[4:5], exec, s[28:29]
	v_and_b32_e32 v8, 0x3fffc00, v121
	v_add_u32_e32 v8, v8, v16
	v_lshl_add_u32 v8, v8, 6, v156
	s_or_saveexec_b64 s[4:5], s[4:5]
	v_mov_b32_e32 v9, 63
	s_xor_b64 exec, exec, s[4:5]
	s_cbranch_execz .LBB0_259
	v_add_lshl_u32 v8, v122, v16, 12
	v_mov_b32_e32 v9, 0xfff
	s_branch .LBB0_259

.LBB0_454:
	s_ashr_i32 s27, s26, 31
	s_lshl_b32 s25, s24, 9
	s_and_b32 s25, s25, 0x600
	s_lshl_b64 s[28:29], s[26:27], 19
	s_add_u32 s27, s6, s28
	s_addc_u32 s29, s7, s29
	s_add_u32 s28, s27, s25
	s_addc_u32 s29, s29, 0
	s_waitcnt vmcnt(0)
	ds_read_b128 v[0:3], v93
	ds_read_b128 v[4:7], v93 offset:1024
	ds_read_b128 v[8:11], v93 offset:2048
	ds_read_b128 v[12:15], v93 offset:3072
	s_and_b64 s[30:31], s[38:39], exec
	s_cselect_b32 s45, s29, s41
	s_cselect_b32 s44, s28, s40
	s_ashr_i32 s25, s24, 31
	s_lshl_b64 s[30:31], s[24:25], 17
	s_add_u32 s30, s12, s30
	s_addc_u32 s31, s13, s31
	s_and_b64 s[38:39], s[38:39], exec
	s_cselect_b32 s39, s31, s43
	s_cselect_b32 s38, s30, s42
	s_add_u32 s62, s40, 0x40080
	s_addc_u32 s63, s41, 0
	s_mov_b32 m0, s59
	v_lshl_add_u64 v[48:49], s[62:63], 0, v[86:87]
	ds_read_b128 v[16:19], v91
	ds_read_b128 v[20:23], v91 offset:1024
	ds_read_b128 v[24:27], v91 offset:2048
	ds_read_b128 v[28:31], v91 offset:3072
	ds_read_b128 v[32:35], v91 offset:4096
	ds_read_b128 v[36:39], v91 offset:5120
	ds_read_b128 v[40:43], v91 offset:6144
	ds_read_b128 v[44:47], v91 offset:7168
	global_load_lds_dwordx4 v[48:49], off
	v_lshl_add_u64 v[48:49], s[62:63], 0, v[82:83]
	s_mov_b32 m0, s60
	s_nop 0
	global_load_lds_dwordx4 v[48:49], off
	s_waitcnt lgkmcnt(8)
	s_barrier
	s_waitcnt lgkmcnt(0)
	s_setprio 1
	s_waitcnt lgkmcnt(0)
	v_mfma_f32_16x16x32_bf16 v[48:51], v[0:3], v[16:19], 0
	v_mfma_f32_16x16x32_bf16 v[52:55], v[8:11], v[16:19], 0
	v_mfma_f32_16x16x32_bf16 v[56:59], v[0:3], v[24:27], 0
	v_mfma_f32_16x16x32_bf16 v[60:63], v[8:11], v[24:27], 0
	v_mfma_f32_16x16x32_bf16 v[64:67], v[0:3], v[32:35], 0
	v_mfma_f32_16x16x32_bf16 v[68:71], v[8:11], v[32:35], 0
	v_mfma_f32_16x16x32_bf16 v[72:75], v[0:3], v[40:43], 0
	v_mfma_f32_16x16x32_bf16 v[76:79], v[8:11], v[40:43], 0
	v_mfma_f32_16x16x32_bf16 v[48:51], v[4:7], v[20:23], v[48:51]
	v_mfma_f32_16x16x32_bf16 v[52:55], v[12:15], v[20:23], v[52:55]
	v_mfma_f32_16x16x32_bf16 v[56:59], v[4:7], v[28:31], v[56:59]
	v_mfma_f32_16x16x32_bf16 v[60:63], v[12:15], v[28:31], v[60:63]
	v_mfma_f32_16x16x32_bf16 v[64:67], v[4:7], v[36:39], v[64:67]
	v_mfma_f32_16x16x32_bf16 v[68:71], v[12:15], v[36:39], v[68:71]
	v_mfma_f32_16x16x32_bf16 v[72:75], v[4:7], v[44:47], v[72:75]
	v_mfma_f32_16x16x32_bf16 v[76:79], v[12:15], v[44:47], v[76:79]
	s_setprio 0
	s_barrier
	v_lshl_add_u64 v[212:213], s[42:43], 0, v[84:85]
	s_mov_b32 m0, s35
	v_lshl_add_u64 v[114:115], v[212:213], 0, s[18:19]
	v_lshl_add_u64 v[214:215], s[42:43], 0, v[80:81]
	s_waitcnt vmcnt(0)
	ds_read_b128 v[98:101], v94
	ds_read_b128 v[102:105], v94 offset:1024
	ds_read_b128 v[106:109], v94 offset:2048
	ds_read_b128 v[110:113], v94 offset:3072
	global_load_lds_dwordx4 v[114:115], off
	v_lshl_add_u64 v[114:115], v[214:215], 0, s[18:19]
	s_mov_b32 m0, s47
	s_nop 0
	global_load_lds_dwordx4 v[114:115], off
	s_barrier
	s_waitcnt lgkmcnt(0)
	s_setprio 1
	s_waitcnt lgkmcnt(0)
	v_mfma_f32_16x16x32_bf16 v[114:117], v[98:101], v[16:19], 0
	v_mfma_f32_16x16x32_bf16 v[16:19], v[106:109], v[16:19], 0
	v_mfma_f32_16x16x32_bf16 v[114:117], v[102:105], v[20:23], v[114:117]
	v_mfma_f32_16x16x32_bf16 v[16:19], v[110:113], v[20:23], v[16:19]
	v_mfma_f32_16x16x32_bf16 v[20:23], v[98:101], v[24:27], 0
	v_mfma_f32_16x16x32_bf16 v[24:27], v[106:109], v[24:27], 0
	v_mfma_f32_16x16x32_bf16 v[20:23], v[102:105], v[28:31], v[20:23]
	v_mfma_f32_16x16x32_bf16 v[24:27], v[110:113], v[28:31], v[24:27]
	v_mfma_f32_16x16x32_bf16 v[28:31], v[98:101], v[32:35], 0
	v_mfma_f32_16x16x32_bf16 v[32:35], v[106:109], v[32:35], 0
	v_mfma_f32_16x16x32_bf16 v[28:31], v[102:105], v[36:39], v[28:31]
	v_mfma_f32_16x16x32_bf16 v[32:35], v[110:113], v[36:39], v[32:35]
	v_mfma_f32_16x16x32_bf16 v[36:39], v[98:101], v[40:43], 0
	v_mfma_f32_16x16x32_bf16 v[40:43], v[106:109], v[40:43], 0
	v_mfma_f32_16x16x32_bf16 v[36:39], v[102:105], v[44:47], v[36:39]
	v_mfma_f32_16x16x32_bf16 v[40:43], v[110:113], v[44:47], v[40:43]
	s_setprio 0
	v_lshl_add_u64 v[216:217], s[40:41], 0, v[86:87]
	s_mov_b32 m0, s46
	v_lshl_add_u64 v[148:149], v[216:217], 0, s[18:19]
	v_lshl_add_u64 v[218:219], s[40:41], 0, v[82:83]
	s_barrier
	s_waitcnt vmcnt(0)
	ds_read_b128 v[44:47], v91 offset:16384
	ds_read_b128 v[118:121], v91 offset:17408
	ds_read_b128 v[122:125], v91 offset:18432
	ds_read_b128 v[126:129], v91 offset:19456
	ds_read_b128 v[130:133], v91 offset:20480
	ds_read_b128 v[134:137], v91 offset:21504
	ds_read_b128 v[138:141], v91 offset:22528
	ds_read_b128 v[142:145], v91 offset:23552
	global_load_lds_dwordx4 v[148:149], off
	v_lshl_add_u64 v[148:149], v[218:219], 0, s[18:19]
	s_mov_b32 m0, s48
	s_nop 0
	global_load_lds_dwordx4 v[148:149], off
	s_barrier
	s_waitcnt lgkmcnt(0)
	s_setprio 1
	s_waitcnt lgkmcnt(0)
	v_mfma_f32_16x16x32_bf16 v[148:151], v[0:3], v[44:47], 0
	v_mfma_f32_16x16x32_bf16 v[156:159], v[0:3], v[122:125], 0
	v_mfma_f32_16x16x32_bf16 v[164:167], v[0:3], v[130:133], 0
	v_mfma_f32_16x16x32_bf16 v[0:3], v[0:3], v[138:141], 0
	v_mfma_f32_16x16x32_bf16 v[148:151], v[4:7], v[118:121], v[148:151]
	v_mfma_f32_16x16x32_bf16 v[152:155], v[8:11], v[44:47], 0
	v_mfma_f32_16x16x32_bf16 v[156:159], v[4:7], v[126:129], v[156:159]
	v_mfma_f32_16x16x32_bf16 v[160:163], v[8:11], v[122:125], 0
	v_mfma_f32_16x16x32_bf16 v[164:167], v[4:7], v[134:137], v[164:167]
	v_mfma_f32_16x16x32_bf16 v[168:171], v[8:11], v[130:133], 0
	v_mfma_f32_16x16x32_bf16 v[0:3], v[4:7], v[142:145], v[0:3]
	v_mfma_f32_16x16x32_bf16 v[4:7], v[8:11], v[138:141], 0
	v_mfma_f32_16x16x32_bf16 v[152:155], v[12:15], v[118:121], v[152:155]
	v_mfma_f32_16x16x32_bf16 v[160:163], v[12:15], v[126:129], v[160:163]
	v_mfma_f32_16x16x32_bf16 v[168:171], v[12:15], v[134:137], v[168:171]
	v_mfma_f32_16x16x32_bf16 v[4:7], v[12:15], v[142:145], v[4:7]
	s_setprio 0
	s_barrier
	s_add_u32 s62, s42, 0x10100
	s_addc_u32 s63, s43, 0
	s_mov_b32 m0, s49
	v_lshl_add_u64 v[8:9], s[62:63], 0, v[84:85]
	global_load_lds_dwordx4 v[8:9], off
	v_lshl_add_u64 v[8:9], s[62:63], 0, v[80:81]
	s_mov_b32 m0, s50
	s_nop 0
	global_load_lds_dwordx4 v[8:9], off
	s_waitcnt vmcnt(6)
	s_barrier
	s_setprio 1
	v_mfma_f32_16x16x32_bf16 v[8:11], v[98:101], v[44:47], 0
	v_mfma_f32_16x16x32_bf16 v[12:15], v[106:109], v[44:47], 0
	v_mfma_f32_16x16x32_bf16 v[8:11], v[102:105], v[118:121], v[8:11]
	v_mfma_f32_16x16x32_bf16 v[12:15], v[110:113], v[118:121], v[12:15]
	v_mfma_f32_16x16x32_bf16 v[44:47], v[98:101], v[122:125], 0
	v_mfma_f32_16x16x32_bf16 v[118:121], v[106:109], v[122:125], 0
	v_mfma_f32_16x16x32_bf16 v[122:125], v[98:101], v[130:133], 0
	v_mfma_f32_16x16x32_bf16 v[98:101], v[98:101], v[138:141], 0
	v_mfma_f32_16x16x32_bf16 v[44:47], v[102:105], v[126:129], v[44:47]
	v_mfma_f32_16x16x32_bf16 v[118:121], v[110:113], v[126:129], v[118:121]
	v_mfma_f32_16x16x32_bf16 v[122:125], v[102:105], v[134:137], v[122:125]
	v_mfma_f32_16x16x32_bf16 v[126:129], v[106:109], v[130:133], 0
	v_mfma_f32_16x16x32_bf16 v[98:101], v[102:105], v[142:145], v[98:101]
	v_mfma_f32_16x16x32_bf16 v[102:105], v[106:109], v[138:141], 0
	v_mfma_f32_16x16x32_bf16 v[126:129], v[110:113], v[134:137], v[126:129]
	v_mfma_f32_16x16x32_bf16 v[102:105], v[110:113], v[142:145], v[102:105]
	s_setprio 0
	s_barrier
	s_waitcnt vmcnt(0)
	ds_read_b128 v[106:109], v95
	ds_read_b128 v[110:113], v95 offset:1024
	ds_read_b128 v[130:133], v95 offset:2048
	ds_read_b128 v[134:137], v95 offset:3072
	s_add_u32 s62, s40, 0x40100
	s_addc_u32 s63, s41, 0
	s_mov_b32 m0, s51
	v_lshl_add_u64 v[196:197], s[62:63], 0, v[86:87]
	ds_read_b128 v[138:141], v91 offset:32768
	ds_read_b128 v[142:145], v91 offset:33792
	ds_read_b128 v[172:175], v91 offset:34816
	ds_read_b128 v[176:179], v91 offset:35840
	ds_read_b128 v[180:183], v91 offset:36864
	ds_read_b128 v[184:187], v91 offset:37888
	ds_read_b128 v[188:191], v91 offset:38912
	ds_read_b128 v[192:195], v91 offset:39936
	global_load_lds_dwordx4 v[196:197], off
	v_lshl_add_u64 v[196:197], s[62:63], 0, v[82:83]
	s_mov_b32 m0, s52
	s_nop 0
	global_load_lds_dwordx4 v[196:197], off
	s_waitcnt lgkmcnt(8)
	s_barrier
	s_waitcnt lgkmcnt(0)
	s_setprio 1
	s_waitcnt lgkmcnt(0)
	v_mfma_f32_16x16x32_bf16 v[48:51], v[106:109], v[138:141], v[48:51]
	v_mfma_f32_16x16x32_bf16 v[52:55], v[130:133], v[138:141], v[52:55]
	v_mfma_f32_16x16x32_bf16 v[56:59], v[106:109], v[172:175], v[56:59]
	v_mfma_f32_16x16x32_bf16 v[60:63], v[130:133], v[172:175], v[60:63]
	v_mfma_f32_16x16x32_bf16 v[64:67], v[106:109], v[180:183], v[64:67]
	v_mfma_f32_16x16x32_bf16 v[68:71], v[130:133], v[180:183], v[68:71]
	v_mfma_f32_16x16x32_bf16 v[72:75], v[106:109], v[188:191], v[72:75]
	v_mfma_f32_16x16x32_bf16 v[76:79], v[130:133], v[188:191], v[76:79]
	v_mfma_f32_16x16x32_bf16 v[48:51], v[110:113], v[142:145], v[48:51]
	v_mfma_f32_16x16x32_bf16 v[52:55], v[134:137], v[142:145], v[52:55]
	v_mfma_f32_16x16x32_bf16 v[56:59], v[110:113], v[176:179], v[56:59]
	v_mfma_f32_16x16x32_bf16 v[60:63], v[134:137], v[176:179], v[60:63]
	v_mfma_f32_16x16x32_bf16 v[64:67], v[110:113], v[184:187], v[64:67]
	v_mfma_f32_16x16x32_bf16 v[68:71], v[134:137], v[184:187], v[68:71]
	v_mfma_f32_16x16x32_bf16 v[72:75], v[110:113], v[192:195], v[72:75]
	v_mfma_f32_16x16x32_bf16 v[76:79], v[134:137], v[192:195], v[76:79]
	s_setprio 0
	s_barrier
	s_mov_b32 m0, s53
	v_lshl_add_u64 v[212:213], v[212:213], 0, s[20:21]
	s_waitcnt vmcnt(0)
	ds_read_b128 v[196:199], v96
	ds_read_b128 v[200:203], v96 offset:1024
	ds_read_b128 v[204:207], v96 offset:2048
	ds_read_b128 v[208:211], v96 offset:3072
	global_load_lds_dwordx4 v[212:213], off
	v_lshl_add_u64 v[212:213], v[214:215], 0, s[20:21]
	s_mov_b32 m0, s54
	s_nop 0
	global_load_lds_dwordx4 v[212:213], off
	s_barrier
	s_waitcnt lgkmcnt(0)
	s_setprio 1
	s_waitcnt lgkmcnt(0)
	v_mfma_f32_16x16x32_bf16 v[114:117], v[196:199], v[138:141], v[114:117]
	v_mfma_f32_16x16x32_bf16 v[16:19], v[204:207], v[138:141], v[16:19]
	v_mfma_f32_16x16x32_bf16 v[20:23], v[196:199], v[172:175], v[20:23]
	v_mfma_f32_16x16x32_bf16 v[24:27], v[204:207], v[172:175], v[24:27]
	v_mfma_f32_16x16x32_bf16 v[28:31], v[196:199], v[180:183], v[28:31]
	v_mfma_f32_16x16x32_bf16 v[32:35], v[204:207], v[180:183], v[32:35]
	v_mfma_f32_16x16x32_bf16 v[36:39], v[196:199], v[188:191], v[36:39]
	v_mfma_f32_16x16x32_bf16 v[40:43], v[204:207], v[188:191], v[40:43]
	v_mfma_f32_16x16x32_bf16 v[114:117], v[200:203], v[142:145], v[114:117]
	v_mfma_f32_16x16x32_bf16 v[16:19], v[208:211], v[142:145], v[16:19]
	v_mfma_f32_16x16x32_bf16 v[20:23], v[200:203], v[176:179], v[20:23]
	v_mfma_f32_16x16x32_bf16 v[24:27], v[208:211], v[176:179], v[24:27]
	v_mfma_f32_16x16x32_bf16 v[28:31], v[200:203], v[184:187], v[28:31]
	v_mfma_f32_16x16x32_bf16 v[32:35], v[208:211], v[184:187], v[32:35]
	v_mfma_f32_16x16x32_bf16 v[36:39], v[200:203], v[192:195], v[36:39]
	v_mfma_f32_16x16x32_bf16 v[40:43], v[208:211], v[192:195], v[40:43]
	s_setprio 0
	s_mov_b32 m0, s55
	v_lshl_add_u64 v[212:213], v[216:217], 0, s[20:21]
	s_barrier
	s_waitcnt vmcnt(0)
	ds_read_b128 v[138:141], v91 offset:49152
	ds_read_b128 v[142:145], v91 offset:50176
	ds_read_b128 v[172:175], v91 offset:51200
	ds_read_b128 v[176:179], v91 offset:52224
	ds_read_b128 v[180:183], v91 offset:53248
	ds_read_b128 v[184:187], v91 offset:54272
	ds_read_b128 v[188:191], v91 offset:55296
	ds_read_b128 v[192:195], v91 offset:56320
	global_load_lds_dwordx4 v[212:213], off
	v_lshl_add_u64 v[212:213], v[218:219], 0, s[20:21]
	s_mov_b32 m0, s56
	s_nop 0
	global_load_lds_dwordx4 v[212:213], off
	s_barrier
	s_waitcnt lgkmcnt(0)
	s_setprio 1
	s_waitcnt lgkmcnt(0)
	v_mfma_f32_16x16x32_bf16 v[148:151], v[106:109], v[138:141], v[148:151]
	v_mfma_f32_16x16x32_bf16 v[152:155], v[130:133], v[138:141], v[152:155]
	v_mfma_f32_16x16x32_bf16 v[156:159], v[106:109], v[172:175], v[156:159]
	v_mfma_f32_16x16x32_bf16 v[160:163], v[130:133], v[172:175], v[160:163]
	v_mfma_f32_16x16x32_bf16 v[164:167], v[106:109], v[180:183], v[164:167]
	v_mfma_f32_16x16x32_bf16 v[168:171], v[130:133], v[180:183], v[168:171]
	v_mfma_f32_16x16x32_bf16 v[0:3], v[106:109], v[188:191], v[0:3]
	v_mfma_f32_16x16x32_bf16 v[4:7], v[130:133], v[188:191], v[4:7]
	v_mfma_f32_16x16x32_bf16 v[148:151], v[110:113], v[142:145], v[148:151]
	v_mfma_f32_16x16x32_bf16 v[152:155], v[134:137], v[142:145], v[152:155]
	v_mfma_f32_16x16x32_bf16 v[156:159], v[110:113], v[176:179], v[156:159]
	v_mfma_f32_16x16x32_bf16 v[160:163], v[134:137], v[176:179], v[160:163]
	v_mfma_f32_16x16x32_bf16 v[164:167], v[110:113], v[184:187], v[164:167]
	v_mfma_f32_16x16x32_bf16 v[168:171], v[134:137], v[184:187], v[168:171]
	v_mfma_f32_16x16x32_bf16 v[0:3], v[110:113], v[192:195], v[0:3]
	v_mfma_f32_16x16x32_bf16 v[4:7], v[134:137], v[192:195], v[4:7]
	s_setprio 0
	s_barrier
	s_add_u32 s42, s42, 0x10180
	s_addc_u32 s43, s43, 0
	s_mov_b32 m0, s57
	v_lshl_add_u64 v[106:107], s[42:43], 0, v[84:85]
	global_load_lds_dwordx4 v[106:107], off
	v_lshl_add_u64 v[106:107], s[42:43], 0, v[80:81]
	s_mov_b32 m0, s58
	s_nop 0
	global_load_lds_dwordx4 v[106:107], off
	s_waitcnt vmcnt(6)
	s_barrier
	s_setprio 1
	v_mfma_f32_16x16x32_bf16 v[8:11], v[196:199], v[138:141], v[8:11]
	v_mfma_f32_16x16x32_bf16 v[12:15], v[204:207], v[138:141], v[12:15]
	v_mfma_f32_16x16x32_bf16 v[44:47], v[196:199], v[172:175], v[44:47]
	v_mfma_f32_16x16x32_bf16 v[106:109], v[204:207], v[172:175], v[118:121]
	v_mfma_f32_16x16x32_bf16 v[110:113], v[196:199], v[180:183], v[122:125]
	v_mfma_f32_16x16x32_bf16 v[118:121], v[204:207], v[180:183], v[126:129]
	v_mfma_f32_16x16x32_bf16 v[98:101], v[196:199], v[188:191], v[98:101]
	v_mfma_f32_16x16x32_bf16 v[102:105], v[204:207], v[188:191], v[102:105]
	v_mfma_f32_16x16x32_bf16 v[8:11], v[200:203], v[142:145], v[8:11]
	v_mfma_f32_16x16x32_bf16 v[12:15], v[208:211], v[142:145], v[12:15]
	v_mfma_f32_16x16x32_bf16 v[44:47], v[200:203], v[176:179], v[44:47]
	v_mfma_f32_16x16x32_bf16 v[106:109], v[208:211], v[176:179], v[106:109]
	v_mfma_f32_16x16x32_bf16 v[110:113], v[200:203], v[184:187], v[110:113]
	v_mfma_f32_16x16x32_bf16 v[118:121], v[208:211], v[184:187], v[118:121]
	v_mfma_f32_16x16x32_bf16 v[98:101], v[200:203], v[192:195], v[98:101]
	v_mfma_f32_16x16x32_bf16 v[102:105], v[208:211], v[192:195], v[102:105]
	s_setprio 0
	s_barrier
	s_waitcnt vmcnt(0)
	ds_read_b128 v[122:125], v93
	ds_read_b128 v[126:129], v93 offset:1024
	ds_read_b128 v[130:133], v93 offset:2048
	ds_read_b128 v[134:137], v93 offset:3072
	s_add_u32 s40, s40, 0x40180
	s_addc_u32 s41, s41, 0
	s_mov_b32 m0, s59
	v_lshl_add_u64 v[196:197], s[40:41], 0, v[86:87]
	ds_read_b128 v[138:141], v91
	ds_read_b128 v[142:145], v91 offset:1024
	ds_read_b128 v[172:175], v91 offset:2048
	ds_read_b128 v[176:179], v91 offset:3072
	ds_read_b128 v[180:183], v91 offset:4096
	ds_read_b128 v[184:187], v91 offset:5120
	ds_read_b128 v[188:191], v91 offset:6144
	ds_read_b128 v[192:195], v91 offset:7168
	global_load_lds_dwordx4 v[196:197], off
	v_lshl_add_u64 v[196:197], s[40:41], 0, v[82:83]
	s_mov_b32 m0, s60
	s_nop 0
	global_load_lds_dwordx4 v[196:197], off
	s_waitcnt lgkmcnt(8)
	s_barrier
	s_waitcnt lgkmcnt(0)
	s_setprio 1
	s_waitcnt lgkmcnt(0)
	v_mfma_f32_16x16x32_bf16 v[48:51], v[122:125], v[138:141], v[48:51]
	v_mfma_f32_16x16x32_bf16 v[52:55], v[130:133], v[138:141], v[52:55]
	v_mfma_f32_16x16x32_bf16 v[56:59], v[122:125], v[172:175], v[56:59]
	v_mfma_f32_16x16x32_bf16 v[60:63], v[130:133], v[172:175], v[60:63]
	v_mfma_f32_16x16x32_bf16 v[64:67], v[122:125], v[180:183], v[64:67]
	v_mfma_f32_16x16x32_bf16 v[68:71], v[130:133], v[180:183], v[68:71]
	v_mfma_f32_16x16x32_bf16 v[72:75], v[122:125], v[188:191], v[72:75]
	v_mfma_f32_16x16x32_bf16 v[76:79], v[130:133], v[188:191], v[76:79]
	v_mfma_f32_16x16x32_bf16 v[48:51], v[126:129], v[142:145], v[48:51]
	v_mfma_f32_16x16x32_bf16 v[52:55], v[134:137], v[142:145], v[52:55]
	v_mfma_f32_16x16x32_bf16 v[56:59], v[126:129], v[176:179], v[56:59]
	v_mfma_f32_16x16x32_bf16 v[60:63], v[134:137], v[176:179], v[60:63]
	v_mfma_f32_16x16x32_bf16 v[64:67], v[126:129], v[184:187], v[64:67]
	v_mfma_f32_16x16x32_bf16 v[68:71], v[134:137], v[184:187], v[68:71]
	v_mfma_f32_16x16x32_bf16 v[72:75], v[126:129], v[192:195], v[72:75]
	v_mfma_f32_16x16x32_bf16 v[76:79], v[134:137], v[192:195], v[76:79]
	s_setprio 0
	s_barrier
	s_mov_b32 m0, s35
	v_lshl_add_u64 v[236:237], s[38:39], 0, v[84:85]
	s_waitcnt vmcnt(0)
	ds_read_b128 v[196:199], v94
	ds_read_b128 v[200:203], v94 offset:1024
	ds_read_b128 v[204:207], v94 offset:2048
	ds_read_b128 v[208:211], v94 offset:3072
	global_load_lds_dwordx4 v[236:237], off
	v_lshl_add_u64 v[238:239], s[38:39], 0, v[80:81]
	s_mov_b32 m0, s47
	s_nop 0
	global_load_lds_dwordx4 v[238:239], off
	s_barrier
	s_waitcnt lgkmcnt(0)
	s_setprio 1
	s_waitcnt lgkmcnt(0)
	v_mfma_f32_16x16x32_bf16 v[114:117], v[196:199], v[138:141], v[114:117]
	v_mfma_f32_16x16x32_bf16 v[16:19], v[204:207], v[138:141], v[16:19]
	v_mfma_f32_16x16x32_bf16 v[20:23], v[196:199], v[172:175], v[20:23]
	v_mfma_f32_16x16x32_bf16 v[24:27], v[204:207], v[172:175], v[24:27]
	v_mfma_f32_16x16x32_bf16 v[28:31], v[196:199], v[180:183], v[28:31]
	v_mfma_f32_16x16x32_bf16 v[32:35], v[204:207], v[180:183], v[32:35]
	v_mfma_f32_16x16x32_bf16 v[36:39], v[196:199], v[188:191], v[36:39]
	v_mfma_f32_16x16x32_bf16 v[40:43], v[204:207], v[188:191], v[40:43]
	v_mfma_f32_16x16x32_bf16 v[114:117], v[200:203], v[142:145], v[114:117]
	v_mfma_f32_16x16x32_bf16 v[16:19], v[208:211], v[142:145], v[16:19]
	v_mfma_f32_16x16x32_bf16 v[20:23], v[200:203], v[176:179], v[20:23]
	v_mfma_f32_16x16x32_bf16 v[24:27], v[208:211], v[176:179], v[24:27]
	v_mfma_f32_16x16x32_bf16 v[28:31], v[200:203], v[184:187], v[28:31]
	v_mfma_f32_16x16x32_bf16 v[32:35], v[208:211], v[184:187], v[32:35]
	v_mfma_f32_16x16x32_bf16 v[36:39], v[200:203], v[192:195], v[36:39]
	v_mfma_f32_16x16x32_bf16 v[40:43], v[208:211], v[192:195], v[40:43]
	s_setprio 0
	s_mov_b32 m0, s46
	v_lshl_add_u64 v[244:245], s[44:45], 0, v[86:87]
	s_barrier
	s_waitcnt vmcnt(0)
	ds_read_b128 v[138:141], v91 offset:16384
	ds_read_b128 v[142:145], v91 offset:17408
	ds_read_b128 v[172:175], v91 offset:18432
	ds_read_b128 v[176:179], v91 offset:19456
	ds_read_b128 v[180:183], v91 offset:20480
	ds_read_b128 v[184:187], v91 offset:21504
	ds_read_b128 v[188:191], v91 offset:22528
	ds_read_b128 v[192:195], v91 offset:23552
	global_load_lds_dwordx4 v[244:245], off
	v_lshl_add_u64 v[246:247], s[44:45], 0, v[82:83]
	s_mov_b32 m0, s48
	s_nop 0
	global_load_lds_dwordx4 v[246:247], off
	s_barrier
	s_waitcnt lgkmcnt(0)
	s_setprio 1
	s_waitcnt lgkmcnt(0)
	v_mfma_f32_16x16x32_bf16 v[148:151], v[122:125], v[138:141], v[148:151]
	v_mfma_f32_16x16x32_bf16 v[152:155], v[130:133], v[138:141], v[152:155]
	v_mfma_f32_16x16x32_bf16 v[156:159], v[122:125], v[172:175], v[156:159]
	v_mfma_f32_16x16x32_bf16 v[160:163], v[130:133], v[172:175], v[160:163]
	v_mfma_f32_16x16x32_bf16 v[164:167], v[122:125], v[180:183], v[164:167]
	v_mfma_f32_16x16x32_bf16 v[168:171], v[130:133], v[180:183], v[168:171]
	v_mfma_f32_16x16x32_bf16 v[0:3], v[122:125], v[188:191], v[0:3]
	v_mfma_f32_16x16x32_bf16 v[4:7], v[130:133], v[188:191], v[4:7]
	v_mfma_f32_16x16x32_bf16 v[148:151], v[126:129], v[142:145], v[148:151]
	v_mfma_f32_16x16x32_bf16 v[152:155], v[134:137], v[142:145], v[152:155]
	v_mfma_f32_16x16x32_bf16 v[156:159], v[126:129], v[176:179], v[156:159]
	v_mfma_f32_16x16x32_bf16 v[160:163], v[134:137], v[176:179], v[160:163]
	v_mfma_f32_16x16x32_bf16 v[164:167], v[126:129], v[184:187], v[164:167]
	v_mfma_f32_16x16x32_bf16 v[168:171], v[134:137], v[184:187], v[168:171]
	v_mfma_f32_16x16x32_bf16 v[0:3], v[126:129], v[192:195], v[0:3]
	v_mfma_f32_16x16x32_bf16 v[122:125], v[134:137], v[192:195], v[4:7]
	s_setprio 0
	s_barrier
	s_add_u32 s40, s38, 0x10000
	s_addc_u32 s41, s39, 0
	s_mov_b32 m0, s49
	v_lshl_add_u64 v[4:5], s[40:41], 0, v[84:85]
	global_load_lds_dwordx4 v[4:5], off
	v_lshl_add_u64 v[4:5], s[40:41], 0, v[80:81]
	s_mov_b32 m0, s50
	s_nop 0
	global_load_lds_dwordx4 v[4:5], off
	s_waitcnt vmcnt(6)
	s_barrier
	s_setprio 1
	v_mfma_f32_16x16x32_bf16 v[4:7], v[196:199], v[138:141], v[8:11]
	v_mfma_f32_16x16x32_bf16 v[8:11], v[200:203], v[142:145], v[4:7]
	v_mfma_f32_16x16x32_bf16 v[4:7], v[204:207], v[138:141], v[12:15]
	v_mfma_f32_16x16x32_bf16 v[12:15], v[208:211], v[142:145], v[4:7]
	v_mfma_f32_16x16x32_bf16 v[4:7], v[196:199], v[172:175], v[44:47]
	v_mfma_f32_16x16x32_bf16 v[44:47], v[200:203], v[176:179], v[4:7]
	v_mfma_f32_16x16x32_bf16 v[4:7], v[204:207], v[172:175], v[106:109]
	v_mfma_f32_16x16x32_bf16 v[106:109], v[208:211], v[176:179], v[4:7]
	v_mfma_f32_16x16x32_bf16 v[4:7], v[196:199], v[180:183], v[110:113]
	v_mfma_f32_16x16x32_bf16 v[110:113], v[200:203], v[184:187], v[4:7]
	v_mfma_f32_16x16x32_bf16 v[4:7], v[204:207], v[180:183], v[118:121]
	v_mfma_f32_16x16x32_bf16 v[118:121], v[208:211], v[184:187], v[4:7]
	v_mfma_f32_16x16x32_bf16 v[4:7], v[196:199], v[188:191], v[98:101]
	v_mfma_f32_16x16x32_bf16 v[98:101], v[200:203], v[192:195], v[4:7]
	v_mfma_f32_16x16x32_bf16 v[4:7], v[204:207], v[188:191], v[102:105]
	v_mfma_f32_16x16x32_bf16 v[102:105], v[208:211], v[192:195], v[4:7]
	s_setprio 0
	s_barrier
	s_waitcnt vmcnt(0)
	s_nop 3
	ds_read_b128 v[4:7], v95
	ds_read_b128 v[126:129], v95 offset:1024
	ds_read_b128 v[130:133], v95 offset:2048
	ds_read_b128 v[134:137], v95 offset:3072
	s_add_u32 s40, s44, 0x40000
	s_addc_u32 s41, s45, 0
	s_mov_b32 m0, s51
	v_lshl_add_u64 v[196:197], s[40:41], 0, v[86:87]
	ds_read_b128 v[138:141], v91 offset:32768
	ds_read_b128 v[142:145], v91 offset:33792
	ds_read_b128 v[172:175], v91 offset:34816
	ds_read_b128 v[176:179], v91 offset:35840
	ds_read_b128 v[180:183], v91 offset:36864
	ds_read_b128 v[184:187], v91 offset:37888
	ds_read_b128 v[188:191], v91 offset:38912
	ds_read_b128 v[192:195], v91 offset:39936
	global_load_lds_dwordx4 v[196:197], off
	v_lshl_add_u64 v[196:197], s[40:41], 0, v[82:83]
	s_mov_b32 m0, s52
	s_nop 0
	global_load_lds_dwordx4 v[196:197], off
	s_waitcnt lgkmcnt(8)
	s_barrier
	s_waitcnt lgkmcnt(0)
	s_setprio 1
	s_waitcnt lgkmcnt(0)
	v_mfma_f32_16x16x32_bf16 v[48:51], v[4:7], v[138:141], v[48:51]
	v_mfma_f32_16x16x32_bf16 v[196:199], v[126:129], v[142:145], v[48:51]
	v_mfma_f32_16x16x32_bf16 v[48:51], v[130:133], v[138:141], v[52:55]
	v_mfma_f32_16x16x32_bf16 v[200:203], v[134:137], v[142:145], v[48:51]
	v_mfma_f32_16x16x32_bf16 v[48:51], v[4:7], v[172:175], v[56:59]
	v_mfma_f32_16x16x32_bf16 v[204:207], v[126:129], v[176:179], v[48:51]
	v_mfma_f32_16x16x32_bf16 v[48:51], v[130:133], v[172:175], v[60:63]
	v_mfma_f32_16x16x32_bf16 v[208:211], v[134:137], v[176:179], v[48:51]
	v_mfma_f32_16x16x32_bf16 v[48:51], v[4:7], v[180:183], v[64:67]
	v_mfma_f32_16x16x32_bf16 v[212:215], v[126:129], v[184:187], v[48:51]
	v_mfma_f32_16x16x32_bf16 v[48:51], v[130:133], v[180:183], v[68:71]
	v_mfma_f32_16x16x32_bf16 v[216:219], v[134:137], v[184:187], v[48:51]
	v_mfma_f32_16x16x32_bf16 v[48:51], v[4:7], v[188:191], v[72:75]
	v_mfma_f32_16x16x32_bf16 v[52:55], v[126:129], v[192:195], v[48:51]
	v_mfma_f32_16x16x32_bf16 v[48:51], v[130:133], v[188:191], v[76:79]
	v_mfma_f32_16x16x32_bf16 v[48:51], v[134:137], v[192:195], v[48:51]
	s_setprio 0
	s_barrier
	s_mov_b32 m0, s53
	v_lshl_add_u64 v[56:57], v[236:237], 0, s[16:17]
	s_waitcnt vmcnt(0)
	ds_read_b128 v[220:223], v96
	ds_read_b128 v[224:227], v96 offset:1024
	ds_read_b128 v[228:231], v96 offset:2048
	ds_read_b128 v[232:235], v96 offset:3072
	global_load_lds_dwordx4 v[56:57], off
	v_lshl_add_u64 v[56:57], v[238:239], 0, s[16:17]
	s_mov_b32 m0, s54
	s_nop 0
	global_load_lds_dwordx4 v[56:57], off
	s_barrier
	s_waitcnt lgkmcnt(0)
	s_setprio 1
	s_waitcnt lgkmcnt(0)
	v_mfma_f32_16x16x32_bf16 v[16:19], v[228:231], v[138:141], v[16:19]
	v_mfma_f32_16x16x32_bf16 v[56:59], v[220:223], v[138:141], v[114:117]
	v_mfma_f32_16x16x32_bf16 v[138:141], v[232:235], v[142:145], v[16:19]
	v_mfma_f32_16x16x32_bf16 v[16:19], v[220:223], v[172:175], v[20:23]
	v_mfma_f32_16x16x32_bf16 v[114:117], v[224:227], v[142:145], v[56:59]
	v_mfma_f32_16x16x32_bf16 v[142:145], v[224:227], v[176:179], v[16:19]
	v_mfma_f32_16x16x32_bf16 v[16:19], v[228:231], v[172:175], v[24:27]
	v_mfma_f32_16x16x32_bf16 v[172:175], v[232:235], v[176:179], v[16:19]
	v_mfma_f32_16x16x32_bf16 v[16:19], v[220:223], v[180:183], v[28:31]
	v_mfma_f32_16x16x32_bf16 v[176:179], v[224:227], v[184:187], v[16:19]
	v_mfma_f32_16x16x32_bf16 v[16:19], v[228:231], v[180:183], v[32:35]
	v_mfma_f32_16x16x32_bf16 v[180:183], v[232:235], v[184:187], v[16:19]
	v_mfma_f32_16x16x32_bf16 v[16:19], v[220:223], v[188:191], v[36:39]
	v_mfma_f32_16x16x32_bf16 v[68:71], v[224:227], v[192:195], v[16:19]
	v_mfma_f32_16x16x32_bf16 v[16:19], v[228:231], v[188:191], v[40:43]
	v_mfma_f32_16x16x32_bf16 v[60:63], v[232:235], v[192:195], v[16:19]
	s_setprio 0
	s_mov_b32 m0, s55
	s_nop 4
	v_lshl_add_u64 v[16:17], v[244:245], 0, s[16:17]
	s_barrier
	s_waitcnt vmcnt(0)
	ds_read_b128 v[24:27], v91 offset:49152
	ds_read_b128 v[28:31], v91 offset:50176
	ds_read_b128 v[40:43], v91 offset:51200
	ds_read_b128 v[184:187], v91 offset:52224
	ds_read_b128 v[188:191], v91 offset:53248
	ds_read_b128 v[192:195], v91 offset:54272
	ds_read_b128 v[236:239], v91 offset:55296
	ds_read_b128 v[240:243], v91 offset:56320
	global_load_lds_dwordx4 v[16:17], off
	v_lshl_add_u64 v[16:17], v[246:247], 0, s[16:17]
	s_mov_b32 m0, s56
	s_nop 0
	global_load_lds_dwordx4 v[16:17], off
	s_barrier
	s_waitcnt lgkmcnt(0)
	s_setprio 1
	s_waitcnt lgkmcnt(0)
	v_mfma_f32_16x16x32_bf16 v[16:19], v[4:7], v[24:27], v[148:151]
	v_mfma_f32_16x16x32_bf16 v[64:67], v[126:129], v[28:31], v[16:19]
	v_mfma_f32_16x16x32_bf16 v[16:19], v[130:133], v[24:27], v[152:155]
	v_mfma_f32_16x16x32_bf16 v[56:59], v[134:137], v[28:31], v[16:19]
	v_mfma_f32_16x16x32_bf16 v[16:19], v[4:7], v[40:43], v[156:159]
	v_mfma_f32_16x16x32_bf16 v[36:39], v[126:129], v[184:187], v[16:19]
	v_mfma_f32_16x16x32_bf16 v[16:19], v[130:133], v[40:43], v[160:163]
	v_mfma_f32_16x16x32_bf16 v[32:35], v[134:137], v[184:187], v[16:19]
	v_mfma_f32_16x16x32_bf16 v[16:19], v[4:7], v[188:191], v[164:167]
	v_mfma_f32_16x16x32_bf16 v[0:3], v[4:7], v[236:239], v[0:3]
	v_mfma_f32_16x16x32_bf16 v[20:23], v[126:129], v[192:195], v[16:19]
	v_mfma_f32_16x16x32_bf16 v[16:19], v[130:133], v[188:191], v[168:171]
	v_mfma_f32_16x16x32_bf16 v[4:7], v[126:129], v[240:243], v[0:3]
	v_mfma_f32_16x16x32_bf16 v[0:3], v[130:133], v[236:239], v[122:125]
	v_mfma_f32_16x16x32_bf16 v[16:19], v[134:137], v[192:195], v[16:19]
	v_mfma_f32_16x16x32_bf16 v[0:3], v[134:137], v[240:243], v[0:3]
	s_setprio 0
	s_barrier
	s_add_u32 s38, s38, 0x10080
	s_addc_u32 s39, s39, 0
	s_mov_b32 m0, s57
	v_lshl_add_u64 v[72:73], s[38:39], 0, v[84:85]
	global_load_lds_dwordx4 v[72:73], off
	v_lshl_add_u64 v[72:73], s[38:39], 0, v[80:81]
	s_mov_b32 m0, s58
	s_nop 0
	global_load_lds_dwordx4 v[72:73], off
	s_waitcnt vmcnt(6)
	s_barrier
	s_setprio 1
	v_mfma_f32_16x16x32_bf16 v[8:11], v[220:223], v[24:27], v[8:11]
	v_mfma_f32_16x16x32_bf16 v[76:79], v[224:227], v[28:31], v[8:11]
	v_mfma_f32_16x16x32_bf16 v[8:11], v[228:231], v[24:27], v[12:15]
	v_mfma_f32_16x16x32_bf16 v[72:75], v[232:235], v[28:31], v[8:11]
	v_mfma_f32_16x16x32_bf16 v[8:11], v[220:223], v[40:43], v[44:47]
	v_mfma_f32_16x16x32_bf16 v[44:47], v[224:227], v[184:187], v[8:11]
	v_mfma_f32_16x16x32_bf16 v[8:11], v[228:231], v[40:43], v[106:109]
	v_mfma_f32_16x16x32_bf16 v[40:43], v[232:235], v[184:187], v[8:11]
	v_mfma_f32_16x16x32_bf16 v[8:11], v[220:223], v[188:191], v[110:113]
	v_mfma_f32_16x16x32_bf16 v[28:31], v[224:227], v[192:195], v[8:11]
	v_mfma_f32_16x16x32_bf16 v[8:11], v[228:231], v[188:191], v[118:121]
	v_mfma_f32_16x16x32_bf16 v[24:27], v[232:235], v[192:195], v[8:11]
	v_mfma_f32_16x16x32_bf16 v[8:11], v[220:223], v[236:239], v[98:101]
	v_mfma_f32_16x16x32_bf16 v[12:15], v[224:227], v[240:243], v[8:11]
	v_mfma_f32_16x16x32_bf16 v[8:11], v[228:231], v[236:239], v[102:105]
	v_mfma_f32_16x16x32_bf16 v[8:11], v[232:235], v[240:243], v[8:11]
	s_setprio 0
	s_lshl_b32 s25, s36, 8
	s_and_b32 s25, s25, 0x300
	s_cmp_lt_i32 s36, 4
	s_cselect_b32 s37, s5, s9
	s_cselect_b32 s36, s4, s8
	s_lshl_b32 s27, s34, 18
	v_cvt_pk_bf16_f32 v98, v196, v197
	s_or_b32 s25, s27, s25
	v_cvt_pk_bf16_f32 v99, v198, v199
	v_add_u32_e32 v88, s25, v92
	v_cvt_pk_bf16_f32 v100, v200, v201
	v_cvt_pk_bf16_f32 v101, v202, v203
	v_lshl_add_u64 v[102:103], v[88:89], 1, s[36:37]
	s_barrier
	global_store_dwordx4 v[102:103], v[98:101], off
	s_nop 1
	v_add_u32_e32 v102, 0x80, v88
	v_cvt_pk_bf16_f32 v98, v114, v115
	v_cvt_pk_bf16_f32 v99, v116, v117
	v_cvt_pk_bf16_f32 v100, v138, v139
	v_mov_b32_e32 v103, v89
	v_cvt_pk_bf16_f32 v101, v140, v141
	v_lshl_add_u64 v[102:103], v[102:103], 1, s[36:37]
	global_store_dwordx4 v[102:103], v[98:101], off
	s_nop 1
	v_add_u32_e32 v102, 0x4000, v88
	v_cvt_pk_bf16_f32 v98, v204, v205
	v_cvt_pk_bf16_f32 v99, v206, v207
	v_cvt_pk_bf16_f32 v100, v208, v209
	v_mov_b32_e32 v103, v89
	v_cvt_pk_bf16_f32 v101, v210, v211
	v_lshl_add_u64 v[102:103], v[102:103], 1, s[36:37]
	global_store_dwordx4 v[102:103], v[98:101], off
	s_nop 1
	v_add_u32_e32 v102, 0x4080, v88
	v_cvt_pk_bf16_f32 v98, v142, v143
	v_cvt_pk_bf16_f32 v99, v144, v145
	v_cvt_pk_bf16_f32 v100, v172, v173
	v_mov_b32_e32 v103, v89
	v_cvt_pk_bf16_f32 v101, v174, v175
	v_lshl_add_u64 v[102:103], v[102:103], 1, s[36:37]
	global_store_dwordx4 v[102:103], v[98:101], off
	s_nop 1
	v_add_u32_e32 v102, 0x8000, v88
	v_cvt_pk_bf16_f32 v98, v212, v213
	v_cvt_pk_bf16_f32 v99, v214, v215
	v_cvt_pk_bf16_f32 v100, v216, v217
	v_mov_b32_e32 v103, v89
	v_cvt_pk_bf16_f32 v101, v218, v219
	v_lshl_add_u64 v[102:103], v[102:103], 1, s[36:37]
	global_store_dwordx4 v[102:103], v[98:101], off
	s_nop 1
	v_cvt_pk_bf16_f32 v98, v176, v177
	v_cvt_pk_bf16_f32 v99, v178, v179
	v_cvt_pk_bf16_f32 v52, v52, v53
	v_cvt_pk_bf16_f32 v100, v180, v181
	v_add_u32_e32 v102, 0x8080, v88
	v_mov_b32_e32 v103, v89
	v_cvt_pk_bf16_f32 v101, v182, v183
	v_lshl_add_u64 v[102:103], v[102:103], 1, s[36:37]
	v_cvt_pk_bf16_f32 v53, v54, v55
	v_cvt_pk_bf16_f32 v54, v48, v49
	global_store_dwordx4 v[102:103], v[98:101], off
	s_nop 1
	v_add_u32_e32 v98, 0xc000, v88
	v_mov_b32_e32 v99, v89
	v_cvt_pk_bf16_f32 v55, v50, v51
	v_lshl_add_u64 v[48:49], v[98:99], 1, s[36:37]
	global_store_dwordx4 v[48:49], v[52:55], off
	v_cvt_pk_bf16_f32 v48, v68, v69
	v_cvt_pk_bf16_f32 v49, v70, v71
	v_cvt_pk_bf16_f32 v50, v60, v61
	v_cvt_pk_bf16_f32 v51, v62, v63
	v_add_u32_e32 v52, 0xc080, v88
	v_mov_b32_e32 v53, v89
	v_lshl_add_u64 v[52:53], v[52:53], 1, s[36:37]
	global_store_dwordx4 v[52:53], v[48:51], off
	s_nop 1
	v_cvt_pk_bf16_f32 v48, v64, v65
	v_cvt_pk_bf16_f32 v49, v66, v67
	v_cvt_pk_bf16_f32 v50, v56, v57
	v_add_u32_e32 v52, 0x20000, v88
	v_cvt_pk_bf16_f32 v51, v58, v59
	v_mov_b32_e32 v53, v89
	v_lshl_add_u64 v[52:53], v[52:53], 1, s[36:37]
	global_store_dwordx4 v[52:53], v[48:51], off
	s_nop 1
	v_cvt_pk_bf16_f32 v48, v76, v77
	v_cvt_pk_bf16_f32 v49, v78, v79
	v_cvt_pk_bf16_f32 v50, v72, v73
	v_cvt_pk_bf16_f32 v36, v36, v37
	v_cvt_pk_bf16_f32 v51, v74, v75
	v_add_u32_e32 v52, 0x20080, v88
	v_mov_b32_e32 v53, v89
	v_lshl_add_u64 v[52:53], v[52:53], 1, s[36:37]
	v_cvt_pk_bf16_f32 v37, v38, v39
	v_cvt_pk_bf16_f32 v38, v32, v33
	global_store_dwordx4 v[52:53], v[48:51], off
	s_nop 1
	v_add_u32_e32 v48, 0x24000, v88
	v_mov_b32_e32 v49, v89
	v_cvt_pk_bf16_f32 v39, v34, v35
	v_lshl_add_u64 v[32:33], v[48:49], 1, s[36:37]
	global_store_dwordx4 v[32:33], v[36:39], off
	v_cvt_pk_bf16_f32 v32, v44, v45
	v_cvt_pk_bf16_f32 v33, v46, v47
	v_cvt_pk_bf16_f32 v34, v40, v41
	v_cvt_pk_bf16_f32 v20, v20, v21
	v_cvt_pk_bf16_f32 v35, v42, v43
	v_add_u32_e32 v36, 0x24080, v88
	v_mov_b32_e32 v37, v89
	v_lshl_add_u64 v[36:37], v[36:37], 1, s[36:37]
	v_cvt_pk_bf16_f32 v21, v22, v23
	v_cvt_pk_bf16_f32 v22, v16, v17
	global_store_dwordx4 v[36:37], v[32:35], off
	s_nop 1
	v_add_u32_e32 v32, 0x28000, v88
	v_mov_b32_e32 v33, v89
	v_cvt_pk_bf16_f32 v23, v18, v19
	v_lshl_add_u64 v[16:17], v[32:33], 1, s[36:37]
	global_store_dwordx4 v[16:17], v[20:23], off
	v_cvt_pk_bf16_f32 v16, v28, v29
	v_cvt_pk_bf16_f32 v17, v30, v31
	v_cvt_pk_bf16_f32 v18, v24, v25
	v_cvt_pk_bf16_f32 v4, v4, v5
	v_cvt_pk_bf16_f32 v19, v26, v27
	v_add_u32_e32 v20, 0x28080, v88
	v_mov_b32_e32 v21, v89
	v_lshl_add_u64 v[20:21], v[20:21], 1, s[36:37]
	v_cvt_pk_bf16_f32 v5, v6, v7
	v_cvt_pk_bf16_f32 v6, v0, v1
	global_store_dwordx4 v[20:21], v[16:19], off
	s_nop 1
	v_add_u32_e32 v16, 0x2c000, v88
	v_mov_b32_e32 v17, v89
	v_cvt_pk_bf16_f32 v7, v2, v3
	v_lshl_add_u64 v[0:1], v[16:17], 1, s[36:37]
	global_store_dwordx4 v[0:1], v[4:7], off
	v_cvt_pk_bf16_f32 v0, v12, v13
	v_cvt_pk_bf16_f32 v1, v14, v15
	v_cvt_pk_bf16_f32 v2, v8, v9
	v_add_u32_e32 v88, 0x2c080, v88
	v_cvt_pk_bf16_f32 v3, v10, v11
	v_lshl_add_u64 v[4:5], v[88:89], 1, s[36:37]
	s_andn2_b64 vcc, exec, s[22:23]
	s_mov_b32 s36, s24
	s_mov_b32 s34, s26
	s_mov_b64 s[42:43], s[30:31]
	s_mov_b64 s[40:41], s[28:29]
	global_store_dwordx4 v[4:5], v[0:3], off
	s_cbranch_vccz .LBB0_457

.LBB0_466:
	s_or_b64 exec, exec, s[4:5]
	v_cvt_pk_bf16_f32 v4, v4, v5
	v_cvt_pk_bf16_f32 v5, v6, v7
	v_cvt_pk_bf16_f32 v6, v0, v1
	v_and_or_b32 v136, v9, v120, v8
	v_cvt_pk_bf16_f32 v7, v2, v3
	v_lshl_add_u64 v[0:1], v[136:137], 1, s[10:11]
	global_store_dwordx4 v[0:1], v[4:7], off

.LBB0_474:
	s_andn2_b64 vcc, exec, s[30:31]
	s_cbranch_vccnz .LBB0_467
	v_lshl_add_u32 v148, s4, 8, v140
	v_lshl_add_u32 v150, s28, 8, v138
	v_cmp_lt_i32_e32 vcc, s66, v148
	v_lshl_add_u32 v149, v148, 4, v145
	s_and_saveexec_b64 s[4:5], vcc
	s_xor_b64 s[4:5], exec, s[4:5]
	v_and_b32_e32 v136, 0x3fffc00, v149
	v_add_u32_e32 v136, v136, v150
	v_lshl_add_u32 v136, v136, 6, v147
	s_or_saveexec_b64 s[4:5], s[4:5]
	v_lshrrev_b32_e32 v151, 2, v148
	v_mov_b32_e32 v152, 63
	v_and_b32_e32 v151, 0xffc00, v151
	s_xor_b64 exec, exec, s[4:5]
	v_add_lshl_u32 v136, v151, v150, 12
	v_mov_b32_e32 v152, 0xfff
	s_or_b64 exec, exec, s[4:5]
	v_cvt_pk_bf16_f32 v124, v124, v125
	v_cvt_pk_bf16_f32 v125, v126, v127
	v_cvt_pk_bf16_f32 v126, v120, v121
	v_and_or_b32 v136, v152, v148, v136
	v_cvt_pk_bf16_f32 v127, v122, v123
	v_lshl_add_u64 v[120:121], v[136:137], 1, s[10:11]
	global_store_dwordx4 v[120:121], v[124:127], off
	v_add_u32_e32 v120, 0x80, v148
	v_cmp_lt_i32_e64 s[4:5], s67, v148
	v_lshl_add_u32 v121, v120, 4, v145
	s_and_saveexec_b64 s[28:29], s[4:5]
	s_xor_b64 s[28:29], exec, s[28:29]
	v_and_b32_e32 v122, 0x3fffc00, v121
	v_add_u32_e32 v122, v122, v150
	v_lshl_add_u32 v123, v122, 6, v147
	s_or_saveexec_b64 s[28:29], s[28:29]
	v_lshrrev_b32_e32 v122, 2, v120
	v_mov_b32_e32 v124, 63
	v_and_b32_e32 v122, 0xffc00, v122
	s_xor_b64 exec, exec, s[28:29]
	v_add_lshl_u32 v123, v122, v150, 12
	v_mov_b32_e32 v124, 0xfff
	s_or_b64 exec, exec, s[28:29]
	v_cvt_pk_bf16_f32 v116, v116, v117
	v_cvt_pk_bf16_f32 v117, v118, v119
	v_cvt_pk_bf16_f32 v118, v112, v113
	v_and_or_b32 v136, v124, v120, v123
	v_cvt_pk_bf16_f32 v119, v114, v115
	v_lshl_add_u64 v[112:113], v[136:137], 1, s[10:11]
	global_store_dwordx4 v[112:113], v[116:119], off
	v_or_b32_e32 v112, 16, v150
	s_and_saveexec_b64 s[28:29], vcc
	s_xor_b64 s[28:29], exec, s[28:29]
	v_and_b32_e32 v113, 0x3fffc00, v149
	v_add_u32_e32 v113, v113, v112
	v_lshl_add_u32 v113, v113, 6, v147
	s_or_saveexec_b64 s[28:29], s[28:29]
	v_mov_b32_e32 v114, 63
	s_xor_b64 exec, exec, s[28:29]
	v_add_lshl_u32 v113, v151, v112, 12
	v_mov_b32_e32 v114, 0xfff
	s_or_b64 exec, exec, s[28:29]
	v_cvt_pk_bf16_f32 v108, v108, v109
	v_cvt_pk_bf16_f32 v109, v110, v111
	v_cvt_pk_bf16_f32 v110, v104, v105
	v_and_or_b32 v136, v114, v148, v113
	v_cvt_pk_bf16_f32 v111, v106, v107
	v_lshl_add_u64 v[104:105], v[136:137], 1, s[10:11]
	global_store_dwordx4 v[104:105], v[108:111], off
	s_and_saveexec_b64 s[28:29], s[4:5]
	s_xor_b64 s[28:29], exec, s[28:29]
	v_and_b32_e32 v104, 0x3fffc00, v121
	v_add_u32_e32 v104, v104, v112
	v_lshl_add_u32 v104, v104, 6, v147
	s_or_saveexec_b64 s[28:29], s[28:29]
	v_mov_b32_e32 v105, 63
	s_xor_b64 exec, exec, s[28:29]
	v_add_lshl_u32 v104, v122, v112, 12
	v_mov_b32_e32 v105, 0xfff
	s_or_b64 exec, exec, s[28:29]
	v_cvt_pk_bf16_f32 v100, v100, v101
	v_cvt_pk_bf16_f32 v101, v102, v103
	v_cvt_pk_bf16_f32 v102, v96, v97
	v_and_or_b32 v136, v105, v120, v104
	v_cvt_pk_bf16_f32 v103, v98, v99
	v_lshl_add_u64 v[96:97], v[136:137], 1, s[10:11]
	global_store_dwordx4 v[96:97], v[100:103], off
	v_or_b32_e32 v96, 32, v150
	s_and_saveexec_b64 s[28:29], vcc
	s_xor_b64 s[28:29], exec, s[28:29]
	v_and_b32_e32 v97, 0x3fffc00, v149
	v_add_u32_e32 v97, v97, v96
	v_lshl_add_u32 v97, v97, 6, v147
	s_or_saveexec_b64 s[28:29], s[28:29]
	v_mov_b32_e32 v98, 63
	s_xor_b64 exec, exec, s[28:29]
	v_add_lshl_u32 v97, v151, v96, 12
	v_mov_b32_e32 v98, 0xfff
	s_or_b64 exec, exec, s[28:29]
	v_cvt_pk_bf16_f32 v92, v92, v93
	v_cvt_pk_bf16_f32 v93, v94, v95
	v_cvt_pk_bf16_f32 v94, v88, v89
	v_and_or_b32 v136, v98, v148, v97
	v_cvt_pk_bf16_f32 v95, v90, v91
	v_lshl_add_u64 v[88:89], v[136:137], 1, s[10:11]
	global_store_dwordx4 v[88:89], v[92:95], off
	s_and_saveexec_b64 s[28:29], s[4:5]
	s_xor_b64 s[28:29], exec, s[28:29]
	v_and_b32_e32 v88, 0x3fffc00, v121
	v_add_u32_e32 v88, v88, v96
	v_lshl_add_u32 v88, v88, 6, v147
	s_or_saveexec_b64 s[28:29], s[28:29]
	v_mov_b32_e32 v89, 63
	s_xor_b64 exec, exec, s[28:29]
	v_add_lshl_u32 v88, v122, v96, 12
	v_mov_b32_e32 v89, 0xfff
	s_or_b64 exec, exec, s[28:29]
	v_cvt_pk_bf16_f32 v84, v84, v85
	v_cvt_pk_bf16_f32 v85, v86, v87
	v_cvt_pk_bf16_f32 v86, v80, v81
	v_and_or_b32 v136, v89, v120, v88
	v_cvt_pk_bf16_f32 v87, v82, v83
	v_lshl_add_u64 v[80:81], v[136:137], 1, s[10:11]
	global_store_dwordx4 v[80:81], v[84:87], off
	v_or_b32_e32 v80, 48, v150
	s_and_saveexec_b64 s[28:29], vcc
	s_xor_b64 s[28:29], exec, s[28:29]
	v_and_b32_e32 v81, 0x3fffc00, v149
	v_add_u32_e32 v81, v81, v80
	v_lshl_add_u32 v81, v81, 6, v147
	s_or_saveexec_b64 s[28:29], s[28:29]
	v_mov_b32_e32 v82, 63
	s_xor_b64 exec, exec, s[28:29]
	v_add_lshl_u32 v81, v151, v80, 12
	v_mov_b32_e32 v82, 0xfff
	s_or_b64 exec, exec, s[28:29]
	v_cvt_pk_bf16_f32 v76, v76, v77
	v_cvt_pk_bf16_f32 v77, v78, v79
	v_cvt_pk_bf16_f32 v78, v72, v73
	v_and_or_b32 v136, v82, v148, v81
	v_cvt_pk_bf16_f32 v79, v74, v75
	v_lshl_add_u64 v[72:73], v[136:137], 1, s[10:11]
	global_store_dwordx4 v[72:73], v[76:79], off
	s_and_saveexec_b64 s[28:29], s[4:5]
	s_xor_b64 s[28:29], exec, s[28:29]
	v_and_b32_e32 v72, 0x3fffc00, v121
	v_add_u32_e32 v72, v72, v80
	v_lshl_add_u32 v72, v72, 6, v147
	s_or_saveexec_b64 s[28:29], s[28:29]
	v_mov_b32_e32 v73, 63
	s_xor_b64 exec, exec, s[28:29]
	v_add_lshl_u32 v72, v122, v80, 12
	v_mov_b32_e32 v73, 0xfff
	s_or_b64 exec, exec, s[28:29]
	v_cvt_pk_bf16_f32 v68, v68, v69
	v_cvt_pk_bf16_f32 v69, v70, v71
	v_cvt_pk_bf16_f32 v70, v64, v65
	v_and_or_b32 v136, v73, v120, v72
	v_cvt_pk_bf16_f32 v71, v66, v67
	v_lshl_add_u64 v[64:65], v[136:137], 1, s[10:11]
	global_store_dwordx4 v[64:65], v[68:71], off
	v_add_u32_e32 v64, 0x80, v150
	s_and_saveexec_b64 s[28:29], vcc
	s_xor_b64 s[28:29], exec, s[28:29]
	v_and_b32_e32 v65, 0x3fffc00, v149
	v_add_u32_e32 v65, v65, v64
	v_lshl_add_u32 v65, v65, 6, v147
	s_or_saveexec_b64 s[28:29], s[28:29]
	v_mov_b32_e32 v66, 63
	s_xor_b64 exec, exec, s[28:29]
	v_add_lshl_u32 v65, v151, v64, 12
	v_mov_b32_e32 v66, 0xfff
	s_or_b64 exec, exec, s[28:29]
	v_cvt_pk_bf16_f32 v60, v60, v61
	v_cvt_pk_bf16_f32 v61, v62, v63
	v_cvt_pk_bf16_f32 v62, v56, v57
	v_and_or_b32 v136, v66, v148, v65
	v_cvt_pk_bf16_f32 v63, v58, v59
	v_lshl_add_u64 v[56:57], v[136:137], 1, s[10:11]
	global_store_dwordx4 v[56:57], v[60:63], off
	s_and_saveexec_b64 s[28:29], s[4:5]
	s_xor_b64 s[28:29], exec, s[28:29]
	v_and_b32_e32 v56, 0x3fffc00, v121
	v_add_u32_e32 v56, v56, v64
	v_lshl_add_u32 v56, v56, 6, v147
	s_or_saveexec_b64 s[28:29], s[28:29]
	v_mov_b32_e32 v57, 63
	s_xor_b64 exec, exec, s[28:29]
	v_add_lshl_u32 v56, v122, v64, 12
	v_mov_b32_e32 v57, 0xfff
	s_or_b64 exec, exec, s[28:29]
	v_cvt_pk_bf16_f32 v52, v52, v53
	v_cvt_pk_bf16_f32 v53, v54, v55
	v_cvt_pk_bf16_f32 v54, v48, v49
	v_and_or_b32 v136, v57, v120, v56
	v_cvt_pk_bf16_f32 v55, v50, v51
	v_lshl_add_u64 v[48:49], v[136:137], 1, s[10:11]
	global_store_dwordx4 v[48:49], v[52:55], off
	v_add_u32_e32 v48, 0x90, v150
	s_and_saveexec_b64 s[28:29], vcc
	s_xor_b64 s[28:29], exec, s[28:29]
	v_and_b32_e32 v49, 0x3fffc00, v149
	v_add_u32_e32 v49, v49, v48
	v_lshl_add_u32 v49, v49, 6, v147
	s_or_saveexec_b64 s[28:29], s[28:29]
	v_mov_b32_e32 v50, 63
	s_xor_b64 exec, exec, s[28:29]
	v_add_lshl_u32 v49, v151, v48, 12
	v_mov_b32_e32 v50, 0xfff
	s_or_b64 exec, exec, s[28:29]
	v_cvt_pk_bf16_f32 v44, v44, v45
	v_cvt_pk_bf16_f32 v45, v46, v47
	v_cvt_pk_bf16_f32 v46, v40, v41
	v_and_or_b32 v136, v50, v148, v49
	v_cvt_pk_bf16_f32 v47, v42, v43
	v_lshl_add_u64 v[40:41], v[136:137], 1, s[10:11]
	global_store_dwordx4 v[40:41], v[44:47], off
	s_and_saveexec_b64 s[28:29], s[4:5]
	s_xor_b64 s[28:29], exec, s[28:29]
	v_and_b32_e32 v40, 0x3fffc00, v121
	v_add_u32_e32 v40, v40, v48
	v_lshl_add_u32 v40, v40, 6, v147
	s_or_saveexec_b64 s[28:29], s[28:29]
	v_mov_b32_e32 v41, 63
	s_xor_b64 exec, exec, s[28:29]
	v_add_lshl_u32 v40, v122, v48, 12
	v_mov_b32_e32 v41, 0xfff
	s_or_b64 exec, exec, s[28:29]
	v_cvt_pk_bf16_f32 v36, v36, v37
	v_cvt_pk_bf16_f32 v37, v38, v39
	v_cvt_pk_bf16_f32 v38, v32, v33
	v_and_or_b32 v136, v41, v120, v40
	v_cvt_pk_bf16_f32 v39, v34, v35
	v_lshl_add_u64 v[32:33], v[136:137], 1, s[10:11]
	global_store_dwordx4 v[32:33], v[36:39], off
	v_add_u32_e32 v32, 0xa0, v150
	s_and_saveexec_b64 s[28:29], vcc
	s_xor_b64 s[28:29], exec, s[28:29]
	v_and_b32_e32 v33, 0x3fffc00, v149
	v_add_u32_e32 v33, v33, v32
	v_lshl_add_u32 v33, v33, 6, v147
	s_or_saveexec_b64 s[28:29], s[28:29]
	v_mov_b32_e32 v34, 63
	s_xor_b64 exec, exec, s[28:29]
	v_add_lshl_u32 v33, v151, v32, 12
	v_mov_b32_e32 v34, 0xfff
	s_or_b64 exec, exec, s[28:29]
	v_cvt_pk_bf16_f32 v28, v28, v29
	v_cvt_pk_bf16_f32 v29, v30, v31
	v_cvt_pk_bf16_f32 v30, v24, v25
	v_and_or_b32 v136, v34, v148, v33
	v_cvt_pk_bf16_f32 v31, v26, v27
	v_lshl_add_u64 v[24:25], v[136:137], 1, s[10:11]
	global_store_dwordx4 v[24:25], v[28:31], off
	s_and_saveexec_b64 s[28:29], s[4:5]
	s_xor_b64 s[28:29], exec, s[28:29]
	v_and_b32_e32 v24, 0x3fffc00, v121
	v_add_u32_e32 v24, v24, v32
	v_lshl_add_u32 v24, v24, 6, v147
	s_or_saveexec_b64 s[28:29], s[28:29]
	v_mov_b32_e32 v25, 63
	s_xor_b64 exec, exec, s[28:29]
	v_add_lshl_u32 v24, v122, v32, 12
	v_mov_b32_e32 v25, 0xfff
	s_or_b64 exec, exec, s[28:29]
	v_cvt_pk_bf16_f32 v20, v20, v21
	v_cvt_pk_bf16_f32 v21, v22, v23
	v_cvt_pk_bf16_f32 v22, v16, v17
	v_and_or_b32 v136, v25, v120, v24
	v_cvt_pk_bf16_f32 v23, v18, v19
	v_lshl_add_u64 v[16:17], v[136:137], 1, s[10:11]
	global_store_dwordx4 v[16:17], v[20:23], off
	v_add_u32_e32 v16, 0xb0, v150
	s_and_saveexec_b64 s[28:29], vcc
	s_xor_b64 s[28:29], exec, s[28:29]
	v_and_b32_e32 v17, 0x3fffc00, v149
	v_add_u32_e32 v17, v17, v16
	v_lshl_add_u32 v17, v17, 6, v147
	s_or_saveexec_b64 s[28:29], s[28:29]
	v_mov_b32_e32 v18, 63
	s_xor_b64 exec, exec, s[28:29]
	v_add_lshl_u32 v17, v151, v16, 12
	v_mov_b32_e32 v18, 0xfff
	s_or_b64 exec, exec, s[28:29]
	v_cvt_pk_bf16_f32 v12, v12, v13
	v_cvt_pk_bf16_f32 v13, v14, v15
	v_cvt_pk_bf16_f32 v14, v8, v9
	v_and_or_b32 v136, v18, v148, v17
	v_cvt_pk_bf16_f32 v15, v10, v11
	v_lshl_add_u64 v[8:9], v[136:137], 1, s[10:11]
	global_store_dwordx4 v[8:9], v[12:15], off
	s_and_saveexec_b64 s[28:29], s[4:5]
	s_xor_b64 s[4:5], exec, s[28:29]
	v_and_b32_e32 v8, 0x3fffc00, v121
	v_add_u32_e32 v8, v8, v16
	v_lshl_add_u32 v8, v8, 6, v147
	s_or_saveexec_b64 s[4:5], s[4:5]
	v_mov_b32_e32 v9, 63
	s_xor_b64 exec, exec, s[4:5]
	s_cbranch_execz .LBB0_466
	v_add_lshl_u32 v8, v122, v16, 12
	v_mov_b32_e32 v9, 0xfff
	s_branch .LBB0_466

.LBB0_595:
	s_waitcnt vmcnt(0)
	v_cvt_pk_bf16_f32 v42, v18, v19
	v_lshlrev_b32_e32 v41, 3, v38
	s_movk_i32 s4, 0xffc0
	v_cvt_pk_bf16_f32 v43, v20, v21
	v_and_or_b32 v0, v138, s4, v41
	v_mul_u32_u24_e32 v39, 0x210, v35
	s_mov_b32 s4, 0x1e000
	v_cvt_pk_bf16_f32 v44, v22, v23
	v_add3_u32 v0, v0, v39, s4
	v_cvt_pk_bf16_f32 v45, v24, v25
	ds_write2_b64 v0, v[42:43], v[44:45] offset1:2
	v_cvt_pk_bf16_f32 v42, v26, v27
	v_cvt_pk_bf16_f32 v43, v28, v29
	v_cvt_pk_bf16_f32 v44, v30, v31
	v_cvt_pk_bf16_f32 v45, v32, v33
	ds_write2_b64 v0, v[42:43], v[44:45] offset0:4 offset1:6
	v_cvt_pk_bf16_f32 v42, v2, v3
	v_cvt_pk_bf16_f32 v43, v4, v5
	v_cvt_pk_bf16_f32 v44, v6, v7
	v_cvt_pk_bf16_f32 v45, v8, v9
	v_add_u32_e32 v0, 0x4000, v0
	ds_write2_b64 v0, v[42:43], v[44:45] offset0:64 offset1:66
	v_cvt_pk_bf16_f32 v42, v10, v11
	v_cvt_pk_bf16_f32 v43, v12, v13
	v_cvt_pk_bf16_f32 v44, v14, v15
	v_and_b32_e32 v40, 63, v36
	v_cvt_pk_bf16_f32 v45, v16, v17
	v_cmp_gt_i32_e64 s[4:5], s12, v138
	v_lshl_add_u32 v103, v138, 2, v125
	ds_write2_b64 v0, v[42:43], v[44:45] offset0:68 offset1:70
	s_and_saveexec_b64 s[6:7], s[4:5]
	ds_write_b32 v103, v141
	s_or_b64 exec, exec, s[6:7]
	s_lshl_b32 s6, s65, 6
	s_add_i32 s8, s6, 0x10000
	s_lshl_b32 s9, s65, 12
	s_and_b64 s[6:7], s[84:85], exec
	s_cselect_b32 s86, s8, s9
	s_lshl_b32 s6, s65, 10
	s_lshl_b32 s22, s2, 8
	s_or_b32 s6, s22, s6
	s_ashr_i32 s7, s6, 31
	s_lshl_b64 s[8:9], s[6:7], 12
	s_lshl_b64 s[6:7], s[6:7], 6
	s_add_u32 s10, s6, 0x4000000
	s_load_dwordx8 s[24:31], s[0:1], 0x178
	s_addc_u32 s11, s7, 0
	s_and_b64 s[6:7], s[84:85], exec
	s_cselect_b32 s12, 6, 12
	s_cselect_b32 s7, s11, s9
	s_cselect_b32 s6, s10, s8
	s_ashr_i32 s87, s86, 31
	s_lshl_b64 s[8:9], s[86:87], 11
	s_waitcnt lgkmcnt(0)
	s_add_u32 s10, s24, s8
	s_addc_u32 s11, s25, s9
	s_lshl_b32 s13, s2, 9
	s_add_u32 s88, s10, s13
	s_addc_u32 s89, s11, 0
	s_add_u32 s8, s28, s8
	s_addc_u32 s9, s29, s9
	s_add_u32 s90, s8, s13
	s_addc_u32 s91, s9, 0
	s_load_dwordx4 s[8:11], s[0:1], 0x198
	s_lshl_b64 s[6:7], s[6:7], 1
	v_lshlrev_b32_e32 v0, 3, v138
	s_add_u32 s92, s30, s6
	v_ashrrev_i32_e32 v42, 5, v138
	v_and_b32_e32 v43, 0xf8, v0
	s_addc_u32 s93, s31, s7
	v_lshl_or_b32 v46, v42, 10, v43
	v_mov_b32_e32 v47, v1
	s_waitcnt lgkmcnt(0)
	s_add_u32 s6, s8, s6
	v_lshlrev_b64 v[104:105], 1, v[46:47]
	v_add_u32_e32 v62, 0x4000, v46
	v_add_u32_e32 v74, 0x8000, v46
	v_add_u32_e32 v46, 0xc000, v46
	s_addc_u32 s7, s9, s7
	s_lshl_b32 s8, s64, s12
	v_ashrrev_i32_e32 v45, 3, v138
	v_lshlrev_b64 v[114:115], 1, v[46:47]
	s_lshl_b32 s8, s8, 1
	v_and_b32_e32 v143, 56, v0
	v_lshl_add_u64 v[48:49], s[88:89], 0, v[104:105]
	v_add_u32_e32 v34, 0x80, v45
	v_lshl_add_u64 v[46:47], s[88:89], 0, v[114:115]
	s_add_u32 s6, s6, s8
	global_load_dwordx4 v[50:53], v[48:49], off
	global_load_dwordx4 v[86:89], v[46:47], off
	v_lshl_add_u64 v[48:49], s[90:91], 0, v[104:105]
	v_lshl_add_u32 v0, v45, s12, v143
	v_mov_b32_e32 v63, v1
	v_add_u32_e32 v44, 64, v45
	v_mov_b32_e32 v75, v1
	v_lshl_add_u32 v112, v34, s12, v143
	v_lshl_add_u64 v[46:47], s[90:91], 0, v[114:115]
	v_add_u32_e32 v34, 0xc0, v45
	s_addc_u32 s7, s7, 0
	global_load_dwordx4 v[54:57], v[48:49], off
	global_load_dwordx4 v[90:93], v[46:47], off
	v_lshlrev_b64 v[48:49], 1, v[0:1]
	v_lshlrev_b64 v[106:107], 1, v[62:63]
	v_lshl_add_u32 v108, v44, s12, v143
	v_mov_b32_e32 v109, v1
	v_lshlrev_b64 v[110:111], 1, v[74:75]
	v_mov_b32_e32 v113, v1
	v_lshl_add_u32 v116, v34, s12, v143
	v_mov_b32_e32 v117, v1
	v_lshl_add_u64 v[58:59], s[92:93], 0, v[48:49]
	v_lshl_add_u64 v[62:63], s[88:89], 0, v[106:107]
	v_lshl_add_u64 v[66:67], s[90:91], 0, v[106:107]
	v_lshl_add_u64 v[70:71], v[108:109], 1, s[92:93]
	v_lshl_add_u64 v[74:75], s[88:89], 0, v[110:111]
	v_lshl_add_u64 v[78:79], s[90:91], 0, v[110:111]
	v_lshl_add_u64 v[82:83], v[112:113], 1, s[92:93]
	v_lshl_add_u64 v[46:47], v[116:117], 1, s[92:93]
	v_lshl_add_u64 v[118:119], s[6:7], 0, v[48:49]
	global_load_dwordx4 v[58:61], v[58:59], off
	v_lshl_or_b32 v34, v40, 3, s2
	global_load_dwordx4 v[62:65], v[62:63], off
	v_cmp_lt_u32_e64 s[6:7], 63, v138
	global_load_dwordx4 v[66:69], v[66:67], off
	v_cmp_gt_u32_e64 s[8:9], 64, v138
	global_load_dwordx4 v[70:73], v[70:71], off
	v_mov_b32_e32 v145, 0
	global_load_dwordx4 v[74:77], v[74:75], off
	v_lshlrev_b32_e32 v34, 2, v34
	global_load_dwordx4 v[78:81], v[78:79], off
	v_mov_b32_e32 v144, 0
	global_load_dwordx4 v[82:85], v[82:83], off
	s_nop 0
	global_load_dwordx4 v[94:97], v[46:47], off
	global_load_dwordx4 v[98:101], v[118:119], off nt
	s_and_saveexec_b64 s[10:11], s[8:9]
	s_cbranch_execz .LBB0_599
	s_load_dwordx4 s[16:19], s[0:1], 0x198
	s_lshl_b64 s[12:13], s[86:87], 5
	s_waitcnt lgkmcnt(0)
	s_add_u32 s12, s18, s12
	s_addc_u32 s13, s19, s13
	global_load_dword v144, v34, s[12:13]
	global_load_dword v145, v34, s[12:13] offset:16

.LBB0_661:
	s_or_b64 exec, exec, s[62:63]
	s_and_b64 s[62:63], s[96:97], exec
	s_cselect_b32 s62, 0x26b00, s81
	v_mov_b32_e32 v122, s62
	ds_read_b32 v122, v122
	ds_read_b128 v[194:197], v161
	ds_read_b128 v[198:201], v161 offset:32
	ds_read_b128 v[202:205], v174
	ds_read_b128 v[206:209], v174 offset:32
	s_waitcnt lgkmcnt(4)
	v_pk_mul_f32 v[32:33], v[32:33], v[122:123] op_sel_hi:[1,0]
	v_pk_mul_f32 v[30:31], v[30:31], v[122:123] op_sel_hi:[1,0]
	v_pk_mul_f32 v[28:29], v[28:29], v[122:123] op_sel_hi:[1,0]
	v_pk_mul_f32 v[26:27], v[26:27], v[122:123] op_sel_hi:[1,0]
	v_pk_mul_f32 v[24:25], v[24:25], v[122:123] op_sel_hi:[1,0]
	v_pk_mul_f32 v[22:23], v[22:23], v[122:123] op_sel_hi:[1,0]
	v_pk_mul_f32 v[20:21], v[20:21], v[122:123] op_sel_hi:[1,0]
	v_pk_mul_f32 v[18:19], v[18:19], v[122:123] op_sel_hi:[1,0]
	v_pk_mul_f32 v[16:17], v[16:17], v[122:123] op_sel_hi:[1,0]
	v_pk_mul_f32 v[14:15], v[14:15], v[122:123] op_sel_hi:[1,0]
	s_waitcnt lgkmcnt(1)
	v_mfma_f32_32x32x16_bf16 v[18:33], v[194:197], v[202:205], v[18:33]
	ds_read_b128 v[202:205], v174 offset:4608
	v_mul_f32_e64 v12, v12, v122
	v_mul_f32_e64 v13, v13, v122
	v_mul_f32_e64 v10, v10, v122
	v_mul_f32_e64 v11, v11, v122
	v_pk_mul_f32 v[8:9], v[8:9], v[122:123] op_sel_hi:[1,0]
	v_pk_mul_f32 v[6:7], v[6:7], v[122:123] op_sel_hi:[1,0]
	v_pk_mul_f32 v[4:5], v[4:5], v[122:123] op_sel_hi:[1,0]
	v_pk_mul_f32 v[2:3], v[2:3], v[122:123] op_sel_hi:[1,0]
	s_waitcnt lgkmcnt(1)
	v_mfma_f32_32x32x16_bf16 v[18:33], v[198:201], v[206:209], v[18:33]
	s_waitcnt lgkmcnt(0)
	v_mfma_f32_32x32x16_bf16 v[2:17], v[194:197], v[202:205], v[2:17]
	ds_read_b128 v[194:197], v174 offset:4640
	s_waitcnt lgkmcnt(0)
	v_mfma_f32_32x32x16_bf16 v[2:17], v[198:201], v[194:197], v[2:17]
	ds_read_b128 v[194:197], v161 offset:64
	ds_read_b128 v[198:201], v174 offset:64
	s_waitcnt lgkmcnt(0)
	v_mfma_f32_32x32x16_bf16 v[18:33], v[194:197], v[198:201], v[18:33]
	ds_read_b128 v[198:201], v174 offset:4672
	s_waitcnt lgkmcnt(0)
	v_mfma_f32_32x32x16_bf16 v[2:17], v[194:197], v[198:201], v[2:17]
	ds_read_b128 v[194:197], v161 offset:96
	ds_read_b128 v[198:201], v174 offset:96
	s_waitcnt lgkmcnt(0)
	v_mfma_f32_32x32x16_bf16 v[18:33], v[194:197], v[198:201], v[18:33]
	ds_read_b128 v[198:201], v174 offset:4704
	s_waitcnt lgkmcnt(0)
	v_mfma_f32_32x32x16_bf16 v[2:17], v[194:197], v[198:201], v[2:17]
	s_nop 8
	v_cvt_pk_bf16_f32 v194, v18, v19
	v_cvt_pk_bf16_f32 v195, v20, v21
	v_cvt_pk_bf16_f32 v196, v22, v23
	v_cvt_pk_bf16_f32 v197, v24, v25
	ds_write2_b64 v175, v[194:195], v[196:197] offset1:2
	v_cvt_pk_bf16_f32 v198, v26, v27
	v_cvt_pk_bf16_f32 v199, v28, v29
	v_cvt_pk_bf16_f32 v200, v30, v31
	v_cvt_pk_bf16_f32 v201, v32, v33
	ds_write2_b64 v175, v[198:199], v[200:201] offset0:4 offset1:6
	v_add_u32_e32 v193, 0x4000, v175
	v_cvt_pk_bf16_f32 v202, v2, v3
	v_cvt_pk_bf16_f32 v203, v4, v5
	v_cvt_pk_bf16_f32 v204, v6, v7
	v_cvt_pk_bf16_f32 v205, v8, v9
	ds_write2_b64 v193, v[202:203], v[204:205] offset0:64 offset1:66
	v_cvt_pk_bf16_f32 v206, v10, v11
	v_cvt_pk_bf16_f32 v207, v12, v13
	v_cvt_pk_bf16_f32 v208, v14, v15
	v_cvt_pk_bf16_f32 v209, v16, v17
	ds_write2_b64 v193, v[206:207], v[208:209] offset0:68 offset1:70
	s_and_saveexec_b64 s[62:63], s[4:5]
	s_cbranch_execz .LBB0_665
	v_mov_b32_e32 v193, 0
	s_mov_b32 s69, 0

.LBB0_733:
	s_waitcnt vmcnt(0)
	ds_read_b128 v[148:151], v144
	ds_read_b128 v[152:155], v144 offset:1024
	ds_read_b128 v[156:159], v144 offset:2048
	ds_read_b128 v[160:163], v144 offset:3072
	s_add_u32 s26, s24, 0xfffc0080
	s_addc_u32 s27, s25, -1
	s_cmp_eq_u32 s62, 12
	s_cselect_b32 s29, s7, s27
	s_cselect_b32 s28, s17, s26
	s_cselect_b32 s27, s15, vcc_hi
	s_cselect_b32 s26, s23, vcc_lo
	s_mov_b32 m0, s31
	v_lshl_add_u64 v[198:199], s[24:25], 0, v[136:137]
	ds_read_b128 v[164:167], v142
	ds_read_b128 v[168:171], v142 offset:1024
	ds_read_b128 v[172:175], v142 offset:2048
	ds_read_b128 v[176:179], v142 offset:3072
	ds_read_b128 v[182:185], v142 offset:4096
	ds_read_b128 v[186:189], v142 offset:5120
	ds_read_b128 v[190:193], v142 offset:6144
	ds_read_b128 v[194:197], v142 offset:7168
	global_load_lds_dwordx4 v[198:199], off
	v_lshl_add_u64 v[198:199], s[24:25], 0, v[138:139]
	s_mov_b32 m0, s94
	s_nop 0
	global_load_lds_dwordx4 v[198:199], off
	s_waitcnt lgkmcnt(8)
	s_barrier
	s_waitcnt lgkmcnt(0)
	s_setprio 1
	s_waitcnt lgkmcnt(0)
	v_mfma_f32_16x16x32_bf16 v[126:129], v[148:151], v[164:167], v[126:129]
	v_mfma_f32_16x16x32_bf16 v[122:125], v[156:159], v[164:167], v[122:125]
	v_mfma_f32_16x16x32_bf16 v[114:117], v[148:151], v[172:175], v[114:117]
	v_mfma_f32_16x16x32_bf16 v[106:109], v[156:159], v[172:175], v[106:109]
	v_mfma_f32_16x16x32_bf16 v[98:101], v[148:151], v[182:185], v[98:101]
	v_mfma_f32_16x16x32_bf16 v[90:93], v[156:159], v[182:185], v[90:93]
	v_mfma_f32_16x16x32_bf16 v[82:85], v[148:151], v[190:193], v[82:85]
	v_mfma_f32_16x16x32_bf16 v[74:77], v[156:159], v[190:193], v[74:77]
	v_mfma_f32_16x16x32_bf16 v[126:129], v[152:155], v[168:171], v[126:129]
	v_mfma_f32_16x16x32_bf16 v[122:125], v[160:163], v[168:171], v[122:125]
	v_mfma_f32_16x16x32_bf16 v[114:117], v[152:155], v[176:179], v[114:117]
	v_mfma_f32_16x16x32_bf16 v[106:109], v[160:163], v[176:179], v[106:109]
	v_mfma_f32_16x16x32_bf16 v[98:101], v[152:155], v[186:189], v[98:101]
	v_mfma_f32_16x16x32_bf16 v[90:93], v[160:163], v[186:189], v[90:93]
	v_mfma_f32_16x16x32_bf16 v[82:85], v[152:155], v[194:197], v[82:85]
	v_mfma_f32_16x16x32_bf16 v[74:77], v[160:163], v[194:197], v[74:77]
	s_setprio 0
	s_barrier
	s_mov_b32 m0, s36
	v_lshl_add_u64 v[214:215], s[26:27], 0, v[0:1]
	s_waitcnt vmcnt(0)
	ds_read_b128 v[198:201], v145
	ds_read_b128 v[202:205], v145 offset:1024
	ds_read_b128 v[206:209], v145 offset:2048
	ds_read_b128 v[210:213], v145 offset:3072
	global_load_lds_dwordx4 v[214:215], off
	v_lshl_add_u64 v[216:217], s[26:27], 0, v[134:135]
	s_mov_b32 m0, s37
	s_nop 0
	global_load_lds_dwordx4 v[216:217], off
	s_barrier
	s_waitcnt lgkmcnt(0)
	s_setprio 1
	s_waitcnt lgkmcnt(0)
	v_mfma_f32_16x16x32_bf16 v[118:121], v[198:201], v[164:167], v[118:121]
	v_mfma_f32_16x16x32_bf16 v[110:113], v[206:209], v[164:167], v[110:113]
	v_mfma_f32_16x16x32_bf16 v[102:105], v[198:201], v[172:175], v[102:105]
	v_mfma_f32_16x16x32_bf16 v[94:97], v[206:209], v[172:175], v[94:97]
	v_mfma_f32_16x16x32_bf16 v[86:89], v[198:201], v[182:185], v[86:89]
	v_mfma_f32_16x16x32_bf16 v[78:81], v[206:209], v[182:185], v[78:81]
	v_mfma_f32_16x16x32_bf16 v[70:73], v[198:201], v[190:193], v[70:73]
	v_mfma_f32_16x16x32_bf16 v[66:69], v[206:209], v[190:193], v[66:69]
	v_mfma_f32_16x16x32_bf16 v[118:121], v[202:205], v[168:171], v[118:121]
	v_mfma_f32_16x16x32_bf16 v[110:113], v[210:213], v[168:171], v[110:113]
	v_mfma_f32_16x16x32_bf16 v[102:105], v[202:205], v[176:179], v[102:105]
	v_mfma_f32_16x16x32_bf16 v[94:97], v[210:213], v[176:179], v[94:97]
	v_mfma_f32_16x16x32_bf16 v[86:89], v[202:205], v[186:189], v[86:89]
	v_mfma_f32_16x16x32_bf16 v[78:81], v[210:213], v[186:189], v[78:81]
	v_mfma_f32_16x16x32_bf16 v[70:73], v[202:205], v[194:197], v[70:73]
	v_mfma_f32_16x16x32_bf16 v[66:69], v[210:213], v[194:197], v[66:69]
	s_setprio 0
	s_mov_b32 m0, s89
	v_lshl_add_u64 v[222:223], s[28:29], 0, v[130:131]
	s_barrier
	s_waitcnt vmcnt(0)
	ds_read_b128 v[164:167], v142 offset:16384
	ds_read_b128 v[168:171], v142 offset:17408
	ds_read_b128 v[172:175], v142 offset:18432
	ds_read_b128 v[176:179], v142 offset:19456
	ds_read_b128 v[182:185], v142 offset:20480
	ds_read_b128 v[186:189], v142 offset:21504
	ds_read_b128 v[190:193], v142 offset:22528
	ds_read_b128 v[194:197], v142 offset:23552
	global_load_lds_dwordx4 v[222:223], off
	v_lshl_add_u64 v[224:225], s[28:29], 0, v[132:133]
	s_mov_b32 m0, s38
	s_nop 0
	global_load_lds_dwordx4 v[224:225], off
	s_barrier
	s_waitcnt lgkmcnt(0)
	s_setprio 1
	s_waitcnt lgkmcnt(0)
	v_mfma_f32_16x16x32_bf16 v[62:65], v[148:151], v[164:167], v[62:65]
	v_mfma_f32_16x16x32_bf16 v[58:61], v[156:159], v[164:167], v[58:61]
	v_mfma_f32_16x16x32_bf16 v[50:53], v[148:151], v[172:175], v[50:53]
	v_mfma_f32_16x16x32_bf16 v[42:45], v[156:159], v[172:175], v[42:45]
	v_mfma_f32_16x16x32_bf16 v[34:37], v[148:151], v[182:185], v[34:37]
	v_mfma_f32_16x16x32_bf16 v[26:29], v[156:159], v[182:185], v[26:29]
	v_mfma_f32_16x16x32_bf16 v[18:21], v[148:151], v[190:193], v[18:21]
	v_mfma_f32_16x16x32_bf16 v[10:13], v[156:159], v[190:193], v[10:13]
	v_mfma_f32_16x16x32_bf16 v[62:65], v[152:155], v[168:171], v[62:65]
	v_mfma_f32_16x16x32_bf16 v[58:61], v[160:163], v[168:171], v[58:61]
	v_mfma_f32_16x16x32_bf16 v[50:53], v[152:155], v[176:179], v[50:53]
	v_mfma_f32_16x16x32_bf16 v[42:45], v[160:163], v[176:179], v[42:45]
	v_mfma_f32_16x16x32_bf16 v[34:37], v[152:155], v[186:189], v[34:37]
	v_mfma_f32_16x16x32_bf16 v[26:29], v[160:163], v[186:189], v[26:29]
	v_mfma_f32_16x16x32_bf16 v[18:21], v[152:155], v[194:197], v[18:21]
	v_mfma_f32_16x16x32_bf16 v[10:13], v[160:163], v[194:197], v[10:13]
	s_setprio 0
	s_barrier
	s_add_u32 s76, s26, 0x40000
	s_addc_u32 s77, s27, 0
	s_mov_b32 m0, s39
	v_lshl_add_u64 v[148:149], s[76:77], 0, v[0:1]
	global_load_lds_dwordx4 v[148:149], off
	v_lshl_add_u64 v[148:149], s[76:77], 0, v[134:135]
	s_mov_b32 m0, s60
	s_nop 0
	global_load_lds_dwordx4 v[148:149], off
	s_waitcnt vmcnt(6)
	s_barrier
	s_setprio 1
	v_mfma_f32_16x16x32_bf16 v[54:57], v[198:201], v[164:167], v[54:57]
	v_mfma_f32_16x16x32_bf16 v[46:49], v[206:209], v[164:167], v[46:49]
	v_mfma_f32_16x16x32_bf16 v[38:41], v[198:201], v[172:175], v[38:41]
	v_mfma_f32_16x16x32_bf16 v[30:33], v[206:209], v[172:175], v[30:33]
	v_mfma_f32_16x16x32_bf16 v[22:25], v[198:201], v[182:185], v[22:25]
	v_mfma_f32_16x16x32_bf16 v[14:17], v[206:209], v[182:185], v[14:17]
	v_mfma_f32_16x16x32_bf16 v[6:9], v[198:201], v[190:193], v[6:9]
	v_mfma_f32_16x16x32_bf16 v[2:5], v[206:209], v[190:193], v[2:5]
	v_mfma_f32_16x16x32_bf16 v[54:57], v[202:205], v[168:171], v[54:57]
	v_mfma_f32_16x16x32_bf16 v[46:49], v[210:213], v[168:171], v[46:49]
	v_mfma_f32_16x16x32_bf16 v[38:41], v[202:205], v[176:179], v[38:41]
	v_mfma_f32_16x16x32_bf16 v[30:33], v[210:213], v[176:179], v[30:33]
	v_mfma_f32_16x16x32_bf16 v[22:25], v[202:205], v[186:189], v[22:25]
	v_mfma_f32_16x16x32_bf16 v[14:17], v[210:213], v[186:189], v[14:17]
	v_mfma_f32_16x16x32_bf16 v[6:9], v[202:205], v[194:197], v[6:9]
	v_mfma_f32_16x16x32_bf16 v[2:5], v[210:213], v[194:197], v[2:5]
	s_setprio 0
	s_barrier
	s_waitcnt vmcnt(0)
	ds_read_b128 v[148:151], v146
	ds_read_b128 v[152:155], v146 offset:1024
	ds_read_b128 v[156:159], v146 offset:2048
	ds_read_b128 v[160:163], v146 offset:3072
	s_add_u32 s28, s28, 0x40000
	s_addc_u32 s29, s29, 0
	s_mov_b32 m0, s68
	v_lshl_add_u64 v[198:199], s[28:29], 0, v[130:131]
	ds_read_b128 v[164:167], v142 offset:32768
	ds_read_b128 v[168:171], v142 offset:33792
	ds_read_b128 v[172:175], v142 offset:34816
	ds_read_b128 v[176:179], v142 offset:35840
	ds_read_b128 v[182:185], v142 offset:36864
	ds_read_b128 v[186:189], v142 offset:37888
	ds_read_b128 v[190:193], v142 offset:38912
	ds_read_b128 v[194:197], v142 offset:39936
	global_load_lds_dwordx4 v[198:199], off
	v_lshl_add_u64 v[198:199], s[28:29], 0, v[132:133]
	s_mov_b32 m0, s69
	s_nop 0
	global_load_lds_dwordx4 v[198:199], off
	s_waitcnt lgkmcnt(8)
	s_barrier
	s_waitcnt lgkmcnt(0)
	s_setprio 1
	s_waitcnt lgkmcnt(0)
	v_mfma_f32_16x16x32_bf16 v[126:129], v[148:151], v[164:167], v[126:129]
	v_mfma_f32_16x16x32_bf16 v[122:125], v[156:159], v[164:167], v[122:125]
	v_mfma_f32_16x16x32_bf16 v[114:117], v[148:151], v[172:175], v[114:117]
	v_mfma_f32_16x16x32_bf16 v[106:109], v[156:159], v[172:175], v[106:109]
	v_mfma_f32_16x16x32_bf16 v[98:101], v[148:151], v[182:185], v[98:101]
	v_mfma_f32_16x16x32_bf16 v[90:93], v[156:159], v[182:185], v[90:93]
	v_mfma_f32_16x16x32_bf16 v[82:85], v[148:151], v[190:193], v[82:85]
	v_mfma_f32_16x16x32_bf16 v[74:77], v[156:159], v[190:193], v[74:77]
	v_mfma_f32_16x16x32_bf16 v[126:129], v[152:155], v[168:171], v[126:129]
	v_mfma_f32_16x16x32_bf16 v[122:125], v[160:163], v[168:171], v[122:125]
	v_mfma_f32_16x16x32_bf16 v[114:117], v[152:155], v[176:179], v[114:117]
	v_mfma_f32_16x16x32_bf16 v[106:109], v[160:163], v[176:179], v[106:109]
	v_mfma_f32_16x16x32_bf16 v[98:101], v[152:155], v[186:189], v[98:101]
	v_mfma_f32_16x16x32_bf16 v[90:93], v[160:163], v[186:189], v[90:93]
	v_mfma_f32_16x16x32_bf16 v[82:85], v[152:155], v[194:197], v[82:85]
	v_mfma_f32_16x16x32_bf16 v[74:77], v[160:163], v[194:197], v[74:77]
	s_setprio 0
	s_barrier
	s_mov_b32 m0, s75
	v_lshl_add_u64 v[214:215], v[214:215], 0, s[84:85]
	s_waitcnt vmcnt(0)
	ds_read_b128 v[198:201], v147
	ds_read_b128 v[202:205], v147 offset:1024
	ds_read_b128 v[206:209], v147 offset:2048
	ds_read_b128 v[210:213], v147 offset:3072
	global_load_lds_dwordx4 v[214:215], off
	v_lshl_add_u64 v[214:215], v[216:217], 0, s[84:85]
	s_mov_b32 m0, s82
	s_nop 0
	global_load_lds_dwordx4 v[214:215], off
	s_barrier
	s_waitcnt lgkmcnt(0)
	s_setprio 1
	s_waitcnt lgkmcnt(0)
	v_mfma_f32_16x16x32_bf16 v[118:121], v[198:201], v[164:167], v[118:121]
	v_mfma_f32_16x16x32_bf16 v[110:113], v[206:209], v[164:167], v[110:113]
	v_mfma_f32_16x16x32_bf16 v[102:105], v[198:201], v[172:175], v[102:105]
	v_mfma_f32_16x16x32_bf16 v[94:97], v[206:209], v[172:175], v[94:97]
	v_mfma_f32_16x16x32_bf16 v[86:89], v[198:201], v[182:185], v[86:89]
	v_mfma_f32_16x16x32_bf16 v[78:81], v[206:209], v[182:185], v[78:81]
	v_mfma_f32_16x16x32_bf16 v[70:73], v[198:201], v[190:193], v[70:73]
	v_mfma_f32_16x16x32_bf16 v[66:69], v[206:209], v[190:193], v[66:69]
	v_mfma_f32_16x16x32_bf16 v[118:121], v[202:205], v[168:171], v[118:121]
	v_mfma_f32_16x16x32_bf16 v[110:113], v[210:213], v[168:171], v[110:113]
	v_mfma_f32_16x16x32_bf16 v[102:105], v[202:205], v[176:179], v[102:105]
	v_mfma_f32_16x16x32_bf16 v[94:97], v[210:213], v[176:179], v[94:97]
	v_mfma_f32_16x16x32_bf16 v[86:89], v[202:205], v[186:189], v[86:89]
	v_mfma_f32_16x16x32_bf16 v[78:81], v[210:213], v[186:189], v[78:81]
	v_mfma_f32_16x16x32_bf16 v[70:73], v[202:205], v[194:197], v[70:73]
	v_mfma_f32_16x16x32_bf16 v[66:69], v[210:213], v[194:197], v[66:69]
	s_setprio 0
	s_mov_b32 m0, s92
	v_lshl_add_u64 v[214:215], v[222:223], 0, s[84:85]
	s_barrier
	s_waitcnt vmcnt(0)
	ds_read_b128 v[164:167], v142 offset:49152
	ds_read_b128 v[168:171], v142 offset:50176
	ds_read_b128 v[172:175], v142 offset:51200
	ds_read_b128 v[176:179], v142 offset:52224
	ds_read_b128 v[182:185], v142 offset:53248
	ds_read_b128 v[186:189], v142 offset:54272
	ds_read_b128 v[190:193], v142 offset:55296
	ds_read_b128 v[194:197], v142 offset:56320
	global_load_lds_dwordx4 v[214:215], off
	v_lshl_add_u64 v[214:215], v[224:225], 0, s[84:85]
	s_mov_b32 m0, s93
	s_nop 0
	global_load_lds_dwordx4 v[214:215], off
	s_barrier
	s_waitcnt lgkmcnt(0)
	s_setprio 1
	s_waitcnt lgkmcnt(0)
	v_mfma_f32_16x16x32_bf16 v[62:65], v[148:151], v[164:167], v[62:65]
	v_mfma_f32_16x16x32_bf16 v[58:61], v[156:159], v[164:167], v[58:61]
	v_mfma_f32_16x16x32_bf16 v[50:53], v[148:151], v[172:175], v[50:53]
	v_mfma_f32_16x16x32_bf16 v[42:45], v[156:159], v[172:175], v[42:45]
	v_mfma_f32_16x16x32_bf16 v[34:37], v[148:151], v[182:185], v[34:37]
	v_mfma_f32_16x16x32_bf16 v[26:29], v[156:159], v[182:185], v[26:29]
	v_mfma_f32_16x16x32_bf16 v[18:21], v[148:151], v[190:193], v[18:21]
	v_mfma_f32_16x16x32_bf16 v[10:13], v[156:159], v[190:193], v[10:13]
	v_mfma_f32_16x16x32_bf16 v[62:65], v[152:155], v[168:171], v[62:65]
	v_mfma_f32_16x16x32_bf16 v[58:61], v[160:163], v[168:171], v[58:61]
	v_mfma_f32_16x16x32_bf16 v[50:53], v[152:155], v[176:179], v[50:53]
	v_mfma_f32_16x16x32_bf16 v[42:45], v[160:163], v[176:179], v[42:45]
	v_mfma_f32_16x16x32_bf16 v[34:37], v[152:155], v[186:189], v[34:37]
	v_mfma_f32_16x16x32_bf16 v[26:29], v[160:163], v[186:189], v[26:29]
	v_mfma_f32_16x16x32_bf16 v[18:21], v[152:155], v[194:197], v[18:21]
	v_mfma_f32_16x16x32_bf16 v[10:13], v[160:163], v[194:197], v[10:13]
	s_setprio 0
	s_barrier
	s_add_u32 s26, s26, 0x40080
	s_addc_u32 s27, s27, 0
	s_mov_b32 m0, s96
	v_lshl_add_u64 v[148:149], s[26:27], 0, v[0:1]
	global_load_lds_dwordx4 v[148:149], off
	v_lshl_add_u64 v[148:149], s[26:27], 0, v[134:135]
	s_mov_b32 m0, s97
	s_nop 0
	global_load_lds_dwordx4 v[148:149], off
	s_waitcnt vmcnt(6)
	s_barrier
	s_setprio 1
	v_mfma_f32_16x16x32_bf16 v[54:57], v[198:201], v[164:167], v[54:57]
	v_mfma_f32_16x16x32_bf16 v[46:49], v[206:209], v[164:167], v[46:49]
	v_mfma_f32_16x16x32_bf16 v[38:41], v[198:201], v[172:175], v[38:41]
	v_mfma_f32_16x16x32_bf16 v[30:33], v[206:209], v[172:175], v[30:33]
	v_mfma_f32_16x16x32_bf16 v[22:25], v[198:201], v[182:185], v[22:25]
	v_mfma_f32_16x16x32_bf16 v[14:17], v[206:209], v[182:185], v[14:17]
	v_mfma_f32_16x16x32_bf16 v[6:9], v[198:201], v[190:193], v[6:9]
	v_mfma_f32_16x16x32_bf16 v[2:5], v[206:209], v[190:193], v[2:5]
	v_mfma_f32_16x16x32_bf16 v[54:57], v[202:205], v[168:171], v[54:57]
	v_mfma_f32_16x16x32_bf16 v[46:49], v[210:213], v[168:171], v[46:49]
	v_mfma_f32_16x16x32_bf16 v[38:41], v[202:205], v[176:179], v[38:41]
	v_mfma_f32_16x16x32_bf16 v[30:33], v[210:213], v[176:179], v[30:33]
	v_mfma_f32_16x16x32_bf16 v[22:25], v[202:205], v[186:189], v[22:25]
	v_mfma_f32_16x16x32_bf16 v[14:17], v[210:213], v[186:189], v[14:17]
	v_mfma_f32_16x16x32_bf16 v[6:9], v[202:205], v[194:197], v[6:9]
	v_mfma_f32_16x16x32_bf16 v[2:5], v[210:213], v[194:197], v[2:5]
	s_setprio 0
	s_add_i32 s62, s62, 2
	s_add_u32 s24, s24, 0x100
	s_addc_u32 s25, s25, 0
	s_add_u32 vcc_lo, vcc_lo, 0x100
	s_addc_u32 vcc_hi, vcc_hi, 0
	s_cmp_gt_u32 s62, 13
	s_barrier
	s_cbranch_scc0 .LBB0_733
	v_lshl_add_u32 v149, s6, 8, v143
	v_add_u32_e32 v140, -8, v149
	v_lshl_add_u32 v148, s22, 8, v141
	v_cmp_gt_u32_e32 vcc, s71, v140
	s_and_saveexec_b64 s[6:7], vcc
	s_cbranch_execz .LBB0_736
	v_cvt_pk_bf16_f32 v126, v126, v127
	v_cvt_pk_bf16_f32 v127, v128, v129
	v_cvt_pk_bf16_f32 v128, v122, v123
	v_cvt_pk_bf16_f32 v129, v124, v125
	v_mad_u64_u32 v[122:123], s[22:23], v148, s71, v[140:141]
	v_mov_b32_e32 v123, v1
	v_lshl_add_u64 v[122:123], v[122:123], 1, s[10:11]
	global_store_dwordx4 v[122:123], v[126:129], off
.LBB0_736:
	s_or_b64 exec, exec, s[6:7]
	v_add_u32_e32 v122, 0x78, v149
	v_cmp_gt_u32_e64 s[6:7], s71, v122
	s_and_saveexec_b64 s[22:23], s[6:7]
	s_cbranch_execz .LBB0_751
	v_cvt_pk_bf16_f32 v118, v118, v119
	v_cvt_pk_bf16_f32 v119, v120, v121
	v_cvt_pk_bf16_f32 v120, v110, v111
	v_cvt_pk_bf16_f32 v121, v112, v113
	v_mad_u64_u32 v[110:111], s[24:25], v148, s71, v[122:123]
	v_mov_b32_e32 v111, v1
	v_lshl_add_u64 v[110:111], v[110:111], 1, s[10:11]
	global_store_dwordx4 v[110:111], v[118:121], off
	s_or_b64 exec, exec, s[22:23]
	v_or_b32_e32 v110, 16, v148
	s_and_saveexec_b64 s[22:23], vcc
	s_cbranch_execnz .LBB0_752

.LBB0_739:
	v_cvt_pk_bf16_f32 v102, v102, v103
	v_cvt_pk_bf16_f32 v103, v104, v105
	v_cvt_pk_bf16_f32 v104, v94, v95
	v_cvt_pk_bf16_f32 v105, v96, v97
	v_mad_u64_u32 v[94:95], s[24:25], v110, s71, v[122:123]
	v_mov_b32_e32 v95, v1
	v_lshl_add_u64 v[94:95], v[94:95], 1, s[10:11]
	global_store_dwordx4 v[94:95], v[102:105], off
	s_or_b64 exec, exec, s[22:23]
	v_or_b32_e32 v94, 32, v148
	s_and_saveexec_b64 s[22:23], vcc
	s_cbranch_execnz .LBB0_754

.LBB0_741:
	v_cvt_pk_bf16_f32 v86, v86, v87
	v_cvt_pk_bf16_f32 v87, v88, v89
	v_cvt_pk_bf16_f32 v88, v78, v79
	v_cvt_pk_bf16_f32 v89, v80, v81
	v_mad_u64_u32 v[78:79], s[24:25], v94, s71, v[122:123]
	v_mov_b32_e32 v79, v1
	v_lshl_add_u64 v[78:79], v[78:79], 1, s[10:11]
	global_store_dwordx4 v[78:79], v[86:89], off
	s_or_b64 exec, exec, s[22:23]
	v_or_b32_e32 v78, 48, v148
	s_and_saveexec_b64 s[22:23], vcc
	s_cbranch_execnz .LBB0_756

.LBB0_743:
	v_cvt_pk_bf16_f32 v70, v70, v71
	v_cvt_pk_bf16_f32 v71, v72, v73
	v_cvt_pk_bf16_f32 v72, v66, v67
	v_cvt_pk_bf16_f32 v73, v68, v69
	v_mad_u64_u32 v[66:67], s[24:25], v78, s71, v[122:123]
	v_mov_b32_e32 v67, v1
	v_lshl_add_u64 v[66:67], v[66:67], 1, s[10:11]
	global_store_dwordx4 v[66:67], v[70:73], off
	s_or_b64 exec, exec, s[22:23]
	v_add_u32_e32 v66, 0x80, v148
	s_and_saveexec_b64 s[22:23], vcc
	s_cbranch_execnz .LBB0_758

.LBB0_745:
	v_cvt_pk_bf16_f32 v54, v54, v55
	v_cvt_pk_bf16_f32 v55, v56, v57
	v_cvt_pk_bf16_f32 v56, v46, v47
	v_cvt_pk_bf16_f32 v57, v48, v49
	v_mad_u64_u32 v[46:47], s[24:25], v66, s71, v[122:123]
	v_mov_b32_e32 v47, v1
	v_lshl_add_u64 v[46:47], v[46:47], 1, s[10:11]
	global_store_dwordx4 v[46:47], v[54:57], off
	s_or_b64 exec, exec, s[22:23]
	v_add_u32_e32 v46, 0x90, v148
	s_and_saveexec_b64 s[22:23], vcc
	s_cbranch_execnz .LBB0_760

.LBB0_747:
	v_cvt_pk_bf16_f32 v38, v38, v39
	v_cvt_pk_bf16_f32 v39, v40, v41
	v_cvt_pk_bf16_f32 v40, v30, v31
	v_cvt_pk_bf16_f32 v41, v32, v33
	v_mad_u64_u32 v[30:31], s[24:25], v46, s71, v[122:123]
	v_mov_b32_e32 v31, v1
	v_lshl_add_u64 v[30:31], v[30:31], 1, s[10:11]
	global_store_dwordx4 v[30:31], v[38:41], off
	s_or_b64 exec, exec, s[22:23]
	v_add_u32_e32 v30, 0xa0, v148
	s_and_saveexec_b64 s[22:23], vcc
	s_cbranch_execnz .LBB0_762

.LBB0_749:
	v_cvt_pk_bf16_f32 v22, v22, v23
	v_cvt_pk_bf16_f32 v23, v24, v25
	v_cvt_pk_bf16_f32 v24, v14, v15
	v_cvt_pk_bf16_f32 v25, v16, v17
	v_mad_u64_u32 v[14:15], s[24:25], v30, s71, v[122:123]
	v_mov_b32_e32 v15, v1
	v_lshl_add_u64 v[14:15], v[14:15], 1, s[10:11]
	global_store_dwordx4 v[14:15], v[22:25], off
	s_or_b64 exec, exec, s[22:23]
	v_add_u32_e32 v14, 0xb0, v148
	s_and_saveexec_b64 s[22:23], vcc
	s_cbranch_execnz .LBB0_764

.LBB0_752:
	v_cvt_pk_bf16_f32 v111, v114, s0
	v_cvt_pk_bf16_f32 v114, v106, v107
	v_cvt_pk_bf16_f32 v112, v115, s0
	v_lshlrev_b32_e32 v112, 16, v112
	v_cvt_pk_bf16_f32 v115, v108, v109
	v_mad_u64_u32 v[106:107], s[24:25], v110, s71, v[140:141]
	v_or_b32_sdwa v112, v112, v111 dst_sel:DWORD dst_unused:UNUSED_PAD src0_sel:DWORD src1_sel:WORD_0
	v_mov_b32_e32 v107, v1
	v_cvt_pk_bf16_f32 v113, v116, v117
	v_lshl_add_u64 v[106:107], v[106:107], 1, s[10:11]
	global_store_dwordx4 v[106:107], v[112:115], off
	s_or_b64 exec, exec, s[22:23]
	s_and_saveexec_b64 s[22:23], s[6:7]
	s_cbranch_execnz .LBB0_739

.LBB0_754:
	v_cvt_pk_bf16_f32 v95, v98, s0
	v_cvt_pk_bf16_f32 v98, v90, v91
	v_cvt_pk_bf16_f32 v96, v99, s0
	v_lshlrev_b32_e32 v96, 16, v96
	v_cvt_pk_bf16_f32 v99, v92, v93
	v_mad_u64_u32 v[90:91], s[24:25], v94, s71, v[140:141]
	v_or_b32_sdwa v96, v96, v95 dst_sel:DWORD dst_unused:UNUSED_PAD src0_sel:DWORD src1_sel:WORD_0
	v_mov_b32_e32 v91, v1
	v_cvt_pk_bf16_f32 v97, v100, v101
	v_lshl_add_u64 v[90:91], v[90:91], 1, s[10:11]
	global_store_dwordx4 v[90:91], v[96:99], off
	s_or_b64 exec, exec, s[22:23]
	s_and_saveexec_b64 s[22:23], s[6:7]
	s_cbranch_execnz .LBB0_741

.LBB0_756:
	v_cvt_pk_bf16_f32 v79, v82, s0
	v_cvt_pk_bf16_f32 v82, v74, v75
	v_cvt_pk_bf16_f32 v80, v83, s0
	v_lshlrev_b32_e32 v80, 16, v80
	v_cvt_pk_bf16_f32 v83, v76, v77
	v_mad_u64_u32 v[74:75], s[24:25], v78, s71, v[140:141]
	v_or_b32_sdwa v80, v80, v79 dst_sel:DWORD dst_unused:UNUSED_PAD src0_sel:DWORD src1_sel:WORD_0
	v_mov_b32_e32 v75, v1
	v_cvt_pk_bf16_f32 v81, v84, v85
	v_lshl_add_u64 v[74:75], v[74:75], 1, s[10:11]
	global_store_dwordx4 v[74:75], v[80:83], off
	s_or_b64 exec, exec, s[22:23]
	s_and_saveexec_b64 s[22:23], s[6:7]
	s_cbranch_execnz .LBB0_743

.LBB0_758:
	v_cvt_pk_bf16_f32 v62, v62, v63
	v_cvt_pk_bf16_f32 v63, v64, v65
	v_cvt_pk_bf16_f32 v64, v58, v59
	v_cvt_pk_bf16_f32 v65, v60, v61
	v_mad_u64_u32 v[58:59], s[24:25], v66, s71, v[140:141]
	v_mov_b32_e32 v59, v1
	v_lshl_add_u64 v[58:59], v[58:59], 1, s[10:11]
	global_store_dwordx4 v[58:59], v[62:65], off
	s_or_b64 exec, exec, s[22:23]
	s_and_saveexec_b64 s[22:23], s[6:7]
	s_cbranch_execnz .LBB0_745

.LBB0_760:
	v_cvt_pk_bf16_f32 v47, v50, s0
	v_cvt_pk_bf16_f32 v50, v42, v43
	v_cvt_pk_bf16_f32 v48, v51, s0
	v_lshlrev_b32_e32 v48, 16, v48
	v_cvt_pk_bf16_f32 v51, v44, v45
	v_mad_u64_u32 v[42:43], s[24:25], v46, s71, v[140:141]
	v_or_b32_sdwa v48, v48, v47 dst_sel:DWORD dst_unused:UNUSED_PAD src0_sel:DWORD src1_sel:WORD_0
	v_mov_b32_e32 v43, v1
	v_cvt_pk_bf16_f32 v49, v52, v53
	v_lshl_add_u64 v[42:43], v[42:43], 1, s[10:11]
	global_store_dwordx4 v[42:43], v[48:51], off
	s_or_b64 exec, exec, s[22:23]
	s_and_saveexec_b64 s[22:23], s[6:7]
	s_cbranch_execnz .LBB0_747

.LBB0_762:
	v_cvt_pk_bf16_f32 v31, v34, s0
	v_cvt_pk_bf16_f32 v34, v26, v27
	v_cvt_pk_bf16_f32 v32, v35, s0
	v_lshlrev_b32_e32 v32, 16, v32
	v_cvt_pk_bf16_f32 v35, v28, v29
	v_mad_u64_u32 v[26:27], s[24:25], v30, s71, v[140:141]
	v_or_b32_sdwa v32, v32, v31 dst_sel:DWORD dst_unused:UNUSED_PAD src0_sel:DWORD src1_sel:WORD_0
	v_mov_b32_e32 v27, v1
	v_cvt_pk_bf16_f32 v33, v36, v37
	v_lshl_add_u64 v[26:27], v[26:27], 1, s[10:11]
	global_store_dwordx4 v[26:27], v[32:35], off
	s_or_b64 exec, exec, s[22:23]
	s_and_saveexec_b64 s[22:23], s[6:7]
	s_cbranch_execnz .LBB0_749

.LBB0_764:
	v_cvt_pk_bf16_f32 v15, v18, s0
	v_cvt_pk_bf16_f32 v18, v10, v11
	v_cvt_pk_bf16_f32 v16, v19, s0
	v_lshlrev_b32_e32 v16, 16, v16
	v_cvt_pk_bf16_f32 v19, v12, v13
	v_mad_u64_u32 v[10:11], s[24:25], v14, s71, v[140:141]
	v_or_b32_sdwa v16, v16, v15 dst_sel:DWORD dst_unused:UNUSED_PAD src0_sel:DWORD src1_sel:WORD_0
	v_mov_b32_e32 v11, v1
	v_cvt_pk_bf16_f32 v17, v20, v21
	v_lshl_add_u64 v[10:11], v[10:11], 1, s[10:11]
	global_store_dwordx4 v[10:11], v[16:19], off
	s_or_b64 exec, exec, s[22:23]
	s_and_saveexec_b64 s[22:23], s[6:7]
	s_cbranch_execz .LBB0_729
.LBB0_765:
	v_cvt_pk_bf16_f32 v6, v6, v7
	v_cvt_pk_bf16_f32 v7, v8, v9
	v_cvt_pk_bf16_f32 v8, v2, v3
	v_cvt_pk_bf16_f32 v9, v4, v5
	v_mad_u64_u32 v[2:3], s[6:7], v14, s71, v[122:123]
	v_mov_b32_e32 v3, v1
	v_lshl_add_u64 v[2:3], v[2:3], 1, s[10:11]
	global_store_dwordx4 v[2:3], v[6:9], off
	s_branch .LBB0_729

.LBB0_781:
	v_add_u32_e32 v140, 0x10000, v143
	s_waitcnt vmcnt(0)
	ds_read_b128 v[146:149], v140
	ds_read_b128 v[150:153], v140 offset:1024
	ds_read_b128 v[154:157], v140 offset:2048
	ds_read_b128 v[158:161], v140 offset:3072
	s_add_u32 s26, s24, 0xfffc0080
	s_addc_u32 s27, s25, -1
	s_cmp_eq_u32 vcc_lo, 12
	s_cselect_b32 s29, s7, s27
	s_cselect_b32 s28, s17, s26
	s_cselect_b32 s27, s15, s94
	s_cselect_b32 s26, s23, s89
	v_lshl_add_u64 v[178:179], s[24:25], 0, v[136:137]
	s_add_i32 m0, s30, 0xc000
	ds_read_b128 v[162:165], v142
	ds_read_b128 v[166:169], v142 offset:1024
	ds_read_b128 v[170:173], v142 offset:2048
	ds_read_b128 v[174:177], v142 offset:3072
	ds_read_b128 v[182:185], v142 offset:4096
	ds_read_b128 v[186:189], v142 offset:5120
	ds_read_b128 v[190:193], v142 offset:6144
	ds_read_b128 v[194:197], v142 offset:7168
	global_load_lds_dwordx4 v[178:179], off
	v_lshl_add_u64 v[178:179], s[24:25], 0, v[138:139]
	s_add_i32 m0, s30, 0xe000
	s_nop 0
	global_load_lds_dwordx4 v[178:179], off
	s_waitcnt lgkmcnt(8)
	s_barrier
	s_waitcnt lgkmcnt(0)
	s_setprio 1
	s_waitcnt lgkmcnt(0)
	v_mfma_f32_16x16x32_bf16 v[126:129], v[146:149], v[162:165], v[126:129]
	v_mfma_f32_16x16x32_bf16 v[122:125], v[154:157], v[162:165], v[122:125]
	v_mfma_f32_16x16x32_bf16 v[114:117], v[146:149], v[170:173], v[114:117]
	v_mfma_f32_16x16x32_bf16 v[106:109], v[154:157], v[170:173], v[106:109]
	v_mfma_f32_16x16x32_bf16 v[98:101], v[146:149], v[182:185], v[98:101]
	v_mfma_f32_16x16x32_bf16 v[90:93], v[154:157], v[182:185], v[90:93]
	v_mfma_f32_16x16x32_bf16 v[82:85], v[146:149], v[190:193], v[82:85]
	v_mfma_f32_16x16x32_bf16 v[74:77], v[154:157], v[190:193], v[74:77]
	v_mfma_f32_16x16x32_bf16 v[126:129], v[150:153], v[166:169], v[126:129]
	v_mfma_f32_16x16x32_bf16 v[122:125], v[158:161], v[166:169], v[122:125]
	v_mfma_f32_16x16x32_bf16 v[114:117], v[150:153], v[174:177], v[114:117]
	v_mfma_f32_16x16x32_bf16 v[106:109], v[158:161], v[174:177], v[106:109]
	v_mfma_f32_16x16x32_bf16 v[98:101], v[150:153], v[186:189], v[98:101]
	v_mfma_f32_16x16x32_bf16 v[90:93], v[158:161], v[186:189], v[90:93]
	v_mfma_f32_16x16x32_bf16 v[82:85], v[150:153], v[194:197], v[82:85]
	v_mfma_f32_16x16x32_bf16 v[74:77], v[158:161], v[194:197], v[74:77]
	s_setprio 0
	s_barrier
	s_mov_b32 m0, s35
	v_add_u32_e32 v140, 0x14000, v143
	v_lshl_add_u64 v[178:179], s[26:27], 0, v[0:1]
	s_waitcnt vmcnt(0)
	ds_read_b128 v[198:201], v140
	ds_read_b128 v[202:205], v140 offset:1024
	ds_read_b128 v[206:209], v140 offset:2048
	ds_read_b128 v[210:213], v140 offset:3072
	global_load_lds_dwordx4 v[178:179], off
	v_lshl_add_u64 v[214:215], s[26:27], 0, v[134:135]
	s_mov_b32 m0, s36
	s_nop 0
	global_load_lds_dwordx4 v[214:215], off
	s_barrier
	s_waitcnt lgkmcnt(0)
	s_setprio 1
	s_waitcnt lgkmcnt(0)
	v_mfma_f32_16x16x32_bf16 v[118:121], v[198:201], v[162:165], v[118:121]
	v_mfma_f32_16x16x32_bf16 v[110:113], v[206:209], v[162:165], v[110:113]
	v_mfma_f32_16x16x32_bf16 v[102:105], v[198:201], v[170:173], v[102:105]
	v_mfma_f32_16x16x32_bf16 v[94:97], v[206:209], v[170:173], v[94:97]
	v_mfma_f32_16x16x32_bf16 v[86:89], v[198:201], v[182:185], v[86:89]
	v_mfma_f32_16x16x32_bf16 v[78:81], v[206:209], v[182:185], v[78:81]
	v_mfma_f32_16x16x32_bf16 v[70:73], v[198:201], v[190:193], v[70:73]
	v_mfma_f32_16x16x32_bf16 v[66:69], v[206:209], v[190:193], v[66:69]
	v_mfma_f32_16x16x32_bf16 v[118:121], v[202:205], v[166:169], v[118:121]
	v_mfma_f32_16x16x32_bf16 v[110:113], v[210:213], v[166:169], v[110:113]
	v_mfma_f32_16x16x32_bf16 v[102:105], v[202:205], v[174:177], v[102:105]
	v_mfma_f32_16x16x32_bf16 v[94:97], v[210:213], v[174:177], v[94:97]
	v_mfma_f32_16x16x32_bf16 v[86:89], v[202:205], v[186:189], v[86:89]
	v_mfma_f32_16x16x32_bf16 v[78:81], v[210:213], v[186:189], v[78:81]
	v_mfma_f32_16x16x32_bf16 v[70:73], v[202:205], v[194:197], v[70:73]
	v_mfma_f32_16x16x32_bf16 v[66:69], v[210:213], v[194:197], v[66:69]
	s_setprio 0
	s_mov_b32 m0, s30
	v_lshl_add_u64 v[216:217], s[28:29], 0, v[130:131]
	s_barrier
	s_waitcnt vmcnt(0)
	ds_read_b128 v[162:165], v142 offset:16384
	ds_read_b128 v[166:169], v142 offset:17408
	ds_read_b128 v[170:173], v142 offset:18432
	ds_read_b128 v[174:177], v142 offset:19456
	ds_read_b128 v[182:185], v142 offset:20480
	ds_read_b128 v[186:189], v142 offset:21504
	ds_read_b128 v[190:193], v142 offset:22528
	ds_read_b128 v[194:197], v142 offset:23552
	global_load_lds_dwordx4 v[216:217], off
	v_lshl_add_u64 v[222:223], s[28:29], 0, v[132:133]
	s_mov_b32 m0, s37
	s_nop 0
	global_load_lds_dwordx4 v[222:223], off
	s_barrier
	s_waitcnt lgkmcnt(0)
	s_setprio 1
	s_waitcnt lgkmcnt(0)
	v_mfma_f32_16x16x32_bf16 v[62:65], v[146:149], v[162:165], v[62:65]
	v_mfma_f32_16x16x32_bf16 v[58:61], v[154:157], v[162:165], v[58:61]
	v_mfma_f32_16x16x32_bf16 v[50:53], v[146:149], v[170:173], v[50:53]
	v_mfma_f32_16x16x32_bf16 v[42:45], v[154:157], v[170:173], v[42:45]
	v_mfma_f32_16x16x32_bf16 v[34:37], v[146:149], v[182:185], v[34:37]
	v_mfma_f32_16x16x32_bf16 v[26:29], v[154:157], v[182:185], v[26:29]
	v_mfma_f32_16x16x32_bf16 v[18:21], v[146:149], v[190:193], v[18:21]
	v_mfma_f32_16x16x32_bf16 v[10:13], v[154:157], v[190:193], v[10:13]
	v_mfma_f32_16x16x32_bf16 v[62:65], v[150:153], v[166:169], v[62:65]
	v_mfma_f32_16x16x32_bf16 v[58:61], v[158:161], v[166:169], v[58:61]
	v_mfma_f32_16x16x32_bf16 v[50:53], v[150:153], v[174:177], v[50:53]
	v_mfma_f32_16x16x32_bf16 v[42:45], v[158:161], v[174:177], v[42:45]
	v_mfma_f32_16x16x32_bf16 v[34:37], v[150:153], v[186:189], v[34:37]
	v_mfma_f32_16x16x32_bf16 v[26:29], v[158:161], v[186:189], v[26:29]
	v_mfma_f32_16x16x32_bf16 v[18:21], v[150:153], v[194:197], v[18:21]
	v_mfma_f32_16x16x32_bf16 v[10:13], v[158:161], v[194:197], v[10:13]
	s_setprio 0
	s_barrier
	s_add_u32 s76, s26, 0x40000
	s_addc_u32 s77, s27, 0
	s_mov_b32 m0, s38
	v_lshl_add_u64 v[146:147], s[76:77], 0, v[0:1]
	global_load_lds_dwordx4 v[146:147], off
	v_lshl_add_u64 v[146:147], s[76:77], 0, v[134:135]
	s_mov_b32 m0, s39
	s_nop 0
	global_load_lds_dwordx4 v[146:147], off
	s_waitcnt vmcnt(6)
	s_barrier
	s_setprio 1
	v_mfma_f32_16x16x32_bf16 v[54:57], v[198:201], v[162:165], v[54:57]
	v_mfma_f32_16x16x32_bf16 v[46:49], v[206:209], v[162:165], v[46:49]
	v_mfma_f32_16x16x32_bf16 v[38:41], v[198:201], v[170:173], v[38:41]
	v_mfma_f32_16x16x32_bf16 v[30:33], v[206:209], v[170:173], v[30:33]
	v_mfma_f32_16x16x32_bf16 v[22:25], v[198:201], v[182:185], v[22:25]
	v_mfma_f32_16x16x32_bf16 v[14:17], v[206:209], v[182:185], v[14:17]
	v_mfma_f32_16x16x32_bf16 v[6:9], v[198:201], v[190:193], v[6:9]
	v_mfma_f32_16x16x32_bf16 v[2:5], v[206:209], v[190:193], v[2:5]
	v_mfma_f32_16x16x32_bf16 v[54:57], v[202:205], v[166:169], v[54:57]
	v_mfma_f32_16x16x32_bf16 v[46:49], v[210:213], v[166:169], v[46:49]
	v_mfma_f32_16x16x32_bf16 v[38:41], v[202:205], v[174:177], v[38:41]
	v_mfma_f32_16x16x32_bf16 v[30:33], v[210:213], v[174:177], v[30:33]
	v_mfma_f32_16x16x32_bf16 v[22:25], v[202:205], v[186:189], v[22:25]
	v_mfma_f32_16x16x32_bf16 v[14:17], v[210:213], v[186:189], v[14:17]
	v_mfma_f32_16x16x32_bf16 v[6:9], v[202:205], v[194:197], v[6:9]
	v_mfma_f32_16x16x32_bf16 v[2:5], v[210:213], v[194:197], v[2:5]
	s_setprio 0
	v_add_u32_e32 v140, 0x18000, v143
	s_barrier
	s_waitcnt vmcnt(0)
	ds_read_b128 v[146:149], v140
	ds_read_b128 v[150:153], v140 offset:1024
	ds_read_b128 v[154:157], v140 offset:2048
	ds_read_b128 v[158:161], v140 offset:3072
	s_add_u32 s28, s28, 0x40000
	s_addc_u32 s29, s29, 0
	s_mov_b32 m0, s60
	v_lshl_add_u64 v[198:199], s[28:29], 0, v[130:131]
	ds_read_b128 v[162:165], v142 offset:32768
	ds_read_b128 v[166:169], v142 offset:33792
	ds_read_b128 v[170:173], v142 offset:34816
	ds_read_b128 v[174:177], v142 offset:35840
	ds_read_b128 v[182:185], v142 offset:36864
	ds_read_b128 v[186:189], v142 offset:37888
	ds_read_b128 v[190:193], v142 offset:38912
	ds_read_b128 v[194:197], v142 offset:39936
	global_load_lds_dwordx4 v[198:199], off
	v_lshl_add_u64 v[198:199], s[28:29], 0, v[132:133]
	s_mov_b32 m0, s68
	s_nop 0
	global_load_lds_dwordx4 v[198:199], off
	s_waitcnt lgkmcnt(8)
	s_barrier
	s_waitcnt lgkmcnt(0)
	s_setprio 1
	s_waitcnt lgkmcnt(0)
	v_mfma_f32_16x16x32_bf16 v[126:129], v[146:149], v[162:165], v[126:129]
	v_mfma_f32_16x16x32_bf16 v[122:125], v[154:157], v[162:165], v[122:125]
	v_mfma_f32_16x16x32_bf16 v[114:117], v[146:149], v[170:173], v[114:117]
	v_mfma_f32_16x16x32_bf16 v[106:109], v[154:157], v[170:173], v[106:109]
	v_mfma_f32_16x16x32_bf16 v[98:101], v[146:149], v[182:185], v[98:101]
	v_mfma_f32_16x16x32_bf16 v[90:93], v[154:157], v[182:185], v[90:93]
	v_mfma_f32_16x16x32_bf16 v[82:85], v[146:149], v[190:193], v[82:85]
	v_mfma_f32_16x16x32_bf16 v[74:77], v[154:157], v[190:193], v[74:77]
	v_mfma_f32_16x16x32_bf16 v[126:129], v[150:153], v[166:169], v[126:129]
	v_mfma_f32_16x16x32_bf16 v[122:125], v[158:161], v[166:169], v[122:125]
	v_mfma_f32_16x16x32_bf16 v[114:117], v[150:153], v[174:177], v[114:117]
	v_mfma_f32_16x16x32_bf16 v[106:109], v[158:161], v[174:177], v[106:109]
	v_mfma_f32_16x16x32_bf16 v[98:101], v[150:153], v[186:189], v[98:101]
	v_mfma_f32_16x16x32_bf16 v[90:93], v[158:161], v[186:189], v[90:93]
	v_mfma_f32_16x16x32_bf16 v[82:85], v[150:153], v[194:197], v[82:85]
	v_mfma_f32_16x16x32_bf16 v[74:77], v[158:161], v[194:197], v[74:77]
	s_setprio 0
	s_barrier
	s_mov_b32 m0, s75
	v_add_u32_e32 v140, 0x1c000, v143
	v_lshl_add_u64 v[178:179], v[178:179], 0, s[84:85]
	s_waitcnt vmcnt(0)
	ds_read_b128 v[198:201], v140
	ds_read_b128 v[202:205], v140 offset:1024
	ds_read_b128 v[206:209], v140 offset:2048
	ds_read_b128 v[210:213], v140 offset:3072
	global_load_lds_dwordx4 v[178:179], off
	v_lshl_add_u64 v[178:179], v[214:215], 0, s[84:85]
	s_mov_b32 m0, s82
	s_nop 0
	global_load_lds_dwordx4 v[178:179], off
	s_barrier
	s_waitcnt lgkmcnt(0)
	s_setprio 1
	s_waitcnt lgkmcnt(0)
	v_mfma_f32_16x16x32_bf16 v[118:121], v[198:201], v[162:165], v[118:121]
	v_mfma_f32_16x16x32_bf16 v[110:113], v[206:209], v[162:165], v[110:113]
	v_mfma_f32_16x16x32_bf16 v[102:105], v[198:201], v[170:173], v[102:105]
	v_mfma_f32_16x16x32_bf16 v[94:97], v[206:209], v[170:173], v[94:97]
	v_mfma_f32_16x16x32_bf16 v[86:89], v[198:201], v[182:185], v[86:89]
	v_mfma_f32_16x16x32_bf16 v[78:81], v[206:209], v[182:185], v[78:81]
	v_mfma_f32_16x16x32_bf16 v[70:73], v[198:201], v[190:193], v[70:73]
	v_mfma_f32_16x16x32_bf16 v[66:69], v[206:209], v[190:193], v[66:69]
	v_mfma_f32_16x16x32_bf16 v[118:121], v[202:205], v[166:169], v[118:121]
	v_mfma_f32_16x16x32_bf16 v[110:113], v[210:213], v[166:169], v[110:113]
	v_mfma_f32_16x16x32_bf16 v[102:105], v[202:205], v[174:177], v[102:105]
	v_mfma_f32_16x16x32_bf16 v[94:97], v[210:213], v[174:177], v[94:97]
	v_mfma_f32_16x16x32_bf16 v[86:89], v[202:205], v[186:189], v[86:89]
	v_mfma_f32_16x16x32_bf16 v[78:81], v[210:213], v[186:189], v[78:81]
	v_mfma_f32_16x16x32_bf16 v[70:73], v[202:205], v[194:197], v[70:73]
	v_mfma_f32_16x16x32_bf16 v[66:69], v[210:213], v[194:197], v[66:69]
	s_setprio 0
	s_mov_b32 m0, s92
	v_lshl_add_u64 v[178:179], v[216:217], 0, s[84:85]
	s_barrier
	s_waitcnt vmcnt(0)
	ds_read_b128 v[162:165], v142 offset:49152
	ds_read_b128 v[166:169], v142 offset:50176
	ds_read_b128 v[170:173], v142 offset:51200
	ds_read_b128 v[174:177], v142 offset:52224
	ds_read_b128 v[182:185], v142 offset:53248
	ds_read_b128 v[186:189], v142 offset:54272
	ds_read_b128 v[190:193], v142 offset:55296
	ds_read_b128 v[194:197], v142 offset:56320
	global_load_lds_dwordx4 v[178:179], off
	v_lshl_add_u64 v[178:179], v[222:223], 0, s[84:85]
	s_mov_b32 m0, s93
	s_nop 0
	global_load_lds_dwordx4 v[178:179], off
	s_barrier
	s_waitcnt lgkmcnt(0)
	s_setprio 1
	s_waitcnt lgkmcnt(0)
	v_mfma_f32_16x16x32_bf16 v[62:65], v[146:149], v[162:165], v[62:65]
	v_mfma_f32_16x16x32_bf16 v[58:61], v[154:157], v[162:165], v[58:61]
	v_mfma_f32_16x16x32_bf16 v[50:53], v[146:149], v[170:173], v[50:53]
	v_mfma_f32_16x16x32_bf16 v[42:45], v[154:157], v[170:173], v[42:45]
	v_mfma_f32_16x16x32_bf16 v[34:37], v[146:149], v[182:185], v[34:37]
	v_mfma_f32_16x16x32_bf16 v[26:29], v[154:157], v[182:185], v[26:29]
	v_mfma_f32_16x16x32_bf16 v[18:21], v[146:149], v[190:193], v[18:21]
	v_mfma_f32_16x16x32_bf16 v[10:13], v[154:157], v[190:193], v[10:13]
	v_mfma_f32_16x16x32_bf16 v[62:65], v[150:153], v[166:169], v[62:65]
	v_mfma_f32_16x16x32_bf16 v[58:61], v[158:161], v[166:169], v[58:61]
	v_mfma_f32_16x16x32_bf16 v[50:53], v[150:153], v[174:177], v[50:53]
	v_mfma_f32_16x16x32_bf16 v[42:45], v[158:161], v[174:177], v[42:45]
	v_mfma_f32_16x16x32_bf16 v[34:37], v[150:153], v[186:189], v[34:37]
	v_mfma_f32_16x16x32_bf16 v[26:29], v[158:161], v[186:189], v[26:29]
	v_mfma_f32_16x16x32_bf16 v[18:21], v[150:153], v[194:197], v[18:21]
	v_mfma_f32_16x16x32_bf16 v[10:13], v[158:161], v[194:197], v[10:13]
	s_setprio 0
	s_barrier
	s_add_u32 s26, s26, 0x40080
	s_addc_u32 s27, s27, 0
	s_mov_b32 m0, s96
	v_lshl_add_u64 v[146:147], s[26:27], 0, v[0:1]
	global_load_lds_dwordx4 v[146:147], off
	v_lshl_add_u64 v[146:147], s[26:27], 0, v[134:135]
	s_mov_b32 m0, s97
	s_nop 0
	global_load_lds_dwordx4 v[146:147], off
	s_waitcnt vmcnt(6)
	s_barrier
	s_setprio 1
	v_mfma_f32_16x16x32_bf16 v[54:57], v[198:201], v[162:165], v[54:57]
	v_mfma_f32_16x16x32_bf16 v[46:49], v[206:209], v[162:165], v[46:49]
	v_mfma_f32_16x16x32_bf16 v[38:41], v[198:201], v[170:173], v[38:41]
	v_mfma_f32_16x16x32_bf16 v[30:33], v[206:209], v[170:173], v[30:33]
	v_mfma_f32_16x16x32_bf16 v[22:25], v[198:201], v[182:185], v[22:25]
	v_mfma_f32_16x16x32_bf16 v[14:17], v[206:209], v[182:185], v[14:17]
	v_mfma_f32_16x16x32_bf16 v[6:9], v[198:201], v[190:193], v[6:9]
	v_mfma_f32_16x16x32_bf16 v[2:5], v[206:209], v[190:193], v[2:5]
	v_mfma_f32_16x16x32_bf16 v[54:57], v[202:205], v[166:169], v[54:57]
	v_mfma_f32_16x16x32_bf16 v[46:49], v[210:213], v[166:169], v[46:49]
	v_mfma_f32_16x16x32_bf16 v[38:41], v[202:205], v[174:177], v[38:41]
	v_mfma_f32_16x16x32_bf16 v[30:33], v[210:213], v[174:177], v[30:33]
	v_mfma_f32_16x16x32_bf16 v[22:25], v[202:205], v[186:189], v[22:25]
	v_mfma_f32_16x16x32_bf16 v[14:17], v[210:213], v[186:189], v[14:17]
	v_mfma_f32_16x16x32_bf16 v[6:9], v[202:205], v[194:197], v[6:9]
	v_mfma_f32_16x16x32_bf16 v[2:5], v[210:213], v[194:197], v[2:5]
	s_setprio 0
	s_add_i32 vcc_lo, vcc_lo, 2
	s_add_u32 s24, s24, 0x100
	s_addc_u32 s25, s25, 0
	s_add_u32 s89, s89, 0x100
	s_addc_u32 s94, s94, 0
	s_cmp_gt_u32 vcc_lo, 13
	s_barrier
	s_cbranch_scc0 .LBB0_781
	s_cmp_lt_i32 s22, s69
	s_cselect_b64 s[24:25], -1, 0
	s_and_b64 s[24:25], s[24:25], exec
	s_cselect_b32 s7, 0, s69
	v_lshl_add_u32 v146, s6, 8, v144
	s_cselect_b32 s25, s9, s11
	s_cselect_b32 s24, s8, s10
	s_sub_i32 s7, s22, s7
	v_add_u32_e32 v140, -8, v146
	v_lshl_add_u32 v145, s7, 8, v141
	v_cmp_gt_u32_e32 vcc, s71, v140
	s_and_saveexec_b64 s[6:7], vcc
	s_cbranch_execz .LBB0_784
	v_cvt_pk_bf16_f32 v126, v126, v127
	v_cvt_pk_bf16_f32 v127, v128, v129
	v_cvt_pk_bf16_f32 v128, v122, v123
	v_cvt_pk_bf16_f32 v129, v124, v125
	v_mad_u64_u32 v[122:123], s[22:23], v145, s71, v[140:141]
	v_mov_b32_e32 v123, v1
	v_lshl_add_u64 v[122:123], v[122:123], 1, s[24:25]
	global_store_dwordx4 v[122:123], v[126:129], off
.LBB0_784:
	s_or_b64 exec, exec, s[6:7]
	v_add_u32_e32 v122, 0x78, v146
	v_cmp_gt_u32_e64 s[6:7], s71, v122
	s_and_saveexec_b64 s[22:23], s[6:7]
	s_mul_hi_i32 s94, s64, 0x2d80
	s_cbranch_execz .LBB0_799
	v_cvt_pk_bf16_f32 v118, v118, v119
	v_cvt_pk_bf16_f32 v119, v120, v121
	v_cvt_pk_bf16_f32 v120, v110, v111
	v_cvt_pk_bf16_f32 v121, v112, v113
	v_mad_u64_u32 v[110:111], s[26:27], v145, s71, v[122:123]
	v_mov_b32_e32 v111, v1
	v_lshl_add_u64 v[110:111], v[110:111], 1, s[24:25]
	global_store_dwordx4 v[110:111], v[118:121], off
	s_or_b64 exec, exec, s[22:23]
	v_or_b32_e32 v110, 16, v145
	s_and_saveexec_b64 s[22:23], vcc
	s_cbranch_execnz .LBB0_800

.LBB0_787:
	v_cvt_pk_bf16_f32 v102, v102, v103
	v_cvt_pk_bf16_f32 v103, v104, v105
	v_cvt_pk_bf16_f32 v104, v94, v95
	v_cvt_pk_bf16_f32 v105, v96, v97
	v_mad_u64_u32 v[94:95], s[26:27], v110, s71, v[122:123]
	v_mov_b32_e32 v95, v1
	v_lshl_add_u64 v[94:95], v[94:95], 1, s[24:25]
	global_store_dwordx4 v[94:95], v[102:105], off
	s_or_b64 exec, exec, s[22:23]
	v_or_b32_e32 v94, 32, v145
	s_and_saveexec_b64 s[22:23], vcc
	s_cbranch_execnz .LBB0_802

.LBB0_789:
	v_cvt_pk_bf16_f32 v86, v86, v87
	v_cvt_pk_bf16_f32 v87, v88, v89
	v_cvt_pk_bf16_f32 v88, v78, v79
	v_cvt_pk_bf16_f32 v89, v80, v81
	v_mad_u64_u32 v[78:79], s[26:27], v94, s71, v[122:123]
	v_mov_b32_e32 v79, v1
	v_lshl_add_u64 v[78:79], v[78:79], 1, s[24:25]
	global_store_dwordx4 v[78:79], v[86:89], off
	s_or_b64 exec, exec, s[22:23]
	v_or_b32_e32 v78, 48, v145
	s_and_saveexec_b64 s[22:23], vcc
	s_cbranch_execnz .LBB0_804

.LBB0_791:
	v_cvt_pk_bf16_f32 v70, v70, v71
	v_cvt_pk_bf16_f32 v71, v72, v73
	v_cvt_pk_bf16_f32 v72, v66, v67
	v_cvt_pk_bf16_f32 v73, v68, v69
	v_mad_u64_u32 v[66:67], s[26:27], v78, s71, v[122:123]
	v_mov_b32_e32 v67, v1
	v_lshl_add_u64 v[66:67], v[66:67], 1, s[24:25]
	global_store_dwordx4 v[66:67], v[70:73], off
	s_or_b64 exec, exec, s[22:23]
	v_add_u32_e32 v66, 0x80, v145
	s_and_saveexec_b64 s[22:23], vcc
	s_cbranch_execnz .LBB0_806

.LBB0_793:
	v_cvt_pk_bf16_f32 v54, v54, v55
	v_cvt_pk_bf16_f32 v55, v56, v57
	v_cvt_pk_bf16_f32 v56, v46, v47
	v_cvt_pk_bf16_f32 v57, v48, v49
	v_mad_u64_u32 v[46:47], s[26:27], v66, s71, v[122:123]
	v_mov_b32_e32 v47, v1
	v_lshl_add_u64 v[46:47], v[46:47], 1, s[24:25]
	global_store_dwordx4 v[46:47], v[54:57], off
	s_or_b64 exec, exec, s[22:23]
	v_add_u32_e32 v46, 0x90, v145
	s_and_saveexec_b64 s[22:23], vcc
	s_cbranch_execnz .LBB0_808

.LBB0_795:
	v_cvt_pk_bf16_f32 v38, v38, v39
	v_cvt_pk_bf16_f32 v39, v40, v41
	v_cvt_pk_bf16_f32 v40, v30, v31
	v_cvt_pk_bf16_f32 v41, v32, v33
	v_mad_u64_u32 v[30:31], s[26:27], v46, s71, v[122:123]
	v_mov_b32_e32 v31, v1
	v_lshl_add_u64 v[30:31], v[30:31], 1, s[24:25]
	global_store_dwordx4 v[30:31], v[38:41], off
	s_or_b64 exec, exec, s[22:23]
	v_add_u32_e32 v30, 0xa0, v145
	s_and_saveexec_b64 s[22:23], vcc
	s_cbranch_execnz .LBB0_810

.LBB0_797:
	v_cvt_pk_bf16_f32 v22, v22, v23
	v_cvt_pk_bf16_f32 v23, v24, v25
	v_cvt_pk_bf16_f32 v24, v14, v15
	v_cvt_pk_bf16_f32 v25, v16, v17
	v_mad_u64_u32 v[14:15], s[26:27], v30, s71, v[122:123]
	v_mov_b32_e32 v15, v1
	v_lshl_add_u64 v[14:15], v[14:15], 1, s[24:25]
	global_store_dwordx4 v[14:15], v[22:25], off
	s_or_b64 exec, exec, s[22:23]
	v_add_u32_e32 v14, 0xb0, v145
	s_and_saveexec_b64 s[22:23], vcc
	s_cbranch_execnz .LBB0_812

.LBB0_800:
	v_cvt_pk_bf16_f32 v111, v114, s0
	v_cvt_pk_bf16_f32 v114, v106, v107
	v_cvt_pk_bf16_f32 v112, v115, s0
	v_lshlrev_b32_e32 v112, 16, v112
	v_cvt_pk_bf16_f32 v115, v108, v109
	v_mad_u64_u32 v[106:107], s[26:27], v110, s71, v[140:141]
	v_or_b32_sdwa v112, v112, v111 dst_sel:DWORD dst_unused:UNUSED_PAD src0_sel:DWORD src1_sel:WORD_0
	v_mov_b32_e32 v107, v1
	v_cvt_pk_bf16_f32 v113, v116, v117
	v_lshl_add_u64 v[106:107], v[106:107], 1, s[24:25]
	global_store_dwordx4 v[106:107], v[112:115], off
	s_or_b64 exec, exec, s[22:23]
	s_and_saveexec_b64 s[22:23], s[6:7]
	s_cbranch_execnz .LBB0_787

.LBB0_802:
	v_cvt_pk_bf16_f32 v95, v98, s0
	v_cvt_pk_bf16_f32 v98, v90, v91
	v_cvt_pk_bf16_f32 v96, v99, s0
	v_lshlrev_b32_e32 v96, 16, v96
	v_cvt_pk_bf16_f32 v99, v92, v93
	v_mad_u64_u32 v[90:91], s[26:27], v94, s71, v[140:141]
	v_or_b32_sdwa v96, v96, v95 dst_sel:DWORD dst_unused:UNUSED_PAD src0_sel:DWORD src1_sel:WORD_0
	v_mov_b32_e32 v91, v1
	v_cvt_pk_bf16_f32 v97, v100, v101
	v_lshl_add_u64 v[90:91], v[90:91], 1, s[24:25]
	global_store_dwordx4 v[90:91], v[96:99], off
	s_or_b64 exec, exec, s[22:23]
	s_and_saveexec_b64 s[22:23], s[6:7]
	s_cbranch_execnz .LBB0_789

.LBB0_804:
	v_cvt_pk_bf16_f32 v79, v82, s0
	v_cvt_pk_bf16_f32 v82, v74, v75
	v_cvt_pk_bf16_f32 v80, v83, s0
	v_lshlrev_b32_e32 v80, 16, v80
	v_cvt_pk_bf16_f32 v83, v76, v77
	v_mad_u64_u32 v[74:75], s[26:27], v78, s71, v[140:141]
	v_or_b32_sdwa v80, v80, v79 dst_sel:DWORD dst_unused:UNUSED_PAD src0_sel:DWORD src1_sel:WORD_0
	v_mov_b32_e32 v75, v1
	v_cvt_pk_bf16_f32 v81, v84, v85
	v_lshl_add_u64 v[74:75], v[74:75], 1, s[24:25]
	global_store_dwordx4 v[74:75], v[80:83], off
	s_or_b64 exec, exec, s[22:23]
	s_and_saveexec_b64 s[22:23], s[6:7]
	s_cbranch_execnz .LBB0_791

.LBB0_806:
	v_cvt_pk_bf16_f32 v62, v62, v63
	v_cvt_pk_bf16_f32 v63, v64, v65
	v_cvt_pk_bf16_f32 v64, v58, v59
	v_cvt_pk_bf16_f32 v65, v60, v61
	v_mad_u64_u32 v[58:59], s[26:27], v66, s71, v[140:141]
	v_mov_b32_e32 v59, v1
	v_lshl_add_u64 v[58:59], v[58:59], 1, s[24:25]
	global_store_dwordx4 v[58:59], v[62:65], off
	s_or_b64 exec, exec, s[22:23]
	s_and_saveexec_b64 s[22:23], s[6:7]
	s_cbranch_execnz .LBB0_793

.LBB0_808:
	v_cvt_pk_bf16_f32 v47, v50, s0
	v_cvt_pk_bf16_f32 v50, v42, v43
	v_cvt_pk_bf16_f32 v48, v51, s0
	v_lshlrev_b32_e32 v48, 16, v48
	v_cvt_pk_bf16_f32 v51, v44, v45
	v_mad_u64_u32 v[42:43], s[26:27], v46, s71, v[140:141]
	v_or_b32_sdwa v48, v48, v47 dst_sel:DWORD dst_unused:UNUSED_PAD src0_sel:DWORD src1_sel:WORD_0
	v_mov_b32_e32 v43, v1
	v_cvt_pk_bf16_f32 v49, v52, v53
	v_lshl_add_u64 v[42:43], v[42:43], 1, s[24:25]
	global_store_dwordx4 v[42:43], v[48:51], off
	s_or_b64 exec, exec, s[22:23]
	s_and_saveexec_b64 s[22:23], s[6:7]
	s_cbranch_execnz .LBB0_795

.LBB0_810:
	v_cvt_pk_bf16_f32 v31, v34, s0
	v_cvt_pk_bf16_f32 v34, v26, v27
	v_cvt_pk_bf16_f32 v32, v35, s0
	v_lshlrev_b32_e32 v32, 16, v32
	v_cvt_pk_bf16_f32 v35, v28, v29
	v_mad_u64_u32 v[26:27], s[26:27], v30, s71, v[140:141]
	v_or_b32_sdwa v32, v32, v31 dst_sel:DWORD dst_unused:UNUSED_PAD src0_sel:DWORD src1_sel:WORD_0
	v_mov_b32_e32 v27, v1
	v_cvt_pk_bf16_f32 v33, v36, v37
	v_lshl_add_u64 v[26:27], v[26:27], 1, s[24:25]
	global_store_dwordx4 v[26:27], v[32:35], off
	s_or_b64 exec, exec, s[22:23]
	s_and_saveexec_b64 s[22:23], s[6:7]
	s_cbranch_execnz .LBB0_797

.LBB0_812:
	v_cvt_pk_bf16_f32 v15, v18, s0
	v_cvt_pk_bf16_f32 v18, v10, v11
	v_cvt_pk_bf16_f32 v16, v19, s0
	v_lshlrev_b32_e32 v16, 16, v16
	v_cvt_pk_bf16_f32 v19, v12, v13
	v_mad_u64_u32 v[10:11], s[26:27], v14, s71, v[140:141]
	v_or_b32_sdwa v16, v16, v15 dst_sel:DWORD dst_unused:UNUSED_PAD src0_sel:DWORD src1_sel:WORD_0
	v_mov_b32_e32 v11, v1
	v_cvt_pk_bf16_f32 v17, v20, v21
	v_lshl_add_u64 v[10:11], v[10:11], 1, s[24:25]
	global_store_dwordx4 v[10:11], v[16:19], off
	s_or_b64 exec, exec, s[22:23]
	s_and_saveexec_b64 s[22:23], s[6:7]
	s_cbranch_execz .LBB0_777
.LBB0_813:
	v_cvt_pk_bf16_f32 v6, v6, v7
	v_cvt_pk_bf16_f32 v7, v8, v9
	v_cvt_pk_bf16_f32 v8, v2, v3
	v_cvt_pk_bf16_f32 v9, v4, v5
	v_mad_u64_u32 v[2:3], s[6:7], v14, s71, v[122:123]
	v_mov_b32_e32 v3, v1
	v_lshl_add_u64 v[2:3], v[2:3], 1, s[24:25]
	global_store_dwordx4 v[2:3], v[6:9], off
	s_branch .LBB0_777

.LBB0_863:
	s_ashr_i32 s6, s4, 31
	v_lshl_add_u64 v[30:31], s[14:15], 0, v[14:15]
	s_abs_i32 s8, s4
	s_xor_b32 s9, s6, s21
	v_add_co_u32_e64 v30, s[6:7], s89, v30
	s_mul_hi_u32 s10, s8, s23
	s_nop 0
	v_addc_co_u32_e64 v31, s[6:7], 0, v31, s[6:7]
	s_mul_i32 s6, s10, s22
	s_sub_i32 s6, s8, s6
	s_add_i32 s7, s10, 1
	s_sub_i32 s8, s6, s22
	s_cmp_ge_u32 s6, s22
	s_cselect_b32 s7, s7, s10
	s_cselect_b32 s6, s8, s6
	s_add_i32 s8, s7, 1
	v_lshl_add_u64 v[34:35], s[14:15], 0, v[18:19]
	s_cmp_ge_u32 s6, s22
	v_lshl_add_u64 v[32:33], s[14:15], 0, v[16:17]
	global_load_ushort v29, v[34:35], off
	s_nop 0
	global_load_dwordx2 v[34:35], v[32:33], off
	s_cselect_b32 s6, s8, s7
	global_load_dwordx3 v[30:32], v[30:31], off
	s_xor_b32 s6, s6, s9
	s_sub_i32 s6, s6, s9
	s_mul_i32 s7, s6, s20
	s_mul_hi_i32 s8, s5, s6
	s_mul_i32 s9, s5, s6
	s_mul_i32 s6, s24, s6
	v_add_u32_e32 v36, s6, v28
	v_ashrrev_i32_e32 v37, 31, v36
	v_lshlrev_b64 v[36:37], 2, v[36:37]
	v_lshl_add_u64 v[38:39], s[56:57], 0, v[36:37]
	v_lshl_add_u64 v[36:37], s[58:59], 0, v[36:37]
	global_load_dword v53, v[38:39], off
	global_load_dword v55, v[36:37], off
	s_ashr_i32 s6, s7, 31
	s_sub_u32 s7, s9, s7
	s_subb_u32 s8, s8, s6
	s_add_u32 s6, s25, s7
	s_addc_u32 s7, s26, s8
	s_lshl_b64 s[8:9], s[6:7], 9
	s_lshl_b64 s[6:7], s[6:7], 7
	v_lshl_add_u64 v[40:41], v[8:9], 0, s[6:7]
	v_lshl_add_u64 v[38:39], v[6:7], 0, s[8:9]
	s_add_i32 s4, s4, s64
	s_add_u32 s25, s25, s64
	s_addc_u32 s26, s26, s65
	v_lshl_add_u64 v[20:21], s[12:13], 0, v[14:15]
	s_add_u32 s12, s12, s60
	s_addc_u32 s13, s13, s62
	s_add_u32 s14, s14, s75
	s_addc_u32 s15, s15, s94
	v_add_u32_e32 v28, s95, v28
	s_cmp_lt_i32 s4, s3
	s_waitcnt vmcnt(0)
	v_lshlrev_b32_e32 v29, 16, v29
	v_mul_f32_e32 v56, v29, v29
	v_lshlrev_b32_e32 v36, 16, v34
	v_lshlrev_b32_e32 v49, 16, v31
	v_and_b32_e32 v51, 0xffff0000, v31
	ds_bpermute_b32 v31, v22, v56
	v_and_b32_e32 v37, 0xffff0000, v34
	v_lshlrev_b32_e32 v34, 16, v35
	v_and_b32_e32 v35, 0xffff0000, v35
	v_pk_mul_f32 v[42:43], v[36:37], v[36:37]
	v_lshlrev_b32_e32 v48, 16, v30
	v_and_b32_e32 v50, 0xffff0000, v30
	v_pk_mul_f32 v[44:45], v[34:35], v[34:35]
	v_lshlrev_b32_e32 v47, 16, v32
	v_and_b32_e32 v46, 0xffff0000, v32
	v_add_f32_e32 v57, v42, v43
	v_mov_b32_e32 v32, v48
	v_mov_b32_e32 v33, v50
	v_mul_f32_e32 v30, v50, v50
	v_mul_f32_e32 v52, v49, v49
	v_add_f32_e32 v44, v44, v57
	s_waitcnt lgkmcnt(0)
	v_pk_fma_f32 v[32:33], v[32:33], v[32:33], v[30:31] op_sel_hi:[1,1,0]
	v_mov_b32_e32 v42, v51
	v_mov_b32_e32 v43, v49
	v_add_f32_e32 v44, v45, v44
	v_pk_add_f32 v[32:33], v[32:33], v[52:53] op_sel_hi:[1,0]
	v_mul_f32_e32 v54, v47, v47
	ds_bpermute_b32 v45, v22, v44
	v_pk_fma_f32 v[32:33], v[42:43], v[42:43], v[32:33]
	s_waitcnt lgkmcnt(0)
	v_add_f32_e32 v42, v44, v45
	v_pk_add_f32 v[32:33], v[54:55], v[32:33] op_sel_hi:[0,1]
	v_pk_fma_f32 v[32:33], v[46:47], v[46:47], v[32:33]
	ds_bpermute_b32 v30, v22, v32
	ds_bpermute_b32 v43, v23, v42
	v_mov_b32_e32 v33, v56
	s_waitcnt lgkmcnt(1)
	v_pk_add_f32 v[30:31], v[32:33], v[30:31]
	ds_bpermute_b32 v33, v23, v31
	ds_bpermute_b32 v32, v23, v30
	s_waitcnt lgkmcnt(2)
	v_add_f32_e32 v42, v42, v43
	ds_bpermute_b32 v43, v24, v42
	s_waitcnt lgkmcnt(1)
	v_pk_add_f32 v[30:31], v[30:31], v[32:33]
	ds_bpermute_b32 v33, v24, v31
	ds_bpermute_b32 v32, v24, v30
	s_waitcnt lgkmcnt(2)
	v_add_f32_e32 v42, v42, v43
	ds_bpermute_b32 v43, v25, v42
	s_waitcnt lgkmcnt(1)
	v_pk_add_f32 v[30:31], v[30:31], v[32:33]
	ds_bpermute_b32 v33, v25, v31
	ds_bpermute_b32 v32, v25, v30
	s_waitcnt lgkmcnt(2)
	v_add_f32_e32 v42, v42, v43
	ds_bpermute_b32 v43, v26, v42
	s_waitcnt lgkmcnt(1)
	v_pk_add_f32 v[30:31], v[30:31], v[32:33]
	ds_bpermute_b32 v33, v26, v31
	ds_bpermute_b32 v32, v26, v30
	s_waitcnt lgkmcnt(2)
	v_add_f32_e32 v42, v42, v43
	ds_bpermute_b32 v43, v27, v42
	s_waitcnt lgkmcnt(1)
	v_pk_add_f32 v[30:31], v[30:31], v[32:33]
	ds_bpermute_b32 v33, v27, v31
	ds_bpermute_b32 v32, v27, v30
	s_waitcnt lgkmcnt(2)
	v_add_f32_e32 v42, v42, v43
	v_fmamk_f32 v42, v42, 0x3b800000, v180
	v_mul_f32_e32 v43, 0x4b800000, v42
	v_cmp_gt_f32_e64 s[6:7], s91, v42
	s_waitcnt lgkmcnt(0)
	v_pk_add_f32 v[30:31], v[30:31], v[32:33]
	v_cndmask_b32_e64 v42, v42, v43, s[6:7]
	v_rsq_f32_e32 v32, v42
	v_pk_fma_f32 v[30:31], v[30:31], s[92:93], v[180:181] op_sel_hi:[1,1,0]
	s_nop 0
	v_mul_f32_e32 v33, 0x4b800000, v31
	v_cmp_gt_f32_e64 s[10:11], s91, v31
	v_mul_f32_e32 v42, 0x4b800000, v30
	v_cmp_gt_f32_e64 s[8:9], s91, v30
	v_cndmask_b32_e64 v31, v31, v33, s[10:11]
	s_nop 0
	v_cndmask_b32_e64 v30, v30, v42, s[8:9]
	v_rsq_f32_e32 v42, v31
	v_rsq_f32_e32 v43, v30
	v_mul_f32_e32 v30, 0x45800000, v32
	v_cndmask_b32_e64 v30, v32, v30, s[6:7]
	v_pk_mul_f32 v[32:33], v[30:31], v[36:37] op_sel_hi:[0,1]
	v_pk_mul_f32 v[34:35], v[30:31], v[34:35] op_sel_hi:[0,1]
	v_pk_mul_f32 v[30:31], v[2:3], v[32:33]
	v_pk_mul_f32 v[32:33], v[4:5], v[34:35]
	v_mul_f32_e32 v35, 0x45800000, v42
	v_mul_f32_e32 v34, 0x45800000, v43
	v_cndmask_b32_e64 v35, v42, v35, s[10:11]
	v_cvt_pk_bf16_f32 v36, v31, s0
	v_cndmask_b32_e64 v34, v43, v34, s[8:9]
	v_mul_f32_e32 v29, v35, v29
	v_lshlrev_b32_e32 v52, 16, v36
	v_pk_mul_f32 v[36:37], v[34:35], v[48:49] op_sel_hi:[0,1]
	v_mul_f32_e32 v47, v34, v47
	v_mul_f32_e32 v29, v0, v29
	v_cvt_pk_bf16_f32 v36, v36, v37
	v_cvt_pk_bf16_f32 v37, v47, s0
	ds_bpermute_b32 v47, v22, v29
	v_pk_mul_f32 v[42:43], v[34:35], v[50:51] op_sel_hi:[0,1]
	v_mul_f32_e32 v34, v34, v46
	v_cvt_pk_bf16_f32 v35, v42, v43
	v_cvt_pk_bf16_f32 v34, v34, s0
	v_and_b32_e32 v42, 0xffff0000, v35
	v_lshlrev_b32_e32 v43, 16, v35
	v_lshlrev_b32_e32 v46, 16, v34
	v_cvt_pk_bf16_f32 v44, v30, s0
	v_or_b32_sdwa v35, v42, v36 dst_sel:DWORD dst_unused:UNUSED_PAD src0_sel:DWORD src1_sel:WORD_1
	v_or_b32_sdwa v34, v43, v36 dst_sel:DWORD dst_unused:UNUSED_PAD src0_sel:DWORD src1_sel:WORD_0
	v_or_b32_sdwa v36, v46, v37 dst_sel:DWORD dst_unused:UNUSED_PAD src0_sel:DWORD src1_sel:WORD_0
	v_or_b32_sdwa v44, v52, v44 dst_sel:DWORD dst_unused:UNUSED_PAD src0_sel:DWORD src1_sel:WORD_0
	v_cvt_pk_bf16_f32 v45, v32, v33
	global_store_dwordx3 v[20:21], v[34:36], off
	global_store_dwordx4 v[12:13], v[30:33], off
	global_store_dwordx2 v[38:39], v[44:45], off
	s_waitcnt lgkmcnt(0)
	v_mul_f32_e32 v20, v55, v47
	v_cndmask_b32_e64 v20, v20, -v20, vcc
	v_fmac_f32_e32 v20, v53, v29
	v_lshl_add_u64 v[12:13], v[12:13], 0, s[78:79]
	global_store_dword v[10:11], v20, off
	v_cvt_pk_bf16_f32 v20, v20, s0
	v_lshl_add_u64 v[10:11], v[10:11], 0, s[76:77]
	global_store_short v[40:41], v20, off
	s_cbranch_scc1 .LBB0_863

.LBB0_867:
	s_ashr_i32 s6, s3, 31
	v_lshl_add_u64 v[30:31], s[14:15], 0, v[14:15]
	s_abs_i32 s8, s3
	s_xor_b32 s9, s6, s5
	v_add_co_u32_e64 v30, s[6:7], s89, v30
	s_mul_hi_u32 s10, s8, s22
	s_nop 0
	v_addc_co_u32_e64 v31, s[6:7], 0, v31, s[6:7]
	s_mul_i32 s6, s10, s21
	s_sub_i32 s6, s8, s6
	s_add_i32 s7, s10, 1
	s_sub_i32 s8, s6, s21
	s_cmp_ge_u32 s6, s21
	s_cselect_b32 s7, s7, s10
	s_cselect_b32 s6, s8, s6
	s_add_i32 s8, s7, 1
	v_lshl_add_u64 v[34:35], s[14:15], 0, v[18:19]
	s_cmp_ge_u32 s6, s21
	v_lshl_add_u64 v[32:33], s[14:15], 0, v[16:17]
	global_load_ushort v29, v[34:35], off
	s_nop 0
	global_load_dwordx2 v[34:35], v[32:33], off
	s_cselect_b32 s6, s8, s7
	global_load_dwordx3 v[30:32], v[30:31], off
	s_xor_b32 s6, s6, s9
	s_sub_i32 s6, s6, s9
	s_mul_i32 s7, s6, s20
	s_mul_hi_i32 s8, s4, s6
	s_mul_i32 s9, s4, s6
	s_mul_i32 s6, s23, s6
	v_add_u32_e32 v36, s6, v28
	v_ashrrev_i32_e32 v37, 31, v36
	v_lshlrev_b64 v[36:37], 2, v[36:37]
	v_lshl_add_u64 v[38:39], s[56:57], 0, v[36:37]
	v_lshl_add_u64 v[36:37], s[58:59], 0, v[36:37]
	global_load_dword v53, v[38:39], off
	global_load_dword v55, v[36:37], off
	s_ashr_i32 s6, s7, 31
	s_sub_u32 s7, s9, s7
	s_subb_u32 s8, s8, s6
	s_add_u32 s6, s24, s7
	s_addc_u32 s7, s25, s8
	s_lshl_b64 s[8:9], s[6:7], 9
	s_lshl_b64 s[6:7], s[6:7], 7
	v_lshl_add_u64 v[40:41], v[8:9], 0, s[6:7]
	v_lshl_add_u64 v[38:39], v[6:7], 0, s[8:9]
	s_add_i32 s3, s3, s64
	s_add_u32 s24, s24, s64
	s_addc_u32 s25, s25, s65
	v_lshl_add_u64 v[20:21], s[12:13], 0, v[14:15]
	s_add_u32 s12, s12, s60
	s_addc_u32 s13, s13, s62
	s_add_u32 s14, s14, s75
	s_addc_u32 s15, s15, s94
	v_add_u32_e32 v28, s95, v28
	s_cmp_lt_i32 s3, s2
	s_waitcnt vmcnt(0)
	v_lshlrev_b32_e32 v29, 16, v29
	v_mul_f32_e32 v56, v29, v29
	v_lshlrev_b32_e32 v36, 16, v34
	v_lshlrev_b32_e32 v49, 16, v31
	v_and_b32_e32 v51, 0xffff0000, v31
	ds_bpermute_b32 v31, v22, v56
	v_and_b32_e32 v37, 0xffff0000, v34
	v_lshlrev_b32_e32 v34, 16, v35
	v_and_b32_e32 v35, 0xffff0000, v35
	v_pk_mul_f32 v[42:43], v[36:37], v[36:37]
	v_lshlrev_b32_e32 v48, 16, v30
	v_and_b32_e32 v50, 0xffff0000, v30
	v_pk_mul_f32 v[44:45], v[34:35], v[34:35]
	v_lshlrev_b32_e32 v47, 16, v32
	v_and_b32_e32 v46, 0xffff0000, v32
	v_add_f32_e32 v57, v42, v43
	v_mov_b32_e32 v32, v48
	v_mov_b32_e32 v33, v50
	v_mul_f32_e32 v30, v50, v50
	v_mul_f32_e32 v52, v49, v49
	v_add_f32_e32 v44, v44, v57
	s_waitcnt lgkmcnt(0)
	v_pk_fma_f32 v[32:33], v[32:33], v[32:33], v[30:31] op_sel_hi:[1,1,0]
	v_mov_b32_e32 v42, v51
	v_mov_b32_e32 v43, v49
	v_add_f32_e32 v44, v45, v44
	v_pk_add_f32 v[32:33], v[32:33], v[52:53] op_sel_hi:[1,0]
	v_mul_f32_e32 v54, v47, v47
	ds_bpermute_b32 v45, v22, v44
	v_pk_fma_f32 v[32:33], v[42:43], v[42:43], v[32:33]
	s_waitcnt lgkmcnt(0)
	v_add_f32_e32 v42, v44, v45
	v_pk_add_f32 v[32:33], v[54:55], v[32:33] op_sel_hi:[0,1]
	v_pk_fma_f32 v[32:33], v[46:47], v[46:47], v[32:33]
	ds_bpermute_b32 v30, v22, v32
	ds_bpermute_b32 v43, v23, v42
	v_mov_b32_e32 v33, v56
	s_waitcnt lgkmcnt(1)
	v_pk_add_f32 v[30:31], v[32:33], v[30:31]
	ds_bpermute_b32 v33, v23, v31
	ds_bpermute_b32 v32, v23, v30
	s_waitcnt lgkmcnt(2)
	v_add_f32_e32 v42, v42, v43
	ds_bpermute_b32 v43, v24, v42
	s_waitcnt lgkmcnt(1)
	v_pk_add_f32 v[30:31], v[30:31], v[32:33]
	ds_bpermute_b32 v33, v24, v31
	ds_bpermute_b32 v32, v24, v30
	s_waitcnt lgkmcnt(2)
	v_add_f32_e32 v42, v42, v43
	ds_bpermute_b32 v43, v25, v42
	s_waitcnt lgkmcnt(1)
	v_pk_add_f32 v[30:31], v[30:31], v[32:33]
	ds_bpermute_b32 v33, v25, v31
	ds_bpermute_b32 v32, v25, v30
	s_waitcnt lgkmcnt(2)
	v_add_f32_e32 v42, v42, v43
	ds_bpermute_b32 v43, v26, v42
	s_waitcnt lgkmcnt(1)
	v_pk_add_f32 v[30:31], v[30:31], v[32:33]
	ds_bpermute_b32 v33, v26, v31
	ds_bpermute_b32 v32, v26, v30
	s_waitcnt lgkmcnt(2)
	v_add_f32_e32 v42, v42, v43
	ds_bpermute_b32 v43, v27, v42
	s_waitcnt lgkmcnt(1)
	v_pk_add_f32 v[30:31], v[30:31], v[32:33]
	ds_bpermute_b32 v33, v27, v31
	ds_bpermute_b32 v32, v27, v30
	s_waitcnt lgkmcnt(2)
	v_add_f32_e32 v42, v42, v43
	v_fmamk_f32 v42, v42, 0x3b800000, v180
	v_mul_f32_e32 v43, 0x4b800000, v42
	v_cmp_gt_f32_e64 s[6:7], s91, v42
	s_waitcnt lgkmcnt(0)
	v_pk_add_f32 v[30:31], v[30:31], v[32:33]
	v_cndmask_b32_e64 v42, v42, v43, s[6:7]
	v_rsq_f32_e32 v32, v42
	v_pk_fma_f32 v[30:31], v[30:31], s[92:93], v[180:181] op_sel_hi:[1,1,0]
	s_nop 0
	v_mul_f32_e32 v33, 0x4b800000, v31
	v_cmp_gt_f32_e64 s[10:11], s91, v31
	v_mul_f32_e32 v42, 0x4b800000, v30
	v_cmp_gt_f32_e64 s[8:9], s91, v30
	v_cndmask_b32_e64 v31, v31, v33, s[10:11]
	s_nop 0
	v_cndmask_b32_e64 v30, v30, v42, s[8:9]
	v_rsq_f32_e32 v42, v31
	v_rsq_f32_e32 v43, v30
	v_mul_f32_e32 v30, 0x45800000, v32
	v_cndmask_b32_e64 v30, v32, v30, s[6:7]
	v_pk_mul_f32 v[32:33], v[30:31], v[36:37] op_sel_hi:[0,1]
	v_pk_mul_f32 v[34:35], v[30:31], v[34:35] op_sel_hi:[0,1]
	v_pk_mul_f32 v[30:31], v[2:3], v[32:33]
	v_pk_mul_f32 v[32:33], v[4:5], v[34:35]
	v_mul_f32_e32 v35, 0x45800000, v42
	v_mul_f32_e32 v34, 0x45800000, v43
	v_cndmask_b32_e64 v35, v42, v35, s[10:11]
	v_cvt_pk_bf16_f32 v36, v31, s0
	v_cndmask_b32_e64 v34, v43, v34, s[8:9]
	v_mul_f32_e32 v29, v35, v29
	v_lshlrev_b32_e32 v52, 16, v36
	v_pk_mul_f32 v[36:37], v[34:35], v[48:49] op_sel_hi:[0,1]
	v_mul_f32_e32 v47, v34, v47
	v_mul_f32_e32 v29, v0, v29
	v_cvt_pk_bf16_f32 v36, v36, v37
	v_cvt_pk_bf16_f32 v37, v47, s0
	ds_bpermute_b32 v47, v22, v29
	v_pk_mul_f32 v[42:43], v[34:35], v[50:51] op_sel_hi:[0,1]
	v_mul_f32_e32 v34, v34, v46
	v_cvt_pk_bf16_f32 v35, v42, v43
	v_cvt_pk_bf16_f32 v34, v34, s0
	v_and_b32_e32 v42, 0xffff0000, v35
	v_lshlrev_b32_e32 v43, 16, v35
	v_lshlrev_b32_e32 v46, 16, v34
	v_cvt_pk_bf16_f32 v44, v30, s0
	v_or_b32_sdwa v35, v42, v36 dst_sel:DWORD dst_unused:UNUSED_PAD src0_sel:DWORD src1_sel:WORD_1
	v_or_b32_sdwa v34, v43, v36 dst_sel:DWORD dst_unused:UNUSED_PAD src0_sel:DWORD src1_sel:WORD_0
	v_or_b32_sdwa v36, v46, v37 dst_sel:DWORD dst_unused:UNUSED_PAD src0_sel:DWORD src1_sel:WORD_0
	v_or_b32_sdwa v44, v52, v44 dst_sel:DWORD dst_unused:UNUSED_PAD src0_sel:DWORD src1_sel:WORD_0
	v_cvt_pk_bf16_f32 v45, v32, v33
	global_store_dwordx3 v[20:21], v[34:36], off
	global_store_dwordx4 v[12:13], v[30:33], off
	global_store_dwordx2 v[38:39], v[44:45], off
	s_waitcnt lgkmcnt(0)
	v_mul_f32_e32 v20, v55, v47
	v_cndmask_b32_e64 v20, v20, -v20, vcc
	v_fmac_f32_e32 v20, v53, v29
	v_lshl_add_u64 v[12:13], v[12:13], 0, s[78:79]
	global_store_dword v[10:11], v20, off
	v_cvt_pk_bf16_f32 v20, v20, s0
	v_lshl_add_u64 v[10:11], v[10:11], 0, s[76:77]
	global_store_short v[40:41], v20, off
	s_cbranch_scc1 .LBB0_867

.LBB0_926:
	v_add_u32_e32 v140, 0x10000, v143
	s_waitcnt vmcnt(0)
	ds_read_b128 v[146:149], v140
	ds_read_b128 v[150:153], v140 offset:1024
	ds_read_b128 v[154:157], v140 offset:2048
	ds_read_b128 v[158:161], v140 offset:3072
	s_add_u32 s6, s20, 0x100
	s_addc_u32 s7, s21, 0
	s_cmp_eq_u32 s96, 2
	s_cselect_b32 s25, s17, s7
	s_cselect_b32 s24, s16, s6
	s_cselect_b32 s23, s19, s94
	s_cselect_b32 s22, s18, s93
	v_lshl_add_u64 v[178:179], s[20:21], 0, v[136:137]
	s_add_i32 m0, s27, 0xc000
	ds_read_b128 v[162:165], v142
	ds_read_b128 v[166:169], v142 offset:1024
	ds_read_b128 v[170:173], v142 offset:2048
	ds_read_b128 v[174:177], v142 offset:3072
	ds_read_b128 v[182:185], v142 offset:4096
	ds_read_b128 v[186:189], v142 offset:5120
	ds_read_b128 v[190:193], v142 offset:6144
	ds_read_b128 v[194:197], v142 offset:7168
	global_load_lds_dwordx4 v[178:179], off
	v_lshl_add_u64 v[178:179], s[20:21], 0, v[138:139]
	s_add_i32 m0, s27, 0xe000
	s_nop 0
	global_load_lds_dwordx4 v[178:179], off
	s_waitcnt lgkmcnt(8)
	s_barrier
	s_waitcnt lgkmcnt(0)
	s_setprio 1
	s_waitcnt lgkmcnt(0)
	v_mfma_f32_16x16x32_bf16 v[126:129], v[146:149], v[162:165], v[126:129]
	v_mfma_f32_16x16x32_bf16 v[122:125], v[154:157], v[162:165], v[122:125]
	v_mfma_f32_16x16x32_bf16 v[114:117], v[146:149], v[170:173], v[114:117]
	v_mfma_f32_16x16x32_bf16 v[106:109], v[154:157], v[170:173], v[106:109]
	v_mfma_f32_16x16x32_bf16 v[98:101], v[146:149], v[182:185], v[98:101]
	v_mfma_f32_16x16x32_bf16 v[90:93], v[154:157], v[182:185], v[90:93]
	v_mfma_f32_16x16x32_bf16 v[82:85], v[146:149], v[190:193], v[82:85]
	v_mfma_f32_16x16x32_bf16 v[74:77], v[154:157], v[190:193], v[74:77]
	v_mfma_f32_16x16x32_bf16 v[126:129], v[150:153], v[166:169], v[126:129]
	v_mfma_f32_16x16x32_bf16 v[122:125], v[158:161], v[166:169], v[122:125]
	v_mfma_f32_16x16x32_bf16 v[114:117], v[150:153], v[174:177], v[114:117]
	v_mfma_f32_16x16x32_bf16 v[106:109], v[158:161], v[174:177], v[106:109]
	v_mfma_f32_16x16x32_bf16 v[98:101], v[150:153], v[186:189], v[98:101]
	v_mfma_f32_16x16x32_bf16 v[90:93], v[158:161], v[186:189], v[90:93]
	v_mfma_f32_16x16x32_bf16 v[82:85], v[150:153], v[194:197], v[82:85]
	v_mfma_f32_16x16x32_bf16 v[74:77], v[158:161], v[194:197], v[74:77]
	s_setprio 0
	s_barrier
	s_mov_b32 m0, s28
	v_add_u32_e32 v140, 0x14000, v143
	v_lshl_add_u64 v[178:179], s[22:23], 0, v[0:1]
	s_waitcnt vmcnt(0)
	ds_read_b128 v[198:201], v140
	ds_read_b128 v[202:205], v140 offset:1024
	ds_read_b128 v[206:209], v140 offset:2048
	ds_read_b128 v[210:213], v140 offset:3072
	global_load_lds_dwordx4 v[178:179], off
	v_lshl_add_u64 v[214:215], s[22:23], 0, v[134:135]
	s_mov_b32 m0, s29
	s_nop 0
	global_load_lds_dwordx4 v[214:215], off
	s_barrier
	s_waitcnt lgkmcnt(0)
	s_setprio 1
	s_waitcnt lgkmcnt(0)
	v_mfma_f32_16x16x32_bf16 v[118:121], v[198:201], v[162:165], v[118:121]
	v_mfma_f32_16x16x32_bf16 v[110:113], v[206:209], v[162:165], v[110:113]
	v_mfma_f32_16x16x32_bf16 v[102:105], v[198:201], v[170:173], v[102:105]
	v_mfma_f32_16x16x32_bf16 v[94:97], v[206:209], v[170:173], v[94:97]
	v_mfma_f32_16x16x32_bf16 v[86:89], v[198:201], v[182:185], v[86:89]
	v_mfma_f32_16x16x32_bf16 v[78:81], v[206:209], v[182:185], v[78:81]
	v_mfma_f32_16x16x32_bf16 v[70:73], v[198:201], v[190:193], v[70:73]
	v_mfma_f32_16x16x32_bf16 v[66:69], v[206:209], v[190:193], v[66:69]
	v_mfma_f32_16x16x32_bf16 v[118:121], v[202:205], v[166:169], v[118:121]
	v_mfma_f32_16x16x32_bf16 v[110:113], v[210:213], v[166:169], v[110:113]
	v_mfma_f32_16x16x32_bf16 v[102:105], v[202:205], v[174:177], v[102:105]
	v_mfma_f32_16x16x32_bf16 v[94:97], v[210:213], v[174:177], v[94:97]
	v_mfma_f32_16x16x32_bf16 v[86:89], v[202:205], v[186:189], v[86:89]
	v_mfma_f32_16x16x32_bf16 v[78:81], v[210:213], v[186:189], v[78:81]
	v_mfma_f32_16x16x32_bf16 v[70:73], v[202:205], v[194:197], v[70:73]
	v_mfma_f32_16x16x32_bf16 v[66:69], v[210:213], v[194:197], v[66:69]
	s_setprio 0
	s_mov_b32 m0, s27
	v_lshl_add_u64 v[216:217], s[24:25], 0, v[130:131]
	s_barrier
	s_waitcnt vmcnt(0)
	ds_read_b128 v[162:165], v142 offset:16384
	ds_read_b128 v[166:169], v142 offset:17408
	ds_read_b128 v[170:173], v142 offset:18432
	ds_read_b128 v[174:177], v142 offset:19456
	ds_read_b128 v[182:185], v142 offset:20480
	ds_read_b128 v[186:189], v142 offset:21504
	ds_read_b128 v[190:193], v142 offset:22528
	ds_read_b128 v[194:197], v142 offset:23552
	global_load_lds_dwordx4 v[216:217], off
	v_lshl_add_u64 v[222:223], s[24:25], 0, v[132:133]
	s_mov_b32 m0, s30
	s_nop 0
	global_load_lds_dwordx4 v[222:223], off
	s_barrier
	s_waitcnt lgkmcnt(0)
	s_setprio 1
	s_waitcnt lgkmcnt(0)
	v_mfma_f32_16x16x32_bf16 v[62:65], v[146:149], v[162:165], v[62:65]
	v_mfma_f32_16x16x32_bf16 v[58:61], v[154:157], v[162:165], v[58:61]
	v_mfma_f32_16x16x32_bf16 v[50:53], v[146:149], v[170:173], v[50:53]
	v_mfma_f32_16x16x32_bf16 v[42:45], v[154:157], v[170:173], v[42:45]
	v_mfma_f32_16x16x32_bf16 v[34:37], v[146:149], v[182:185], v[34:37]
	v_mfma_f32_16x16x32_bf16 v[26:29], v[154:157], v[182:185], v[26:29]
	v_mfma_f32_16x16x32_bf16 v[18:21], v[146:149], v[190:193], v[18:21]
	v_mfma_f32_16x16x32_bf16 v[10:13], v[154:157], v[190:193], v[10:13]
	v_mfma_f32_16x16x32_bf16 v[62:65], v[150:153], v[166:169], v[62:65]
	v_mfma_f32_16x16x32_bf16 v[58:61], v[158:161], v[166:169], v[58:61]
	v_mfma_f32_16x16x32_bf16 v[50:53], v[150:153], v[174:177], v[50:53]
	v_mfma_f32_16x16x32_bf16 v[42:45], v[158:161], v[174:177], v[42:45]
	v_mfma_f32_16x16x32_bf16 v[34:37], v[150:153], v[186:189], v[34:37]
	v_mfma_f32_16x16x32_bf16 v[26:29], v[158:161], v[186:189], v[26:29]
	v_mfma_f32_16x16x32_bf16 v[18:21], v[150:153], v[194:197], v[18:21]
	v_mfma_f32_16x16x32_bf16 v[10:13], v[158:161], v[194:197], v[10:13]
	s_setprio 0
	s_barrier
	s_add_u32 s20, s22, 0x18000
	s_addc_u32 s21, s23, 0
	s_mov_b32 m0, s31
	v_lshl_add_u64 v[146:147], s[20:21], 0, v[0:1]
	global_load_lds_dwordx4 v[146:147], off
	v_lshl_add_u64 v[146:147], s[20:21], 0, v[134:135]
	s_mov_b32 m0, s34
	s_nop 0
	global_load_lds_dwordx4 v[146:147], off
	s_waitcnt vmcnt(6)
	s_barrier
	s_setprio 1
	v_mfma_f32_16x16x32_bf16 v[54:57], v[198:201], v[162:165], v[54:57]
	v_mfma_f32_16x16x32_bf16 v[46:49], v[206:209], v[162:165], v[46:49]
	v_mfma_f32_16x16x32_bf16 v[38:41], v[198:201], v[170:173], v[38:41]
	v_mfma_f32_16x16x32_bf16 v[30:33], v[206:209], v[170:173], v[30:33]
	v_mfma_f32_16x16x32_bf16 v[22:25], v[198:201], v[182:185], v[22:25]
	v_mfma_f32_16x16x32_bf16 v[14:17], v[206:209], v[182:185], v[14:17]
	v_mfma_f32_16x16x32_bf16 v[6:9], v[198:201], v[190:193], v[6:9]
	v_mfma_f32_16x16x32_bf16 v[2:5], v[206:209], v[190:193], v[2:5]
	v_mfma_f32_16x16x32_bf16 v[54:57], v[202:205], v[166:169], v[54:57]
	v_mfma_f32_16x16x32_bf16 v[46:49], v[210:213], v[166:169], v[46:49]
	v_mfma_f32_16x16x32_bf16 v[38:41], v[202:205], v[174:177], v[38:41]
	v_mfma_f32_16x16x32_bf16 v[30:33], v[210:213], v[174:177], v[30:33]
	v_mfma_f32_16x16x32_bf16 v[22:25], v[202:205], v[186:189], v[22:25]
	v_mfma_f32_16x16x32_bf16 v[14:17], v[210:213], v[186:189], v[14:17]
	v_mfma_f32_16x16x32_bf16 v[6:9], v[202:205], v[194:197], v[6:9]
	v_mfma_f32_16x16x32_bf16 v[2:5], v[210:213], v[194:197], v[2:5]
	s_setprio 0
	v_add_u32_e32 v140, 0x18000, v143
	s_barrier
	s_waitcnt vmcnt(0)
	ds_read_b128 v[146:149], v140
	ds_read_b128 v[150:153], v140 offset:1024
	ds_read_b128 v[154:157], v140 offset:2048
	ds_read_b128 v[158:161], v140 offset:3072
	s_add_u32 s20, s24, 0x18000
	s_addc_u32 s21, s25, 0
	s_mov_b32 m0, s35
	v_lshl_add_u64 v[198:199], s[20:21], 0, v[130:131]
	ds_read_b128 v[162:165], v142 offset:32768
	ds_read_b128 v[166:169], v142 offset:33792
	ds_read_b128 v[170:173], v142 offset:34816
	ds_read_b128 v[174:177], v142 offset:35840
	ds_read_b128 v[182:185], v142 offset:36864
	ds_read_b128 v[186:189], v142 offset:37888
	ds_read_b128 v[190:193], v142 offset:38912
	ds_read_b128 v[194:197], v142 offset:39936
	global_load_lds_dwordx4 v[198:199], off
	v_lshl_add_u64 v[198:199], s[20:21], 0, v[132:133]
	s_mov_b32 m0, s36
	s_nop 0
	global_load_lds_dwordx4 v[198:199], off
	s_waitcnt lgkmcnt(8)
	s_barrier
	s_waitcnt lgkmcnt(0)
	s_setprio 1
	s_waitcnt lgkmcnt(0)
	v_mfma_f32_16x16x32_bf16 v[126:129], v[146:149], v[162:165], v[126:129]
	v_mfma_f32_16x16x32_bf16 v[122:125], v[154:157], v[162:165], v[122:125]
	v_mfma_f32_16x16x32_bf16 v[114:117], v[146:149], v[170:173], v[114:117]
	v_mfma_f32_16x16x32_bf16 v[106:109], v[154:157], v[170:173], v[106:109]
	v_mfma_f32_16x16x32_bf16 v[98:101], v[146:149], v[182:185], v[98:101]
	v_mfma_f32_16x16x32_bf16 v[90:93], v[154:157], v[182:185], v[90:93]
	v_mfma_f32_16x16x32_bf16 v[82:85], v[146:149], v[190:193], v[82:85]
	v_mfma_f32_16x16x32_bf16 v[74:77], v[154:157], v[190:193], v[74:77]
	v_mfma_f32_16x16x32_bf16 v[126:129], v[150:153], v[166:169], v[126:129]
	v_mfma_f32_16x16x32_bf16 v[122:125], v[158:161], v[166:169], v[122:125]
	v_mfma_f32_16x16x32_bf16 v[114:117], v[150:153], v[174:177], v[114:117]
	v_mfma_f32_16x16x32_bf16 v[106:109], v[158:161], v[174:177], v[106:109]
	v_mfma_f32_16x16x32_bf16 v[98:101], v[150:153], v[186:189], v[98:101]
	v_mfma_f32_16x16x32_bf16 v[90:93], v[158:161], v[186:189], v[90:93]
	v_mfma_f32_16x16x32_bf16 v[82:85], v[150:153], v[194:197], v[82:85]
	v_mfma_f32_16x16x32_bf16 v[74:77], v[158:161], v[194:197], v[74:77]
	s_setprio 0
	s_barrier
	s_mov_b32 m0, s37
	v_add_u32_e32 v140, 0x1c000, v143
	v_lshl_add_u64 v[178:179], v[178:179], 0, s[84:85]
	s_waitcnt vmcnt(0)
	ds_read_b128 v[198:201], v140
	ds_read_b128 v[202:205], v140 offset:1024
	ds_read_b128 v[206:209], v140 offset:2048
	ds_read_b128 v[210:213], v140 offset:3072
	global_load_lds_dwordx4 v[178:179], off
	v_lshl_add_u64 v[178:179], v[214:215], 0, s[84:85]
	s_mov_b32 m0, s38
	s_nop 0
	global_load_lds_dwordx4 v[178:179], off
	s_barrier
	s_waitcnt lgkmcnt(0)
	s_setprio 1
	s_waitcnt lgkmcnt(0)
	v_mfma_f32_16x16x32_bf16 v[118:121], v[198:201], v[162:165], v[118:121]
	v_mfma_f32_16x16x32_bf16 v[110:113], v[206:209], v[162:165], v[110:113]
	v_mfma_f32_16x16x32_bf16 v[102:105], v[198:201], v[170:173], v[102:105]
	v_mfma_f32_16x16x32_bf16 v[94:97], v[206:209], v[170:173], v[94:97]
	v_mfma_f32_16x16x32_bf16 v[86:89], v[198:201], v[182:185], v[86:89]
	v_mfma_f32_16x16x32_bf16 v[78:81], v[206:209], v[182:185], v[78:81]
	v_mfma_f32_16x16x32_bf16 v[70:73], v[198:201], v[190:193], v[70:73]
	v_mfma_f32_16x16x32_bf16 v[66:69], v[206:209], v[190:193], v[66:69]
	v_mfma_f32_16x16x32_bf16 v[118:121], v[202:205], v[166:169], v[118:121]
	v_mfma_f32_16x16x32_bf16 v[110:113], v[210:213], v[166:169], v[110:113]
	v_mfma_f32_16x16x32_bf16 v[102:105], v[202:205], v[174:177], v[102:105]
	v_mfma_f32_16x16x32_bf16 v[94:97], v[210:213], v[174:177], v[94:97]
	v_mfma_f32_16x16x32_bf16 v[86:89], v[202:205], v[186:189], v[86:89]
	v_mfma_f32_16x16x32_bf16 v[78:81], v[210:213], v[186:189], v[78:81]
	v_mfma_f32_16x16x32_bf16 v[70:73], v[202:205], v[194:197], v[70:73]
	v_mfma_f32_16x16x32_bf16 v[66:69], v[210:213], v[194:197], v[66:69]
	s_setprio 0
	s_mov_b32 m0, s39
	v_lshl_add_u64 v[178:179], v[216:217], 0, s[84:85]
	s_barrier
	s_waitcnt vmcnt(0)
	ds_read_b128 v[162:165], v142 offset:49152
	ds_read_b128 v[166:169], v142 offset:50176
	ds_read_b128 v[170:173], v142 offset:51200
	ds_read_b128 v[174:177], v142 offset:52224
	ds_read_b128 v[182:185], v142 offset:53248
	ds_read_b128 v[186:189], v142 offset:54272
	ds_read_b128 v[190:193], v142 offset:55296
	ds_read_b128 v[194:197], v142 offset:56320
	global_load_lds_dwordx4 v[178:179], off
	v_lshl_add_u64 v[178:179], v[222:223], 0, s[84:85]
	s_mov_b32 m0, s60
	s_nop 0
	global_load_lds_dwordx4 v[178:179], off
	s_barrier
	s_waitcnt lgkmcnt(0)
	s_setprio 1
	s_waitcnt lgkmcnt(0)
	v_mfma_f32_16x16x32_bf16 v[62:65], v[146:149], v[162:165], v[62:65]
	v_mfma_f32_16x16x32_bf16 v[58:61], v[154:157], v[162:165], v[58:61]
	v_mfma_f32_16x16x32_bf16 v[50:53], v[146:149], v[170:173], v[50:53]
	v_mfma_f32_16x16x32_bf16 v[42:45], v[154:157], v[170:173], v[42:45]
	v_mfma_f32_16x16x32_bf16 v[34:37], v[146:149], v[182:185], v[34:37]
	v_mfma_f32_16x16x32_bf16 v[26:29], v[154:157], v[182:185], v[26:29]
	v_mfma_f32_16x16x32_bf16 v[18:21], v[146:149], v[190:193], v[18:21]
	v_mfma_f32_16x16x32_bf16 v[10:13], v[154:157], v[190:193], v[10:13]
	v_mfma_f32_16x16x32_bf16 v[62:65], v[150:153], v[166:169], v[62:65]
	v_mfma_f32_16x16x32_bf16 v[58:61], v[158:161], v[166:169], v[58:61]
	v_mfma_f32_16x16x32_bf16 v[50:53], v[150:153], v[174:177], v[50:53]
	v_mfma_f32_16x16x32_bf16 v[42:45], v[158:161], v[174:177], v[42:45]
	v_mfma_f32_16x16x32_bf16 v[34:37], v[150:153], v[186:189], v[34:37]
	v_mfma_f32_16x16x32_bf16 v[26:29], v[158:161], v[186:189], v[26:29]
	v_mfma_f32_16x16x32_bf16 v[18:21], v[150:153], v[194:197], v[18:21]
	v_mfma_f32_16x16x32_bf16 v[10:13], v[158:161], v[194:197], v[10:13]
	s_setprio 0
	s_barrier
	s_add_u32 s20, s22, 0x18080
	s_addc_u32 s21, s23, 0
	s_mov_b32 m0, s68
	v_lshl_add_u64 v[146:147], s[20:21], 0, v[0:1]
	global_load_lds_dwordx4 v[146:147], off
	v_lshl_add_u64 v[146:147], s[20:21], 0, v[134:135]
	s_mov_b32 m0, s69
	s_nop 0
	global_load_lds_dwordx4 v[146:147], off
	s_waitcnt vmcnt(6)
	s_barrier
	s_setprio 1
	v_mfma_f32_16x16x32_bf16 v[54:57], v[198:201], v[162:165], v[54:57]
	v_mfma_f32_16x16x32_bf16 v[46:49], v[206:209], v[162:165], v[46:49]
	v_mfma_f32_16x16x32_bf16 v[38:41], v[198:201], v[170:173], v[38:41]
	v_mfma_f32_16x16x32_bf16 v[30:33], v[206:209], v[170:173], v[30:33]
	v_mfma_f32_16x16x32_bf16 v[22:25], v[198:201], v[182:185], v[22:25]
	v_mfma_f32_16x16x32_bf16 v[14:17], v[206:209], v[182:185], v[14:17]
	v_mfma_f32_16x16x32_bf16 v[6:9], v[198:201], v[190:193], v[6:9]
	v_mfma_f32_16x16x32_bf16 v[2:5], v[206:209], v[190:193], v[2:5]
	v_mfma_f32_16x16x32_bf16 v[54:57], v[202:205], v[166:169], v[54:57]
	v_mfma_f32_16x16x32_bf16 v[46:49], v[210:213], v[166:169], v[46:49]
	v_mfma_f32_16x16x32_bf16 v[38:41], v[202:205], v[174:177], v[38:41]
	v_mfma_f32_16x16x32_bf16 v[30:33], v[210:213], v[174:177], v[30:33]
	v_mfma_f32_16x16x32_bf16 v[22:25], v[202:205], v[186:189], v[22:25]
	v_mfma_f32_16x16x32_bf16 v[14:17], v[210:213], v[186:189], v[14:17]
	v_mfma_f32_16x16x32_bf16 v[6:9], v[202:205], v[194:197], v[6:9]
	v_mfma_f32_16x16x32_bf16 v[2:5], v[210:213], v[194:197], v[2:5]
	s_setprio 0
	s_add_i32 s96, s96, 2
	s_add_u32 s93, s93, 0x100
	s_addc_u32 s94, s94, 0
	s_cmp_gt_u32 s96, 3
	s_mov_b64 s[20:21], s[6:7]
	s_barrier
	s_cbranch_scc0 .LBB0_926
	v_lshl_add_u32 v140, s90, 8, v144
	v_lshl_add_u32 v145, s92, 8, v141
	v_cmp_gt_u32_e32 vcc, s63, v140
	s_and_saveexec_b64 s[6:7], vcc
	s_cbranch_execz .LBB0_929
	v_cvt_pk_bf16_f32 v126, v126, v127
	v_cvt_pk_bf16_f32 v127, v128, v129
	v_cvt_pk_bf16_f32 v128, v122, v123
	v_cvt_pk_bf16_f32 v129, v124, v125
	v_mad_u64_u32 v[122:123], s[20:21], v145, s63, v[140:141]
	v_mov_b32_e32 v123, v1
	v_lshl_add_u64 v[122:123], v[122:123], 1, s[10:11]
	global_store_dwordx4 v[122:123], v[126:129], off
.LBB0_929:
	s_or_b64 exec, exec, s[6:7]
	v_add_u32_e32 v122, 0x80, v140
	v_cmp_gt_u32_e64 s[6:7], s63, v122
	s_and_saveexec_b64 s[20:21], s[6:7]
	s_mul_hi_i32 s94, s64, 0x2d80
	s_cbranch_execz .LBB0_944
	v_cvt_pk_bf16_f32 v118, v118, v119
	v_cvt_pk_bf16_f32 v119, v120, v121
	v_cvt_pk_bf16_f32 v120, v110, v111
	v_cvt_pk_bf16_f32 v121, v112, v113
	v_mad_u64_u32 v[110:111], s[22:23], v145, s63, v[122:123]
	v_mov_b32_e32 v111, v1
	v_lshl_add_u64 v[110:111], v[110:111], 1, s[10:11]
	global_store_dwordx4 v[110:111], v[118:121], off
	s_or_b64 exec, exec, s[20:21]
	v_or_b32_e32 v110, 16, v145
	s_and_saveexec_b64 s[20:21], vcc
	s_cbranch_execnz .LBB0_945

.LBB0_932:
	v_cvt_pk_bf16_f32 v102, v102, v103
	v_cvt_pk_bf16_f32 v103, v104, v105
	v_cvt_pk_bf16_f32 v104, v94, v95
	v_cvt_pk_bf16_f32 v105, v96, v97
	v_mad_u64_u32 v[94:95], s[22:23], v110, s63, v[122:123]
	v_mov_b32_e32 v95, v1
	v_lshl_add_u64 v[94:95], v[94:95], 1, s[10:11]
	global_store_dwordx4 v[94:95], v[102:105], off
	s_or_b64 exec, exec, s[20:21]
	v_or_b32_e32 v94, 32, v145
	s_and_saveexec_b64 s[20:21], vcc
	s_cbranch_execnz .LBB0_947

.LBB0_934:
	v_cvt_pk_bf16_f32 v86, v86, v87
	v_cvt_pk_bf16_f32 v87, v88, v89
	v_cvt_pk_bf16_f32 v88, v78, v79
	v_cvt_pk_bf16_f32 v89, v80, v81
	v_mad_u64_u32 v[78:79], s[22:23], v94, s63, v[122:123]
	v_mov_b32_e32 v79, v1
	v_lshl_add_u64 v[78:79], v[78:79], 1, s[10:11]
	global_store_dwordx4 v[78:79], v[86:89], off
	s_or_b64 exec, exec, s[20:21]
	v_or_b32_e32 v78, 48, v145
	s_and_saveexec_b64 s[20:21], vcc
	s_cbranch_execnz .LBB0_949

.LBB0_936:
	v_cvt_pk_bf16_f32 v70, v70, v71
	v_cvt_pk_bf16_f32 v71, v72, v73
	v_cvt_pk_bf16_f32 v72, v66, v67
	v_cvt_pk_bf16_f32 v73, v68, v69
	v_mad_u64_u32 v[66:67], s[22:23], v78, s63, v[122:123]
	v_mov_b32_e32 v67, v1
	v_lshl_add_u64 v[66:67], v[66:67], 1, s[10:11]
	global_store_dwordx4 v[66:67], v[70:73], off
	s_or_b64 exec, exec, s[20:21]
	v_add_u32_e32 v66, 0x80, v145
	s_and_saveexec_b64 s[20:21], vcc
	s_cbranch_execnz .LBB0_951

.LBB0_938:
	v_cvt_pk_bf16_f32 v54, v54, v55
	v_cvt_pk_bf16_f32 v55, v56, v57
	v_cvt_pk_bf16_f32 v56, v46, v47
	v_cvt_pk_bf16_f32 v57, v48, v49
	v_mad_u64_u32 v[46:47], s[22:23], v66, s63, v[122:123]
	v_mov_b32_e32 v47, v1
	v_lshl_add_u64 v[46:47], v[46:47], 1, s[10:11]
	global_store_dwordx4 v[46:47], v[54:57], off
	s_or_b64 exec, exec, s[20:21]
	v_add_u32_e32 v46, 0x90, v145
	s_and_saveexec_b64 s[20:21], vcc
	s_cbranch_execnz .LBB0_953

.LBB0_940:
	v_cvt_pk_bf16_f32 v38, v38, v39
	v_cvt_pk_bf16_f32 v39, v40, v41
	v_cvt_pk_bf16_f32 v40, v30, v31
	v_cvt_pk_bf16_f32 v41, v32, v33
	v_mad_u64_u32 v[30:31], s[22:23], v46, s63, v[122:123]
	v_mov_b32_e32 v31, v1
	v_lshl_add_u64 v[30:31], v[30:31], 1, s[10:11]
	global_store_dwordx4 v[30:31], v[38:41], off
	s_or_b64 exec, exec, s[20:21]
	v_add_u32_e32 v30, 0xa0, v145
	s_and_saveexec_b64 s[20:21], vcc
	s_cbranch_execnz .LBB0_955

.LBB0_942:
	v_cvt_pk_bf16_f32 v22, v22, v23
	v_cvt_pk_bf16_f32 v23, v24, v25
	v_cvt_pk_bf16_f32 v24, v14, v15
	v_cvt_pk_bf16_f32 v25, v16, v17
	v_mad_u64_u32 v[14:15], s[22:23], v30, s63, v[122:123]
	v_mov_b32_e32 v15, v1
	v_lshl_add_u64 v[14:15], v[14:15], 1, s[10:11]
	global_store_dwordx4 v[14:15], v[22:25], off
	s_or_b64 exec, exec, s[20:21]
	v_add_u32_e32 v14, 0xb0, v145
	s_and_saveexec_b64 s[20:21], vcc
	s_cbranch_execnz .LBB0_957

.LBB0_945:
	v_cvt_pk_bf16_f32 v111, v114, s0
	v_cvt_pk_bf16_f32 v114, v106, v107
	v_cvt_pk_bf16_f32 v112, v115, s0
	v_lshlrev_b32_e32 v112, 16, v112
	v_cvt_pk_bf16_f32 v115, v108, v109
	v_mad_u64_u32 v[106:107], s[22:23], v110, s63, v[140:141]
	v_or_b32_sdwa v112, v112, v111 dst_sel:DWORD dst_unused:UNUSED_PAD src0_sel:DWORD src1_sel:WORD_0
	v_mov_b32_e32 v107, v1
	v_cvt_pk_bf16_f32 v113, v116, v117
	v_lshl_add_u64 v[106:107], v[106:107], 1, s[10:11]
	global_store_dwordx4 v[106:107], v[112:115], off
	s_or_b64 exec, exec, s[20:21]
	s_and_saveexec_b64 s[20:21], s[6:7]
	s_cbranch_execnz .LBB0_932

.LBB0_947:
	v_cvt_pk_bf16_f32 v95, v98, s0
	v_cvt_pk_bf16_f32 v98, v90, v91
	v_cvt_pk_bf16_f32 v96, v99, s0
	v_lshlrev_b32_e32 v96, 16, v96
	v_cvt_pk_bf16_f32 v99, v92, v93
	v_mad_u64_u32 v[90:91], s[22:23], v94, s63, v[140:141]
	v_or_b32_sdwa v96, v96, v95 dst_sel:DWORD dst_unused:UNUSED_PAD src0_sel:DWORD src1_sel:WORD_0
	v_mov_b32_e32 v91, v1
	v_cvt_pk_bf16_f32 v97, v100, v101
	v_lshl_add_u64 v[90:91], v[90:91], 1, s[10:11]
	global_store_dwordx4 v[90:91], v[96:99], off
	s_or_b64 exec, exec, s[20:21]
	s_and_saveexec_b64 s[20:21], s[6:7]
	s_cbranch_execnz .LBB0_934

.LBB0_949:
	v_cvt_pk_bf16_f32 v79, v82, s0
	v_cvt_pk_bf16_f32 v82, v74, v75
	v_cvt_pk_bf16_f32 v80, v83, s0
	v_lshlrev_b32_e32 v80, 16, v80
	v_cvt_pk_bf16_f32 v83, v76, v77
	v_mad_u64_u32 v[74:75], s[22:23], v78, s63, v[140:141]
	v_or_b32_sdwa v80, v80, v79 dst_sel:DWORD dst_unused:UNUSED_PAD src0_sel:DWORD src1_sel:WORD_0
	v_mov_b32_e32 v75, v1
	v_cvt_pk_bf16_f32 v81, v84, v85
	v_lshl_add_u64 v[74:75], v[74:75], 1, s[10:11]
	global_store_dwordx4 v[74:75], v[80:83], off
	s_or_b64 exec, exec, s[20:21]
	s_and_saveexec_b64 s[20:21], s[6:7]
	s_cbranch_execnz .LBB0_936

.LBB0_951:
	v_cvt_pk_bf16_f32 v62, v62, v63
	v_cvt_pk_bf16_f32 v63, v64, v65
	v_cvt_pk_bf16_f32 v64, v58, v59
	v_cvt_pk_bf16_f32 v65, v60, v61
	v_mad_u64_u32 v[58:59], s[22:23], v66, s63, v[140:141]
	v_mov_b32_e32 v59, v1
	v_lshl_add_u64 v[58:59], v[58:59], 1, s[10:11]
	global_store_dwordx4 v[58:59], v[62:65], off
	s_or_b64 exec, exec, s[20:21]
	s_and_saveexec_b64 s[20:21], s[6:7]
	s_cbranch_execnz .LBB0_938

.LBB0_953:
	v_cvt_pk_bf16_f32 v47, v50, s0
	v_cvt_pk_bf16_f32 v50, v42, v43
	v_cvt_pk_bf16_f32 v48, v51, s0
	v_lshlrev_b32_e32 v48, 16, v48
	v_cvt_pk_bf16_f32 v51, v44, v45
	v_mad_u64_u32 v[42:43], s[22:23], v46, s63, v[140:141]
	v_or_b32_sdwa v48, v48, v47 dst_sel:DWORD dst_unused:UNUSED_PAD src0_sel:DWORD src1_sel:WORD_0
	v_mov_b32_e32 v43, v1
	v_cvt_pk_bf16_f32 v49, v52, v53
	v_lshl_add_u64 v[42:43], v[42:43], 1, s[10:11]
	global_store_dwordx4 v[42:43], v[48:51], off
	s_or_b64 exec, exec, s[20:21]
	s_and_saveexec_b64 s[20:21], s[6:7]
	s_cbranch_execnz .LBB0_940

.LBB0_955:
	v_cvt_pk_bf16_f32 v31, v34, s0
	v_cvt_pk_bf16_f32 v34, v26, v27
	v_cvt_pk_bf16_f32 v32, v35, s0
	v_lshlrev_b32_e32 v32, 16, v32
	v_cvt_pk_bf16_f32 v35, v28, v29
	v_mad_u64_u32 v[26:27], s[22:23], v30, s63, v[140:141]
	v_or_b32_sdwa v32, v32, v31 dst_sel:DWORD dst_unused:UNUSED_PAD src0_sel:DWORD src1_sel:WORD_0
	v_mov_b32_e32 v27, v1
	v_cvt_pk_bf16_f32 v33, v36, v37
	v_lshl_add_u64 v[26:27], v[26:27], 1, s[10:11]
	global_store_dwordx4 v[26:27], v[32:35], off
	s_or_b64 exec, exec, s[20:21]
	s_and_saveexec_b64 s[20:21], s[6:7]
	s_cbranch_execnz .LBB0_942

.LBB0_957:
	v_cvt_pk_bf16_f32 v15, v18, s0
	v_cvt_pk_bf16_f32 v18, v10, v11
	v_cvt_pk_bf16_f32 v16, v19, s0
	v_lshlrev_b32_e32 v16, 16, v16
	v_cvt_pk_bf16_f32 v19, v12, v13
	v_mad_u64_u32 v[10:11], s[22:23], v14, s63, v[140:141]
	v_or_b32_sdwa v16, v16, v15 dst_sel:DWORD dst_unused:UNUSED_PAD src0_sel:DWORD src1_sel:WORD_0
	v_mov_b32_e32 v11, v1
	v_cvt_pk_bf16_f32 v17, v20, v21
	v_lshl_add_u64 v[10:11], v[10:11], 1, s[10:11]
	global_store_dwordx4 v[10:11], v[16:19], off
	s_or_b64 exec, exec, s[20:21]
	s_and_saveexec_b64 s[20:21], s[6:7]
	s_cbranch_execz .LBB0_918
.LBB0_958:
	v_cvt_pk_bf16_f32 v6, v6, v7
	v_cvt_pk_bf16_f32 v7, v8, v9
	v_cvt_pk_bf16_f32 v8, v2, v3
	v_cvt_pk_bf16_f32 v9, v4, v5
	v_mad_u64_u32 v[2:3], s[6:7], v14, s63, v[122:123]
	v_mov_b32_e32 v3, v1
	v_lshl_add_u64 v[2:3], v[2:3], 1, s[10:11]
	global_store_dwordx4 v[2:3], v[6:9], off
	s_branch .LBB0_918

.LBB0_964:
	s_or_b64 exec, exec, s[6:7]
	v_lshl_or_b32 v134, v131, 5, v130
	v_lshlrev_b32_e32 v130, 2, v134
	s_waitcnt lgkmcnt(0)
	s_barrier
	global_load_dword v135, v130, s[44:45]
	global_load_dword v136, v130, s[44:45] offset:64
	v_lshl_add_u32 v143, v138, 2, v219
	ds_read_b128 v[150:153], v143
	ds_read_b128 v[154:157], v143 offset:16
	ds_read_b128 v[158:161], v143 offset:32
	ds_read_b128 v[162:165], v143 offset:48
	s_mov_b32 s2, 0x358637bd
	s_waitcnt lgkmcnt(3)
	v_mov_b32_e32 v131, v150
	s_waitcnt lgkmcnt(2)
	v_mov_b32_e32 v130, v154
	v_mov_b32_e32 v150, v155
	v_pk_add_f32 v[130:131], v[130:131], v[150:151]
	v_mov_b32_e32 v140, v156
	v_mov_b32_e32 v141, v152
	v_pk_add_f32 v[130:131], v[140:141], v[130:131]
	v_mov_b32_e32 v152, v157
	v_pk_add_f32 v[140:141], v[152:153], v[130:131]
	v_mov_b64_e32 v[130:131], s[2:3]
	v_pk_fma_f32 v[140:141], v[140:141], s[74:75], v[130:131] op_sel_hi:[1,0,0]
	s_waitcnt lgkmcnt(0)
	v_mov_b32_e32 v150, v164
	v_mul_f32_e32 v137, 0x4b800000, v141
	v_cmp_gt_f32_e64 s[6:7], s91, v141
	v_cmp_gt_f32_e32 vcc, s91, v140
	v_mov_b32_e32 v151, v160
	v_cndmask_b32_e64 v137, v141, v137, s[6:7]
	v_rsq_f32_e32 v137, v137
	v_mov_b32_e32 v141, v158
	v_mov_b32_e32 v158, v163
	v_mov_b32_e32 v160, v165
	v_mul_f32_e32 v138, 0x45800000, v137
	v_cndmask_b32_e64 v137, v137, v138, s[6:7]
	v_lshl_add_u32 v144, v144, 4, v219
	v_cvt_pk_bf16_f32 v58, v58, v59
	v_cvt_pk_bf16_f32 v59, v60, v61
	v_cvt_pk_bf16_f32 v50, v50, v51
	v_cvt_pk_bf16_f32 v51, v52, v53
	v_cvt_pk_bf16_f32 v42, v42, v43
	v_cvt_pk_bf16_f32 v43, v44, v45
	v_cvt_pk_bf16_f32 v34, v34, v35
	v_cvt_pk_bf16_f32 v35, v36, v37
	v_cvt_pk_bf16_f32 v26, v26, v27
	v_cvt_pk_bf16_f32 v27, v28, v29
	v_cvt_pk_bf16_f32 v18, v18, v19
	v_cvt_pk_bf16_f32 v19, v20, v21
	v_cvt_pk_bf16_f32 v10, v10, v11
	s_waitcnt vmcnt(0)
	v_mul_f32_e32 v138, v136, v137
	v_mul_f32_e32 v126, v126, v138
	v_mul_f32_e32 v138, 0x4b800000, v140
	v_cndmask_b32_e32 v138, v140, v138, vcc
	v_rsq_f32_e32 v138, v138
	s_nop 0
	v_mul_f32_e32 v140, 0x45800000, v138
	v_cndmask_b32_e32 v138, v138, v140, vcc
	v_mul_f32_e32 v140, v136, v138
	v_mul_f32_e32 v127, v127, v140
	v_mov_b32_e32 v140, v162
	v_pk_add_f32 v[140:141], v[140:141], v[158:159]
	v_cvt_pk_bf16_f32 v11, v12, v13
	v_pk_add_f32 v[140:141], v[150:151], v[140:141]
	v_pk_add_f32 v[140:141], v[160:161], v[140:141]
	v_pk_fma_f32 v[150:151], v[140:141], s[74:75], v[130:131] op_sel_hi:[1,0,0]
	v_mul_f32_e32 v140, 0x4b800000, v151
	v_cmp_gt_f32_e64 s[6:7], s91, v151
	v_cmp_gt_f32_e32 vcc, s91, v150
	v_cvt_pk_bf16_f32 v2, v2, v3
	v_cndmask_b32_e64 v140, v151, v140, s[6:7]
	v_rsq_f32_e32 v140, v140
	s_nop 0
	v_mul_f32_e32 v141, 0x45800000, v140
	v_cndmask_b32_e64 v140, v140, v141, s[6:7]
	v_mul_f32_e32 v141, v136, v140
	v_mul_f32_e32 v128, v128, v141
	v_mul_f32_e32 v141, 0x4b800000, v150
	v_cndmask_b32_e32 v141, v150, v141, vcc
	v_rsq_f32_e32 v141, v141
	v_cvt_pk_bf16_f32 v3, v4, v5
	v_mul_f32_e32 v150, 0x45800000, v141
	v_cndmask_b32_e32 v141, v141, v150, vcc
	v_mul_f32_e32 v150, v136, v141
	v_mul_f32_e32 v129, v129, v150
	ds_read_b128 v[150:153], v144
	ds_read_b128 v[154:157], v143 offset:272
	s_waitcnt lgkmcnt(1)
	v_mov_b32_e32 v159, v150
	s_waitcnt lgkmcnt(0)
	v_mov_b32_e32 v158, v154
	v_mov_b32_e32 v150, v155
	v_pk_add_f32 v[150:151], v[158:159], v[150:151]
	v_mov_b32_e32 v154, v156
	v_mov_b32_e32 v155, v152
	v_pk_add_f32 v[150:151], v[154:155], v[150:151]
	v_mov_b32_e32 v152, v157
	v_pk_add_f32 v[150:151], v[152:153], v[150:151]
	s_nop 0
	v_pk_fma_f32 v[150:151], v[150:151], s[74:75], v[130:131] op_sel_hi:[1,0,0]
	s_nop 0
	v_mul_f32_e32 v144, 0x4b800000, v151
	v_cmp_gt_f32_e64 s[6:7], s91, v151
	v_cmp_gt_f32_e32 vcc, s91, v150
	s_nop 0
	v_cndmask_b32_e64 v144, v151, v144, s[6:7]
	v_rsq_f32_e32 v144, v144
	s_nop 0
	v_mul_f32_e32 v151, 0x45800000, v144
	v_cndmask_b32_e64 v151, v144, v151, s[6:7]
	v_mul_f32_e32 v144, v135, v151
	v_mul_f32_e32 v144, v118, v144
	v_mul_f32_e32 v118, v136, v151
	v_mul_f32_e32 v118, v122, v118
	v_mul_f32_e32 v122, 0x4b800000, v150
	v_cndmask_b32_e32 v122, v150, v122, vcc
	v_rsq_f32_e32 v122, v122
	v_cvt_pk_bf16_f32 v118, v118, s0
	v_mul_f32_e32 v150, 0x45800000, v122
	v_cndmask_b32_e32 v150, v122, v150, vcc
	v_mul_f32_e32 v122, v135, v150
	v_mul_f32_e32 v122, v119, v122
	v_mul_f32_e32 v119, v136, v150
	ds_read_b128 v[150:153], v143 offset:288
	ds_read_b128 v[154:157], v143 offset:304
	v_mul_f32_e32 v119, v123, v119
	v_cvt_pk_bf16_f32 v122, v122, s0
	s_waitcnt lgkmcnt(1)
	v_mov_b32_e32 v159, v150
	s_waitcnt lgkmcnt(0)
	v_mov_b32_e32 v158, v154
	v_mov_b32_e32 v150, v155
	v_pk_add_f32 v[150:151], v[158:159], v[150:151]
	v_mov_b32_e32 v154, v156
	v_mov_b32_e32 v155, v152
	v_pk_add_f32 v[150:151], v[154:155], v[150:151]
	v_mov_b32_e32 v152, v157
	v_pk_add_f32 v[150:151], v[152:153], v[150:151]
	s_nop 0
	v_pk_fma_f32 v[150:151], v[150:151], s[74:75], v[130:131] op_sel_hi:[1,0,0]
	s_nop 0
	v_mul_f32_e32 v123, 0x4b800000, v151
	v_cmp_gt_f32_e64 s[6:7], s91, v151
	v_cmp_gt_f32_e32 vcc, s91, v150
	s_nop 0
	v_cndmask_b32_e64 v123, v151, v123, s[6:7]
	v_rsq_f32_e32 v123, v123
	s_nop 0
	v_mul_f32_e32 v151, 0x45800000, v123
	v_cndmask_b32_e64 v151, v123, v151, s[6:7]
	v_mul_f32_e32 v123, v135, v151
	v_mul_f32_e32 v123, v120, v123
	v_mul_f32_e32 v120, v136, v151
	v_mul_f32_e32 v120, v124, v120
	v_mul_f32_e32 v124, 0x4b800000, v150
	v_cndmask_b32_e32 v124, v150, v124, vcc
	v_rsq_f32_e32 v124, v124
	s_nop 0
	v_mul_f32_e32 v150, 0x45800000, v124
	v_cndmask_b32_e32 v150, v124, v150, vcc
	v_mul_f32_e32 v124, v135, v150
	v_mul_f32_e32 v124, v121, v124
	v_mul_f32_e32 v121, v136, v150
	v_mul_f32_e32 v121, v125, v121
	v_lshl_add_u32 v125, v149, 4, v219
	ds_read_b128 v[150:153], v125
	ds_read_b128 v[154:157], v143 offset:528
	v_cvt_pk_bf16_f32 v124, v124, s0
	s_waitcnt lgkmcnt(1)
	v_mov_b32_e32 v159, v150
	s_waitcnt lgkmcnt(0)
	v_mov_b32_e32 v158, v154
	v_mov_b32_e32 v150, v155
	v_pk_add_f32 v[150:151], v[158:159], v[150:151]
	v_mov_b32_e32 v154, v156
	v_mov_b32_e32 v155, v152
	v_pk_add_f32 v[150:151], v[154:155], v[150:151]
	v_mov_b32_e32 v152, v157
	v_pk_add_f32 v[150:151], v[152:153], v[150:151]
	s_nop 0
	v_pk_fma_f32 v[150:151], v[150:151], s[74:75], v[130:131] op_sel_hi:[1,0,0]
	s_nop 0
	v_mul_f32_e32 v125, 0x4b800000, v151
	v_cmp_gt_f32_e64 s[6:7], s91, v151
	v_cmp_gt_f32_e32 vcc, s91, v150
	s_nop 0
	v_cndmask_b32_e64 v125, v151, v125, s[6:7]
	v_rsq_f32_e32 v125, v125
	s_nop 0
	v_mul_f32_e32 v149, 0x45800000, v125
	v_cndmask_b32_e64 v149, v125, v149, s[6:7]
	v_mul_f32_e32 v125, v135, v149
	v_mul_f32_e32 v125, v110, v125
	v_mul_f32_e32 v110, v136, v149
	v_mul_f32_e32 v110, v114, v110
	v_mul_f32_e32 v114, 0x4b800000, v150
	v_cndmask_b32_e32 v114, v150, v114, vcc
	ds_read_b128 v[150:153], v143 offset:544
	ds_read_b128 v[154:157], v143 offset:560
	v_rsq_f32_e32 v114, v114
	v_cvt_pk_bf16_f32 v110, v110, s0
	s_waitcnt lgkmcnt(1)
	v_mov_b32_e32 v159, v150
	s_waitcnt lgkmcnt(0)
	v_mov_b32_e32 v158, v154
	v_mov_b32_e32 v150, v155
	v_mul_f32_e32 v149, 0x45800000, v114
	v_pk_add_f32 v[150:151], v[158:159], v[150:151]
	v_mov_b32_e32 v154, v156
	v_mov_b32_e32 v155, v152
	v_cndmask_b32_e32 v149, v114, v149, vcc
	v_pk_add_f32 v[150:151], v[154:155], v[150:151]
	v_mov_b32_e32 v152, v157
	v_mul_f32_e32 v114, v135, v149
	v_pk_add_f32 v[150:151], v[152:153], v[150:151]
	v_mul_f32_e32 v114, v111, v114
	v_mul_f32_e32 v111, v136, v149
	v_pk_fma_f32 v[150:151], v[150:151], s[74:75], v[130:131] op_sel_hi:[1,0,0]
	v_mul_f32_e32 v111, v115, v111
	v_mul_f32_e32 v115, 0x4b800000, v151
	v_cmp_gt_f32_e64 s[6:7], s91, v151
	v_cmp_gt_f32_e32 vcc, s91, v150
	v_cvt_pk_bf16_f32 v114, v114, s0
	v_cndmask_b32_e64 v115, v151, v115, s[6:7]
	v_rsq_f32_e32 v115, v115
	s_nop 0
	v_mul_f32_e32 v149, 0x45800000, v115
	v_cndmask_b32_e64 v149, v115, v149, s[6:7]
	v_mul_f32_e32 v115, v135, v149
	v_mul_f32_e32 v115, v112, v115
	v_mul_f32_e32 v112, v136, v149
	v_mul_f32_e32 v112, v116, v112
	v_mul_f32_e32 v116, 0x4b800000, v150
	v_cndmask_b32_e32 v116, v150, v116, vcc
	v_rsq_f32_e32 v116, v116
	s_nop 0
	v_mul_f32_e32 v149, 0x45800000, v116
	v_cndmask_b32_e32 v149, v116, v149, vcc
	v_mul_f32_e32 v116, v135, v149
	v_mul_f32_e32 v116, v113, v116
	v_mul_f32_e32 v113, v136, v149
	v_mul_f32_e32 v113, v117, v113
	v_lshl_add_u32 v117, v148, 4, v219
	ds_read_b128 v[148:151], v117
	ds_read_b128 v[152:155], v143 offset:784
	v_cvt_pk_bf16_f32 v116, v116, s0
	s_waitcnt lgkmcnt(1)
	v_mov_b32_e32 v157, v148
	s_waitcnt lgkmcnt(0)
	v_mov_b32_e32 v156, v152
	v_mov_b32_e32 v148, v153
	v_pk_add_f32 v[148:149], v[156:157], v[148:149]
	v_mov_b32_e32 v152, v154
	v_mov_b32_e32 v153, v150
	v_pk_add_f32 v[148:149], v[152:153], v[148:149]
	v_mov_b32_e32 v150, v155
	v_pk_add_f32 v[148:149], v[150:151], v[148:149]
	s_nop 0
	v_pk_fma_f32 v[148:149], v[148:149], s[74:75], v[130:131] op_sel_hi:[1,0,0]
	s_nop 0
	v_mul_f32_e32 v117, 0x4b800000, v149
	v_cmp_gt_f32_e64 s[6:7], s91, v149
	v_cmp_gt_f32_e32 vcc, s91, v148
	s_nop 0
	v_cndmask_b32_e64 v117, v149, v117, s[6:7]
	v_rsq_f32_e32 v117, v117
	s_nop 0
	v_mul_f32_e32 v149, 0x45800000, v117
	v_cndmask_b32_e64 v149, v117, v149, s[6:7]
	v_mul_f32_e32 v117, v135, v149
	v_mul_f32_e32 v117, v102, v117
	v_mul_f32_e32 v102, v136, v149
	v_mul_f32_e32 v102, v106, v102
	v_mul_f32_e32 v106, 0x4b800000, v148
	v_cndmask_b32_e32 v106, v148, v106, vcc
	v_rsq_f32_e32 v106, v106
	v_cvt_pk_bf16_f32 v102, v102, s0
	v_mul_f32_e32 v148, 0x45800000, v106
	v_cndmask_b32_e32 v148, v106, v148, vcc
	v_mul_f32_e32 v106, v135, v148
	v_mul_f32_e32 v106, v103, v106
	v_mul_f32_e32 v103, v136, v148
	ds_read_b128 v[148:151], v143 offset:800
	ds_read_b128 v[152:155], v143 offset:816
	v_mul_f32_e32 v103, v107, v103
	v_cvt_pk_bf16_f32 v106, v106, s0
	s_waitcnt lgkmcnt(1)
	v_mov_b32_e32 v157, v148
	s_waitcnt lgkmcnt(0)
	v_mov_b32_e32 v156, v152
	v_mov_b32_e32 v148, v153
	v_pk_add_f32 v[148:149], v[156:157], v[148:149]
	v_mov_b32_e32 v152, v154
	v_mov_b32_e32 v153, v150
	v_pk_add_f32 v[148:149], v[152:153], v[148:149]
	v_mov_b32_e32 v150, v155
	v_pk_add_f32 v[148:149], v[150:151], v[148:149]
	s_nop 0
	v_pk_fma_f32 v[148:149], v[148:149], s[74:75], v[130:131] op_sel_hi:[1,0,0]
	s_nop 0
	v_mul_f32_e32 v107, 0x4b800000, v149
	v_cmp_gt_f32_e64 s[6:7], s91, v149
	v_cmp_gt_f32_e32 vcc, s91, v148
	s_nop 0
	v_cndmask_b32_e64 v107, v149, v107, s[6:7]
	v_rsq_f32_e32 v107, v107
	s_nop 0
	v_mul_f32_e32 v149, 0x45800000, v107
	v_cndmask_b32_e64 v149, v107, v149, s[6:7]
	v_mul_f32_e32 v107, v135, v149
	v_mul_f32_e32 v107, v104, v107
	v_mul_f32_e32 v104, v136, v149
	v_mul_f32_e32 v104, v108, v104
	v_mul_f32_e32 v108, 0x4b800000, v148
	v_cndmask_b32_e32 v108, v148, v108, vcc
	v_rsq_f32_e32 v108, v108
	v_cvt_pk_bf16_f32 v104, v104, s0
	v_mul_f32_e32 v148, 0x45800000, v108
	v_cndmask_b32_e32 v148, v108, v148, vcc
	v_mul_f32_e32 v108, v135, v148
	v_mul_f32_e32 v108, v105, v108
	v_mul_f32_e32 v105, v136, v148
	v_mul_f32_e32 v105, v109, v105
	v_lshl_add_u32 v109, v147, 4, v219
	ds_read_b128 v[148:151], v109
	ds_read_b128 v[152:155], v143 offset:2064
	v_cvt_pk_bf16_f32 v108, v108, s0
	s_waitcnt lgkmcnt(1)
	v_mov_b32_e32 v157, v148
	s_waitcnt lgkmcnt(0)
	v_mov_b32_e32 v156, v152
	v_mov_b32_e32 v148, v153
	v_pk_add_f32 v[148:149], v[156:157], v[148:149]
	v_mov_b32_e32 v152, v154
	v_mov_b32_e32 v153, v150
	v_pk_add_f32 v[148:149], v[152:153], v[148:149]
	v_mov_b32_e32 v150, v155
	v_pk_add_f32 v[148:149], v[150:151], v[148:149]
	s_nop 0
	v_pk_fma_f32 v[148:149], v[148:149], s[74:75], v[130:131] op_sel_hi:[1,0,0]
	s_nop 0
	v_mul_f32_e32 v109, 0x4b800000, v149
	v_cmp_gt_f32_e64 s[6:7], s91, v149
	v_cmp_gt_f32_e32 vcc, s91, v148
	s_nop 0
	v_cndmask_b32_e64 v109, v149, v109, s[6:7]
	v_rsq_f32_e32 v109, v109
	s_nop 0
	v_mul_f32_e32 v147, 0x45800000, v109
	v_cndmask_b32_e64 v147, v109, v147, s[6:7]
	v_mul_f32_e32 v109, v135, v147
	v_mul_f32_e32 v109, v94, v109
	v_mul_f32_e32 v94, v136, v147
	v_mul_f32_e32 v94, v98, v94
	v_mul_f32_e32 v98, 0x4b800000, v148
	v_cndmask_b32_e32 v98, v148, v98, vcc
	ds_read_b128 v[148:151], v143 offset:2080
	ds_read_b128 v[152:155], v143 offset:2096
	v_rsq_f32_e32 v98, v98
	s_waitcnt lgkmcnt(1)
	v_mov_b32_e32 v157, v148
	s_waitcnt lgkmcnt(0)
	v_mov_b32_e32 v156, v152
	v_mov_b32_e32 v148, v153
	v_mul_f32_e32 v147, 0x45800000, v98
	v_pk_add_f32 v[148:149], v[156:157], v[148:149]
	v_mov_b32_e32 v152, v154
	v_mov_b32_e32 v153, v150
	v_cndmask_b32_e32 v147, v98, v147, vcc
	v_pk_add_f32 v[148:149], v[152:153], v[148:149]
	v_mov_b32_e32 v150, v155
	v_mul_f32_e32 v98, v135, v147
	v_pk_add_f32 v[148:149], v[150:151], v[148:149]
	v_mul_f32_e32 v98, v95, v98
	v_mul_f32_e32 v95, v136, v147
	v_pk_fma_f32 v[148:149], v[148:149], s[74:75], v[130:131] op_sel_hi:[1,0,0]
	v_mul_f32_e32 v95, v99, v95
	v_mul_f32_e32 v99, 0x4b800000, v149
	v_cmp_gt_f32_e64 s[6:7], s91, v149
	v_cmp_gt_f32_e32 vcc, s91, v148
	s_nop 0
	v_cndmask_b32_e64 v99, v149, v99, s[6:7]
	v_rsq_f32_e32 v99, v99
	s_nop 0
	v_mul_f32_e32 v147, 0x45800000, v99
	v_cndmask_b32_e64 v147, v99, v147, s[6:7]
	v_mul_f32_e32 v99, v135, v147
	v_mul_f32_e32 v99, v96, v99
	v_mul_f32_e32 v96, v136, v147
	v_mul_f32_e32 v96, v100, v96
	v_mul_f32_e32 v100, 0x4b800000, v148
	v_cndmask_b32_e32 v100, v148, v100, vcc
	v_rsq_f32_e32 v100, v100
	s_nop 0
	v_mul_f32_e32 v147, 0x45800000, v100
	v_cndmask_b32_e32 v147, v100, v147, vcc
	v_mul_f32_e32 v100, v135, v147
	v_mul_f32_e32 v100, v97, v100
	v_mul_f32_e32 v97, v136, v147
	v_mul_f32_e32 v97, v101, v97
	v_lshl_add_u32 v101, v146, 4, v219
	ds_read_b128 v[146:149], v101
	ds_read_b128 v[150:153], v143 offset:2320
	s_waitcnt lgkmcnt(1)
	v_mov_b32_e32 v155, v146
	s_waitcnt lgkmcnt(0)
	v_mov_b32_e32 v154, v150
	v_mov_b32_e32 v146, v151
	v_pk_add_f32 v[146:147], v[154:155], v[146:147]
	v_mov_b32_e32 v150, v152
	v_mov_b32_e32 v151, v148
	v_pk_add_f32 v[146:147], v[150:151], v[146:147]
	v_mov_b32_e32 v148, v153
	v_pk_add_f32 v[146:147], v[148:149], v[146:147]
	s_nop 0
	v_pk_fma_f32 v[146:147], v[146:147], s[74:75], v[130:131] op_sel_hi:[1,0,0]
	s_nop 0
	v_mul_f32_e32 v101, 0x4b800000, v147
	v_cmp_gt_f32_e64 s[6:7], s91, v147
	v_cmp_gt_f32_e32 vcc, s91, v146
	s_nop 0
	v_cndmask_b32_e64 v101, v147, v101, s[6:7]
	v_rsq_f32_e32 v101, v101
	s_nop 0
	v_mul_f32_e32 v147, 0x45800000, v101
	v_cndmask_b32_e64 v147, v101, v147, s[6:7]
	v_mul_f32_e32 v101, v135, v147
	v_mul_f32_e32 v101, v86, v101
	v_mul_f32_e32 v86, v136, v147
	v_mul_f32_e32 v86, v90, v86
	v_mul_f32_e32 v90, 0x4b800000, v146
	v_cndmask_b32_e32 v90, v146, v90, vcc
	v_rsq_f32_e32 v90, v90
	s_nop 0
	v_mul_f32_e32 v146, 0x45800000, v90
	v_cndmask_b32_e32 v146, v90, v146, vcc
	v_mul_f32_e32 v90, v135, v146
	v_mul_f32_e32 v90, v87, v90
	v_mul_f32_e32 v87, v136, v146
	ds_read_b128 v[146:149], v143 offset:2336
	ds_read_b128 v[150:153], v143 offset:2352
	v_mul_f32_e32 v87, v91, v87
	s_waitcnt lgkmcnt(1)
	v_mov_b32_e32 v155, v146
	s_waitcnt lgkmcnt(0)
	v_mov_b32_e32 v154, v150
	v_mov_b32_e32 v146, v151
	v_pk_add_f32 v[146:147], v[154:155], v[146:147]
	v_mov_b32_e32 v150, v152
	v_mov_b32_e32 v151, v148
	v_pk_add_f32 v[146:147], v[150:151], v[146:147]
	v_mov_b32_e32 v148, v153
	v_pk_add_f32 v[146:147], v[148:149], v[146:147]
	s_nop 0
	v_pk_fma_f32 v[146:147], v[146:147], s[74:75], v[130:131] op_sel_hi:[1,0,0]
	s_nop 0
	v_mul_f32_e32 v91, 0x4b800000, v147
	v_cmp_gt_f32_e64 s[6:7], s91, v147
	v_cmp_gt_f32_e32 vcc, s91, v146
	s_nop 0
	v_cndmask_b32_e64 v91, v147, v91, s[6:7]
	v_rsq_f32_e32 v91, v91
	s_nop 0
	v_mul_f32_e32 v147, 0x45800000, v91
	v_cndmask_b32_e64 v147, v91, v147, s[6:7]
	v_mul_f32_e32 v91, v135, v147
	v_mul_f32_e32 v91, v88, v91
	v_mul_f32_e32 v88, v136, v147
	v_mul_f32_e32 v88, v92, v88
	v_mul_f32_e32 v92, 0x4b800000, v146
	v_cndmask_b32_e32 v92, v146, v92, vcc
	v_rsq_f32_e32 v92, v92
	s_nop 0
	v_mul_f32_e32 v146, 0x45800000, v92
	v_cndmask_b32_e32 v146, v92, v146, vcc
	v_mul_f32_e32 v92, v135, v146
	v_mul_f32_e32 v92, v89, v92
	v_mul_f32_e32 v89, v136, v146
	v_mul_f32_e32 v89, v93, v89
	v_lshl_add_u32 v93, v145, 4, v219
	ds_read_b128 v[146:149], v93
	ds_read_b128 v[150:153], v143 offset:2576
	s_waitcnt lgkmcnt(1)
	v_mov_b32_e32 v155, v146
	s_waitcnt lgkmcnt(0)
	v_mov_b32_e32 v154, v150
	v_mov_b32_e32 v146, v151
	v_pk_add_f32 v[146:147], v[154:155], v[146:147]
	v_mov_b32_e32 v150, v152
	v_mov_b32_e32 v151, v148
	v_pk_add_f32 v[146:147], v[150:151], v[146:147]
	v_mov_b32_e32 v148, v153
	v_pk_add_f32 v[146:147], v[148:149], v[146:147]
	s_nop 0
	v_pk_fma_f32 v[146:147], v[146:147], s[74:75], v[130:131] op_sel_hi:[1,0,0]
	s_nop 0
	v_mul_f32_e32 v93, 0x4b800000, v147
	v_cmp_gt_f32_e64 s[6:7], s91, v147
	v_cmp_gt_f32_e32 vcc, s91, v146
	s_nop 0
	v_cndmask_b32_e64 v93, v147, v93, s[6:7]
	v_rsq_f32_e32 v93, v93
	s_nop 0
	v_mul_f32_e32 v145, 0x45800000, v93
	v_cndmask_b32_e64 v145, v93, v145, s[6:7]
	v_mul_f32_e32 v93, v135, v145
	v_mul_f32_e32 v93, v78, v93
	v_mul_f32_e32 v78, v136, v145
	v_mul_f32_e32 v78, v82, v78
	v_mul_f32_e32 v82, 0x4b800000, v146
	v_cndmask_b32_e32 v82, v146, v82, vcc
	ds_read_b128 v[146:149], v143 offset:2592
	ds_read_b128 v[150:153], v143 offset:2608
	v_rsq_f32_e32 v82, v82
	s_waitcnt lgkmcnt(1)
	v_mov_b32_e32 v155, v146
	s_waitcnt lgkmcnt(0)
	v_mov_b32_e32 v154, v150
	v_mov_b32_e32 v146, v151
	v_mul_f32_e32 v145, 0x45800000, v82
	v_pk_add_f32 v[146:147], v[154:155], v[146:147]
	v_mov_b32_e32 v150, v152
	v_mov_b32_e32 v151, v148
	v_cndmask_b32_e32 v145, v82, v145, vcc
	v_pk_add_f32 v[146:147], v[150:151], v[146:147]
	v_mov_b32_e32 v148, v153
	v_mul_f32_e32 v82, v135, v145
	v_pk_add_f32 v[146:147], v[148:149], v[146:147]
	v_mul_f32_e32 v82, v79, v82
	v_mul_f32_e32 v79, v136, v145
	v_pk_fma_f32 v[146:147], v[146:147], s[74:75], v[130:131] op_sel_hi:[1,0,0]
	v_mul_f32_e32 v79, v83, v79
	v_mul_f32_e32 v83, 0x4b800000, v147
	v_cmp_gt_f32_e64 s[6:7], s91, v147
	v_cmp_gt_f32_e32 vcc, s91, v146
	s_nop 0
	v_cndmask_b32_e64 v83, v147, v83, s[6:7]
	v_rsq_f32_e32 v83, v83
	s_nop 0
	v_mul_f32_e32 v145, 0x45800000, v83
	v_cndmask_b32_e64 v145, v83, v145, s[6:7]
	v_mul_f32_e32 v83, v135, v145
	v_mul_f32_e32 v83, v80, v83
	v_mul_f32_e32 v80, v136, v145
	v_mul_f32_e32 v80, v84, v80
	v_mul_f32_e32 v84, 0x4b800000, v146
	v_cndmask_b32_e32 v84, v146, v84, vcc
	v_rsq_f32_e32 v84, v84
	s_nop 0
	v_mul_f32_e32 v145, 0x45800000, v84
	v_cndmask_b32_e32 v145, v84, v145, vcc
	v_mul_f32_e32 v84, v135, v145
	v_mul_f32_e32 v84, v81, v84
	v_mul_f32_e32 v81, v136, v145
	v_mul_f32_e32 v81, v85, v81
	v_lshl_add_u32 v85, v142, 4, v219
	ds_read_b128 v[146:149], v85
	ds_read_b128 v[150:153], v143 offset:2832
	s_waitcnt lgkmcnt(1)
	v_mov_b32_e32 v155, v146
	s_waitcnt lgkmcnt(0)
	v_mov_b32_e32 v154, v150
	v_mov_b32_e32 v146, v151
	v_pk_add_f32 v[146:147], v[154:155], v[146:147]
	v_mov_b32_e32 v150, v152
	v_mov_b32_e32 v151, v148
	v_pk_add_f32 v[146:147], v[150:151], v[146:147]
	v_mov_b32_e32 v148, v153
	v_pk_add_f32 v[146:147], v[148:149], v[146:147]
	s_nop 0
	v_pk_fma_f32 v[146:147], v[146:147], s[74:75], v[130:131] op_sel_hi:[1,0,0]
	s_nop 0
	v_mul_f32_e32 v85, 0x4b800000, v147
	v_cmp_gt_f32_e64 s[6:7], s91, v147
	v_cmp_gt_f32_e32 vcc, s91, v146
	s_nop 0
	v_cndmask_b32_e64 v85, v147, v85, s[6:7]
	v_rsq_f32_e32 v85, v85
	s_nop 0
	v_mul_f32_e32 v142, 0x45800000, v85
	v_cndmask_b32_e64 v142, v85, v142, s[6:7]
	v_mul_f32_e32 v85, v135, v142
	v_mul_f32_e32 v85, v70, v85
	v_mul_f32_e32 v70, v136, v142
	v_mul_f32_e32 v74, v74, v70
	v_mul_f32_e32 v70, 0x4b800000, v146
	v_cndmask_b32_e32 v70, v146, v70, vcc
	v_rsq_f32_e32 v70, v70
	ds_read_b128 v[146:149], v143 offset:2848
	v_mul_f32_e32 v142, 0x45800000, v70
	v_cndmask_b32_e32 v70, v70, v142, vcc
	v_mul_f32_e32 v142, v135, v70
	v_mul_f32_e32 v70, v136, v70
	v_mul_f32_e32 v142, v71, v142
	v_mul_f32_e32 v71, v75, v70
	v_lshl_add_u32 v70, v139, 2, v219
	ds_read_b128 v[150:153], v70
	s_waitcnt lgkmcnt(1)
	v_mov_b32_e32 v155, v146
	s_waitcnt lgkmcnt(0)
	v_mov_b32_e32 v154, v150
	v_mov_b32_e32 v146, v151
	v_pk_add_f32 v[146:147], v[154:155], v[146:147]
	v_mov_b32_e32 v150, v152
	v_mov_b32_e32 v151, v148
	v_pk_add_f32 v[146:147], v[150:151], v[146:147]
	v_mov_b32_e32 v148, v153
	v_pk_add_f32 v[146:147], v[148:149], v[146:147]
	s_nop 0
	v_pk_fma_f32 v[146:147], v[146:147], s[74:75], v[130:131] op_sel_hi:[1,0,0]
	s_nop 0
	v_mul_f32_e32 v70, 0x4b800000, v147
	v_cmp_gt_f32_e64 s[6:7], s91, v147
	v_cmp_gt_f32_e32 vcc, s91, v146
	s_nop 0
	v_cndmask_b32_e64 v70, v147, v70, s[6:7]
	v_rsq_f32_e32 v70, v70
	s_nop 0
	v_mul_f32_e32 v75, 0x45800000, v70
	v_cndmask_b32_e64 v70, v70, v75, s[6:7]
	v_mul_f32_e32 v75, v135, v70
	v_mul_f32_e32 v70, v136, v70
	v_mul_f32_e32 v130, v72, v75
	v_mul_f32_e32 v75, v76, v70
	v_mul_f32_e32 v70, 0x4b800000, v146
	v_cndmask_b32_e32 v70, v146, v70, vcc
	v_rsq_f32_e32 v70, v70
	s_nop 0
	v_mul_f32_e32 v72, 0x45800000, v70
	v_cndmask_b32_e32 v70, v70, v72, vcc
	v_mul_f32_e32 v72, v135, v70
	v_mul_f32_e32 v70, v136, v70
	v_mul_f32_e32 v76, v73, v72
	v_mul_f32_e32 v73, v77, v70
	v_lshl_add_u32 v77, s16, 8, v0
	v_mul_f32_e32 v0, v135, v137
	v_mul_f32_e32 v0, v66, v0
	v_cvt_pk_bf16_f32 v66, v0, s0
	v_mul_f32_e32 v0, v135, v138
	v_or_b32_e32 v70, v77, v133
	v_mul_f32_e32 v137, v67, v0
	v_mul_f32_e32 v0, v135, v140
	v_lshlrev_b32_e32 v72, 10, v70
	v_mul_f32_e32 v138, v68, v0
	v_mul_f32_e32 v0, v135, v141
	v_lshl_or_b32 v67, s14, 7, v134
	v_or_b32_e32 v131, 0x400, v72
	v_mul_f32_e32 v135, v69, v0
	v_add_u32_e32 v0, v67, v72
	v_or_b32_e32 v133, 0x800, v72
	v_lshl_add_u64 v[68:69], v[0:1], 1, s[8:9]
	v_add_u32_e32 v0, v131, v67
	v_or_b32_e32 v136, 0xc00, v72
	global_store_short v[68:69], v66, off
	v_cvt_pk_bf16_f32 v66, v137, s0
	v_lshl_add_u64 v[68:69], v[0:1], 1, s[8:9]
	v_add_u32_e32 v0, v133, v67
	global_store_short v[68:69], v66, off
	v_cvt_pk_bf16_f32 v66, v138, s0
	v_lshl_add_u64 v[68:69], v[0:1], 1, s[8:9]
	v_add_u32_e32 v0, v136, v67
	global_store_short v[68:69], v66, off
	v_cvt_pk_bf16_f32 v66, v135, s0
	v_lshl_add_u64 v[68:69], v[0:1], 1, s[8:9]
	global_store_short v[68:69], v66, off
	v_or_b32_e32 v69, 16, v67
	v_add_u32_e32 v0, v69, v72
	v_cvt_pk_bf16_f32 v66, v126, s0
	v_lshl_add_u64 v[134:135], v[0:1], 1, s[8:9]
	v_add_u32_e32 v0, v69, v131
	global_store_short v[134:135], v66, off
	v_cvt_pk_bf16_f32 v66, v127, s0
	v_lshl_add_u64 v[126:127], v[0:1], 1, s[8:9]
	v_add_u32_e32 v0, v69, v133
	global_store_short v[126:127], v66, off
	v_cvt_pk_bf16_f32 v66, v128, s0
	v_lshl_add_u64 v[126:127], v[0:1], 1, s[8:9]
	v_add_u32_e32 v0, v69, v136
	global_store_short v[126:127], v66, off
	v_cvt_pk_bf16_f32 v66, v129, s0
	v_lshl_add_u64 v[126:127], v[0:1], 1, s[8:9]
	v_or_b32_e32 v72, 16, v70
	global_store_short v[126:127], v66, off
	v_lshlrev_b32_e32 v66, 10, v72
	v_or_b32_e32 v68, 0x400, v66
	v_add_u32_e32 v0, v66, v67
	v_or_b32_e32 v128, 0x800, v66
	v_cvt_pk_bf16_f32 v131, v144, s0
	v_lshl_add_u64 v[126:127], v[0:1], 1, s[8:9]
	v_add_u32_e32 v0, v68, v67
	v_or_b32_e32 v129, 0xc00, v66
	global_store_short v[126:127], v131, off
	v_lshl_add_u64 v[126:127], v[0:1], 1, s[8:9]
	v_add_u32_e32 v0, v128, v67
	global_store_short v[126:127], v122, off
	v_cvt_pk_bf16_f32 v126, v123, s0
	v_lshl_add_u64 v[122:123], v[0:1], 1, s[8:9]
	v_add_u32_e32 v0, v129, v67
	global_store_short v[122:123], v126, off
	v_lshl_add_u64 v[122:123], v[0:1], 1, s[8:9]
	v_add_u32_e32 v0, v69, v66
	global_store_short v[122:123], v124, off
	v_lshl_add_u64 v[122:123], v[0:1], 1, s[8:9]
	v_add_u32_e32 v0, v68, v69
	global_store_short v[122:123], v118, off
	v_cvt_pk_bf16_f32 v66, v119, s0
	v_lshl_add_u64 v[118:119], v[0:1], 1, s[8:9]
	v_add_u32_e32 v0, v128, v69
	global_store_short v[118:119], v66, off
	v_cvt_pk_bf16_f32 v66, v120, s0
	v_lshl_add_u64 v[118:119], v[0:1], 1, s[8:9]
	v_add_u32_e32 v0, v129, v69
	global_store_short v[118:119], v66, off
	v_cvt_pk_bf16_f32 v66, v121, s0
	v_lshl_add_u64 v[118:119], v[0:1], 1, s[8:9]
	v_or_b32_e32 v68, 32, v70
	global_store_short v[118:119], v66, off
	v_lshlrev_b32_e32 v66, 10, v68
	v_or_b32_e32 v120, 0x400, v66
	v_add_u32_e32 v0, v66, v67
	v_or_b32_e32 v121, 0x800, v66
	v_cvt_pk_bf16_f32 v123, v125, s0
	v_lshl_add_u64 v[118:119], v[0:1], 1, s[8:9]
	v_add_u32_e32 v0, v120, v67
	v_or_b32_e32 v122, 0xc00, v66
	global_store_short v[118:119], v123, off
	v_lshl_add_u64 v[118:119], v[0:1], 1, s[8:9]
	v_add_u32_e32 v0, v121, v67
	global_store_short v[118:119], v114, off
	v_cvt_pk_bf16_f32 v118, v115, s0
	v_lshl_add_u64 v[114:115], v[0:1], 1, s[8:9]
	v_add_u32_e32 v0, v122, v67
	global_store_short v[114:115], v118, off
	v_lshl_add_u64 v[114:115], v[0:1], 1, s[8:9]
	v_add_u32_e32 v0, v69, v66
	global_store_short v[114:115], v116, off
	v_lshl_add_u64 v[114:115], v[0:1], 1, s[8:9]
	v_add_u32_e32 v0, v120, v69
	global_store_short v[114:115], v110, off
	v_cvt_pk_bf16_f32 v66, v111, s0
	v_lshl_add_u64 v[110:111], v[0:1], 1, s[8:9]
	v_add_u32_e32 v0, v121, v69
	global_store_short v[110:111], v66, off
	v_cvt_pk_bf16_f32 v66, v112, s0
	v_lshl_add_u64 v[110:111], v[0:1], 1, s[8:9]
	v_add_u32_e32 v0, v122, v69
	global_store_short v[110:111], v66, off
	v_cvt_pk_bf16_f32 v66, v113, s0
	v_lshl_add_u64 v[110:111], v[0:1], 1, s[8:9]
	global_store_short v[110:111], v66, off
	v_or_b32_e32 v66, 48, v70
	v_lshlrev_b32_e32 v112, 10, v66
	v_or_b32_e32 v113, 0x400, v112
	v_add_u32_e32 v0, v112, v67
	v_or_b32_e32 v114, 0x800, v112
	v_cvt_pk_bf16_f32 v116, v117, s0
	v_lshl_add_u64 v[110:111], v[0:1], 1, s[8:9]
	v_add_u32_e32 v0, v113, v67
	v_or_b32_e32 v115, 0xc00, v112
	global_store_short v[110:111], v116, off
	v_lshl_add_u64 v[110:111], v[0:1], 1, s[8:9]
	v_add_u32_e32 v0, v114, v67
	global_store_short v[110:111], v106, off
	v_cvt_pk_bf16_f32 v110, v107, s0
	v_lshl_add_u64 v[106:107], v[0:1], 1, s[8:9]
	v_add_u32_e32 v0, v115, v67
	global_store_short v[106:107], v110, off
	v_lshl_add_u64 v[106:107], v[0:1], 1, s[8:9]
	v_add_u32_e32 v0, v69, v112
	global_store_short v[106:107], v108, off
	v_lshl_add_u64 v[106:107], v[0:1], 1, s[8:9]
	v_add_u32_e32 v0, v113, v69
	global_store_short v[106:107], v102, off
	v_cvt_pk_bf16_f32 v106, v103, s0
	v_lshl_add_u64 v[102:103], v[0:1], 1, s[8:9]
	v_add_u32_e32 v0, v114, v69
	global_store_short v[102:103], v106, off
	v_lshl_add_u64 v[102:103], v[0:1], 1, s[8:9]
	v_add_u32_e32 v0, v115, v69
	v_ashrrev_i32_e32 v77, 31, v77
	global_store_short v[102:103], v104, off
	v_lshl_add_u64 v[102:103], v[0:1], 1, s[8:9]
	v_cvt_pk_bf16_f32 v0, v62, s0
	v_add_u32_e32 v62, v70, v77
	v_cvt_pk_bf16_f32 v104, v105, s0
	v_xor_b32_e32 v62, v62, v77
	global_store_short v[102:103], v104, off
	v_mul_hi_u32 v103, v62, v132
	v_mul_lo_u32 v104, v103, s24
	v_sub_u32_e32 v62, v62, v104
	v_cmp_le_u32_e32 vcc, s24, v62
	v_add_u32_e32 v104, 1, v103
	v_xor_b32_e32 v102, s27, v77
	v_cndmask_b32_e32 v103, v103, v104, vcc
	v_subrev_u32_e32 v104, s24, v62
	v_cndmask_b32_e32 v62, v62, v104, vcc
	v_cmp_le_u32_e32 vcc, s24, v62
	v_add_u32_e32 v62, 1, v103
	s_nop 0
	v_cndmask_b32_e32 v62, v103, v62, vcc
	v_xor_b32_e32 v62, v62, v102
	v_sub_u32_e32 v103, v62, v102
	v_cvt_pk_bf16_f32 v62, v63, s0
	v_lshlrev_b32_e32 v62, 16, v62
	v_or_b32_sdwa v62, v62, v0 dst_sel:DWORD dst_unused:UNUSED_PAD src0_sel:DWORD src1_sel:WORD_0
	v_cvt_pk_bf16_f32 v63, v64, v65
	v_mul_lo_u32 v0, v103, s88
	v_add_u32_e32 v64, v0, v67
	v_add_u32_e32 v0, v0, v69
	v_mad_u64_u32 v[64:65], s[6:7], v64, s5, v[70:71]
	v_mad_u64_u32 v[60:61], s[6:7], v0, s5, v[70:71]
	v_and_b32_e32 v65, 0x78, v67
	v_lshlrev_b32_e32 v65, 4, v65
	v_xor_b32_e32 v64, v64, v65
	v_mov_b32_e32 v65, v1
	v_and_b32_e32 v61, 0x78, v69
	v_lshlrev_b32_e32 v61, 4, v61
	v_xor_b32_e32 v60, v60, v61
	v_mov_b32_e32 v61, v1
	v_cvt_pk_bf16_f32 v0, v54, s0
	v_add_u32_e32 v54, v72, v77
	v_lshl_add_u64 v[64:65], v[64:65], 1, s[10:11]
	v_lshl_add_u64 v[60:61], v[60:61], 1, s[10:11]
	v_xor_b32_e32 v54, v54, v77
	global_store_dwordx2 v[64:65], v[62:63], off
	global_store_dwordx2 v[60:61], v[58:59], off
	v_mul_hi_u32 v58, v54, v132
	v_mul_lo_u32 v59, v58, s24
	v_sub_u32_e32 v54, v54, v59
	v_cmp_le_u32_e32 vcc, s24, v54
	v_add_u32_e32 v59, 1, v58
	s_nop 0
	v_cndmask_b32_e32 v58, v58, v59, vcc
	v_subrev_u32_e32 v59, s24, v54
	v_cndmask_b32_e32 v54, v54, v59, vcc
	v_cmp_le_u32_e32 vcc, s24, v54
	v_add_u32_e32 v54, 1, v58
	s_nop 0
	v_cndmask_b32_e32 v54, v58, v54, vcc
	v_xor_b32_e32 v54, v54, v102
	v_sub_u32_e32 v58, v54, v102
	v_cvt_pk_bf16_f32 v54, v55, s0
	v_lshlrev_b32_e32 v54, 16, v54
	v_or_b32_sdwa v54, v54, v0 dst_sel:DWORD dst_unused:UNUSED_PAD src0_sel:DWORD src1_sel:WORD_0
	v_cvt_pk_bf16_f32 v55, v56, v57
	v_mul_lo_u32 v0, v58, s88
	v_add_u32_e32 v56, v0, v67
	v_add_u32_e32 v0, v0, v69
	v_mad_u64_u32 v[56:57], s[6:7], v56, s5, v[72:73]
	v_mad_u64_u32 v[52:53], s[6:7], v0, s5, v[72:73]
	v_and_b32_e32 v57, 0x78, v67
	v_lshlrev_b32_e32 v57, 4, v57
	v_xor_b32_e32 v56, v56, v57
	v_mov_b32_e32 v57, v1
	v_and_b32_e32 v53, 0x78, v69
	v_lshlrev_b32_e32 v53, 4, v53
	v_xor_b32_e32 v52, v52, v53
	v_mov_b32_e32 v53, v1
	v_cvt_pk_bf16_f32 v0, v46, s0
	v_add_u32_e32 v46, v68, v77
	v_lshl_add_u64 v[56:57], v[56:57], 1, s[10:11]
	v_lshl_add_u64 v[52:53], v[52:53], 1, s[10:11]
	v_xor_b32_e32 v46, v46, v77
	global_store_dwordx2 v[56:57], v[54:55], off
	global_store_dwordx2 v[52:53], v[50:51], off
	v_mul_hi_u32 v50, v46, v132
	v_mul_lo_u32 v51, v50, s24
	v_sub_u32_e32 v46, v46, v51
	v_cmp_le_u32_e32 vcc, s24, v46
	v_add_u32_e32 v51, 1, v50
	s_nop 0
	v_cndmask_b32_e32 v50, v50, v51, vcc
	v_subrev_u32_e32 v51, s24, v46
	v_cndmask_b32_e32 v46, v46, v51, vcc
	v_cmp_le_u32_e32 vcc, s24, v46
	v_add_u32_e32 v46, 1, v50
	s_nop 0
	v_cndmask_b32_e32 v46, v50, v46, vcc
	v_xor_b32_e32 v46, v46, v102
	v_sub_u32_e32 v50, v46, v102
	v_cvt_pk_bf16_f32 v46, v47, s0
	v_lshlrev_b32_e32 v46, 16, v46
	v_or_b32_sdwa v46, v46, v0 dst_sel:DWORD dst_unused:UNUSED_PAD src0_sel:DWORD src1_sel:WORD_0
	v_cvt_pk_bf16_f32 v47, v48, v49
	v_mul_lo_u32 v0, v50, s88
	v_add_u32_e32 v48, v0, v67
	v_add_u32_e32 v0, v0, v69
	v_mad_u64_u32 v[48:49], s[6:7], v48, s5, v[68:69]
	v_mad_u64_u32 v[44:45], s[6:7], v0, s5, v[68:69]
	v_and_b32_e32 v49, 0x78, v67
	v_lshlrev_b32_e32 v49, 4, v49
	v_xor_b32_e32 v48, v48, v49
	v_mov_b32_e32 v49, v1
	v_and_b32_e32 v45, 0x78, v69
	v_lshlrev_b32_e32 v45, 4, v45
	v_xor_b32_e32 v44, v44, v45
	v_mov_b32_e32 v45, v1
	v_cvt_pk_bf16_f32 v0, v38, s0
	v_add_u32_e32 v38, v66, v77
	v_lshl_add_u64 v[48:49], v[48:49], 1, s[10:11]
	v_lshl_add_u64 v[44:45], v[44:45], 1, s[10:11]
	v_xor_b32_e32 v38, v38, v77
	global_store_dwordx2 v[48:49], v[46:47], off
	global_store_dwordx2 v[44:45], v[42:43], off
	v_mul_hi_u32 v42, v38, v132
	v_mul_lo_u32 v43, v42, s24
	v_sub_u32_e32 v38, v38, v43
	v_cmp_le_u32_e32 vcc, s24, v38
	v_add_u32_e32 v43, 1, v42
	v_cvt_pk_bf16_f32 v44, v85, s0
	v_cndmask_b32_e32 v42, v42, v43, vcc
	v_subrev_u32_e32 v43, s24, v38
	v_cndmask_b32_e32 v38, v38, v43, vcc
	v_cmp_le_u32_e32 vcc, s24, v38
	v_add_u32_e32 v38, 1, v42
	v_cvt_pk_bf16_f32 v43, v93, s0
	v_cndmask_b32_e32 v38, v42, v38, vcc
	v_xor_b32_e32 v38, v38, v102
	v_sub_u32_e32 v42, v38, v102
	v_cvt_pk_bf16_f32 v38, v39, s0
	v_lshlrev_b32_e32 v38, 16, v38
	v_or_b32_sdwa v38, v38, v0 dst_sel:DWORD dst_unused:UNUSED_PAD src0_sel:DWORD src1_sel:WORD_0
	v_cvt_pk_bf16_f32 v39, v40, v41
	v_mul_lo_u32 v0, v42, s88
	v_add_u32_e32 v40, v0, v67
	v_mad_u64_u32 v[40:41], s[6:7], v40, s5, v[66:67]
	v_add_u32_e32 v0, v0, v69
	v_and_b32_e32 v41, 0x78, v67
	v_lshlrev_b32_e32 v41, 4, v41
	v_xor_b32_e32 v40, v40, v41
	v_mov_b32_e32 v41, v1
	v_mad_u64_u32 v[36:37], s[6:7], v0, s5, v[66:67]
	v_lshl_add_u64 v[40:41], v[40:41], 1, s[10:11]
	v_and_b32_e32 v37, 0x78, v69
	v_lshlrev_b32_e32 v37, 4, v37
	v_xor_b32_e32 v36, v36, v37
	v_mov_b32_e32 v37, v1
	global_store_dwordx2 v[40:41], v[38:39], off
	v_lshl_add_u64 v[36:37], v[36:37], 1, s[10:11]
	v_add_u32_e32 v40, 0x80, v70
	global_store_dwordx2 v[36:37], v[34:35], off
	v_lshlrev_b32_e32 v36, 10, v40
	v_or_b32_e32 v37, 0x400, v36
	v_add_u32_e32 v0, v36, v67
	v_or_b32_e32 v38, 0x800, v36
	v_cvt_pk_bf16_f32 v41, v109, s0
	v_lshl_add_u64 v[34:35], v[0:1], 1, s[8:9]
	v_add_u32_e32 v0, v37, v67
	v_or_b32_e32 v39, 0xc00, v36
	global_store_short v[34:35], v41, off
	v_cvt_pk_bf16_f32 v41, v98, s0
	v_lshl_add_u64 v[34:35], v[0:1], 1, s[8:9]
	v_add_u32_e32 v0, v38, v67
	global_store_short v[34:35], v41, off
	v_cvt_pk_bf16_f32 v41, v99, s0
	v_lshl_add_u64 v[34:35], v[0:1], 1, s[8:9]
	v_add_u32_e32 v0, v39, v67
	global_store_short v[34:35], v41, off
	v_cvt_pk_bf16_f32 v41, v100, s0
	v_lshl_add_u64 v[34:35], v[0:1], 1, s[8:9]
	v_add_u32_e32 v0, v69, v36
	global_store_short v[34:35], v41, off
	v_cvt_pk_bf16_f32 v41, v94, s0
	v_lshl_add_u64 v[34:35], v[0:1], 1, s[8:9]
	v_add_u32_e32 v0, v37, v69
	global_store_short v[34:35], v41, off
	v_cvt_pk_bf16_f32 v36, v95, s0
	v_lshl_add_u64 v[34:35], v[0:1], 1, s[8:9]
	v_add_u32_e32 v0, v38, v69
	global_store_short v[34:35], v36, off
	v_cvt_pk_bf16_f32 v36, v96, s0
	v_lshl_add_u64 v[34:35], v[0:1], 1, s[8:9]
	v_add_u32_e32 v0, v39, v69
	global_store_short v[34:35], v36, off
	v_cvt_pk_bf16_f32 v36, v97, s0
	v_lshl_add_u64 v[34:35], v[0:1], 1, s[8:9]
	v_add_u32_e32 v38, 0x90, v70
	global_store_short v[34:35], v36, off
	v_lshlrev_b32_e32 v36, 10, v38
	v_or_b32_e32 v37, 0x400, v36
	v_add_u32_e32 v0, v36, v67
	v_or_b32_e32 v39, 0x800, v36
	v_cvt_pk_bf16_f32 v42, v101, s0
	v_lshl_add_u64 v[34:35], v[0:1], 1, s[8:9]
	v_add_u32_e32 v0, v37, v67
	v_or_b32_e32 v41, 0xc00, v36
	global_store_short v[34:35], v42, off
	v_cvt_pk_bf16_f32 v42, v90, s0
	v_lshl_add_u64 v[34:35], v[0:1], 1, s[8:9]
	v_add_u32_e32 v0, v39, v67
	global_store_short v[34:35], v42, off
	v_cvt_pk_bf16_f32 v42, v91, s0
	v_lshl_add_u64 v[34:35], v[0:1], 1, s[8:9]
	v_add_u32_e32 v0, v41, v67
	global_store_short v[34:35], v42, off
	v_cvt_pk_bf16_f32 v42, v92, s0
	v_lshl_add_u64 v[34:35], v[0:1], 1, s[8:9]
	v_add_u32_e32 v0, v69, v36
	global_store_short v[34:35], v42, off
	v_cvt_pk_bf16_f32 v42, v86, s0
	v_lshl_add_u64 v[34:35], v[0:1], 1, s[8:9]
	v_add_u32_e32 v0, v37, v69
	global_store_short v[34:35], v42, off
	v_cvt_pk_bf16_f32 v36, v87, s0
	v_lshl_add_u64 v[34:35], v[0:1], 1, s[8:9]
	v_add_u32_e32 v0, v39, v69
	global_store_short v[34:35], v36, off
	v_cvt_pk_bf16_f32 v36, v88, s0
	v_lshl_add_u64 v[34:35], v[0:1], 1, s[8:9]
	v_add_u32_e32 v0, v41, v69
	global_store_short v[34:35], v36, off
	v_cvt_pk_bf16_f32 v36, v89, s0
	v_lshl_add_u64 v[34:35], v[0:1], 1, s[8:9]
	global_store_short v[34:35], v36, off
	v_add_u32_e32 v36, 0xa0, v70
	v_lshlrev_b32_e32 v37, 10, v36
	v_or_b32_e32 v39, 0x400, v37
	v_add_u32_e32 v0, v37, v67
	v_or_b32_e32 v41, 0x800, v37
	v_lshl_add_u64 v[34:35], v[0:1], 1, s[8:9]
	v_add_u32_e32 v0, v39, v67
	v_or_b32_e32 v42, 0xc00, v37
	global_store_short v[34:35], v43, off
	v_cvt_pk_bf16_f32 v43, v82, s0
	v_lshl_add_u64 v[34:35], v[0:1], 1, s[8:9]
	v_add_u32_e32 v0, v41, v67
	global_store_short v[34:35], v43, off
	v_cvt_pk_bf16_f32 v43, v83, s0
	v_lshl_add_u64 v[34:35], v[0:1], 1, s[8:9]
	v_add_u32_e32 v0, v42, v67
	global_store_short v[34:35], v43, off
	v_cvt_pk_bf16_f32 v43, v84, s0
	v_lshl_add_u64 v[34:35], v[0:1], 1, s[8:9]
	v_add_u32_e32 v0, v69, v37
	global_store_short v[34:35], v43, off
	v_cvt_pk_bf16_f32 v43, v78, s0
	v_lshl_add_u64 v[34:35], v[0:1], 1, s[8:9]
	v_add_u32_e32 v0, v39, v69
	global_store_short v[34:35], v43, off
	v_cvt_pk_bf16_f32 v37, v79, s0
	v_lshl_add_u64 v[34:35], v[0:1], 1, s[8:9]
	v_add_u32_e32 v0, v41, v69
	global_store_short v[34:35], v37, off
	v_cvt_pk_bf16_f32 v37, v80, s0
	v_lshl_add_u64 v[34:35], v[0:1], 1, s[8:9]
	v_add_u32_e32 v0, v42, v69
	global_store_short v[34:35], v37, off
	v_cvt_pk_bf16_f32 v37, v81, s0
	v_lshl_add_u64 v[34:35], v[0:1], 1, s[8:9]
	global_store_short v[34:35], v37, off
	v_add_u32_e32 v34, 0xb0, v70
	v_lshlrev_b32_e32 v35, 10, v34
	v_or_b32_e32 v37, 0x400, v35
	v_add_u32_e32 v0, v35, v67
	v_or_b32_e32 v39, 0x800, v35
	v_lshl_add_u64 v[42:43], v[0:1], 1, s[8:9]
	v_add_u32_e32 v0, v37, v67
	v_or_b32_e32 v41, 0xc00, v35
	global_store_short v[42:43], v44, off
	v_cvt_pk_bf16_f32 v44, v142, s0
	v_lshl_add_u64 v[42:43], v[0:1], 1, s[8:9]
	v_add_u32_e32 v0, v39, v67
	global_store_short v[42:43], v44, off
	v_cvt_pk_bf16_f32 v44, v130, s0
	v_lshl_add_u64 v[42:43], v[0:1], 1, s[8:9]
	v_add_u32_e32 v0, v41, v67
	global_store_short v[42:43], v44, off
	v_cvt_pk_bf16_f32 v44, v76, s0
	v_lshl_add_u64 v[42:43], v[0:1], 1, s[8:9]
	v_add_u32_e32 v0, v69, v35
	global_store_short v[42:43], v44, off
	v_cvt_pk_bf16_f32 v44, v74, s0
	v_lshl_add_u64 v[42:43], v[0:1], 1, s[8:9]
	v_add_u32_e32 v0, v37, v69
	global_store_short v[42:43], v44, off
	v_cvt_pk_bf16_f32 v35, v71, s0
	v_lshl_add_u64 v[42:43], v[0:1], 1, s[8:9]
	v_add_u32_e32 v0, v39, v69
	global_store_short v[42:43], v35, off
	v_cvt_pk_bf16_f32 v35, v75, s0
	v_lshl_add_u64 v[42:43], v[0:1], 1, s[8:9]
	v_add_u32_e32 v0, v41, v69
	global_store_short v[42:43], v35, off
	v_cvt_pk_bf16_f32 v35, v73, s0
	v_lshl_add_u64 v[42:43], v[0:1], 1, s[8:9]
	global_store_short v[42:43], v35, off
	v_sub_u32_e32 v35, 0, v40
	v_max_i32_e32 v35, v40, v35
	v_mul_hi_u32 v37, v35, v132
	v_mul_lo_u32 v39, v37, s24
	v_sub_u32_e32 v35, v35, v39
	v_cmp_le_u32_e32 vcc, s24, v35
	v_add_u32_e32 v39, 1, v37
	v_cvt_pk_bf16_f32 v0, v30, s0
	v_cndmask_b32_e32 v37, v37, v39, vcc
	v_subrev_u32_e32 v39, s24, v35
	v_cndmask_b32_e32 v35, v35, v39, vcc
	v_ashrrev_i32_e32 v30, 31, v40
	v_cmp_le_u32_e32 vcc, s24, v35
	v_add_u32_e32 v35, 1, v37
	v_xor_b32_e32 v30, s27, v30
	v_cndmask_b32_e32 v35, v37, v35, vcc
	v_xor_b32_e32 v35, v35, v30
	v_sub_u32_e32 v35, v35, v30
	v_cvt_pk_bf16_f32 v30, v31, s0
	v_lshlrev_b32_e32 v30, 16, v30
	v_or_b32_sdwa v30, v30, v0 dst_sel:DWORD dst_unused:UNUSED_PAD src0_sel:DWORD src1_sel:WORD_0
	v_cvt_pk_bf16_f32 v31, v32, v33
	v_mul_lo_u32 v0, v35, s88
	v_add_u32_e32 v32, v0, v67
	v_add_u32_e32 v0, v0, v69
	v_mad_u64_u32 v[32:33], s[6:7], v32, s5, v[40:41]
	v_mad_u64_u32 v[28:29], s[6:7], v0, s5, v[40:41]
	v_and_b32_e32 v33, 0x78, v67
	v_lshlrev_b32_e32 v33, 4, v33
	v_xor_b32_e32 v32, v32, v33
	v_mov_b32_e32 v33, v1
	v_and_b32_e32 v29, 0x78, v69
	v_lshlrev_b32_e32 v29, 4, v29
	v_xor_b32_e32 v28, v28, v29
	v_mov_b32_e32 v29, v1
	v_lshl_add_u64 v[32:33], v[32:33], 1, s[10:11]
	v_lshl_add_u64 v[28:29], v[28:29], 1, s[10:11]
	global_store_dwordx2 v[32:33], v[30:31], off
	global_store_dwordx2 v[28:29], v[26:27], off
	v_sub_u32_e32 v26, 0, v38
	v_max_i32_e32 v26, v38, v26
	v_mul_hi_u32 v27, v26, v132
	v_mul_lo_u32 v28, v27, s24
	v_sub_u32_e32 v26, v26, v28
	v_cmp_le_u32_e32 vcc, s24, v26
	v_add_u32_e32 v28, 1, v27
	v_cvt_pk_bf16_f32 v0, v22, s0
	v_cndmask_b32_e32 v27, v27, v28, vcc
	v_subrev_u32_e32 v28, s24, v26
	v_cndmask_b32_e32 v26, v26, v28, vcc
	v_ashrrev_i32_e32 v22, 31, v38
	v_cmp_le_u32_e32 vcc, s24, v26
	v_add_u32_e32 v26, 1, v27
	v_xor_b32_e32 v22, s27, v22
	v_cndmask_b32_e32 v26, v27, v26, vcc
	v_xor_b32_e32 v26, v26, v22
	v_sub_u32_e32 v26, v26, v22
	v_cvt_pk_bf16_f32 v22, v23, s0
	v_lshlrev_b32_e32 v22, 16, v22
	v_or_b32_sdwa v22, v22, v0 dst_sel:DWORD dst_unused:UNUSED_PAD src0_sel:DWORD src1_sel:WORD_0
	v_cvt_pk_bf16_f32 v23, v24, v25
	v_mul_lo_u32 v0, v26, s88
	v_add_u32_e32 v24, v0, v67
	v_add_u32_e32 v0, v0, v69
	v_mad_u64_u32 v[24:25], s[6:7], v24, s5, v[38:39]
	v_mad_u64_u32 v[20:21], s[6:7], v0, s5, v[38:39]
	v_and_b32_e32 v25, 0x78, v67
	v_lshlrev_b32_e32 v25, 4, v25
	v_xor_b32_e32 v24, v24, v25
	v_mov_b32_e32 v25, v1
	v_and_b32_e32 v21, 0x78, v69
	v_lshlrev_b32_e32 v21, 4, v21
	v_xor_b32_e32 v20, v20, v21
	v_mov_b32_e32 v21, v1
	v_lshl_add_u64 v[24:25], v[24:25], 1, s[10:11]
	v_lshl_add_u64 v[20:21], v[20:21], 1, s[10:11]
	global_store_dwordx2 v[24:25], v[22:23], off
	global_store_dwordx2 v[20:21], v[18:19], off
	v_sub_u32_e32 v18, 0, v36
	v_max_i32_e32 v18, v36, v18
	v_mul_hi_u32 v19, v18, v132
	v_mul_lo_u32 v20, v19, s24
	v_sub_u32_e32 v18, v18, v20
	v_cmp_le_u32_e32 vcc, s24, v18
	v_add_u32_e32 v20, 1, v19
	v_cvt_pk_bf16_f32 v0, v14, s0
	v_cndmask_b32_e32 v19, v19, v20, vcc
	v_subrev_u32_e32 v20, s24, v18
	v_cndmask_b32_e32 v18, v18, v20, vcc
	v_ashrrev_i32_e32 v14, 31, v36
	v_cmp_le_u32_e32 vcc, s24, v18
	v_add_u32_e32 v18, 1, v19
	v_xor_b32_e32 v14, s27, v14
	v_cndmask_b32_e32 v18, v19, v18, vcc
	v_xor_b32_e32 v18, v18, v14
	v_sub_u32_e32 v18, v18, v14
	v_cvt_pk_bf16_f32 v14, v15, s0
	v_lshlrev_b32_e32 v14, 16, v14
	v_or_b32_sdwa v14, v14, v0 dst_sel:DWORD dst_unused:UNUSED_PAD src0_sel:DWORD src1_sel:WORD_0
	v_cvt_pk_bf16_f32 v15, v16, v17
	v_mul_lo_u32 v0, v18, s88
	v_add_u32_e32 v16, v0, v67
	v_add_u32_e32 v0, v0, v69
	v_mad_u64_u32 v[16:17], s[6:7], v16, s5, v[36:37]
	v_mad_u64_u32 v[12:13], s[6:7], v0, s5, v[36:37]
	v_and_b32_e32 v17, 0x78, v67
	v_lshlrev_b32_e32 v17, 4, v17
	v_xor_b32_e32 v16, v16, v17
	v_mov_b32_e32 v17, v1
	v_and_b32_e32 v13, 0x78, v69
	v_lshlrev_b32_e32 v13, 4, v13
	v_xor_b32_e32 v12, v12, v13
	v_mov_b32_e32 v13, v1
	v_lshl_add_u64 v[16:17], v[16:17], 1, s[10:11]
	v_lshl_add_u64 v[12:13], v[12:13], 1, s[10:11]
	global_store_dwordx2 v[16:17], v[14:15], off
	global_store_dwordx2 v[12:13], v[10:11], off
	v_sub_u32_e32 v10, 0, v34
	v_max_i32_e32 v10, v34, v10
	v_mul_hi_u32 v11, v10, v132
	v_mul_lo_u32 v12, v11, s24
	v_sub_u32_e32 v10, v10, v12
	v_cmp_le_u32_e32 vcc, s24, v10
	v_add_u32_e32 v12, 1, v11
	v_cvt_pk_bf16_f32 v0, v6, s0
	v_cndmask_b32_e32 v11, v11, v12, vcc
	v_subrev_u32_e32 v12, s24, v10
	v_cndmask_b32_e32 v10, v10, v12, vcc
	v_ashrrev_i32_e32 v6, 31, v34
	v_cmp_le_u32_e32 vcc, s24, v10
	v_add_u32_e32 v10, 1, v11
	v_xor_b32_e32 v6, s27, v6
	v_cndmask_b32_e32 v10, v11, v10, vcc
	v_xor_b32_e32 v10, v10, v6
	v_sub_u32_e32 v10, v10, v6
	v_cvt_pk_bf16_f32 v6, v7, s0
	v_lshlrev_b32_e32 v6, 16, v6
	v_or_b32_sdwa v6, v6, v0 dst_sel:DWORD dst_unused:UNUSED_PAD src0_sel:DWORD src1_sel:WORD_0
	v_cvt_pk_bf16_f32 v7, v8, v9
	v_mul_lo_u32 v0, v10, s88
	v_add_u32_e32 v8, v0, v67
	v_add_u32_e32 v0, v0, v69
	v_mad_u64_u32 v[8:9], s[6:7], v8, s5, v[34:35]
	v_mad_u64_u32 v[4:5], s[6:7], v0, s5, v[34:35]
	v_and_b32_e32 v9, 0x78, v67
	v_lshlrev_b32_e32 v9, 4, v9
	v_xor_b32_e32 v8, v8, v9
	v_mov_b32_e32 v9, v1
	v_and_b32_e32 v5, 0x78, v69
	v_lshlrev_b32_e32 v5, 4, v5
	v_xor_b32_e32 v4, v4, v5
	v_mov_b32_e32 v5, v1
	v_lshl_add_u64 v[8:9], v[8:9], 1, s[10:11]
	v_lshl_add_u64 v[4:5], v[4:5], 1, s[10:11]
	global_store_dwordx2 v[8:9], v[6:7], off
	global_store_dwordx2 v[4:5], v[2:3], off

.LBB0_1052:
	v_add_u32_e32 v140, 0x10000, v143
	s_waitcnt vmcnt(0)
	ds_read_b128 v[146:149], v140
	ds_read_b128 v[150:153], v140 offset:1024
	ds_read_b128 v[154:157], v140 offset:2048
	ds_read_b128 v[158:161], v140 offset:3072
	s_add_u32 s6, s20, 0x100
	s_addc_u32 s7, s21, 0
	s_cmp_eq_u32 s94, 2
	s_cselect_b32 s25, s17, s7
	s_cselect_b32 s24, s16, s6
	s_cselect_b32 s23, s19, s93
	s_cselect_b32 s22, s18, s92
	v_lshl_add_u64 v[178:179], s[20:21], 0, v[136:137]
	s_add_i32 m0, s26, 0xc000
	ds_read_b128 v[162:165], v142
	ds_read_b128 v[166:169], v142 offset:1024
	ds_read_b128 v[170:173], v142 offset:2048
	ds_read_b128 v[174:177], v142 offset:3072
	ds_read_b128 v[182:185], v142 offset:4096
	ds_read_b128 v[186:189], v142 offset:5120
	ds_read_b128 v[190:193], v142 offset:6144
	ds_read_b128 v[194:197], v142 offset:7168
	global_load_lds_dwordx4 v[178:179], off
	v_lshl_add_u64 v[178:179], s[20:21], 0, v[138:139]
	s_add_i32 m0, s26, 0xe000
	s_nop 0
	global_load_lds_dwordx4 v[178:179], off
	s_waitcnt lgkmcnt(8)
	s_barrier
	s_waitcnt lgkmcnt(0)
	s_setprio 1
	s_waitcnt lgkmcnt(0)
	v_mfma_f32_16x16x32_bf16 v[126:129], v[146:149], v[162:165], v[126:129]
	v_mfma_f32_16x16x32_bf16 v[122:125], v[154:157], v[162:165], v[122:125]
	v_mfma_f32_16x16x32_bf16 v[114:117], v[146:149], v[170:173], v[114:117]
	v_mfma_f32_16x16x32_bf16 v[106:109], v[154:157], v[170:173], v[106:109]
	v_mfma_f32_16x16x32_bf16 v[98:101], v[146:149], v[182:185], v[98:101]
	v_mfma_f32_16x16x32_bf16 v[90:93], v[154:157], v[182:185], v[90:93]
	v_mfma_f32_16x16x32_bf16 v[82:85], v[146:149], v[190:193], v[82:85]
	v_mfma_f32_16x16x32_bf16 v[74:77], v[154:157], v[190:193], v[74:77]
	v_mfma_f32_16x16x32_bf16 v[126:129], v[150:153], v[166:169], v[126:129]
	v_mfma_f32_16x16x32_bf16 v[122:125], v[158:161], v[166:169], v[122:125]
	v_mfma_f32_16x16x32_bf16 v[114:117], v[150:153], v[174:177], v[114:117]
	v_mfma_f32_16x16x32_bf16 v[106:109], v[158:161], v[174:177], v[106:109]
	v_mfma_f32_16x16x32_bf16 v[98:101], v[150:153], v[186:189], v[98:101]
	v_mfma_f32_16x16x32_bf16 v[90:93], v[158:161], v[186:189], v[90:93]
	v_mfma_f32_16x16x32_bf16 v[82:85], v[150:153], v[194:197], v[82:85]
	v_mfma_f32_16x16x32_bf16 v[74:77], v[158:161], v[194:197], v[74:77]
	s_setprio 0
	s_barrier
	s_mov_b32 m0, s27
	v_add_u32_e32 v140, 0x14000, v143
	v_lshl_add_u64 v[178:179], s[22:23], 0, v[0:1]
	s_waitcnt vmcnt(0)
	ds_read_b128 v[198:201], v140
	ds_read_b128 v[202:205], v140 offset:1024
	ds_read_b128 v[206:209], v140 offset:2048
	ds_read_b128 v[210:213], v140 offset:3072
	global_load_lds_dwordx4 v[178:179], off
	v_lshl_add_u64 v[214:215], s[22:23], 0, v[134:135]
	s_mov_b32 m0, s28
	s_nop 0
	global_load_lds_dwordx4 v[214:215], off
	s_barrier
	s_waitcnt lgkmcnt(0)
	s_setprio 1
	s_waitcnt lgkmcnt(0)
	v_mfma_f32_16x16x32_bf16 v[118:121], v[198:201], v[162:165], v[118:121]
	v_mfma_f32_16x16x32_bf16 v[110:113], v[206:209], v[162:165], v[110:113]
	v_mfma_f32_16x16x32_bf16 v[102:105], v[198:201], v[170:173], v[102:105]
	v_mfma_f32_16x16x32_bf16 v[94:97], v[206:209], v[170:173], v[94:97]
	v_mfma_f32_16x16x32_bf16 v[86:89], v[198:201], v[182:185], v[86:89]
	v_mfma_f32_16x16x32_bf16 v[78:81], v[206:209], v[182:185], v[78:81]
	v_mfma_f32_16x16x32_bf16 v[70:73], v[198:201], v[190:193], v[70:73]
	v_mfma_f32_16x16x32_bf16 v[66:69], v[206:209], v[190:193], v[66:69]
	v_mfma_f32_16x16x32_bf16 v[118:121], v[202:205], v[166:169], v[118:121]
	v_mfma_f32_16x16x32_bf16 v[110:113], v[210:213], v[166:169], v[110:113]
	v_mfma_f32_16x16x32_bf16 v[102:105], v[202:205], v[174:177], v[102:105]
	v_mfma_f32_16x16x32_bf16 v[94:97], v[210:213], v[174:177], v[94:97]
	v_mfma_f32_16x16x32_bf16 v[86:89], v[202:205], v[186:189], v[86:89]
	v_mfma_f32_16x16x32_bf16 v[78:81], v[210:213], v[186:189], v[78:81]
	v_mfma_f32_16x16x32_bf16 v[70:73], v[202:205], v[194:197], v[70:73]
	v_mfma_f32_16x16x32_bf16 v[66:69], v[210:213], v[194:197], v[66:69]
	s_setprio 0
	s_mov_b32 m0, s26
	v_lshl_add_u64 v[216:217], s[24:25], 0, v[130:131]
	s_barrier
	s_waitcnt vmcnt(0)
	ds_read_b128 v[162:165], v142 offset:16384
	ds_read_b128 v[166:169], v142 offset:17408
	ds_read_b128 v[170:173], v142 offset:18432
	ds_read_b128 v[174:177], v142 offset:19456
	ds_read_b128 v[182:185], v142 offset:20480
	ds_read_b128 v[186:189], v142 offset:21504
	ds_read_b128 v[190:193], v142 offset:22528
	ds_read_b128 v[194:197], v142 offset:23552
	global_load_lds_dwordx4 v[216:217], off
	v_lshl_add_u64 v[222:223], s[24:25], 0, v[132:133]
	s_mov_b32 m0, s29
	s_nop 0
	global_load_lds_dwordx4 v[222:223], off
	s_barrier
	s_waitcnt lgkmcnt(0)
	s_setprio 1
	s_waitcnt lgkmcnt(0)
	v_mfma_f32_16x16x32_bf16 v[62:65], v[146:149], v[162:165], v[62:65]
	v_mfma_f32_16x16x32_bf16 v[58:61], v[154:157], v[162:165], v[58:61]
	v_mfma_f32_16x16x32_bf16 v[50:53], v[146:149], v[170:173], v[50:53]
	v_mfma_f32_16x16x32_bf16 v[42:45], v[154:157], v[170:173], v[42:45]
	v_mfma_f32_16x16x32_bf16 v[34:37], v[146:149], v[182:185], v[34:37]
	v_mfma_f32_16x16x32_bf16 v[26:29], v[154:157], v[182:185], v[26:29]
	v_mfma_f32_16x16x32_bf16 v[18:21], v[146:149], v[190:193], v[18:21]
	v_mfma_f32_16x16x32_bf16 v[10:13], v[154:157], v[190:193], v[10:13]
	v_mfma_f32_16x16x32_bf16 v[62:65], v[150:153], v[166:169], v[62:65]
	v_mfma_f32_16x16x32_bf16 v[58:61], v[158:161], v[166:169], v[58:61]
	v_mfma_f32_16x16x32_bf16 v[50:53], v[150:153], v[174:177], v[50:53]
	v_mfma_f32_16x16x32_bf16 v[42:45], v[158:161], v[174:177], v[42:45]
	v_mfma_f32_16x16x32_bf16 v[34:37], v[150:153], v[186:189], v[34:37]
	v_mfma_f32_16x16x32_bf16 v[26:29], v[158:161], v[186:189], v[26:29]
	v_mfma_f32_16x16x32_bf16 v[18:21], v[150:153], v[194:197], v[18:21]
	v_mfma_f32_16x16x32_bf16 v[10:13], v[158:161], v[194:197], v[10:13]
	s_setprio 0
	s_barrier
	s_add_u32 s20, s22, 0x18000
	s_addc_u32 s21, s23, 0
	s_mov_b32 m0, s30
	v_lshl_add_u64 v[146:147], s[20:21], 0, v[0:1]
	global_load_lds_dwordx4 v[146:147], off
	v_lshl_add_u64 v[146:147], s[20:21], 0, v[134:135]
	s_mov_b32 m0, s31
	s_nop 0
	global_load_lds_dwordx4 v[146:147], off
	s_waitcnt vmcnt(6)
	s_barrier
	s_setprio 1
	v_mfma_f32_16x16x32_bf16 v[54:57], v[198:201], v[162:165], v[54:57]
	v_mfma_f32_16x16x32_bf16 v[46:49], v[206:209], v[162:165], v[46:49]
	v_mfma_f32_16x16x32_bf16 v[38:41], v[198:201], v[170:173], v[38:41]
	v_mfma_f32_16x16x32_bf16 v[30:33], v[206:209], v[170:173], v[30:33]
	v_mfma_f32_16x16x32_bf16 v[22:25], v[198:201], v[182:185], v[22:25]
	v_mfma_f32_16x16x32_bf16 v[14:17], v[206:209], v[182:185], v[14:17]
	v_mfma_f32_16x16x32_bf16 v[6:9], v[198:201], v[190:193], v[6:9]
	v_mfma_f32_16x16x32_bf16 v[2:5], v[206:209], v[190:193], v[2:5]
	v_mfma_f32_16x16x32_bf16 v[54:57], v[202:205], v[166:169], v[54:57]
	v_mfma_f32_16x16x32_bf16 v[46:49], v[210:213], v[166:169], v[46:49]
	v_mfma_f32_16x16x32_bf16 v[38:41], v[202:205], v[174:177], v[38:41]
	v_mfma_f32_16x16x32_bf16 v[30:33], v[210:213], v[174:177], v[30:33]
	v_mfma_f32_16x16x32_bf16 v[22:25], v[202:205], v[186:189], v[22:25]
	v_mfma_f32_16x16x32_bf16 v[14:17], v[210:213], v[186:189], v[14:17]
	v_mfma_f32_16x16x32_bf16 v[6:9], v[202:205], v[194:197], v[6:9]
	v_mfma_f32_16x16x32_bf16 v[2:5], v[210:213], v[194:197], v[2:5]
	s_setprio 0
	v_add_u32_e32 v140, 0x18000, v143
	s_barrier
	s_waitcnt vmcnt(0)
	ds_read_b128 v[146:149], v140
	ds_read_b128 v[150:153], v140 offset:1024
	ds_read_b128 v[154:157], v140 offset:2048
	ds_read_b128 v[158:161], v140 offset:3072
	s_add_u32 s20, s24, 0x18000
	s_addc_u32 s21, s25, 0
	s_mov_b32 m0, s34
	v_lshl_add_u64 v[198:199], s[20:21], 0, v[130:131]
	ds_read_b128 v[162:165], v142 offset:32768
	ds_read_b128 v[166:169], v142 offset:33792
	ds_read_b128 v[170:173], v142 offset:34816
	ds_read_b128 v[174:177], v142 offset:35840
	ds_read_b128 v[182:185], v142 offset:36864
	ds_read_b128 v[186:189], v142 offset:37888
	ds_read_b128 v[190:193], v142 offset:38912
	ds_read_b128 v[194:197], v142 offset:39936
	global_load_lds_dwordx4 v[198:199], off
	v_lshl_add_u64 v[198:199], s[20:21], 0, v[132:133]
	s_mov_b32 m0, s35
	s_nop 0
	global_load_lds_dwordx4 v[198:199], off
	s_waitcnt lgkmcnt(8)
	s_barrier
	s_waitcnt lgkmcnt(0)
	s_setprio 1
	s_waitcnt lgkmcnt(0)
	v_mfma_f32_16x16x32_bf16 v[126:129], v[146:149], v[162:165], v[126:129]
	v_mfma_f32_16x16x32_bf16 v[122:125], v[154:157], v[162:165], v[122:125]
	v_mfma_f32_16x16x32_bf16 v[114:117], v[146:149], v[170:173], v[114:117]
	v_mfma_f32_16x16x32_bf16 v[106:109], v[154:157], v[170:173], v[106:109]
	v_mfma_f32_16x16x32_bf16 v[98:101], v[146:149], v[182:185], v[98:101]
	v_mfma_f32_16x16x32_bf16 v[90:93], v[154:157], v[182:185], v[90:93]
	v_mfma_f32_16x16x32_bf16 v[82:85], v[146:149], v[190:193], v[82:85]
	v_mfma_f32_16x16x32_bf16 v[74:77], v[154:157], v[190:193], v[74:77]
	v_mfma_f32_16x16x32_bf16 v[126:129], v[150:153], v[166:169], v[126:129]
	v_mfma_f32_16x16x32_bf16 v[122:125], v[158:161], v[166:169], v[122:125]
	v_mfma_f32_16x16x32_bf16 v[114:117], v[150:153], v[174:177], v[114:117]
	v_mfma_f32_16x16x32_bf16 v[106:109], v[158:161], v[174:177], v[106:109]
	v_mfma_f32_16x16x32_bf16 v[98:101], v[150:153], v[186:189], v[98:101]
	v_mfma_f32_16x16x32_bf16 v[90:93], v[158:161], v[186:189], v[90:93]
	v_mfma_f32_16x16x32_bf16 v[82:85], v[150:153], v[194:197], v[82:85]
	v_mfma_f32_16x16x32_bf16 v[74:77], v[158:161], v[194:197], v[74:77]
	s_setprio 0
	s_barrier
	s_mov_b32 m0, s36
	v_add_u32_e32 v140, 0x1c000, v143
	v_lshl_add_u64 v[178:179], v[178:179], 0, s[84:85]
	s_waitcnt vmcnt(0)
	ds_read_b128 v[198:201], v140
	ds_read_b128 v[202:205], v140 offset:1024
	ds_read_b128 v[206:209], v140 offset:2048
	ds_read_b128 v[210:213], v140 offset:3072
	global_load_lds_dwordx4 v[178:179], off
	v_lshl_add_u64 v[178:179], v[214:215], 0, s[84:85]
	s_mov_b32 m0, s37
	s_nop 0
	global_load_lds_dwordx4 v[178:179], off
	s_barrier
	s_waitcnt lgkmcnt(0)
	s_setprio 1
	s_waitcnt lgkmcnt(0)
	v_mfma_f32_16x16x32_bf16 v[118:121], v[198:201], v[162:165], v[118:121]
	v_mfma_f32_16x16x32_bf16 v[110:113], v[206:209], v[162:165], v[110:113]
	v_mfma_f32_16x16x32_bf16 v[102:105], v[198:201], v[170:173], v[102:105]
	v_mfma_f32_16x16x32_bf16 v[94:97], v[206:209], v[170:173], v[94:97]
	v_mfma_f32_16x16x32_bf16 v[86:89], v[198:201], v[182:185], v[86:89]
	v_mfma_f32_16x16x32_bf16 v[78:81], v[206:209], v[182:185], v[78:81]
	v_mfma_f32_16x16x32_bf16 v[70:73], v[198:201], v[190:193], v[70:73]
	v_mfma_f32_16x16x32_bf16 v[66:69], v[206:209], v[190:193], v[66:69]
	v_mfma_f32_16x16x32_bf16 v[118:121], v[202:205], v[166:169], v[118:121]
	v_mfma_f32_16x16x32_bf16 v[110:113], v[210:213], v[166:169], v[110:113]
	v_mfma_f32_16x16x32_bf16 v[102:105], v[202:205], v[174:177], v[102:105]
	v_mfma_f32_16x16x32_bf16 v[94:97], v[210:213], v[174:177], v[94:97]
	v_mfma_f32_16x16x32_bf16 v[86:89], v[202:205], v[186:189], v[86:89]
	v_mfma_f32_16x16x32_bf16 v[78:81], v[210:213], v[186:189], v[78:81]
	v_mfma_f32_16x16x32_bf16 v[70:73], v[202:205], v[194:197], v[70:73]
	v_mfma_f32_16x16x32_bf16 v[66:69], v[210:213], v[194:197], v[66:69]
	s_setprio 0
	s_mov_b32 m0, s38
	v_lshl_add_u64 v[178:179], v[216:217], 0, s[84:85]
	s_barrier
	s_waitcnt vmcnt(0)
	ds_read_b128 v[162:165], v142 offset:49152
	ds_read_b128 v[166:169], v142 offset:50176
	ds_read_b128 v[170:173], v142 offset:51200
	ds_read_b128 v[174:177], v142 offset:52224
	ds_read_b128 v[182:185], v142 offset:53248
	ds_read_b128 v[186:189], v142 offset:54272
	ds_read_b128 v[190:193], v142 offset:55296
	ds_read_b128 v[194:197], v142 offset:56320
	global_load_lds_dwordx4 v[178:179], off
	v_lshl_add_u64 v[178:179], v[222:223], 0, s[84:85]
	s_mov_b32 m0, s39
	s_nop 0
	global_load_lds_dwordx4 v[178:179], off
	s_barrier
	s_waitcnt lgkmcnt(0)
	s_setprio 1
	s_waitcnt lgkmcnt(0)
	v_mfma_f32_16x16x32_bf16 v[62:65], v[146:149], v[162:165], v[62:65]
	v_mfma_f32_16x16x32_bf16 v[58:61], v[154:157], v[162:165], v[58:61]
	v_mfma_f32_16x16x32_bf16 v[50:53], v[146:149], v[170:173], v[50:53]
	v_mfma_f32_16x16x32_bf16 v[42:45], v[154:157], v[170:173], v[42:45]
	v_mfma_f32_16x16x32_bf16 v[34:37], v[146:149], v[182:185], v[34:37]
	v_mfma_f32_16x16x32_bf16 v[26:29], v[154:157], v[182:185], v[26:29]
	v_mfma_f32_16x16x32_bf16 v[18:21], v[146:149], v[190:193], v[18:21]
	v_mfma_f32_16x16x32_bf16 v[10:13], v[154:157], v[190:193], v[10:13]
	v_mfma_f32_16x16x32_bf16 v[62:65], v[150:153], v[166:169], v[62:65]
	v_mfma_f32_16x16x32_bf16 v[58:61], v[158:161], v[166:169], v[58:61]
	v_mfma_f32_16x16x32_bf16 v[50:53], v[150:153], v[174:177], v[50:53]
	v_mfma_f32_16x16x32_bf16 v[42:45], v[158:161], v[174:177], v[42:45]
	v_mfma_f32_16x16x32_bf16 v[34:37], v[150:153], v[186:189], v[34:37]
	v_mfma_f32_16x16x32_bf16 v[26:29], v[158:161], v[186:189], v[26:29]
	v_mfma_f32_16x16x32_bf16 v[18:21], v[150:153], v[194:197], v[18:21]
	v_mfma_f32_16x16x32_bf16 v[10:13], v[158:161], v[194:197], v[10:13]
	s_setprio 0
	s_barrier
	s_add_u32 s20, s22, 0x18080
	s_addc_u32 s21, s23, 0
	s_mov_b32 m0, s60
	v_lshl_add_u64 v[146:147], s[20:21], 0, v[0:1]
	global_load_lds_dwordx4 v[146:147], off
	v_lshl_add_u64 v[146:147], s[20:21], 0, v[134:135]
	s_mov_b32 m0, s68
	s_nop 0
	global_load_lds_dwordx4 v[146:147], off
	s_waitcnt vmcnt(6)
	s_barrier
	s_setprio 1
	v_mfma_f32_16x16x32_bf16 v[54:57], v[198:201], v[162:165], v[54:57]
	v_mfma_f32_16x16x32_bf16 v[46:49], v[206:209], v[162:165], v[46:49]
	v_mfma_f32_16x16x32_bf16 v[38:41], v[198:201], v[170:173], v[38:41]
	v_mfma_f32_16x16x32_bf16 v[30:33], v[206:209], v[170:173], v[30:33]
	v_mfma_f32_16x16x32_bf16 v[22:25], v[198:201], v[182:185], v[22:25]
	v_mfma_f32_16x16x32_bf16 v[14:17], v[206:209], v[182:185], v[14:17]
	v_mfma_f32_16x16x32_bf16 v[6:9], v[198:201], v[190:193], v[6:9]
	v_mfma_f32_16x16x32_bf16 v[2:5], v[206:209], v[190:193], v[2:5]
	v_mfma_f32_16x16x32_bf16 v[54:57], v[202:205], v[166:169], v[54:57]
	v_mfma_f32_16x16x32_bf16 v[46:49], v[210:213], v[166:169], v[46:49]
	v_mfma_f32_16x16x32_bf16 v[38:41], v[202:205], v[174:177], v[38:41]
	v_mfma_f32_16x16x32_bf16 v[30:33], v[210:213], v[174:177], v[30:33]
	v_mfma_f32_16x16x32_bf16 v[22:25], v[202:205], v[186:189], v[22:25]
	v_mfma_f32_16x16x32_bf16 v[14:17], v[210:213], v[186:189], v[14:17]
	v_mfma_f32_16x16x32_bf16 v[6:9], v[202:205], v[194:197], v[6:9]
	v_mfma_f32_16x16x32_bf16 v[2:5], v[210:213], v[194:197], v[2:5]
	s_setprio 0
	s_add_i32 s94, s94, 2
	s_add_u32 s92, s92, 0x100
	s_addc_u32 s93, s93, 0
	s_cmp_gt_u32 s94, 3
	s_mov_b64 s[20:21], s[6:7]
	s_barrier
	s_cbranch_scc0 .LBB0_1052
	v_lshl_add_u32 v140, s89, 8, v144
	v_lshl_add_u32 v145, s90, 8, v141
	v_cmp_gt_u32_e32 vcc, s63, v140
	s_and_saveexec_b64 s[6:7], vcc
	s_cbranch_execz .LBB0_1055
	v_cvt_pk_bf16_f32 v126, v126, v127
	v_cvt_pk_bf16_f32 v127, v128, v129
	v_cvt_pk_bf16_f32 v128, v122, v123
	v_cvt_pk_bf16_f32 v129, v124, v125
	v_mad_u64_u32 v[122:123], s[20:21], v145, s63, v[140:141]
	v_mov_b32_e32 v123, v1
	v_lshl_add_u64 v[122:123], v[122:123], 1, s[10:11]
	global_store_dwordx4 v[122:123], v[126:129], off
.LBB0_1055:
	s_or_b64 exec, exec, s[6:7]
	v_add_u32_e32 v122, 0x80, v140
	v_cmp_gt_u32_e64 s[6:7], s63, v122
	s_and_saveexec_b64 s[20:21], s[6:7]
	v_readlane_b32 s76, v255, 8
	s_mov_b32 s92, 0x3b2aaaab
	v_readlane_b32 s77, v255, 9
	s_mov_b32 s93, 0x3c800000
	s_mul_hi_i32 s94, s64, 0x2d80
	s_cbranch_execz .LBB0_1070
	v_cvt_pk_bf16_f32 v118, v118, v119
	v_cvt_pk_bf16_f32 v119, v120, v121
	v_cvt_pk_bf16_f32 v120, v110, v111
	v_cvt_pk_bf16_f32 v121, v112, v113
	v_mad_u64_u32 v[110:111], s[22:23], v145, s63, v[122:123]
	v_mov_b32_e32 v111, v1
	v_lshl_add_u64 v[110:111], v[110:111], 1, s[10:11]
	global_store_dwordx4 v[110:111], v[118:121], off
	s_or_b64 exec, exec, s[20:21]
	v_or_b32_e32 v110, 16, v145
	s_and_saveexec_b64 s[20:21], vcc
	s_cbranch_execnz .LBB0_1071

.LBB0_1090:
	s_or_b64 exec, exec, s[6:7]
	v_lshlrev_b32_e32 v134, 5, v130
	s_waitcnt lgkmcnt(0)
	v_or_b32_e32 v138, v134, v133
	v_lshlrev_b32_e32 v130, 2, v138
	s_barrier
	global_load_dword v139, v130, s[44:45]
	global_load_dword v140, v130, s[44:45] offset:64
	v_lshl_add_u32 v147, v131, 2, v219
	ds_read_b128 v[154:157], v147
	ds_read_b128 v[158:161], v147 offset:16
	ds_read_b128 v[162:165], v147 offset:32
	ds_read_b128 v[166:169], v147 offset:48
	s_mov_b32 s2, 0x358637bd
	s_waitcnt lgkmcnt(3)
	v_mov_b32_e32 v131, v154
	s_waitcnt lgkmcnt(2)
	v_mov_b32_e32 v130, v158
	v_mov_b32_e32 v154, v159
	v_pk_add_f32 v[130:131], v[130:131], v[154:155]
	v_mov_b32_e32 v144, v160
	v_mov_b32_e32 v145, v156
	v_pk_add_f32 v[130:131], v[144:145], v[130:131]
	v_mov_b32_e32 v156, v161
	v_pk_add_f32 v[144:145], v[156:157], v[130:131]
	v_mov_b64_e32 v[130:131], s[2:3]
	v_pk_fma_f32 v[144:145], v[144:145], s[74:75], v[130:131] op_sel_hi:[1,0,0]
	s_waitcnt lgkmcnt(0)
	v_mov_b32_e32 v154, v168
	v_mul_f32_e32 v141, 0x4b800000, v145
	v_cmp_gt_f32_e64 s[6:7], s91, v145
	v_cmp_gt_f32_e32 vcc, s91, v144
	v_mov_b32_e32 v155, v164
	v_cndmask_b32_e64 v141, v145, v141, s[6:7]
	v_rsq_f32_e32 v141, v141
	v_mov_b32_e32 v145, v162
	v_mov_b32_e32 v162, v167
	v_mov_b32_e32 v164, v169
	v_mul_f32_e32 v142, 0x45800000, v141
	v_cndmask_b32_e64 v141, v141, v142, s[6:7]
	v_lshl_add_u32 v148, v148, 4, v219
	v_lshlrev_b32_e32 v0, 8, v0
	s_mul_i32 s2, s14, 0x3fc00
	v_and_b32_e32 v0, 0x3000, v0
	v_cvt_pk_bf16_f32 v62, v62, v63
	v_cvt_pk_bf16_f32 v63, v64, v65
	v_cvt_pk_bf16_f32 v58, v58, v59
	v_cvt_pk_bf16_f32 v59, v60, v61
	v_cvt_pk_bf16_f32 v54, v54, v55
	v_cvt_pk_bf16_f32 v55, v56, v57
	v_cvt_pk_bf16_f32 v50, v50, v51
	v_cvt_pk_bf16_f32 v51, v52, v53
	v_cvt_pk_bf16_f32 v46, v46, v47
	v_cvt_pk_bf16_f32 v47, v48, v49
	v_cvt_pk_bf16_f32 v42, v42, v43
	v_cvt_pk_bf16_f32 v43, v44, v45
	s_waitcnt vmcnt(0)
	v_mul_f32_e32 v142, v140, v141
	v_mul_f32_e32 v126, v126, v142
	v_mul_f32_e32 v142, 0x4b800000, v144
	v_cndmask_b32_e32 v142, v144, v142, vcc
	v_rsq_f32_e32 v142, v142
	v_cvt_pk_bf16_f32 v38, v38, v39
	v_mul_f32_e32 v144, 0x45800000, v142
	v_cndmask_b32_e32 v142, v142, v144, vcc
	v_mul_f32_e32 v144, v140, v142
	v_mul_f32_e32 v127, v127, v144
	v_mov_b32_e32 v144, v166
	v_pk_add_f32 v[144:145], v[144:145], v[162:163]
	v_pk_add_f32 v[144:145], v[154:155], v[144:145]
	v_pk_add_f32 v[144:145], v[164:165], v[144:145]
	v_pk_fma_f32 v[154:155], v[144:145], s[74:75], v[130:131] op_sel_hi:[1,0,0]
	v_cvt_pk_bf16_f32 v39, v40, v41
	v_mul_f32_e32 v144, 0x4b800000, v155
	v_cmp_gt_f32_e64 s[6:7], s91, v155
	v_cmp_gt_f32_e32 vcc, s91, v154
	s_nop 1
	v_cndmask_b32_e64 v144, v155, v144, s[6:7]
	v_rsq_f32_e32 v144, v144
	v_cvt_pk_bf16_f32 v34, v34, v35
	v_mul_f32_e32 v145, 0x45800000, v144
	v_cndmask_b32_e64 v144, v144, v145, s[6:7]
	v_mul_f32_e32 v145, v140, v144
	v_mul_f32_e32 v128, v128, v145
	v_mul_f32_e32 v145, 0x4b800000, v154
	v_cndmask_b32_e32 v145, v154, v145, vcc
	v_rsq_f32_e32 v145, v145
	s_nop 0
	v_mul_f32_e32 v154, 0x45800000, v145
	v_cndmask_b32_e32 v145, v145, v154, vcc
	v_mul_f32_e32 v154, v140, v145
	v_mul_f32_e32 v129, v129, v154
	ds_read_b128 v[154:157], v148
	ds_read_b128 v[158:161], v147 offset:272
	v_cvt_pk_bf16_f32 v35, v36, v37
	s_waitcnt lgkmcnt(1)
	v_mov_b32_e32 v163, v154
	s_waitcnt lgkmcnt(0)
	v_mov_b32_e32 v162, v158
	v_mov_b32_e32 v154, v159
	v_pk_add_f32 v[154:155], v[162:163], v[154:155]
	v_mov_b32_e32 v158, v160
	v_mov_b32_e32 v159, v156
	v_pk_add_f32 v[154:155], v[158:159], v[154:155]
	v_mov_b32_e32 v156, v161
	v_pk_add_f32 v[154:155], v[156:157], v[154:155]
	v_pk_fma_f32 v[154:155], v[154:155], s[74:75], v[130:131] op_sel_hi:[1,0,0]
	v_cvt_pk_bf16_f32 v26, v26, v27
	v_mul_f32_e32 v148, 0x4b800000, v155
	v_cmp_gt_f32_e64 s[6:7], s91, v155
	v_cmp_gt_f32_e32 vcc, s91, v154
	s_nop 1
	v_cndmask_b32_e64 v148, v155, v148, s[6:7]
	v_rsq_f32_e32 v148, v148
	v_cvt_pk_bf16_f32 v27, v28, v29
	v_mul_f32_e32 v155, 0x45800000, v148
	v_cndmask_b32_e64 v155, v148, v155, s[6:7]
	v_mul_f32_e32 v148, v139, v155
	v_mul_f32_e32 v148, v118, v148
	v_mul_f32_e32 v118, v140, v155
	v_mul_f32_e32 v118, v122, v118
	v_mul_f32_e32 v122, 0x4b800000, v154
	v_cndmask_b32_e32 v122, v154, v122, vcc
	v_rsq_f32_e32 v122, v122
	s_nop 0
	v_mul_f32_e32 v154, 0x45800000, v122
	v_cndmask_b32_e32 v154, v122, v154, vcc
	v_mul_f32_e32 v122, v139, v154
	v_mul_f32_e32 v122, v119, v122
	v_mul_f32_e32 v119, v140, v154
	ds_read_b128 v[154:157], v147 offset:288
	ds_read_b128 v[158:161], v147 offset:304
	v_mul_f32_e32 v119, v123, v119
	v_cvt_pk_bf16_f32 v18, v18, v19
	s_waitcnt lgkmcnt(1)
	v_mov_b32_e32 v163, v154
	s_waitcnt lgkmcnt(0)
	v_mov_b32_e32 v162, v158
	v_mov_b32_e32 v154, v159
	v_pk_add_f32 v[154:155], v[162:163], v[154:155]
	v_mov_b32_e32 v158, v160
	v_mov_b32_e32 v159, v156
	v_pk_add_f32 v[154:155], v[158:159], v[154:155]
	v_mov_b32_e32 v156, v161
	v_pk_add_f32 v[154:155], v[156:157], v[154:155]
	v_pk_fma_f32 v[154:155], v[154:155], s[74:75], v[130:131] op_sel_hi:[1,0,0]
	v_mul_f32_e32 v123, 0x4b800000, v155
	v_cmp_gt_f32_e64 s[6:7], s91, v155
	v_cmp_gt_f32_e32 vcc, s91, v154
	v_cvt_pk_bf16_f32 v19, v20, v21
	v_cndmask_b32_e64 v123, v155, v123, s[6:7]
	v_rsq_f32_e32 v123, v123
	s_nop 0
	v_mul_f32_e32 v155, 0x45800000, v123
	v_cndmask_b32_e64 v155, v123, v155, s[6:7]
	v_mul_f32_e32 v123, v139, v155
	v_mul_f32_e32 v123, v120, v123
	v_mul_f32_e32 v120, v140, v155
	v_mul_f32_e32 v120, v124, v120
	v_mul_f32_e32 v124, 0x4b800000, v154
	v_cndmask_b32_e32 v124, v154, v124, vcc
	v_rsq_f32_e32 v124, v124
	v_cvt_pk_bf16_f32 v10, v10, v11
	v_mul_f32_e32 v154, 0x45800000, v124
	v_cndmask_b32_e32 v154, v124, v154, vcc
	v_mul_f32_e32 v124, v139, v154
	v_mul_f32_e32 v124, v121, v124
	v_mul_f32_e32 v121, v140, v154
	v_mul_f32_e32 v121, v125, v121
	v_lshl_add_u32 v125, v153, 4, v219
	ds_read_b128 v[154:157], v125
	ds_read_b128 v[158:161], v147 offset:528
	v_cvt_pk_bf16_f32 v11, v12, v13
	s_waitcnt lgkmcnt(1)
	v_mov_b32_e32 v163, v154
	s_waitcnt lgkmcnt(0)
	v_mov_b32_e32 v162, v158
	v_mov_b32_e32 v154, v159
	v_pk_add_f32 v[154:155], v[162:163], v[154:155]
	v_mov_b32_e32 v158, v160
	v_mov_b32_e32 v159, v156
	v_pk_add_f32 v[154:155], v[158:159], v[154:155]
	v_mov_b32_e32 v156, v161
	v_pk_add_f32 v[154:155], v[156:157], v[154:155]
	v_pk_fma_f32 v[154:155], v[154:155], s[74:75], v[130:131] op_sel_hi:[1,0,0]
	v_mul_f32_e32 v125, 0x4b800000, v155
	v_cmp_gt_f32_e64 s[6:7], s91, v155
	v_cmp_gt_f32_e32 vcc, s91, v154
	v_cvt_pk_bf16_f32 v2, v2, v3
	v_cndmask_b32_e64 v125, v155, v125, s[6:7]
	v_rsq_f32_e32 v125, v125
	s_nop 0
	v_mul_f32_e32 v153, 0x45800000, v125
	v_cndmask_b32_e64 v153, v125, v153, s[6:7]
	v_mul_f32_e32 v125, v139, v153
	v_mul_f32_e32 v125, v110, v125
	v_mul_f32_e32 v110, v140, v153
	v_mul_f32_e32 v110, v114, v110
	v_mul_f32_e32 v114, 0x4b800000, v154
	v_cndmask_b32_e32 v114, v154, v114, vcc
	ds_read_b128 v[154:157], v147 offset:544
	ds_read_b128 v[158:161], v147 offset:560
	v_rsq_f32_e32 v114, v114
	v_cvt_pk_bf16_f32 v3, v4, v5
	s_add_i32 s3, s3, s33
	s_waitcnt lgkmcnt(1)
	v_mov_b32_e32 v163, v154
	s_waitcnt lgkmcnt(0)
	v_mov_b32_e32 v162, v158
	v_mov_b32_e32 v154, v159
	v_mul_f32_e32 v153, 0x45800000, v114
	v_pk_add_f32 v[154:155], v[162:163], v[154:155]
	v_mov_b32_e32 v158, v160
	v_mov_b32_e32 v159, v156
	v_cndmask_b32_e32 v153, v114, v153, vcc
	v_pk_add_f32 v[154:155], v[158:159], v[154:155]
	v_mov_b32_e32 v156, v161
	v_mul_f32_e32 v114, v139, v153
	v_pk_add_f32 v[154:155], v[156:157], v[154:155]
	v_mul_f32_e32 v114, v111, v114
	v_mul_f32_e32 v111, v140, v153
	v_pk_fma_f32 v[154:155], v[154:155], s[74:75], v[130:131] op_sel_hi:[1,0,0]
	v_mul_f32_e32 v111, v115, v111
	v_mul_f32_e32 v115, 0x4b800000, v155
	v_cmp_gt_f32_e64 s[6:7], s91, v155
	v_cmp_gt_f32_e32 vcc, s91, v154
	s_nop 0
	v_cndmask_b32_e64 v115, v155, v115, s[6:7]
	v_rsq_f32_e32 v115, v115
	s_nop 0
	v_mul_f32_e32 v153, 0x45800000, v115
	v_cndmask_b32_e64 v153, v115, v153, s[6:7]
	v_mul_f32_e32 v115, v139, v153
	v_mul_f32_e32 v115, v112, v115
	v_mul_f32_e32 v112, v140, v153
	v_mul_f32_e32 v112, v116, v112
	v_mul_f32_e32 v116, 0x4b800000, v154
	v_cndmask_b32_e32 v116, v154, v116, vcc
	v_rsq_f32_e32 v116, v116
	s_nop 0
	v_mul_f32_e32 v153, 0x45800000, v116
	v_cndmask_b32_e32 v153, v116, v153, vcc
	v_mul_f32_e32 v116, v139, v153
	v_mul_f32_e32 v116, v113, v116
	v_mul_f32_e32 v113, v140, v153
	v_mul_f32_e32 v113, v117, v113
	v_lshl_add_u32 v117, v152, 4, v219
	ds_read_b128 v[152:155], v117
	ds_read_b128 v[156:159], v147 offset:784
	s_waitcnt lgkmcnt(1)
	v_mov_b32_e32 v161, v152
	s_waitcnt lgkmcnt(0)
	v_mov_b32_e32 v160, v156
	v_mov_b32_e32 v152, v157
	v_pk_add_f32 v[152:153], v[160:161], v[152:153]
	v_mov_b32_e32 v156, v158
	v_mov_b32_e32 v157, v154
	v_pk_add_f32 v[152:153], v[156:157], v[152:153]
	v_mov_b32_e32 v154, v159
	v_pk_add_f32 v[152:153], v[154:155], v[152:153]
	s_nop 0
	v_pk_fma_f32 v[152:153], v[152:153], s[74:75], v[130:131] op_sel_hi:[1,0,0]
	s_nop 0
	v_mul_f32_e32 v117, 0x4b800000, v153
	v_cmp_gt_f32_e64 s[6:7], s91, v153
	v_cmp_gt_f32_e32 vcc, s91, v152
	s_nop 0
	v_cndmask_b32_e64 v117, v153, v117, s[6:7]
	v_rsq_f32_e32 v117, v117
	s_nop 0
	v_mul_f32_e32 v153, 0x45800000, v117
	v_cndmask_b32_e64 v153, v117, v153, s[6:7]
	v_mul_f32_e32 v117, v139, v153
	v_mul_f32_e32 v117, v102, v117
	v_mul_f32_e32 v102, v140, v153
	v_mul_f32_e32 v102, v106, v102
	v_mul_f32_e32 v106, 0x4b800000, v152
	v_cndmask_b32_e32 v106, v152, v106, vcc
	v_rsq_f32_e32 v106, v106
	s_nop 0
	v_mul_f32_e32 v152, 0x45800000, v106
	v_cndmask_b32_e32 v152, v106, v152, vcc
	v_mul_f32_e32 v106, v139, v152
	v_mul_f32_e32 v106, v103, v106
	v_mul_f32_e32 v103, v140, v152
	ds_read_b128 v[152:155], v147 offset:800
	ds_read_b128 v[156:159], v147 offset:816
	v_mul_f32_e32 v103, v107, v103
	s_waitcnt lgkmcnt(1)
	v_mov_b32_e32 v161, v152
	s_waitcnt lgkmcnt(0)
	v_mov_b32_e32 v160, v156
	v_mov_b32_e32 v152, v157
	v_pk_add_f32 v[152:153], v[160:161], v[152:153]
	v_mov_b32_e32 v156, v158
	v_mov_b32_e32 v157, v154
	v_pk_add_f32 v[152:153], v[156:157], v[152:153]
	v_mov_b32_e32 v154, v159
	v_pk_add_f32 v[152:153], v[154:155], v[152:153]
	s_nop 0
	v_pk_fma_f32 v[152:153], v[152:153], s[74:75], v[130:131] op_sel_hi:[1,0,0]
	s_nop 0
	v_mul_f32_e32 v107, 0x4b800000, v153
	v_cmp_gt_f32_e64 s[6:7], s91, v153
	v_cmp_gt_f32_e32 vcc, s91, v152
	s_nop 0
	v_cndmask_b32_e64 v107, v153, v107, s[6:7]
	v_rsq_f32_e32 v107, v107
	s_nop 0
	v_mul_f32_e32 v153, 0x45800000, v107
	v_cndmask_b32_e64 v153, v107, v153, s[6:7]
	v_mul_f32_e32 v107, v139, v153
	v_mul_f32_e32 v107, v104, v107
	v_mul_f32_e32 v104, v140, v153
	v_mul_f32_e32 v104, v108, v104
	v_mul_f32_e32 v108, 0x4b800000, v152
	v_cndmask_b32_e32 v108, v152, v108, vcc
	v_rsq_f32_e32 v108, v108
	s_nop 0
	v_mul_f32_e32 v152, 0x45800000, v108
	v_cndmask_b32_e32 v152, v108, v152, vcc
	v_mul_f32_e32 v108, v139, v152
	v_mul_f32_e32 v108, v105, v108
	v_mul_f32_e32 v105, v140, v152
	v_mul_f32_e32 v105, v109, v105
	v_lshl_add_u32 v109, v151, 4, v219
	ds_read_b128 v[152:155], v109
	ds_read_b128 v[156:159], v147 offset:2064
	s_waitcnt lgkmcnt(1)
	v_mov_b32_e32 v161, v152
	s_waitcnt lgkmcnt(0)
	v_mov_b32_e32 v160, v156
	v_mov_b32_e32 v152, v157
	v_pk_add_f32 v[152:153], v[160:161], v[152:153]
	v_mov_b32_e32 v156, v158
	v_mov_b32_e32 v157, v154
	v_pk_add_f32 v[152:153], v[156:157], v[152:153]
	v_mov_b32_e32 v154, v159
	v_pk_add_f32 v[152:153], v[154:155], v[152:153]
	s_nop 0
	v_pk_fma_f32 v[152:153], v[152:153], s[74:75], v[130:131] op_sel_hi:[1,0,0]
	s_nop 0
	v_mul_f32_e32 v109, 0x4b800000, v153
	v_cmp_gt_f32_e64 s[6:7], s91, v153
	v_cmp_gt_f32_e32 vcc, s91, v152
	s_nop 0
	v_cndmask_b32_e64 v109, v153, v109, s[6:7]
	v_rsq_f32_e32 v109, v109
	s_nop 0
	v_mul_f32_e32 v151, 0x45800000, v109
	v_cndmask_b32_e64 v151, v109, v151, s[6:7]
	v_mul_f32_e32 v109, v139, v151
	v_mul_f32_e32 v109, v94, v109
	v_mul_f32_e32 v94, v140, v151
	v_mul_f32_e32 v94, v98, v94
	v_mul_f32_e32 v98, 0x4b800000, v152
	v_cndmask_b32_e32 v98, v152, v98, vcc
	ds_read_b128 v[152:155], v147 offset:2080
	ds_read_b128 v[156:159], v147 offset:2096
	v_rsq_f32_e32 v98, v98
	s_waitcnt lgkmcnt(1)
	v_mov_b32_e32 v161, v152
	s_waitcnt lgkmcnt(0)
	v_mov_b32_e32 v160, v156
	v_mov_b32_e32 v152, v157
	v_mul_f32_e32 v151, 0x45800000, v98
	v_pk_add_f32 v[152:153], v[160:161], v[152:153]
	v_mov_b32_e32 v156, v158
	v_mov_b32_e32 v157, v154
	v_cndmask_b32_e32 v151, v98, v151, vcc
	v_pk_add_f32 v[152:153], v[156:157], v[152:153]
	v_mov_b32_e32 v154, v159
	v_mul_f32_e32 v98, v139, v151
	v_pk_add_f32 v[152:153], v[154:155], v[152:153]
	v_mul_f32_e32 v98, v95, v98
	v_mul_f32_e32 v95, v140, v151
	v_pk_fma_f32 v[152:153], v[152:153], s[74:75], v[130:131] op_sel_hi:[1,0,0]
	v_mul_f32_e32 v95, v99, v95
	v_mul_f32_e32 v99, 0x4b800000, v153
	v_cmp_gt_f32_e64 s[6:7], s91, v153
	v_cmp_gt_f32_e32 vcc, s91, v152
	s_nop 0
	v_cndmask_b32_e64 v99, v153, v99, s[6:7]
	v_rsq_f32_e32 v99, v99
	s_nop 0
	v_mul_f32_e32 v151, 0x45800000, v99
	v_cndmask_b32_e64 v151, v99, v151, s[6:7]
	v_mul_f32_e32 v99, v139, v151
	v_mul_f32_e32 v99, v96, v99
	v_mul_f32_e32 v96, v140, v151
	v_mul_f32_e32 v96, v100, v96
	v_mul_f32_e32 v100, 0x4b800000, v152
	v_cndmask_b32_e32 v100, v152, v100, vcc
	v_rsq_f32_e32 v100, v100
	s_nop 0
	v_mul_f32_e32 v151, 0x45800000, v100
	v_cndmask_b32_e32 v151, v100, v151, vcc
	v_mul_f32_e32 v100, v139, v151
	v_mul_f32_e32 v100, v97, v100
	v_mul_f32_e32 v97, v140, v151
	v_mul_f32_e32 v97, v101, v97
	v_lshl_add_u32 v101, v150, 4, v219
	ds_read_b128 v[150:153], v101
	ds_read_b128 v[154:157], v147 offset:2320
	s_waitcnt lgkmcnt(1)
	v_mov_b32_e32 v159, v150
	s_waitcnt lgkmcnt(0)
	v_mov_b32_e32 v158, v154
	v_mov_b32_e32 v150, v155
	v_pk_add_f32 v[150:151], v[158:159], v[150:151]
	v_mov_b32_e32 v154, v156
	v_mov_b32_e32 v155, v152
	v_pk_add_f32 v[150:151], v[154:155], v[150:151]
	v_mov_b32_e32 v152, v157
	v_pk_add_f32 v[150:151], v[152:153], v[150:151]
	s_nop 0
	v_pk_fma_f32 v[150:151], v[150:151], s[74:75], v[130:131] op_sel_hi:[1,0,0]
	s_nop 0
	v_mul_f32_e32 v101, 0x4b800000, v151
	v_cmp_gt_f32_e64 s[6:7], s91, v151
	v_cmp_gt_f32_e32 vcc, s91, v150
	s_nop 0
	v_cndmask_b32_e64 v101, v151, v101, s[6:7]
	v_rsq_f32_e32 v101, v101
	s_nop 0
	v_mul_f32_e32 v151, 0x45800000, v101
	v_cndmask_b32_e64 v151, v101, v151, s[6:7]
	v_mul_f32_e32 v101, v139, v151
	v_mul_f32_e32 v101, v86, v101
	v_mul_f32_e32 v86, v140, v151
	v_mul_f32_e32 v86, v90, v86
	v_mul_f32_e32 v90, 0x4b800000, v150
	v_cndmask_b32_e32 v90, v150, v90, vcc
	v_rsq_f32_e32 v90, v90
	s_nop 0
	v_mul_f32_e32 v150, 0x45800000, v90
	v_cndmask_b32_e32 v150, v90, v150, vcc
	v_mul_f32_e32 v90, v139, v150
	v_mul_f32_e32 v90, v87, v90
	v_mul_f32_e32 v87, v140, v150
	ds_read_b128 v[150:153], v147 offset:2336
	ds_read_b128 v[154:157], v147 offset:2352
	v_mul_f32_e32 v87, v91, v87
	s_waitcnt lgkmcnt(1)
	v_mov_b32_e32 v159, v150
	s_waitcnt lgkmcnt(0)
	v_mov_b32_e32 v158, v154
	v_mov_b32_e32 v150, v155
	v_pk_add_f32 v[150:151], v[158:159], v[150:151]
	v_mov_b32_e32 v154, v156
	v_mov_b32_e32 v155, v152
	v_pk_add_f32 v[150:151], v[154:155], v[150:151]
	v_mov_b32_e32 v152, v157
	v_pk_add_f32 v[150:151], v[152:153], v[150:151]
	s_nop 0
	v_pk_fma_f32 v[150:151], v[150:151], s[74:75], v[130:131] op_sel_hi:[1,0,0]
	s_nop 0
	v_mul_f32_e32 v91, 0x4b800000, v151
	v_cmp_gt_f32_e64 s[6:7], s91, v151
	v_cmp_gt_f32_e32 vcc, s91, v150
	s_nop 0
	v_cndmask_b32_e64 v91, v151, v91, s[6:7]
	v_rsq_f32_e32 v91, v91
	s_nop 0
	v_mul_f32_e32 v151, 0x45800000, v91
	v_cndmask_b32_e64 v151, v91, v151, s[6:7]
	v_mul_f32_e32 v91, v139, v151
	v_mul_f32_e32 v91, v88, v91
	v_mul_f32_e32 v88, v140, v151
	v_mul_f32_e32 v88, v92, v88
	v_mul_f32_e32 v92, 0x4b800000, v150
	v_cndmask_b32_e32 v92, v150, v92, vcc
	v_rsq_f32_e32 v92, v92
	s_nop 0
	v_mul_f32_e32 v150, 0x45800000, v92
	v_cndmask_b32_e32 v150, v92, v150, vcc
	v_mul_f32_e32 v92, v139, v150
	v_mul_f32_e32 v92, v89, v92
	v_mul_f32_e32 v89, v140, v150
	v_mul_f32_e32 v89, v93, v89
	v_lshl_add_u32 v93, v149, 4, v219
	ds_read_b128 v[150:153], v93
	ds_read_b128 v[154:157], v147 offset:2576
	s_waitcnt lgkmcnt(1)
	v_mov_b32_e32 v159, v150
	s_waitcnt lgkmcnt(0)
	v_mov_b32_e32 v158, v154
	v_mov_b32_e32 v150, v155
	v_pk_add_f32 v[150:151], v[158:159], v[150:151]
	v_mov_b32_e32 v154, v156
	v_mov_b32_e32 v155, v152
	v_pk_add_f32 v[150:151], v[154:155], v[150:151]
	v_mov_b32_e32 v152, v157
	v_pk_add_f32 v[150:151], v[152:153], v[150:151]
	s_nop 0
	v_pk_fma_f32 v[150:151], v[150:151], s[74:75], v[130:131] op_sel_hi:[1,0,0]
	s_nop 0
	v_mul_f32_e32 v93, 0x4b800000, v151
	v_cmp_gt_f32_e64 s[6:7], s91, v151
	v_cmp_gt_f32_e32 vcc, s91, v150
	s_nop 0
	v_cndmask_b32_e64 v93, v151, v93, s[6:7]
	v_rsq_f32_e32 v93, v93
	s_nop 0
	v_mul_f32_e32 v149, 0x45800000, v93
	v_cndmask_b32_e64 v149, v93, v149, s[6:7]
	v_mul_f32_e32 v93, v139, v149
	v_mul_f32_e32 v93, v78, v93
	v_mul_f32_e32 v78, v140, v149
	v_mul_f32_e32 v78, v82, v78
	v_mul_f32_e32 v82, 0x4b800000, v150
	v_cndmask_b32_e32 v82, v150, v82, vcc
	ds_read_b128 v[150:153], v147 offset:2592
	ds_read_b128 v[154:157], v147 offset:2608
	v_rsq_f32_e32 v82, v82
	s_waitcnt lgkmcnt(1)
	v_mov_b32_e32 v159, v150
	s_waitcnt lgkmcnt(0)
	v_mov_b32_e32 v158, v154
	v_mov_b32_e32 v150, v155
	v_mul_f32_e32 v149, 0x45800000, v82
	v_pk_add_f32 v[150:151], v[158:159], v[150:151]
	v_mov_b32_e32 v154, v156
	v_mov_b32_e32 v155, v152
	v_cndmask_b32_e32 v149, v82, v149, vcc
	v_pk_add_f32 v[150:151], v[154:155], v[150:151]
	v_mov_b32_e32 v152, v157
	v_mul_f32_e32 v82, v139, v149
	v_pk_add_f32 v[150:151], v[152:153], v[150:151]
	v_mul_f32_e32 v82, v79, v82
	v_mul_f32_e32 v79, v140, v149
	v_pk_fma_f32 v[150:151], v[150:151], s[74:75], v[130:131] op_sel_hi:[1,0,0]
	v_mul_f32_e32 v79, v83, v79
	v_mul_f32_e32 v83, 0x4b800000, v151
	v_cmp_gt_f32_e64 s[6:7], s91, v151
	v_cmp_gt_f32_e32 vcc, s91, v150
	s_nop 0
	v_cndmask_b32_e64 v83, v151, v83, s[6:7]
	v_rsq_f32_e32 v83, v83
	s_nop 0
	v_mul_f32_e32 v149, 0x45800000, v83
	v_cndmask_b32_e64 v149, v83, v149, s[6:7]
	v_mul_f32_e32 v83, v139, v149
	v_mul_f32_e32 v83, v80, v83
	v_mul_f32_e32 v80, v140, v149
	v_mul_f32_e32 v80, v84, v80
	v_mul_f32_e32 v84, 0x4b800000, v150
	v_cndmask_b32_e32 v84, v150, v84, vcc
	v_rsq_f32_e32 v84, v84
	s_nop 0
	v_mul_f32_e32 v149, 0x45800000, v84
	v_cndmask_b32_e32 v149, v84, v149, vcc
	v_mul_f32_e32 v84, v139, v149
	v_mul_f32_e32 v84, v81, v84
	v_mul_f32_e32 v81, v140, v149
	v_mul_f32_e32 v81, v85, v81
	v_lshl_add_u32 v85, v146, 4, v219
	ds_read_b128 v[150:153], v85
	ds_read_b128 v[154:157], v147 offset:2832
	s_waitcnt lgkmcnt(1)
	v_mov_b32_e32 v159, v150
	s_waitcnt lgkmcnt(0)
	v_mov_b32_e32 v158, v154
	v_mov_b32_e32 v150, v155
	v_pk_add_f32 v[150:151], v[158:159], v[150:151]
	v_mov_b32_e32 v154, v156
	v_mov_b32_e32 v155, v152
	v_pk_add_f32 v[150:151], v[154:155], v[150:151]
	v_mov_b32_e32 v152, v157
	v_pk_add_f32 v[150:151], v[152:153], v[150:151]
	s_nop 0
	v_pk_fma_f32 v[150:151], v[150:151], s[74:75], v[130:131] op_sel_hi:[1,0,0]
	s_nop 0
	v_mul_f32_e32 v85, 0x4b800000, v151
	v_cmp_gt_f32_e64 s[6:7], s91, v151
	v_cmp_gt_f32_e32 vcc, s91, v150
	s_nop 0
	v_cndmask_b32_e64 v85, v151, v85, s[6:7]
	v_rsq_f32_e32 v85, v85
	s_nop 0
	v_mul_f32_e32 v146, 0x45800000, v85
	v_cndmask_b32_e64 v146, v85, v146, s[6:7]
	v_mul_f32_e32 v85, v139, v146
	v_mul_f32_e32 v85, v70, v85
	v_mul_f32_e32 v70, v140, v146
	v_mul_f32_e32 v74, v74, v70
	v_mul_f32_e32 v70, 0x4b800000, v150
	v_cndmask_b32_e32 v70, v150, v70, vcc
	v_rsq_f32_e32 v70, v70
	ds_read_b128 v[150:153], v147 offset:2848
	v_mul_f32_e32 v146, 0x45800000, v70
	v_cndmask_b32_e32 v70, v70, v146, vcc
	v_mul_f32_e32 v146, v139, v70
	v_mul_f32_e32 v70, v140, v70
	v_mul_f32_e32 v146, v71, v146
	v_mul_f32_e32 v71, v75, v70
	v_lshl_add_u32 v70, v143, 2, v219
	ds_read_b128 v[154:157], v70
	s_waitcnt lgkmcnt(1)
	v_mov_b32_e32 v159, v150
	s_waitcnt lgkmcnt(0)
	v_mov_b32_e32 v158, v154
	v_mov_b32_e32 v150, v155
	v_pk_add_f32 v[150:151], v[158:159], v[150:151]
	v_mov_b32_e32 v154, v156
	v_mov_b32_e32 v155, v152
	v_pk_add_f32 v[150:151], v[154:155], v[150:151]
	v_mov_b32_e32 v152, v157
	v_pk_add_f32 v[150:151], v[152:153], v[150:151]
	s_nop 0
	v_pk_fma_f32 v[150:151], v[150:151], s[74:75], v[130:131] op_sel_hi:[1,0,0]
	s_nop 0
	v_mul_f32_e32 v70, 0x4b800000, v151
	v_cmp_gt_f32_e64 s[6:7], s91, v151
	v_cmp_gt_f32_e32 vcc, s91, v150
	s_nop 0
	v_cndmask_b32_e64 v70, v151, v70, s[6:7]
	v_rsq_f32_e32 v70, v70
	s_nop 0
	v_mul_f32_e32 v75, 0x45800000, v70
	v_cndmask_b32_e64 v70, v70, v75, s[6:7]
	v_mul_f32_e32 v75, v139, v70
	v_mul_f32_e32 v70, v140, v70
	v_mul_f32_e32 v130, v72, v75
	v_mul_f32_e32 v75, v76, v70
	v_mul_f32_e32 v70, 0x4b800000, v150
	v_cndmask_b32_e32 v70, v150, v70, vcc
	v_rsq_f32_e32 v70, v70
	s_nop 0
	v_mul_f32_e32 v72, 0x45800000, v70
	v_cndmask_b32_e32 v70, v70, v72, vcc
	v_mul_f32_e32 v72, v139, v70
	v_mul_f32_e32 v76, v73, v72
	v_mul_f32_e32 v72, v139, v141
	v_mul_f32_e32 v66, v66, v72
	v_cvt_pk_bf16_f32 v72, v66, s0
	v_mul_f32_e32 v66, v139, v142
	v_mul_f32_e32 v131, v67, v66
	v_mul_f32_e32 v66, v139, v144
	v_mul_f32_e32 v68, v68, v66
	v_mul_f32_e32 v66, v139, v145
	v_mul_f32_e32 v69, v69, v66
	v_lshlrev_b32_e32 v66, 10, v135
	v_and_b32_e32 v66, 0xffff0000, v66
	v_add3_u32 v0, s2, v66, v0
	v_or_b32_e32 v0, v138, v0
	v_add_u32_e32 v0, s23, v0
	v_lshl_add_u64 v[66:67], v[0:1], 1, s[8:9]
	global_store_short v[66:67], v72, off
	v_add_u32_e32 v66, 0x400, v0
	v_mov_b32_e32 v67, v1
	v_cvt_pk_bf16_f32 v72, v131, s0
	v_lshl_add_u64 v[66:67], v[66:67], 1, s[8:9]
	global_store_short v[66:67], v72, off
	v_add_u32_e32 v66, 0x800, v0
	v_mov_b32_e32 v67, v1
	v_cvt_pk_bf16_f32 v68, v68, s0
	v_lshl_add_u64 v[66:67], v[66:67], 1, s[8:9]
	global_store_short v[66:67], v68, off
	v_add_u32_e32 v66, 0xc00, v0
	v_mov_b32_e32 v67, v1
	v_cvt_pk_bf16_f32 v68, v69, s0
	v_lshl_add_u64 v[66:67], v[66:67], 1, s[8:9]
	global_store_short v[66:67], v68, off
	v_add_u32_e32 v66, 16, v0
	v_mov_b32_e32 v67, v1
	v_cvt_pk_bf16_f32 v68, v126, s0
	v_lshl_add_u64 v[66:67], v[66:67], 1, s[8:9]
	global_store_short v[66:67], v68, off
	v_add_u32_e32 v66, 0x410, v0
	v_mov_b32_e32 v67, v1
	v_cvt_pk_bf16_f32 v68, v127, s0
	v_lshl_add_u64 v[66:67], v[66:67], 1, s[8:9]
	global_store_short v[66:67], v68, off
	v_add_u32_e32 v66, 0x810, v0
	v_mov_b32_e32 v67, v1
	v_cvt_pk_bf16_f32 v68, v128, s0
	v_lshl_add_u64 v[66:67], v[66:67], 1, s[8:9]
	global_store_short v[66:67], v68, off
	v_add_u32_e32 v66, 0xc10, v0
	v_mov_b32_e32 v67, v1
	v_cvt_pk_bf16_f32 v68, v129, s0
	v_lshl_add_u64 v[66:67], v[66:67], 1, s[8:9]
	global_store_short v[66:67], v68, off
	v_add_u32_e32 v66, 0x4000, v0
	v_mov_b32_e32 v67, v1
	v_cvt_pk_bf16_f32 v68, v148, s0
	v_lshl_add_u64 v[66:67], v[66:67], 1, s[8:9]
	global_store_short v[66:67], v68, off
	v_add_u32_e32 v66, 0x4400, v0
	v_mov_b32_e32 v67, v1
	v_cvt_pk_bf16_f32 v68, v122, s0
	v_lshl_add_u64 v[66:67], v[66:67], 1, s[8:9]
	global_store_short v[66:67], v68, off
	v_add_u32_e32 v66, 0x4800, v0
	v_mov_b32_e32 v67, v1
	v_cvt_pk_bf16_f32 v68, v123, s0
	v_lshl_add_u64 v[66:67], v[66:67], 1, s[8:9]
	global_store_short v[66:67], v68, off
	v_add_u32_e32 v66, 0x4c00, v0
	v_mov_b32_e32 v67, v1
	v_cvt_pk_bf16_f32 v68, v124, s0
	v_lshl_add_u64 v[66:67], v[66:67], 1, s[8:9]
	global_store_short v[66:67], v68, off
	v_add_u32_e32 v66, 0x4010, v0
	v_mov_b32_e32 v67, v1
	v_cvt_pk_bf16_f32 v68, v118, s0
	v_lshl_add_u64 v[66:67], v[66:67], 1, s[8:9]
	global_store_short v[66:67], v68, off
	v_add_u32_e32 v66, 0x4410, v0
	v_mov_b32_e32 v67, v1
	v_cvt_pk_bf16_f32 v68, v119, s0
	v_lshl_add_u64 v[66:67], v[66:67], 1, s[8:9]
	global_store_short v[66:67], v68, off
	v_add_u32_e32 v66, 0x4810, v0
	v_mov_b32_e32 v67, v1
	v_cvt_pk_bf16_f32 v68, v120, s0
	v_lshl_add_u64 v[66:67], v[66:67], 1, s[8:9]
	global_store_short v[66:67], v68, off
	v_add_u32_e32 v66, 0x4c10, v0
	v_mov_b32_e32 v67, v1
	v_cvt_pk_bf16_f32 v68, v121, s0
	v_lshl_add_u64 v[66:67], v[66:67], 1, s[8:9]
	global_store_short v[66:67], v68, off
	v_add_u32_e32 v66, 0x8000, v0
	v_mov_b32_e32 v67, v1
	v_cvt_pk_bf16_f32 v69, v125, s0
	v_lshl_add_u64 v[66:67], v[66:67], 1, s[8:9]
	global_store_short v[66:67], v69, off
	v_add_u32_e32 v66, 0x8400, v0
	v_mov_b32_e32 v67, v1
	v_cvt_pk_bf16_f32 v69, v114, s0
	v_lshl_add_u64 v[66:67], v[66:67], 1, s[8:9]
	global_store_short v[66:67], v69, off
	v_add_u32_e32 v66, 0x8800, v0
	v_mov_b32_e32 v67, v1
	v_cvt_pk_bf16_f32 v69, v115, s0
	v_lshl_add_u64 v[66:67], v[66:67], 1, s[8:9]
	global_store_short v[66:67], v69, off
	v_add_u32_e32 v66, 0x8c00, v0
	v_mov_b32_e32 v67, v1
	v_cvt_pk_bf16_f32 v69, v116, s0
	v_lshl_add_u64 v[66:67], v[66:67], 1, s[8:9]
	global_store_short v[66:67], v69, off
	v_add_u32_e32 v66, 0x8010, v0
	v_mov_b32_e32 v67, v1
	v_cvt_pk_bf16_f32 v69, v110, s0
	v_lshl_add_u64 v[66:67], v[66:67], 1, s[8:9]
	global_store_short v[66:67], v69, off
	v_add_u32_e32 v66, 0x8410, v0
	v_mov_b32_e32 v67, v1
	v_cvt_pk_bf16_f32 v69, v111, s0
	v_lshl_add_u64 v[66:67], v[66:67], 1, s[8:9]
	global_store_short v[66:67], v69, off
	v_add_u32_e32 v66, 0x8810, v0
	v_mov_b32_e32 v67, v1
	v_cvt_pk_bf16_f32 v69, v112, s0
	v_lshl_add_u64 v[66:67], v[66:67], 1, s[8:9]
	global_store_short v[66:67], v69, off
	v_add_u32_e32 v66, 0x8c10, v0
	v_mov_b32_e32 v67, v1
	v_cvt_pk_bf16_f32 v69, v113, s0
	v_lshl_add_u64 v[66:67], v[66:67], 1, s[8:9]
	v_add_u32_e32 v110, 0xc000, v0
	v_mov_b32_e32 v111, v1
	global_store_short v[66:67], v69, off
	v_cvt_pk_bf16_f32 v67, v117, s0
	v_lshl_add_u64 v[110:111], v[110:111], 1, s[8:9]
	global_store_short v[110:111], v67, off
	v_add_u32_e32 v110, 0xc400, v0
	v_mov_b32_e32 v111, v1
	v_cvt_pk_bf16_f32 v67, v106, s0
	v_lshl_add_u64 v[110:111], v[110:111], 1, s[8:9]
	global_store_short v[110:111], v67, off
	v_cvt_pk_bf16_f32 v67, v107, s0
	v_add_u32_e32 v106, 0xc800, v0
	v_mov_b32_e32 v107, v1
	v_lshl_add_u64 v[106:107], v[106:107], 1, s[8:9]
	global_store_short v[106:107], v67, off
	v_add_u32_e32 v106, 0xcc00, v0
	v_mov_b32_e32 v107, v1
	v_cvt_pk_bf16_f32 v67, v108, s0
	v_lshl_add_u64 v[106:107], v[106:107], 1, s[8:9]
	global_store_short v[106:107], v67, off
	v_add_u32_e32 v106, 0xc010, v0
	v_mov_b32_e32 v107, v1
	v_cvt_pk_bf16_f32 v67, v102, s0
	v_lshl_add_u64 v[106:107], v[106:107], 1, s[8:9]
	global_store_short v[106:107], v67, off
	v_cvt_pk_bf16_f32 v67, v103, s0
	v_add_u32_e32 v102, 0xc410, v0
	v_mov_b32_e32 v103, v1
	v_lshl_add_u64 v[102:103], v[102:103], 1, s[8:9]
	global_store_short v[102:103], v67, off
	v_add_u32_e32 v102, 0xc810, v0
	v_mov_b32_e32 v103, v1
	v_cvt_pk_bf16_f32 v67, v104, s0
	v_lshl_add_u64 v[102:103], v[102:103], 1, s[8:9]
	v_mul_f32_e32 v70, v140, v70
	global_store_short v[102:103], v67, off
	v_add_u32_e32 v102, 0xcc10, v0
	v_mov_b32_e32 v103, v1
	v_mul_f32_e32 v73, v77, v70
	v_lshl_add_u32 v77, s14, 8, v136
	v_cvt_pk_bf16_f32 v67, v105, s0
	v_lshl_add_u64 v[102:103], v[102:103], 1, s[8:9]
	v_or_b32_e32 v70, v77, v137
	global_store_short v[102:103], v67, off
	v_ashrrev_i32_e32 v67, 31, v77
	v_add_u32_e32 v77, v70, v67
	v_xor_b32_e32 v77, v77, v67
	v_mul_hi_u32 v102, v77, v132
	v_mul_lo_u32 v103, v102, s22
	v_sub_u32_e32 v77, v77, v103
	v_cmp_le_u32_e32 vcc, s22, v77
	v_add_u32_e32 v103, 1, v102
	v_xor_b32_e32 v69, s24, v67
	v_cndmask_b32_e32 v102, v102, v103, vcc
	v_subrev_u32_e32 v103, s22, v77
	v_cndmask_b32_e32 v77, v77, v103, vcc
	v_cmp_le_u32_e32 vcc, s22, v77
	v_add_u32_e32 v77, 1, v102
	s_lshl_b32 s2, s14, 10
	v_cndmask_b32_e32 v77, v102, v77, vcc
	v_xor_b32_e32 v77, v77, v69
	v_mul_lo_u32 v64, v77, s88
	v_add3_u32 v64, v64, v134, v133
	v_mul_i32_i24_e32 v77, 0x3ff, v69
	v_sub_u32_e32 v64, v64, v77
	v_subrev_u32_e32 v64, s2, v64
	v_add_u32_e32 v102, s23, v64
	v_add_u32_e32 v60, 16, v102
	v_mad_u64_u32 v[64:65], s[6:7], v102, s5, v[70:71]
	v_mad_u64_u32 v[60:61], s[6:7], v60, s5, v[70:71]
	v_mov_b32_e32 v65, v1
	v_mov_b32_e32 v61, v1
	v_or_b32_e32 v72, 16, v70
	v_lshl_add_u64 v[64:65], v[64:65], 1, s[10:11]
	v_lshl_add_u64 v[60:61], v[60:61], 1, s[10:11]
	global_store_dwordx2 v[64:65], v[62:63], off
	global_store_dwordx2 v[60:61], v[58:59], off
	v_add_u32_e32 v58, v72, v67
	v_xor_b32_e32 v58, v58, v67
	v_mul_hi_u32 v59, v58, v132
	v_mul_lo_u32 v60, v59, s22
	v_sub_u32_e32 v58, v58, v60
	v_cmp_le_u32_e32 vcc, s22, v58
	v_add_u32_e32 v60, 1, v59
	v_or_b32_e32 v68, 32, v70
	v_cndmask_b32_e32 v59, v59, v60, vcc
	v_subrev_u32_e32 v60, s22, v58
	v_cndmask_b32_e32 v58, v58, v60, vcc
	v_cmp_le_u32_e32 vcc, s22, v58
	v_add_u32_e32 v58, 1, v59
	v_or_b32_e32 v66, 48, v70
	v_cndmask_b32_e32 v58, v59, v58, vcc
	v_xor_b32_e32 v58, v58, v69
	v_mul_lo_u32 v56, v58, s88
	v_add3_u32 v56, v56, v134, v133
	v_sub_u32_e32 v56, v56, v77
	v_subrev_u32_e32 v56, s2, v56
	v_add_u32_e32 v58, s23, v56
	v_add_u32_e32 v52, 16, v58
	v_mad_u64_u32 v[56:57], s[6:7], v58, s5, v[72:73]
	v_mad_u64_u32 v[52:53], s[6:7], v52, s5, v[72:73]
	v_mov_b32_e32 v57, v1
	v_mov_b32_e32 v53, v1
	v_lshl_add_u64 v[56:57], v[56:57], 1, s[10:11]
	v_lshl_add_u64 v[52:53], v[52:53], 1, s[10:11]
	global_store_dwordx2 v[56:57], v[54:55], off
	global_store_dwordx2 v[52:53], v[50:51], off
	v_add_u32_e32 v50, v68, v67
	v_xor_b32_e32 v50, v50, v67
	v_mul_hi_u32 v51, v50, v132
	v_mul_lo_u32 v52, v51, s22
	v_sub_u32_e32 v50, v50, v52
	v_cmp_le_u32_e32 vcc, s22, v50
	v_add_u32_e32 v52, 1, v51
	s_nop 0
	v_cndmask_b32_e32 v51, v51, v52, vcc
	v_subrev_u32_e32 v52, s22, v50
	v_cndmask_b32_e32 v50, v50, v52, vcc
	v_cmp_le_u32_e32 vcc, s22, v50
	v_add_u32_e32 v50, 1, v51
	s_nop 0
	v_cndmask_b32_e32 v50, v51, v50, vcc
	v_xor_b32_e32 v50, v50, v69
	v_mul_lo_u32 v48, v50, s88
	v_add3_u32 v48, v48, v134, v133
	v_sub_u32_e32 v48, v48, v77
	v_subrev_u32_e32 v48, s2, v48
	v_add_u32_e32 v50, s23, v48
	v_add_u32_e32 v44, 16, v50
	v_mad_u64_u32 v[48:49], s[6:7], v50, s5, v[68:69]
	v_mad_u64_u32 v[44:45], s[6:7], v44, s5, v[68:69]
	v_mov_b32_e32 v49, v1
	v_mov_b32_e32 v45, v1
	v_lshl_add_u64 v[48:49], v[48:49], 1, s[10:11]
	v_lshl_add_u64 v[44:45], v[44:45], 1, s[10:11]
	global_store_dwordx2 v[48:49], v[46:47], off
	global_store_dwordx2 v[44:45], v[42:43], off
	v_add_u32_e32 v42, v66, v67
	v_xor_b32_e32 v42, v42, v67
	v_mul_hi_u32 v43, v42, v132
	v_mul_lo_u32 v44, v43, s22
	v_sub_u32_e32 v42, v42, v44
	v_cmp_le_u32_e32 vcc, s22, v42
	v_add_u32_e32 v44, 1, v43
	s_nop 0
	v_cndmask_b32_e32 v43, v43, v44, vcc
	v_subrev_u32_e32 v44, s22, v42
	v_cndmask_b32_e32 v42, v42, v44, vcc
	v_cmp_le_u32_e32 vcc, s22, v42
	v_add_u32_e32 v42, 1, v43
	s_nop 0
	v_cndmask_b32_e32 v42, v43, v42, vcc
	v_xor_b32_e32 v42, v42, v69
	v_mul_lo_u32 v40, v42, s88
	v_add3_u32 v40, v40, v134, v133
	v_sub_u32_e32 v40, v40, v77
	v_subrev_u32_e32 v40, s2, v40
	v_add_u32_e32 v42, s23, v40
	v_add_u32_e32 v36, 16, v42
	v_mad_u64_u32 v[40:41], s[6:7], v42, s5, v[66:67]
	v_mad_u64_u32 v[36:37], s[6:7], v36, s5, v[66:67]
	v_mov_b32_e32 v41, v1
	v_mov_b32_e32 v37, v1
	v_lshl_add_u64 v[40:41], v[40:41], 1, s[10:11]
	v_lshl_add_u64 v[36:37], v[36:37], 1, s[10:11]
	global_store_dwordx2 v[40:41], v[38:39], off
	global_store_dwordx2 v[36:37], v[34:35], off
	v_add_u32_e32 v34, 0x20000, v0
	v_mov_b32_e32 v35, v1
	v_cvt_pk_bf16_f32 v36, v109, s0
	v_lshl_add_u64 v[34:35], v[34:35], 1, s[8:9]
	global_store_short v[34:35], v36, off
	v_add_u32_e32 v34, 0x20400, v0
	v_mov_b32_e32 v35, v1
	v_cvt_pk_bf16_f32 v36, v98, s0
	v_lshl_add_u64 v[34:35], v[34:35], 1, s[8:9]
	global_store_short v[34:35], v36, off
	v_add_u32_e32 v34, 0x20800, v0
	v_mov_b32_e32 v35, v1
	v_cvt_pk_bf16_f32 v36, v99, s0
	v_lshl_add_u64 v[34:35], v[34:35], 1, s[8:9]
	global_store_short v[34:35], v36, off
	v_add_u32_e32 v34, 0x20c00, v0
	v_mov_b32_e32 v35, v1
	v_cvt_pk_bf16_f32 v36, v100, s0
	v_lshl_add_u64 v[34:35], v[34:35], 1, s[8:9]
	global_store_short v[34:35], v36, off
	v_add_u32_e32 v34, 0x20010, v0
	v_mov_b32_e32 v35, v1
	v_cvt_pk_bf16_f32 v36, v94, s0
	v_lshl_add_u64 v[34:35], v[34:35], 1, s[8:9]
	global_store_short v[34:35], v36, off
	v_add_u32_e32 v34, 0x20410, v0
	v_mov_b32_e32 v35, v1
	v_cvt_pk_bf16_f32 v36, v95, s0
	v_lshl_add_u64 v[34:35], v[34:35], 1, s[8:9]
	global_store_short v[34:35], v36, off
	v_add_u32_e32 v34, 0x20810, v0
	v_mov_b32_e32 v35, v1
	v_cvt_pk_bf16_f32 v36, v96, s0
	v_lshl_add_u64 v[34:35], v[34:35], 1, s[8:9]
	global_store_short v[34:35], v36, off
	v_add_u32_e32 v34, 0x20c10, v0
	v_mov_b32_e32 v35, v1
	v_cvt_pk_bf16_f32 v36, v97, s0
	v_lshl_add_u64 v[34:35], v[34:35], 1, s[8:9]
	global_store_short v[34:35], v36, off
	v_add_u32_e32 v34, 0x24000, v0
	v_mov_b32_e32 v35, v1
	v_cvt_pk_bf16_f32 v36, v101, s0
	v_lshl_add_u64 v[34:35], v[34:35], 1, s[8:9]
	global_store_short v[34:35], v36, off
	v_add_u32_e32 v34, 0x24400, v0
	v_mov_b32_e32 v35, v1
	v_cvt_pk_bf16_f32 v36, v90, s0
	v_lshl_add_u64 v[34:35], v[34:35], 1, s[8:9]
	global_store_short v[34:35], v36, off
	v_add_u32_e32 v34, 0x24800, v0
	v_mov_b32_e32 v35, v1
	v_cvt_pk_bf16_f32 v36, v91, s0
	v_lshl_add_u64 v[34:35], v[34:35], 1, s[8:9]
	global_store_short v[34:35], v36, off
	v_add_u32_e32 v34, 0x24c00, v0
	v_mov_b32_e32 v35, v1
	v_cvt_pk_bf16_f32 v36, v92, s0
	v_lshl_add_u64 v[34:35], v[34:35], 1, s[8:9]
	global_store_short v[34:35], v36, off
	v_add_u32_e32 v34, 0x24010, v0
	v_mov_b32_e32 v35, v1
	v_cvt_pk_bf16_f32 v36, v86, s0
	v_lshl_add_u64 v[34:35], v[34:35], 1, s[8:9]
	global_store_short v[34:35], v36, off
	v_add_u32_e32 v34, 0x24410, v0
	v_mov_b32_e32 v35, v1
	v_cvt_pk_bf16_f32 v36, v87, s0
	v_lshl_add_u64 v[34:35], v[34:35], 1, s[8:9]
	global_store_short v[34:35], v36, off
	v_add_u32_e32 v34, 0x24810, v0
	v_mov_b32_e32 v35, v1
	v_cvt_pk_bf16_f32 v36, v88, s0
	v_lshl_add_u64 v[34:35], v[34:35], 1, s[8:9]
	global_store_short v[34:35], v36, off
	v_add_u32_e32 v34, 0x24c10, v0
	v_mov_b32_e32 v35, v1
	v_cvt_pk_bf16_f32 v36, v89, s0
	v_lshl_add_u64 v[34:35], v[34:35], 1, s[8:9]
	global_store_short v[34:35], v36, off
	v_add_u32_e32 v34, 0x28000, v0
	v_mov_b32_e32 v35, v1
	v_cvt_pk_bf16_f32 v37, v93, s0
	v_lshl_add_u64 v[34:35], v[34:35], 1, s[8:9]
	global_store_short v[34:35], v37, off
	v_add_u32_e32 v34, 0x28400, v0
	v_mov_b32_e32 v35, v1
	v_cvt_pk_bf16_f32 v37, v82, s0
	v_lshl_add_u64 v[34:35], v[34:35], 1, s[8:9]
	global_store_short v[34:35], v37, off
	v_add_u32_e32 v34, 0x28800, v0
	v_mov_b32_e32 v35, v1
	v_cvt_pk_bf16_f32 v37, v83, s0
	v_lshl_add_u64 v[34:35], v[34:35], 1, s[8:9]
	global_store_short v[34:35], v37, off
	v_add_u32_e32 v34, 0x28c00, v0
	v_mov_b32_e32 v35, v1
	v_cvt_pk_bf16_f32 v37, v84, s0
	v_lshl_add_u64 v[34:35], v[34:35], 1, s[8:9]
	global_store_short v[34:35], v37, off
	v_add_u32_e32 v34, 0x28010, v0
	v_mov_b32_e32 v35, v1
	v_cvt_pk_bf16_f32 v37, v78, s0
	v_lshl_add_u64 v[34:35], v[34:35], 1, s[8:9]
	global_store_short v[34:35], v37, off
	v_add_u32_e32 v34, 0x28410, v0
	v_mov_b32_e32 v35, v1
	v_cvt_pk_bf16_f32 v37, v79, s0
	v_lshl_add_u64 v[34:35], v[34:35], 1, s[8:9]
	global_store_short v[34:35], v37, off
	v_add_u32_e32 v34, 0x28810, v0
	v_mov_b32_e32 v35, v1
	v_cvt_pk_bf16_f32 v37, v80, s0
	v_lshl_add_u64 v[34:35], v[34:35], 1, s[8:9]
	global_store_short v[34:35], v37, off
	v_add_u32_e32 v34, 0x28c10, v0
	v_mov_b32_e32 v35, v1
	v_cvt_pk_bf16_f32 v37, v81, s0
	v_lshl_add_u64 v[34:35], v[34:35], 1, s[8:9]
	v_add_u32_e32 v42, 0x2c000, v0
	v_mov_b32_e32 v43, v1
	global_store_short v[34:35], v37, off
	v_cvt_pk_bf16_f32 v35, v85, s0
	v_lshl_add_u64 v[42:43], v[42:43], 1, s[8:9]
	global_store_short v[42:43], v35, off
	v_add_u32_e32 v42, 0x2c400, v0
	v_mov_b32_e32 v43, v1
	v_cvt_pk_bf16_f32 v35, v146, s0
	v_lshl_add_u64 v[42:43], v[42:43], 1, s[8:9]
	global_store_short v[42:43], v35, off
	v_add_u32_e32 v42, 0x2c800, v0
	v_mov_b32_e32 v43, v1
	v_cvt_pk_bf16_f32 v35, v130, s0
	v_lshl_add_u64 v[42:43], v[42:43], 1, s[8:9]
	global_store_short v[42:43], v35, off
	v_add_u32_e32 v42, 0x2cc00, v0
	v_mov_b32_e32 v43, v1
	v_cvt_pk_bf16_f32 v35, v76, s0
	v_lshl_add_u64 v[42:43], v[42:43], 1, s[8:9]
	global_store_short v[42:43], v35, off
	v_add_u32_e32 v42, 0x2c010, v0
	v_mov_b32_e32 v43, v1
	v_cvt_pk_bf16_f32 v35, v74, s0
	v_lshl_add_u64 v[42:43], v[42:43], 1, s[8:9]
	global_store_short v[42:43], v35, off
	v_add_u32_e32 v42, 0x2c410, v0
	v_mov_b32_e32 v43, v1
	v_cvt_pk_bf16_f32 v35, v71, s0
	v_lshl_add_u64 v[42:43], v[42:43], 1, s[8:9]
	global_store_short v[42:43], v35, off
	v_add_u32_e32 v42, 0x2c810, v0
	v_mov_b32_e32 v43, v1
	v_add_u32_e32 v40, 0x80, v70
	v_cvt_pk_bf16_f32 v35, v75, s0
	v_lshl_add_u64 v[42:43], v[42:43], 1, s[8:9]
	v_add_u32_e32 v0, 0x2cc10, v0
	global_store_short v[42:43], v35, off
	v_cvt_pk_bf16_f32 v35, v73, s0
	v_lshl_add_u64 v[42:43], v[0:1], 1, s[8:9]
	v_cvt_pk_bf16_f32 v0, v30, s0
	v_ashrrev_i32_e32 v30, 31, v40
	global_store_short v[42:43], v35, off
	v_xor_b32_e32 v35, s24, v30
	v_sub_u32_e32 v30, 0, v40
	v_max_i32_e32 v30, v40, v30
	v_mul_hi_u32 v37, v30, v132
	v_mul_lo_u32 v39, v37, s22
	v_sub_u32_e32 v30, v30, v39
	v_cmp_le_u32_e32 vcc, s22, v30
	v_add_u32_e32 v39, 1, v37
	v_add_u32_e32 v38, 0x90, v70
	v_cndmask_b32_e32 v37, v37, v39, vcc
	v_subrev_u32_e32 v39, s22, v30
	v_cndmask_b32_e32 v30, v30, v39, vcc
	v_cmp_le_u32_e32 vcc, s22, v30
	v_add_u32_e32 v30, 1, v37
	v_add_u32_e32 v36, 0xa0, v70
	v_cndmask_b32_e32 v30, v37, v30, vcc
	v_xor_b32_e32 v37, v30, v35
	v_cvt_pk_bf16_f32 v30, v31, s0
	v_lshlrev_b32_e32 v30, 16, v30
	v_or_b32_sdwa v30, v30, v0 dst_sel:DWORD dst_unused:UNUSED_PAD src0_sel:DWORD src1_sel:WORD_0
	v_cvt_pk_bf16_f32 v31, v32, v33
	v_mul_lo_u32 v0, v37, s88
	v_add3_u32 v0, v0, v134, v133
	v_mul_i32_i24_e32 v32, 0x3ff, v35
	v_sub_u32_e32 v0, v0, v32
	v_subrev_u32_e32 v0, s2, v0
	v_add_u32_e32 v0, s23, v0
	v_mad_u64_u32 v[32:33], s[6:7], v0, s5, v[40:41]
	v_add_u32_e32 v0, 16, v0
	v_mad_u64_u32 v[28:29], s[6:7], v0, s5, v[40:41]
	v_mov_b32_e32 v33, v1
	v_mov_b32_e32 v29, v1
	v_lshl_add_u64 v[32:33], v[32:33], 1, s[10:11]
	v_lshl_add_u64 v[28:29], v[28:29], 1, s[10:11]
	v_cvt_pk_bf16_f32 v0, v22, s0
	v_ashrrev_i32_e32 v22, 31, v38
	global_store_dwordx2 v[32:33], v[30:31], off
	global_store_dwordx2 v[28:29], v[26:27], off
	v_xor_b32_e32 v26, s24, v22
	v_sub_u32_e32 v22, 0, v38
	v_max_i32_e32 v22, v38, v22
	v_mul_hi_u32 v27, v22, v132
	v_mul_lo_u32 v28, v27, s22
	v_sub_u32_e32 v22, v22, v28
	v_cmp_le_u32_e32 vcc, s22, v22
	v_add_u32_e32 v28, 1, v27
	v_add_u32_e32 v34, 0xb0, v70
	v_cndmask_b32_e32 v27, v27, v28, vcc
	v_subrev_u32_e32 v28, s22, v22
	v_cndmask_b32_e32 v22, v22, v28, vcc
	v_cmp_le_u32_e32 vcc, s22, v22
	v_add_u32_e32 v22, 1, v27
	s_nop 0
	v_cndmask_b32_e32 v22, v27, v22, vcc
	v_xor_b32_e32 v27, v22, v26
	v_cvt_pk_bf16_f32 v22, v23, s0
	v_lshlrev_b32_e32 v22, 16, v22
	v_or_b32_sdwa v22, v22, v0 dst_sel:DWORD dst_unused:UNUSED_PAD src0_sel:DWORD src1_sel:WORD_0
	v_cvt_pk_bf16_f32 v23, v24, v25
	v_mul_lo_u32 v0, v27, s88
	v_add3_u32 v0, v0, v134, v133
	v_mul_i32_i24_e32 v24, 0x3ff, v26
	v_sub_u32_e32 v0, v0, v24
	v_subrev_u32_e32 v0, s2, v0
	v_add_u32_e32 v0, s23, v0
	v_mad_u64_u32 v[24:25], s[6:7], v0, s5, v[38:39]
	v_add_u32_e32 v0, 16, v0
	v_mad_u64_u32 v[20:21], s[6:7], v0, s5, v[38:39]
	v_mov_b32_e32 v25, v1
	v_mov_b32_e32 v21, v1
	v_lshl_add_u64 v[24:25], v[24:25], 1, s[10:11]
	v_lshl_add_u64 v[20:21], v[20:21], 1, s[10:11]
	v_cvt_pk_bf16_f32 v0, v14, s0
	v_ashrrev_i32_e32 v14, 31, v36
	global_store_dwordx2 v[24:25], v[22:23], off
	global_store_dwordx2 v[20:21], v[18:19], off
	v_xor_b32_e32 v18, s24, v14
	v_sub_u32_e32 v14, 0, v36
	v_max_i32_e32 v14, v36, v14
	v_mul_hi_u32 v19, v14, v132
	v_mul_lo_u32 v20, v19, s22
	v_sub_u32_e32 v14, v14, v20
	v_cmp_le_u32_e32 vcc, s22, v14
	v_add_u32_e32 v20, 1, v19
	s_nop 0
	v_cndmask_b32_e32 v19, v19, v20, vcc
	v_subrev_u32_e32 v20, s22, v14
	v_cndmask_b32_e32 v14, v14, v20, vcc
	v_cmp_le_u32_e32 vcc, s22, v14
	v_add_u32_e32 v14, 1, v19
	s_nop 0
	v_cndmask_b32_e32 v14, v19, v14, vcc
	v_xor_b32_e32 v19, v14, v18
	v_cvt_pk_bf16_f32 v14, v15, s0
	v_lshlrev_b32_e32 v14, 16, v14
	v_or_b32_sdwa v14, v14, v0 dst_sel:DWORD dst_unused:UNUSED_PAD src0_sel:DWORD src1_sel:WORD_0
	v_cvt_pk_bf16_f32 v15, v16, v17
	v_mul_lo_u32 v0, v19, s88
	v_add3_u32 v0, v0, v134, v133
	v_mul_i32_i24_e32 v16, 0x3ff, v18
	v_sub_u32_e32 v0, v0, v16
	v_subrev_u32_e32 v0, s2, v0
	v_add_u32_e32 v0, s23, v0
	v_mad_u64_u32 v[16:17], s[6:7], v0, s5, v[36:37]
	v_add_u32_e32 v0, 16, v0
	v_mad_u64_u32 v[12:13], s[6:7], v0, s5, v[36:37]
	v_mov_b32_e32 v17, v1
	v_mov_b32_e32 v13, v1
	v_lshl_add_u64 v[16:17], v[16:17], 1, s[10:11]
	v_lshl_add_u64 v[12:13], v[12:13], 1, s[10:11]
	v_cvt_pk_bf16_f32 v0, v6, s0
	v_ashrrev_i32_e32 v6, 31, v34
	global_store_dwordx2 v[16:17], v[14:15], off
	global_store_dwordx2 v[12:13], v[10:11], off
	v_xor_b32_e32 v10, s24, v6
	v_sub_u32_e32 v6, 0, v34
	v_max_i32_e32 v6, v34, v6
	v_mul_hi_u32 v11, v6, v132
	v_mul_lo_u32 v12, v11, s22
	v_sub_u32_e32 v6, v6, v12
	v_cmp_le_u32_e32 vcc, s22, v6
	v_add_u32_e32 v12, 1, v11
	s_nop 0
	v_cndmask_b32_e32 v11, v11, v12, vcc
	v_subrev_u32_e32 v12, s22, v6
	v_cndmask_b32_e32 v6, v6, v12, vcc
	v_cmp_le_u32_e32 vcc, s22, v6
	v_add_u32_e32 v6, 1, v11
	s_nop 0
	v_cndmask_b32_e32 v6, v11, v6, vcc
	v_xor_b32_e32 v11, v6, v10
	v_cvt_pk_bf16_f32 v6, v7, s0
	v_lshlrev_b32_e32 v6, 16, v6
	v_or_b32_sdwa v6, v6, v0 dst_sel:DWORD dst_unused:UNUSED_PAD src0_sel:DWORD src1_sel:WORD_0
	v_cvt_pk_bf16_f32 v7, v8, v9
	v_mul_lo_u32 v0, v11, s88
	v_add3_u32 v0, v0, v134, v133
	v_mul_i32_i24_e32 v8, 0x3ff, v10
	v_sub_u32_e32 v0, v0, v8
	v_subrev_u32_e32 v0, s2, v0
	v_add_u32_e32 v0, s23, v0
	v_mad_u64_u32 v[8:9], s[6:7], v0, s5, v[34:35]
	v_add_u32_e32 v0, 16, v0
	v_mad_u64_u32 v[4:5], s[6:7], v0, s5, v[34:35]
	v_mov_b32_e32 v9, v1
	v_mov_b32_e32 v5, v1
	s_add_i32 s23, s23, s25
	v_lshl_add_u64 v[8:9], v[8:9], 1, s[10:11]
	v_lshl_add_u64 v[4:5], v[4:5], 1, s[10:11]
	s_cmp_lt_i32 s3, s4
	global_store_dwordx2 v[8:9], v[6:7], off
	global_store_dwordx2 v[4:5], v[2:3], off
	s_cbranch_scc0 .LBB0_1161
